# combo10: tile-boundary overlap - last K-iteration stages the missing next-tile buffer, first K-iteration of later tiles skips its first vmcnt wait (on combo9)
# baseline (speedup 1.0000x reference)
; #define LAS __attribute__((address_space(3)))
; #define PG8_STAGE(bufoff, gbase, voff) do { _Pragma("unroll") for (int _i = 0; _i < 2; ++_i) \
;     __builtin_amdgcn_global_load_lds((const unsigned*)((const char*)(gbase) + (voff)[_i]), (LAS unsigned*)(lds + (bufoff) + ldsw + _i * 8192), 16, 0, 0); } while (0)
; #define PG8_BAR __builtin_amdgcn_s_barrier()
; template <class Epi, class Sched = StaticOrder>
; DI void gemm_phase(LAS unsigned char* lds, const Gemm g, const Sched& S, const Epi& E) {
;   const int tid = threadIdx.x, wid = __builtin_amdgcn_readfirstlane(tid >> 6), lane = tid & 63, wr = wid >> 2, wc = wid & 3, fr = lane & 15, fq = lane >> 4;
;   const int K = g.K, nt = K / BK;
;   unsigned voffA[2], voffB[2];
; #pragma unroll
;   for (int i = 0; i < 2; ++i) { int R, C; stage_rc(tid * 16 + i * 8192, R, C); const int Rb = Epi::PERM ? ((R & ~31) + perm32(R & 31)) : R;
;     voffA[i] = (unsigned)(R * K + C) * 2u; voffB[i] = (unsigned)(Rb * K + C) * 2u; }
;   const size_t kstep = (size_t)(BK * 2);
;   const size_t hstep = (size_t)HALF * K * 2;
;   const size_t tstep = 2 * hstep;
;   const unsigned ldsw = (unsigned)wid * 1024u;
;   const int aoff = lds_byte(wr * 64 + fr, fq * 8), boff = lds_byte(wc * 32 + fr, fq * 8);
;     ...
;   Unit cur, nxt; int ui = 0;
;   if (!S.next(0, cur)) return;
;   f32x4 acc[2][2][4][2];
; #pragma unroll
;   for (int a = 0; a < 2; ++a)
; #pragma unroll
;     for (int b = 0; b < 2; ++b)
; #pragma unroll
;       for (int m = 0; m < 4; ++m)
; #pragma unroll
;         for (int n = 0; n < 2; ++n) acc[a][b][m][n] = (f32x4){0.f, 0.f, 0.f, 0.f};
;   bf16x8 At[4][2], B0[2][2], B1[2][2];
;   const char* cA = (const char*)g.A + (size_t)cur.pm * tstep; const char* cB = (const char*)g.Bt + (size_t)cur.pn * tstep;
;   PG8_STAGE(PG8_SB(0, 0), cB, voffB); PG8_STAGE(PG8_SA(0, 0), cA, voffA); PG8_STAGE(PG8_SB(0, 1), cB + hstep, voffB); PG8_STAGE(PG8_SA(0, 1), cA + hstep, voffA);
;   if (wr == 1) PG8_BAR;
; DI void run_gemm(const Params& p, int id, unsigned char* smem) {
;     ...
;   S.init(g.M, g.N, (int)gridDim.x, __builtin_amdgcn_readfirstlane((int)((volatile LAS unsigned*)(LAS unsigned char*)(smem + 131072))[2]));
.LBB0_339:
	v_writelane_b32 v247, 1, 0
	s_add_i32 s0, 0, 0x20008
	v_mov_b32_e32 v0, s0
	ds_read_b32 v0, v0
	v_readfirstlane_b32 s27, v210
	s_waitcnt lgkmcnt(0)
	v_readfirstlane_b32 s25, v0
	s_cmpk_gt_i32 s25, 0x4bf
	s_cbranch_scc1 .LBB0_351
	v_lshrrev_b32_e32 v0, 5, v210
	v_lshrrev_b32_e32 v2, 1, v210
	v_and_b32_e32 v0, 4, v0
	v_bfe_u32 v1, v210, 2, 2
	v_and_b32_e32 v11, 24, v2
	v_or3_b32 v0, v0, v1, v11
	v_lshlrev_b32_e32 v1, 4, v210
	v_add_u32_e32 v8, 0x2000, v1
	v_lshrrev_b32_e32 v2, 7, v8
	s_movk_i32 s0, 0xe0
	v_and_b32_e32 v4, 32, v210
	s_add_u32 s33, s84, 0xc103600
	v_and_or_b32 v3, v2, s0, v0
	v_bitop3_b32 v9, v1, v4, 48 bitop3:0x6c
	v_and_b32_e32 v10, 64, v210
	v_bfe_u32 v12, v210, 2, 4
	s_movk_i32 s0, 0xf0
	s_addc_u32 s38, s85, 0
	v_or_b32_e32 v1, v9, v10
	v_and_or_b32 v2, v2, s0, v12
	s_add_u32 s39, s84, 0x3600
	v_lshl_or_b32 v138, v2, 12, v1
	v_lshrrev_b32_e32 v2, 3, v210
	s_movk_i32 s0, 0x60
	s_addc_u32 s40, s85, 0
	v_and_or_b32 v0, v2, s0, v0
	s_movk_i32 s0, 0x70
	s_ashr_i32 s46, s25, 31
	v_lshl_or_b32 v140, v0, 12, v1
	v_and_or_b32 v0, v2, s0, v12
	s_lshr_b32 s0, s46, 29
	s_add_i32 s0, s25, s0
	s_lshr_b32 s10, s27, 6
	s_ashr_i32 s2, s0, 3
	s_and_b32 s0, s0, -8
	s_lshr_b32 s1, s27, 8
	s_lshl_b32 s41, s10, 10
	s_sub_i32 s0, s25, s0
	s_cmp_lt_i32 s0, 0
	s_movk_i32 s47, 0x99
	s_cselect_b32 s3, s47, 0x98
	s_mul_i32 s0, s3, s0
	s_add_i32 s0, s0, s2
	s_mul_hi_i32 s2, s0, 0x6bca1af3
	s_lshr_b32 s3, s2, 31
	s_ashr_i32 s2, s2, 6
	s_add_i32 s2, s2, s3
	s_lshl_b32 s4, s2, 3
	s_sub_i32 s3, 64, s4
	s_min_u32 s5, s3, 8
	s_mulk_i32 s2, 0x98
	v_lshl_or_b32 v136, v3, 12, v1
	s_sub_i32 s6, s0, s2
	v_cvt_f32_ubyte0_e32 v3, s5
	v_cvt_f32_i32_e32 v2, s6
	v_rcp_iflag_f32_e32 v4, v3
	v_lshl_or_b32 v142, v0, 12, v1
	s_ashr_i32 s0, s6, 30
	s_or_b32 s0, s0, 1
	v_mul_f32_e32 v0, v2, v4
	v_trunc_f32_e32 v0, v0
	v_fma_f32 v1, -v0, v3, v2
	v_cvt_i32_f32_e32 v0, v0
	v_cmp_ge_f32_e64 s[2:3], |v1|, v3
	s_and_b64 s[2:3], s[2:3], exec
	s_cselect_b32 s0, s0, 0
	v_readfirstlane_b32 s2, v0
	s_add_i32 s0, s2, s0
	s_mul_i32 s2, s0, s5
	s_sub_i32 s2, s6, s2
	s_sext_i32_i16 s2, s2
	s_add_i32 s4, s4, s2
	s_ashr_i32 s5, s4, 31
	s_bfe_i64 s[6:7], s[0:1], 0x100000
	s_lshl_b64 s[2:3], s[4:5], 20
	s_lshl_b64 s[6:7], s[6:7], 20
	s_add_u32 s8, s39, s6
	s_addc_u32 s9, s40, s7
	s_add_i32 s48, s41, 0
	s_add_i32 m0, s48, 0x10000
	v_mov_b32_e32 v141, 0
	global_load_lds_dwordx4 v140, s[8:9]
	s_add_i32 m0, s48, 0x12000
	s_add_u32 s6, s33, s2
	global_load_lds_dwordx4 v136, s[8:9]
	s_addc_u32 s7, s38, s3
	s_mov_b32 m0, s48
	s_add_i32 s49, s48, 0x2000
	global_load_lds_dwordx4 v142, s[6:7]
	s_mov_b32 m0, s49
	s_add_u32 s2, s8, 0x80000
	global_load_lds_dwordx4 v138, s[6:7]
	s_addc_u32 s3, s9, 0
	s_add_i32 m0, s48, 0x14000
	v_mov_b32_e32 v137, v141
	global_load_lds_dwordx4 v140, s[2:3]
	s_add_i32 m0, s48, 0x16000
	v_mov_b32_e32 v143, v141
	global_load_lds_dwordx4 v136, s[2:3]
	s_add_u32 s2, s6, 0x80000
	s_addc_u32 s3, s7, 0
	s_add_i32 s50, s48, 0x4000
	s_mov_b32 m0, s50
	s_add_i32 s51, s48, 0x6000
	global_load_lds_dwordx4 v142, s[2:3]
	s_mov_b32 m0, s51
	v_mov_b32_e32 v139, v141
	global_load_lds_dwordx4 v138, s[2:3]
	v_lshl_add_u64 v[6:7], s[8:9], 0, v[140:141]
	v_lshl_add_u64 v[4:5], s[8:9], 0, v[136:137]
	v_lshl_add_u64 v[2:3], s[6:7], 0, v[142:143]
	s_cmp_lg_u32 s1, 1
	v_lshl_add_u64 v[0:1], s[6:7], 0, v[138:139]
	s_cbranch_scc1 .LBB0_342
	s_barrier

; #define PG8_STAGE(bufoff, gbase, voff) do { _Pragma("unroll") for (int _i = 0; _i < 2; ++_i) \
;     __builtin_amdgcn_global_load_lds((const unsigned*)((const char*)(gbase) + (voff)[_i]), (LAS unsigned*)(lds + (bufoff) + ldsw + _i * 8192), 16, 0, 0); } while (0)
; #define PG8_LDA(dst, b, h) do { _Pragma("unroll") for (int m = 0; m < 4; ++m) _Pragma("unroll") for (int k = 0; k < 2; ++k) dst[m][k] = *(const LAS bf16x8*)(lds + PG8_SA(b, h) + aoff + m * 2048 + k * 1024); } while (0)
; #define PG8_LDB(dst, b, h) do { _Pragma("unroll") for (int n = 0; n < 2; ++n) _Pragma("unroll") for (int k = 0; k < 2; ++k) dst[n][k] = *(const LAS bf16x8*)(lds + PG8_SB(b, h) + boff + n * 2048 + k * 1024); } while (0)
; #define PG8_MMA(ai, bj, At, Bt) do { __builtin_amdgcn_s_setprio(1); _Pragma("unroll") for (int m = 0; m < 4; ++m) _Pragma("unroll") for (int n = 0; n < 2; ++n) _Pragma("unroll") for (int k = 0; k < 2; ++k) \
;     acc[ai][bj][m][n] = __builtin_amdgcn_mfma_f32_16x16x32_bf16(Bt[n][k], At[m][k], acc[ai][bj][m][n], 0, 0, 0); __builtin_amdgcn_s_setprio(0); } while (0)
; #define PG8_WAIT_V(n) asm volatile("s_waitcnt vmcnt(" #n ")" ::: "memory")
; #define PG8_WAIT_L(n) asm volatile("s_waitcnt lgkmcnt(" #n ")" ::: "memory")
; #define PG8_BAR __builtin_amdgcn_s_barrier()
; #define PG8_SCHED __builtin_amdgcn_sched_barrier(0)
; template <class Epi, class Sched = StaticOrder>
; DI void gemm_phase(LAS unsigned char* lds, const Gemm g, const Sched& S, const Epi& E) {
;     ...
;     for (int t = 0; t < nt; t += 2) {
;       const bool last = (t == nt - 2);
;       const char* a1 = cA + (size_t)(t + 1) * kstep;
;       const char* a2 = last ? nA : cA + (size_t)(t + 2) * kstep; const char* b2 = last ? nB : cB + (size_t)(t + 2) * kstep;
;       const char* a3 = a2 + kstep; const char* b3 = b2 + kstep;
;       PG8_LDB(B0, 0, 0); PG8_SCHED; PG8_LDA(At, 0, 0); PG8_STAGE(PG8_SA(1, 1), a1 + hstep, voffA);
;       PG8_WAIT_L(8); PG8_BAR; PG8_WAIT_L(0); PG8_MMA(0, 0, At, B0); PG8_BAR; PG8_SCHED;
;       PG8_LDB(B1, 0, 1); PG8_STAGE(PG8_SB(0, 0), b2, voffB);
;       PG8_BAR; PG8_WAIT_L(0); PG8_MMA(0, 1, At, B1); PG8_BAR;
;       PG8_LDA(At, 0, 1); PG8_STAGE(PG8_SA(0, 0), a2, voffA);
;       PG8_BAR; PG8_WAIT_L(0); PG8_MMA(1, 0, At, B0); PG8_BAR; PG8_SCHED;
;       PG8_STAGE(PG8_SB(0, 1), b2 + hstep, voffB);
;       PG8_WAIT_V(6); PG8_BAR; PG8_MMA(1, 1, At, B1); PG8_BAR;
.LBB0_346:
	ds_read_b128 v[128:131], v173
	ds_read_b128 v[132:135], v173 offset:1024
	ds_read_b128 v[154:157], v173 offset:2048
	ds_read_b128 v[158:161], v173 offset:3072
	s_add_u32 s8, s6, 0xfff80080
	s_addc_u32 s9, s7, -1
	s_cmp_eq_u32 s52, 28
	s_cselect_b32 s11, s31, s9
	s_cselect_b32 s10, s42, s8
	s_cselect_b32 s9, s29, s45
	s_cselect_b32 s8, s43, s44
	s_add_i32 m0, s48, 0xc000
	ds_read_b128 v[162:165], v174
	ds_read_b128 v[166:169], v174 offset:1024
	ds_read_b128 v[178:181], v174 offset:2048
	ds_read_b128 v[182:185], v174 offset:3072
	ds_read_b128 v[186:189], v174 offset:4096
	ds_read_b128 v[190:193], v174 offset:5120
	ds_read_b128 v[194:197], v174 offset:6144
	ds_read_b128 v[198:201], v174 offset:7168
	global_load_lds_dwordx4 v146, s[6:7]
	s_add_i32 m0, s48, 0xe000
	s_nop 0
	global_load_lds_dwordx4 v148, s[6:7]
	s_waitcnt lgkmcnt(0)
	s_setprio 1
	s_barrier
	v_mfma_f32_16x16x32_bf16 v[124:127], v[128:131], v[162:165], v[124:127]
	v_mfma_f32_16x16x32_bf16 v[120:123], v[154:157], v[162:165], v[120:123]
	v_mfma_f32_16x16x32_bf16 v[108:111], v[128:131], v[178:181], v[108:111]
	v_mfma_f32_16x16x32_bf16 v[104:107], v[154:157], v[178:181], v[104:107]
	v_mfma_f32_16x16x32_bf16 v[100:103], v[128:131], v[186:189], v[100:103]
	v_mfma_f32_16x16x32_bf16 v[92:95], v[154:157], v[186:189], v[92:95]
	v_mfma_f32_16x16x32_bf16 v[84:87], v[128:131], v[194:197], v[84:87]
	v_mfma_f32_16x16x32_bf16 v[76:79], v[154:157], v[194:197], v[76:79]
	v_mfma_f32_16x16x32_bf16 v[124:127], v[132:135], v[166:169], v[124:127]
	v_mfma_f32_16x16x32_bf16 v[120:123], v[158:161], v[166:169], v[120:123]
	v_mfma_f32_16x16x32_bf16 v[108:111], v[132:135], v[182:185], v[108:111]
	v_mfma_f32_16x16x32_bf16 v[104:107], v[158:161], v[182:185], v[104:107]
	v_mfma_f32_16x16x32_bf16 v[100:103], v[132:135], v[190:193], v[100:103]
	v_mfma_f32_16x16x32_bf16 v[92:95], v[158:161], v[190:193], v[92:95]
	v_mfma_f32_16x16x32_bf16 v[84:87], v[132:135], v[198:201], v[84:87]
	v_mfma_f32_16x16x32_bf16 v[76:79], v[158:161], v[198:201], v[76:79]
	s_barrier
	s_setprio 0
	s_add_i32 s53, s65, s41
	s_add_u32 s98, s8, 0x80
	s_addc_u32 s99, s9, 0
	s_add_u32 s100, s10, 0x80
	s_addc_u32 s101, s11, 0
	s_mov_b32 m0, s53
	ds_read_b128 v[202:205], v175
	ds_read_b128 v[206:209], v175 offset:1024
	ds_read_b128 v[212:215], v175 offset:2048
	ds_read_b128 v[216:219], v175 offset:3072
	global_load_lds_dwordx4 v140, s[8:9]
	s_add_i32 m0, s53, 0x2000
	s_nop 0
	global_load_lds_dwordx4 v136, s[8:9]
	s_waitcnt lgkmcnt(0)
	s_setprio 1
	s_barrier
	v_mfma_f32_16x16x32_bf16 v[116:119], v[202:205], v[162:165], v[116:119]
	v_mfma_f32_16x16x32_bf16 v[112:115], v[212:215], v[162:165], v[112:115]
	v_mfma_f32_16x16x32_bf16 v[96:99], v[202:205], v[178:181], v[96:99]
	v_mfma_f32_16x16x32_bf16 v[88:91], v[212:215], v[178:181], v[88:91]
	v_mfma_f32_16x16x32_bf16 v[80:83], v[202:205], v[186:189], v[80:83]
	v_mfma_f32_16x16x32_bf16 v[72:75], v[212:215], v[186:189], v[72:75]
	v_mfma_f32_16x16x32_bf16 v[68:71], v[202:205], v[194:197], v[68:71]
	v_mfma_f32_16x16x32_bf16 v[64:67], v[212:215], v[194:197], v[64:67]
	v_mfma_f32_16x16x32_bf16 v[116:119], v[206:209], v[166:169], v[116:119]
	v_mfma_f32_16x16x32_bf16 v[112:115], v[216:219], v[166:169], v[112:115]
	v_mfma_f32_16x16x32_bf16 v[96:99], v[206:209], v[182:185], v[96:99]
	v_mfma_f32_16x16x32_bf16 v[88:91], v[216:219], v[182:185], v[88:91]
	v_mfma_f32_16x16x32_bf16 v[80:83], v[206:209], v[190:193], v[80:83]
	v_mfma_f32_16x16x32_bf16 v[72:75], v[216:219], v[190:193], v[72:75]
	v_mfma_f32_16x16x32_bf16 v[68:71], v[206:209], v[198:201], v[68:71]
	v_mfma_f32_16x16x32_bf16 v[64:67], v[216:219], v[198:201], v[64:67]
	s_barrier
	s_setprio 0
	s_mov_b32 m0, s48
	ds_read_b128 v[162:165], v174 offset:16384
	ds_read_b128 v[166:169], v174 offset:17408
	ds_read_b128 v[178:181], v174 offset:18432
	ds_read_b128 v[182:185], v174 offset:19456
	ds_read_b128 v[186:189], v174 offset:20480
	ds_read_b128 v[190:193], v174 offset:21504
	ds_read_b128 v[194:197], v174 offset:22528
	ds_read_b128 v[198:201], v174 offset:23552
	global_load_lds_dwordx4 v142, s[10:11]
	s_mov_b32 m0, s49
	s_nop 0
	global_load_lds_dwordx4 v138, s[10:11]
	s_waitcnt lgkmcnt(0)
	s_setprio 1
	s_barrier
	v_mfma_f32_16x16x32_bf16 v[60:63], v[128:131], v[162:165], v[60:63]
	v_mfma_f32_16x16x32_bf16 v[56:59], v[154:157], v[162:165], v[56:59]
	v_mfma_f32_16x16x32_bf16 v[52:55], v[128:131], v[178:181], v[52:55]
	v_mfma_f32_16x16x32_bf16 v[44:47], v[154:157], v[178:181], v[44:47]
	v_mfma_f32_16x16x32_bf16 v[36:39], v[128:131], v[186:189], v[36:39]
	v_mfma_f32_16x16x32_bf16 v[28:31], v[154:157], v[186:189], v[28:31]
	v_mfma_f32_16x16x32_bf16 v[20:23], v[128:131], v[194:197], v[20:23]
	v_mfma_f32_16x16x32_bf16 v[12:15], v[154:157], v[194:197], v[12:15]
	v_mfma_f32_16x16x32_bf16 v[60:63], v[132:135], v[166:169], v[60:63]
	v_mfma_f32_16x16x32_bf16 v[56:59], v[158:161], v[166:169], v[56:59]
	v_mfma_f32_16x16x32_bf16 v[52:55], v[132:135], v[182:185], v[52:55]
	v_mfma_f32_16x16x32_bf16 v[44:47], v[158:161], v[182:185], v[44:47]
	v_mfma_f32_16x16x32_bf16 v[36:39], v[132:135], v[190:193], v[36:39]
	v_mfma_f32_16x16x32_bf16 v[28:31], v[158:161], v[190:193], v[28:31]
	v_mfma_f32_16x16x32_bf16 v[20:23], v[132:135], v[198:201], v[20:23]
	v_mfma_f32_16x16x32_bf16 v[12:15], v[158:161], v[198:201], v[12:15]
	s_barrier
	s_setprio 0
	s_add_u32 s54, s8, 0x80000
	s_addc_u32 s55, s9, 0
	s_add_i32 s53, s72, s41
	s_mov_b32 m0, s53
	s_nop 0
	global_load_lds_dwordx4 v140, s[54:55]
	s_add_i32 m0, s53, 0x2000
	s_nop 0
	global_load_lds_dwordx4 v136, s[54:55]
	v_readlane_b32 vcc_lo, v247, 0
	s_cmp_eq_u32 s52, vcc_lo
	s_cbranch_scc1 .Lsw_0
	s_waitcnt vmcnt(6)
; #define PG8_STAGE(bufoff, gbase, voff) do { _Pragma("unroll") for (int _i = 0; _i < 2; ++_i) \
;     __builtin_amdgcn_global_load_lds((const unsigned*)((const char*)(gbase) + (voff)[_i]), (LAS unsigned*)(lds + (bufoff) + ldsw + _i * 8192), 16, 0, 0); } while (0)
; #define PG8_LDA(dst, b, h) do { _Pragma("unroll") for (int m = 0; m < 4; ++m) _Pragma("unroll") for (int k = 0; k < 2; ++k) dst[m][k] = *(const LAS bf16x8*)(lds + PG8_SA(b, h) + aoff + m * 2048 + k * 1024); } while (0)
; #define PG8_LDB(dst, b, h) do { _Pragma("unroll") for (int n = 0; n < 2; ++n) _Pragma("unroll") for (int k = 0; k < 2; ++k) dst[n][k] = *(const LAS bf16x8*)(lds + PG8_SB(b, h) + boff + n * 2048 + k * 1024); } while (0)
; #define PG8_MMA(ai, bj, At, Bt) do { __builtin_amdgcn_s_setprio(1); _Pragma("unroll") for (int m = 0; m < 4; ++m) _Pragma("unroll") for (int n = 0; n < 2; ++n) _Pragma("unroll") for (int k = 0; k < 2; ++k) \
;     acc[ai][bj][m][n] = __builtin_amdgcn_mfma_f32_16x16x32_bf16(Bt[n][k], At[m][k], acc[ai][bj][m][n], 0, 0, 0); __builtin_amdgcn_s_setprio(0); } while (0)
; #define PG8_WAIT_V(n) asm volatile("s_waitcnt vmcnt(" #n ")" ::: "memory")
; #define PG8_WAIT_L(n) asm volatile("s_waitcnt lgkmcnt(" #n ")" ::: "memory")
; #define PG8_BAR __builtin_amdgcn_s_barrier()
; #define PG8_SCHED __builtin_amdgcn_sched_barrier(0)
; template <class Epi, class Sched = StaticOrder>
; DI void gemm_phase(LAS unsigned char* lds, const Gemm g, const Sched& S, const Epi& E) {
;     ...
;       PG8_LDB(B0, 1, 0); PG8_SCHED; PG8_LDA(At, 1, 0); PG8_STAGE(PG8_SA(0, 1), a2 + hstep, voffA);
;       PG8_WAIT_L(8); PG8_BAR; PG8_WAIT_L(0); PG8_MMA(0, 0, At, B0); PG8_BAR; PG8_SCHED;
;       PG8_LDB(B1, 1, 1); PG8_STAGE(PG8_SB(1, 0), b3, voffB);
;       PG8_BAR; PG8_WAIT_L(0); PG8_MMA(0, 1, At, B1); PG8_BAR;
;       PG8_LDA(At, 1, 1); PG8_STAGE(PG8_SA(1, 0), a3, voffA);
;       PG8_BAR; PG8_WAIT_L(0); PG8_MMA(1, 0, At, B0); PG8_BAR; PG8_SCHED;
;       PG8_STAGE(PG8_SB(1, 1), b3 + hstep, voffB);
;       PG8_WAIT_V(6); PG8_BAR; PG8_MMA(1, 1, At, B1); PG8_BAR;
.Lsw_0:
	s_setprio 1
	s_barrier
	v_mfma_f32_16x16x32_bf16 v[48:51], v[202:205], v[162:165], v[48:51]
	v_mfma_f32_16x16x32_bf16 v[40:43], v[212:215], v[162:165], v[40:43]
	v_mfma_f32_16x16x32_bf16 v[32:35], v[202:205], v[178:181], v[32:35]
	v_mfma_f32_16x16x32_bf16 v[24:27], v[212:215], v[178:181], v[24:27]
	v_mfma_f32_16x16x32_bf16 v[16:19], v[202:205], v[186:189], v[16:19]
	v_mfma_f32_16x16x32_bf16 v[8:11], v[212:215], v[186:189], v[8:11]
	v_mfma_f32_16x16x32_bf16 v[4:7], v[202:205], v[194:197], v[4:7]
	v_mfma_f32_16x16x32_bf16 v[0:3], v[212:215], v[194:197], v[0:3]
	v_mfma_f32_16x16x32_bf16 v[48:51], v[206:209], v[166:169], v[48:51]
	v_mfma_f32_16x16x32_bf16 v[40:43], v[216:219], v[166:169], v[40:43]
	v_mfma_f32_16x16x32_bf16 v[32:35], v[206:209], v[182:185], v[32:35]
	v_mfma_f32_16x16x32_bf16 v[24:27], v[216:219], v[182:185], v[24:27]
	v_mfma_f32_16x16x32_bf16 v[16:19], v[206:209], v[190:193], v[16:19]
	v_mfma_f32_16x16x32_bf16 v[8:11], v[216:219], v[190:193], v[8:11]
	v_mfma_f32_16x16x32_bf16 v[4:7], v[206:209], v[198:201], v[4:7]
	v_mfma_f32_16x16x32_bf16 v[0:3], v[216:219], v[198:201], v[0:3]
	s_barrier
	s_setprio 0
	s_add_i32 s53, 0, 0x18000
	v_add_u32_e32 v158, s53, v171
	ds_read_b128 v[128:131], v158
	ds_read_b128 v[132:135], v158 offset:1024
	ds_read_b128 v[154:157], v158 offset:2048
	ds_read_b128 v[158:161], v158 offset:3072
	s_add_u32 s10, s10, 0x80000
	s_addc_u32 s11, s11, 0
	s_mov_b32 m0, s50
	ds_read_b128 v[162:165], v174 offset:32768
	ds_read_b128 v[166:169], v174 offset:33792
	ds_read_b128 v[178:181], v174 offset:34816
	ds_read_b128 v[182:185], v174 offset:35840
	ds_read_b128 v[186:189], v174 offset:36864
	ds_read_b128 v[190:193], v174 offset:37888
	ds_read_b128 v[194:197], v174 offset:38912
	ds_read_b128 v[198:201], v174 offset:39936
	global_load_lds_dwordx4 v142, s[10:11]
	s_mov_b32 m0, s51
	s_nop 0
	global_load_lds_dwordx4 v138, s[10:11]
	s_waitcnt lgkmcnt(0)
	s_setprio 1
	s_barrier
	v_mfma_f32_16x16x32_bf16 v[124:127], v[128:131], v[162:165], v[124:127]
	v_mfma_f32_16x16x32_bf16 v[120:123], v[154:157], v[162:165], v[120:123]
	v_mfma_f32_16x16x32_bf16 v[108:111], v[128:131], v[178:181], v[108:111]
	v_mfma_f32_16x16x32_bf16 v[104:107], v[154:157], v[178:181], v[104:107]
	v_mfma_f32_16x16x32_bf16 v[100:103], v[128:131], v[186:189], v[100:103]
	v_mfma_f32_16x16x32_bf16 v[92:95], v[154:157], v[186:189], v[92:95]
	v_mfma_f32_16x16x32_bf16 v[84:87], v[128:131], v[194:197], v[84:87]
	v_mfma_f32_16x16x32_bf16 v[76:79], v[154:157], v[194:197], v[76:79]
	v_mfma_f32_16x16x32_bf16 v[124:127], v[132:135], v[166:169], v[124:127]
	v_mfma_f32_16x16x32_bf16 v[120:123], v[158:161], v[166:169], v[120:123]
	v_mfma_f32_16x16x32_bf16 v[108:111], v[132:135], v[182:185], v[108:111]
	v_mfma_f32_16x16x32_bf16 v[104:107], v[158:161], v[182:185], v[104:107]
	v_mfma_f32_16x16x32_bf16 v[100:103], v[132:135], v[190:193], v[100:103]
	v_mfma_f32_16x16x32_bf16 v[92:95], v[158:161], v[190:193], v[92:95]
	v_mfma_f32_16x16x32_bf16 v[84:87], v[132:135], v[198:201], v[84:87]
	v_mfma_f32_16x16x32_bf16 v[76:79], v[158:161], v[198:201], v[76:79]
	s_barrier
	s_setprio 0
	s_add_i32 s10, 0, 0x1c000
	s_add_i32 s11, s53, s41
	v_add_u32_e32 v177, s10, v171
	s_mov_b32 m0, s11
	ds_read_b128 v[202:205], v177
	ds_read_b128 v[206:209], v177 offset:1024
	ds_read_b128 v[212:215], v177 offset:2048
	ds_read_b128 v[216:219], v177 offset:3072
	global_load_lds_dwordx4 v140, s[98:99]
	s_add_i32 m0, s11, 0x2000
	s_nop 0
	global_load_lds_dwordx4 v136, s[98:99]
	s_waitcnt lgkmcnt(0)
	s_setprio 1
	s_barrier
	v_mfma_f32_16x16x32_bf16 v[116:119], v[202:205], v[162:165], v[116:119]
	v_mfma_f32_16x16x32_bf16 v[112:115], v[212:215], v[162:165], v[112:115]
	v_mfma_f32_16x16x32_bf16 v[96:99], v[202:205], v[178:181], v[96:99]
	v_mfma_f32_16x16x32_bf16 v[88:91], v[212:215], v[178:181], v[88:91]
	v_mfma_f32_16x16x32_bf16 v[80:83], v[202:205], v[186:189], v[80:83]
	v_mfma_f32_16x16x32_bf16 v[72:75], v[212:215], v[186:189], v[72:75]
	v_mfma_f32_16x16x32_bf16 v[68:71], v[202:205], v[194:197], v[68:71]
	v_mfma_f32_16x16x32_bf16 v[64:67], v[212:215], v[194:197], v[64:67]
	v_mfma_f32_16x16x32_bf16 v[116:119], v[206:209], v[166:169], v[116:119]
	v_mfma_f32_16x16x32_bf16 v[112:115], v[216:219], v[166:169], v[112:115]
	v_mfma_f32_16x16x32_bf16 v[96:99], v[206:209], v[182:185], v[96:99]
	v_mfma_f32_16x16x32_bf16 v[88:91], v[216:219], v[182:185], v[88:91]
	v_mfma_f32_16x16x32_bf16 v[80:83], v[206:209], v[190:193], v[80:83]
	v_mfma_f32_16x16x32_bf16 v[72:75], v[216:219], v[190:193], v[72:75]
	v_mfma_f32_16x16x32_bf16 v[68:71], v[206:209], v[198:201], v[68:71]
	v_mfma_f32_16x16x32_bf16 v[64:67], v[216:219], v[198:201], v[64:67]
	s_barrier
	s_setprio 0
	s_mov_b32 m0, s56
	ds_read_b128 v[162:165], v174 offset:49152
	ds_read_b128 v[166:169], v174 offset:50176
	ds_read_b128 v[178:181], v174 offset:51200
	ds_read_b128 v[182:185], v174 offset:52224
	ds_read_b128 v[186:189], v174 offset:53248
	ds_read_b128 v[190:193], v174 offset:54272
	ds_read_b128 v[194:197], v174 offset:55296
	ds_read_b128 v[198:201], v174 offset:56320
	global_load_lds_dwordx4 v142, s[100:101]
	s_mov_b32 m0, s57
	s_nop 0
	global_load_lds_dwordx4 v138, s[100:101]
	s_waitcnt lgkmcnt(0)
	s_setprio 1
	s_barrier
	v_mfma_f32_16x16x32_bf16 v[60:63], v[128:131], v[162:165], v[60:63]
	v_mfma_f32_16x16x32_bf16 v[56:59], v[154:157], v[162:165], v[56:59]
	v_mfma_f32_16x16x32_bf16 v[52:55], v[128:131], v[178:181], v[52:55]
	v_mfma_f32_16x16x32_bf16 v[44:47], v[154:157], v[178:181], v[44:47]
	v_mfma_f32_16x16x32_bf16 v[36:39], v[128:131], v[186:189], v[36:39]
	v_mfma_f32_16x16x32_bf16 v[28:31], v[154:157], v[186:189], v[28:31]
	v_mfma_f32_16x16x32_bf16 v[20:23], v[128:131], v[194:197], v[20:23]
	v_mfma_f32_16x16x32_bf16 v[12:15], v[154:157], v[194:197], v[12:15]
	v_mfma_f32_16x16x32_bf16 v[60:63], v[132:135], v[166:169], v[60:63]
	v_mfma_f32_16x16x32_bf16 v[56:59], v[158:161], v[166:169], v[56:59]
	v_mfma_f32_16x16x32_bf16 v[52:55], v[132:135], v[182:185], v[52:55]
	v_mfma_f32_16x16x32_bf16 v[44:47], v[158:161], v[182:185], v[44:47]
	v_mfma_f32_16x16x32_bf16 v[36:39], v[132:135], v[190:193], v[36:39]
	v_mfma_f32_16x16x32_bf16 v[28:31], v[158:161], v[190:193], v[28:31]
	v_mfma_f32_16x16x32_bf16 v[20:23], v[132:135], v[198:201], v[20:23]
	v_mfma_f32_16x16x32_bf16 v[12:15], v[158:161], v[198:201], v[12:15]
	s_barrier
	s_setprio 0
	s_add_u32 s8, s8, 0x80080
	s_addc_u32 s9, s9, 0
	s_add_i32 s10, s10, s41
	s_mov_b32 m0, s10
	s_nop 0
	global_load_lds_dwordx4 v140, s[8:9]
	s_add_i32 m0, s10, 0x2000
	s_nop 0
	global_load_lds_dwordx4 v136, s[8:9]
	s_waitcnt vmcnt(6)
	s_cmp_eq_u32 s52, 28
	s_cbranch_scc0 .Lxs_0
	s_add_i32 m0, s48, 0xc000
	s_nop 0
	global_load_lds_dwordx4 v146, s[100:101]
	s_add_i32 m0, s48, 0xe000
	s_nop 0
	global_load_lds_dwordx4 v148, s[100:101]
; DI float row_rstd(const float* ssq, int row, int fq) {
;   const f32x4 a = *(const f32x4*)(ssq + (size_t)row * 32 + fq * 8), b = *(const f32x4*)(ssq + (size_t)row * 32 + fq * 8 + 4);
;   float sm = ((a[0] + a[1]) + (a[2] + a[3])) + ((b[0] + b[1]) + (b[2] + b[3]));
;   sm += __shfl_xor(sm, 16); sm += __shfl_xor(sm, 32);
;   return rsqrtf(sm * (1.0f / 2048.f) + 1e-6f);
;   DI void operator()(const f32x4 (&acc)[2][2][4][2], const Unit& u, int wr, int wc, int fr, int fq) const {
;     const int row0 = u.pm * BM + wr * 64 + fr, col0 = u.pn * BM + wc * 32 + 8 * fq;
;     float rsv[2][4];
; #pragma unroll
;     for (int ai = 0; ai < 2; ++ai)
; #pragma unroll
;       for (int m = 0; m < 4; ++m) rsv[ai][m] = row_rstd(ssq, row0 + ai * HALF + m * 16, fq);
.Lxs_0:
	s_add_i32 s52, s52, 2
	s_add_u32 s6, s6, 0x100
	s_addc_u32 s7, s7, 0
	s_add_u32 s44, s44, 0x100
	s_addc_u32 s45, s45, 0
	s_cmp_gt_u32 s52, 29
	s_setprio 1
	s_barrier
	v_mfma_f32_16x16x32_bf16 v[48:51], v[202:205], v[162:165], v[48:51]
	v_mfma_f32_16x16x32_bf16 v[40:43], v[212:215], v[162:165], v[40:43]
	v_mfma_f32_16x16x32_bf16 v[32:35], v[202:205], v[178:181], v[32:35]
	v_mfma_f32_16x16x32_bf16 v[24:27], v[212:215], v[178:181], v[24:27]
	v_mfma_f32_16x16x32_bf16 v[16:19], v[202:205], v[186:189], v[16:19]
	v_mfma_f32_16x16x32_bf16 v[8:11], v[212:215], v[186:189], v[8:11]
	v_mfma_f32_16x16x32_bf16 v[4:7], v[202:205], v[194:197], v[4:7]
	v_mfma_f32_16x16x32_bf16 v[0:3], v[212:215], v[194:197], v[0:3]
	v_mfma_f32_16x16x32_bf16 v[48:51], v[206:209], v[166:169], v[48:51]
	v_mfma_f32_16x16x32_bf16 v[40:43], v[216:219], v[166:169], v[40:43]
	v_mfma_f32_16x16x32_bf16 v[32:35], v[206:209], v[182:185], v[32:35]
	v_mfma_f32_16x16x32_bf16 v[24:27], v[216:219], v[182:185], v[24:27]
	v_mfma_f32_16x16x32_bf16 v[16:19], v[206:209], v[190:193], v[16:19]
	v_mfma_f32_16x16x32_bf16 v[8:11], v[216:219], v[190:193], v[8:11]
	v_mfma_f32_16x16x32_bf16 v[4:7], v[206:209], v[198:201], v[4:7]
	v_mfma_f32_16x16x32_bf16 v[0:3], v[216:219], v[198:201], v[0:3]
	s_barrier
	s_setprio 0
	s_cbranch_scc0 .LBB0_346
	v_writelane_b32 v247, -2, 0
	v_lshl_add_u32 v168, s4, 8, v170
	v_ashrrev_i32_e32 v169, 31, v168
	v_or_b32_e32 v154, 16, v168
	v_lshlrev_b64 v[128:129], 7, v[168:169]
	v_ashrrev_i32_e32 v155, 31, v154
	v_lshl_add_u64 v[128:129], v[144:145], 0, v[128:129]
	v_lshlrev_b64 v[156:157], 7, v[154:155]
	global_load_dwordx4 v[132:135], v[128:129], off
	s_nop 0
	global_load_dwordx4 v[128:131], v[128:129], off offset:16
	v_lshl_add_u64 v[156:157], v[144:145], 0, v[156:157]
	global_load_dwordx4 v[178:181], v[156:157], off
	global_load_dwordx4 v[182:185], v[156:157], off offset:16
	v_or_b32_e32 v160, 32, v168
	v_ashrrev_i32_e32 v161, 31, v160
	v_lshlrev_b64 v[156:157], 7, v[160:161]
	v_lshl_add_u64 v[156:157], v[144:145], 0, v[156:157]
	global_load_dwordx4 v[186:189], v[156:157], off
	global_load_dwordx4 v[190:193], v[156:157], off offset:16
	v_or_b32_e32 v156, 48, v168
	v_ashrrev_i32_e32 v157, 31, v156
	v_lshlrev_b64 v[158:159], 7, v[156:157]
	v_lshl_add_u64 v[158:159], v[144:145], 0, v[158:159]
	global_load_dwordx4 v[194:197], v[158:159], off
	global_load_dwordx4 v[198:201], v[158:159], off offset:16
	v_add_u32_e32 v164, 0x80, v168
	v_ashrrev_i32_e32 v165, 31, v164
	v_lshlrev_b64 v[158:159], 7, v[164:165]
	v_lshl_add_u64 v[158:159], v[144:145], 0, v[158:159]
	global_load_dwordx4 v[202:205], v[158:159], off
	global_load_dwordx4 v[206:209], v[158:159], off offset:16
	v_add_u32_e32 v158, 0x90, v168
	v_ashrrev_i32_e32 v159, 31, v158
	v_lshlrev_b64 v[162:163], 7, v[158:159]
	v_lshl_add_u64 v[162:163], v[144:145], 0, v[162:163]
	global_load_dwordx4 v[212:215], v[162:163], off
	global_load_dwordx4 v[216:219], v[162:163], off offset:16
	v_add_u32_e32 v166, 0xa0, v168
	v_ashrrev_i32_e32 v167, 31, v166
	v_lshlrev_b64 v[162:163], 7, v[166:167]
	v_lshl_add_u64 v[162:163], v[144:145], 0, v[162:163]
	global_load_dwordx4 v[220:223], v[162:163], off
	global_load_dwordx4 v[224:227], v[162:163], off offset:16
	v_add_u32_e32 v162, 0xb0, v168
	v_ashrrev_i32_e32 v163, 31, v162
	v_lshlrev_b64 v[228:229], 7, v[162:163]
	v_lshl_add_u64 v[232:233], v[144:145], 0, v[228:229]
	global_load_dwordx4 v[228:231], v[232:233], off
	s_nop 0
	global_load_dwordx4 v[232:235], v[232:233], off offset:16
	s_waitcnt vmcnt(0)
	v_mov_b32_e32 v236, v132
	v_mov_b32_e32 v237, v128
	v_mov_b32_e32 v128, v133
	v_mov_b32_e32 v132, v134
	v_mov_b32_e32 v133, v130
	v_mov_b32_e32 v130, v135
	v_pk_add_f32 v[130:131], v[132:133], v[130:131]
	v_mov_b32_e32 v132, v178
	v_mov_b32_e32 v133, v182
	v_mov_b32_e32 v182, v179
	v_mov_b32_e32 v134, v180
	v_mov_b32_e32 v135, v184
	v_mov_b32_e32 v184, v181
	v_pk_add_f32 v[128:129], v[236:237], v[128:129]
	v_pk_add_f32 v[132:133], v[132:133], v[182:183]
	v_pk_add_f32 v[134:135], v[134:135], v[184:185]
	v_pk_add_f32 v[128:129], v[128:129], v[130:131]
	v_pk_add_f32 v[130:131], v[132:133], v[134:135]
	v_mov_b32_e32 v133, v128
	v_mov_b32_e32 v132, v130
	v_and_b32_e32 v130, 64, v176
	v_add_u32_e32 v155, 64, v130
	v_xor_b32_e32 v130, 16, v176
	v_cmp_lt_i32_e32 vcc, v130, v155
	v_mov_b32_e32 v128, v131
	v_pk_add_f32 v[128:129], v[132:133], v[128:129]
	v_cndmask_b32_e32 v130, v176, v130, vcc
	v_lshlrev_b32_e32 v157, 2, v130
	ds_bpermute_b32 v131, v157, v129
	ds_bpermute_b32 v130, v157, v128
	v_mov_b32_e32 v178, v186
	v_mov_b32_e32 v179, v190
	v_mov_b32_e32 v190, v187
	v_mov_b32_e32 v186, v194
	s_waitcnt lgkmcnt(0)
	v_pk_add_f32 v[128:129], v[128:129], v[130:131]
	v_xor_b32_e32 v130, 32, v176
	v_cmp_lt_i32_e32 vcc, v130, v155
	v_mov_b32_e32 v187, v198
	v_mov_b32_e32 v198, v195
	v_cndmask_b32_e32 v130, v176, v130, vcc
	v_lshlrev_b32_e32 v155, 2, v130
	ds_bpermute_b32 v131, v155, v129
	ds_bpermute_b32 v130, v155, v128
	v_pk_add_f32 v[182:183], v[186:187], v[198:199]
	v_mov_b32_e32 v180, v188
	v_mov_b32_e32 v181, v192
	v_mov_b32_e32 v192, v189
	s_waitcnt lgkmcnt(0)
; DI unsigned pack2(float lo, float hi) { f32x2 v = {lo, hi}; bf16v2 r = __builtin_convertvector(v, bf16v2); return __builtin_bit_cast(unsigned, r); }
; DI float row_rstd(const float* ssq, int row, int fq) {
;   const f32x4 a = *(const f32x4*)(ssq + (size_t)row * 32 + fq * 8), b = *(const f32x4*)(ssq + (size_t)row * 32 + fq * 8 + 4);
;   float sm = ((a[0] + a[1]) + (a[2] + a[3])) + ((b[0] + b[1]) + (b[2] + b[3]));
;   sm += __shfl_xor(sm, 16); sm += __shfl_xor(sm, 32);
;   return rsqrtf(sm * (1.0f / 2048.f) + 1e-6f);
;   DI void operator()(const f32x4 (&acc)[2][2][4][2], const Unit& u, int wr, int wc, int fr, int fq) const {
;     ...
;       for (int m = 0; m < 4; ++m) rsv[ai][m] = row_rstd(ssq, row0 + ai * HALF + m * 16, fq);
; #pragma unroll
;     for (int ai = 0; ai < 2; ++ai)
; #pragma unroll
;       for (int m = 0; m < 4; ++m) {
;         const int row = row0 + ai * HALF + m * 16;
;         const float rs = rsv[ai][m];
;         bf16_t* rowp = O + (size_t)row * ldc + col0;
; #pragma unroll
;         for (int bj = 0; bj < 2; ++bj) {
;           const f32x4 v0 = acc[ai][bj][m][0] * rs, v1 = acc[ai][bj][m][1] * rs;
;           u32x4 w; w.x = pack2(v0[0], v0[1]); w.y = pack2(v0[2], v0[3]); w.z = pack2(v1[0], v1[1]); w.w = pack2(v1[2], v1[3]);
;           *(u32x4*)(rowp + bj * HALF) = w;
	v_pk_add_f32 v[128:129], v[128:129], v[130:131]
	v_mov_b64_e32 v[130:131], s[26:27]
	v_pk_fma_f32 v[128:129], v[128:129], s[24:25], v[130:131] op_sel_hi:[1,0,0]
	v_mov_b32_e32 v188, v196
	v_mul_f32_e32 v159, 0x4b800000, v129
	v_cmp_gt_f32_e32 vcc, s73, v129
	v_mov_b32_e32 v189, v200
	v_mov_b32_e32 v200, v197
	v_cndmask_b32_e32 v129, v129, v159, vcc
	v_rsq_f32_e32 v129, v129
	v_pk_add_f32 v[178:179], v[178:179], v[190:191]
	v_pk_add_f32 v[180:181], v[180:181], v[192:193]
	v_pk_add_f32 v[184:185], v[188:189], v[200:201]
	v_mul_f32_e32 v159, 0x45800000, v129
	v_cndmask_b32_e32 v198, v129, v159, vcc
	v_pk_mul_f32 v[126:127], v[126:127], v[198:199] op_sel_hi:[1,0]
	v_pk_mul_f32 v[124:125], v[124:125], v[198:199] op_sel_hi:[1,0]
	v_pk_mul_f32 v[122:123], v[122:123], v[198:199] op_sel_hi:[1,0]
	v_pk_mul_f32 v[120:121], v[120:121], v[198:199] op_sel_hi:[1,0]
	v_cvt_pk_bf16_f32 v124, v124, v125
	v_cvt_pk_bf16_f32 v125, v126, v127
	v_cvt_pk_bf16_f32 v127, v122, v123
	v_lshl_or_b32 v122, s5, 8, v172
	v_cvt_pk_bf16_f32 v126, v120, v121
	v_ashrrev_i32_e32 v123, 31, v122
	v_mov_b64_e32 v[120:121], s[2:3]
	v_mad_i64_i32 v[168:169], s[4:5], v168, s76, v[120:121]
	v_lshlrev_b64 v[122:123], 1, v[122:123]
	v_lshl_add_u64 v[168:169], v[168:169], 0, v[122:123]
	global_store_dwordx4 v[168:169], v[124:127], off
	v_mov_b32_e32 v194, v202
	v_mov_b32_e32 v195, v206
	v_pk_add_f32 v[124:125], v[178:179], v[180:181]
	v_pk_add_f32 v[126:127], v[182:183], v[184:185]
	v_mov_b32_e32 v179, v124
	v_mov_b32_e32 v178, v126
	v_mov_b32_e32 v124, v127
	v_pk_add_f32 v[124:125], v[178:179], v[124:125]
	ds_bpermute_b32 v127, v157, v125
	ds_bpermute_b32 v126, v157, v124
	v_mov_b32_e32 v206, v203
	v_mov_b32_e32 v196, v204
	v_mov_b32_e32 v197, v208
	v_mov_b32_e32 v208, v205
	v_mov_b32_e32 v202, v212
	v_mov_b32_e32 v203, v216
	v_mov_b32_e32 v216, v213
	v_mov_b32_e32 v204, v214
	v_mov_b32_e32 v205, v218
	v_mov_b32_e32 v218, v215
	v_pk_add_f32 v[186:187], v[194:195], v[206:207]
	v_pk_add_f32 v[188:189], v[196:197], v[208:209]
	v_pk_add_f32 v[190:191], v[202:203], v[216:217]
	v_pk_add_f32 v[192:193], v[204:205], v[218:219]
	v_pk_mul_f32 v[178:179], v[114:115], v[198:199] op_sel_hi:[1,0]
	s_waitcnt lgkmcnt(0)
	v_pk_add_f32 v[114:115], v[124:125], v[126:127]
	v_pk_add_f32 v[126:127], v[186:187], v[188:189]
	v_pk_add_f32 v[180:181], v[190:191], v[192:193]
	v_mov_b32_e32 v183, v126
	v_mov_b32_e32 v182, v180
	v_mov_b32_e32 v126, v181
	v_pk_add_f32 v[126:127], v[182:183], v[126:127]
	ds_bpermute_b32 v125, v155, v115
	ds_bpermute_b32 v124, v155, v114
	ds_bpermute_b32 v181, v157, v127
	ds_bpermute_b32 v180, v157, v126
	v_mul_f32_e32 v129, 0x4b800000, v128
	v_cmp_gt_f32_e32 vcc, s73, v128
	s_waitcnt lgkmcnt(2)
	v_pk_add_f32 v[114:115], v[114:115], v[124:125]
	v_mov_b32_e32 v194, v220
	s_waitcnt lgkmcnt(0)
	v_pk_add_f32 v[124:125], v[126:127], v[180:181]
	ds_bpermute_b32 v127, v155, v125
	ds_bpermute_b32 v126, v155, v124
	v_pk_fma_f32 v[114:115], v[114:115], s[24:25], v[130:131] op_sel_hi:[1,0,0]
	v_cndmask_b32_e32 v159, v128, v129, vcc
	v_mul_f32_e32 v128, 0x4b800000, v115
	v_cmp_gt_f32_e64 s[4:5], s73, v115
	v_cmp_gt_f32_e64 s[6:7], s73, v114
	v_mov_b32_e32 v195, v224
	v_cndmask_b32_e64 v161, v115, v128, s[4:5]
	v_mul_f32_e32 v115, 0x4b800000, v114
	v_mov_b32_e32 v224, v221
	v_mov_b32_e32 v196, v222
	v_mov_b32_e32 v197, v226
	v_mov_b32_e32 v226, v223
	v_cndmask_b32_e64 v163, v114, v115, s[6:7]
	s_waitcnt lgkmcnt(0)
	v_pk_add_f32 v[114:115], v[124:125], v[126:127]
	v_pk_add_f32 v[132:133], v[194:195], v[224:225]
	v_pk_add_f32 v[134:135], v[196:197], v[226:227]
	v_mov_b32_e32 v194, v228
	v_mov_b32_e32 v195, v232
	v_mov_b32_e32 v232, v229
	v_mov_b32_e32 v196, v230
	v_mov_b32_e32 v197, v234
	v_mov_b32_e32 v234, v231
	v_pk_fma_f32 v[114:115], v[114:115], s[24:25], v[130:131] op_sel_hi:[1,0,0]
	v_pk_add_f32 v[194:195], v[194:195], v[232:233]
	v_pk_add_f32 v[196:197], v[196:197], v[234:235]
	v_mul_f32_e32 v124, 0x4b800000, v115
	v_cmp_gt_f32_e64 s[8:9], s73, v115
	v_pk_add_f32 v[126:127], v[194:195], v[196:197]
	v_cmp_gt_f32_e64 s[10:11], s73, v114
	v_cndmask_b32_e64 v165, v115, v124, s[8:9]
	v_pk_add_f32 v[124:125], v[132:133], v[134:135]
	v_mov_b32_e32 v128, v126
	v_mov_b32_e32 v129, v124
	v_mov_b32_e32 v124, v127
	v_pk_add_f32 v[124:125], v[128:129], v[124:125]
	ds_bpermute_b32 v127, v157, v125
	ds_bpermute_b32 v126, v157, v124
	v_rsq_f32_e32 v128, v159
	v_mul_f32_e32 v115, 0x4b800000, v114
	v_cndmask_b32_e64 v129, v114, v115, s[10:11]
	v_pk_mul_f32 v[116:117], v[116:117], v[198:199] op_sel_hi:[1,0]
	s_waitcnt lgkmcnt(0)
	v_pk_add_f32 v[114:115], v[124:125], v[126:127]
	ds_bpermute_b32 v125, v155, v115
	ds_bpermute_b32 v124, v155, v114
	v_mul_f32_e32 v126, 0x45800000, v128
	v_rsq_f32_e32 v127, v161
	v_cndmask_b32_e32 v126, v128, v126, vcc
	v_rsq_f32_e32 v128, v163
	s_waitcnt lgkmcnt(0)
; DI unsigned pack2(float lo, float hi) { f32x2 v = {lo, hi}; bf16v2 r = __builtin_convertvector(v, bf16v2); return __builtin_bit_cast(unsigned, r); }
;   DI void operator()(const f32x4 (&acc)[2][2][4][2], const Unit& u, int wr, int wc, int fr, int fq) const {
;     ...
; #pragma unroll
;     for (int ai = 0; ai < 2; ++ai)
; #pragma unroll
;       for (int m = 0; m < 4; ++m) {
;         const int row = row0 + ai * HALF + m * 16;
;         const float rs = rsv[ai][m];
;         bf16_t* rowp = O + (size_t)row * ldc + col0;
; #pragma unroll
;         for (int bj = 0; bj < 2; ++bj) {
;           const f32x4 v0 = acc[ai][bj][m][0] * rs, v1 = acc[ai][bj][m][1] * rs;
;           u32x4 w; w.x = pack2(v0[0], v0[1]); w.y = pack2(v0[2], v0[3]); w.z = pack2(v1[0], v1[1]); w.w = pack2(v1[2], v1[3]);
;           *(u32x4*)(rowp + bj * HALF) = w;
;         }
;       }
	v_pk_add_f32 v[114:115], v[114:115], v[124:125]
	v_mul_f32_e32 v124, 0x45800000, v127
	v_cndmask_b32_e64 v124, v127, v124, s[4:5]
	v_mul_f32_e32 v127, 0x45800000, v128
	v_pk_fma_f32 v[114:115], v[114:115], s[24:25], v[130:131] op_sel_hi:[1,0,0]
	v_rsq_f32_e32 v125, v165
	v_cndmask_b32_e64 v128, v128, v127, s[6:7]
	v_rsq_f32_e32 v127, v129
	v_mul_f32_e32 v129, 0x4b800000, v115
	v_cmp_gt_f32_e32 vcc, s73, v115
	v_cmp_gt_f32_e64 s[4:5], s73, v114
	v_pk_mul_f32 v[118:119], v[118:119], v[198:199] op_sel_hi:[1,0]
	v_cndmask_b32_e32 v129, v115, v129, vcc
	v_mul_f32_e32 v115, 0x4b800000, v114
	v_cndmask_b32_e64 v131, v114, v115, s[4:5]
	v_cvt_pk_bf16_f32 v114, v116, v117
	v_rsq_f32_e32 v117, v129
	v_cvt_pk_bf16_f32 v115, v118, v119
	v_rsq_f32_e32 v119, v131
	v_mul_f32_e32 v116, 0x45800000, v125
	v_pk_mul_f32 v[112:113], v[112:113], v[198:199] op_sel_hi:[1,0]
	v_cndmask_b32_e64 v118, v125, v116, s[8:9]
	v_mul_f32_e32 v116, 0x45800000, v127
	v_cndmask_b32_e64 v130, v127, v116, s[10:11]
	v_cvt_pk_bf16_f32 v116, v112, v113
	v_mul_f32_e32 v112, 0x45800000, v117
	v_cndmask_b32_e32 v132, v117, v112, vcc
	v_mul_f32_e32 v112, 0x45800000, v119
	v_cvt_pk_bf16_f32 v117, v178, v179
	v_cndmask_b32_e64 v112, v119, v112, s[4:5]
	global_store_dwordx4 v[168:169], v[114:117], off offset:256
	v_pk_mul_f32 v[110:111], v[110:111], v[126:127] op_sel_hi:[1,0]
	v_pk_mul_f32 v[108:109], v[108:109], v[126:127] op_sel_hi:[1,0]
	v_mad_i64_i32 v[114:115], s[4:5], v154, s76, v[120:121]
	v_pk_mul_f32 v[116:117], v[106:107], v[126:127] op_sel_hi:[1,0]
	v_pk_mul_f32 v[106:107], v[104:105], v[126:127] op_sel_hi:[1,0]
	v_lshl_add_u64 v[114:115], v[114:115], 0, v[122:123]
	v_cvt_pk_bf16_f32 v104, v108, v109
	v_cvt_pk_bf16_f32 v105, v110, v111
	v_cvt_pk_bf16_f32 v106, v106, v107
	v_cvt_pk_bf16_f32 v107, v116, v117
	global_store_dwordx4 v[114:115], v[104:107], off
	v_pk_mul_f32 v[98:99], v[98:99], v[126:127] op_sel_hi:[1,0]
	v_pk_mul_f32 v[96:97], v[96:97], v[126:127] op_sel_hi:[1,0]
	v_pk_mul_f32 v[104:105], v[90:91], v[126:127] op_sel_hi:[1,0]
	v_pk_mul_f32 v[90:91], v[88:89], v[126:127] op_sel_hi:[1,0]
	v_cvt_pk_bf16_f32 v88, v96, v97
	v_cvt_pk_bf16_f32 v89, v98, v99
	v_cvt_pk_bf16_f32 v90, v90, v91
	v_cvt_pk_bf16_f32 v91, v104, v105
	global_store_dwordx4 v[114:115], v[88:91], off offset:256
	v_pk_mul_f32 v[94:95], v[94:95], v[124:125] op_sel_hi:[1,0]
	v_pk_mul_f32 v[92:93], v[92:93], v[124:125] op_sel_hi:[1,0]
	v_mad_i64_i32 v[88:89], s[4:5], v160, s76, v[120:121]
	v_lshl_add_u64 v[96:97], v[88:89], 0, v[122:123]
	v_pk_mul_f32 v[90:91], v[102:103], v[124:125] op_sel_hi:[1,0]
	v_pk_mul_f32 v[88:89], v[100:101], v[124:125] op_sel_hi:[1,0]
	v_pk_mul_f32 v[82:83], v[82:83], v[124:125] op_sel_hi:[1,0]
	v_cvt_pk_bf16_f32 v88, v88, v89
	v_cvt_pk_bf16_f32 v89, v90, v91
	v_cvt_pk_bf16_f32 v90, v92, v93
	v_cvt_pk_bf16_f32 v91, v94, v95
	global_store_dwordx4 v[96:97], v[88:91], off
	v_pk_mul_f32 v[80:81], v[80:81], v[124:125] op_sel_hi:[1,0]
	v_pk_mul_f32 v[78:79], v[78:79], v[128:129] op_sel_hi:[1,0]
	v_pk_mul_f32 v[88:89], v[74:75], v[124:125] op_sel_hi:[1,0]
	v_pk_mul_f32 v[74:75], v[72:73], v[124:125] op_sel_hi:[1,0]
	v_cvt_pk_bf16_f32 v72, v80, v81
	v_cvt_pk_bf16_f32 v73, v82, v83
	v_cvt_pk_bf16_f32 v74, v74, v75
	v_cvt_pk_bf16_f32 v75, v88, v89
	global_store_dwordx4 v[96:97], v[72:75], off offset:256
	v_pk_mul_f32 v[76:77], v[76:77], v[128:129] op_sel_hi:[1,0]
	v_pk_mul_f32 v[70:71], v[70:71], v[128:129] op_sel_hi:[1,0]
	v_mad_i64_i32 v[72:73], s[4:5], v156, s76, v[120:121]
	v_lshl_add_u64 v[80:81], v[72:73], 0, v[122:123]
	v_pk_mul_f32 v[74:75], v[86:87], v[128:129] op_sel_hi:[1,0]
	v_pk_mul_f32 v[72:73], v[84:85], v[128:129] op_sel_hi:[1,0]
	v_pk_mul_f32 v[68:69], v[68:69], v[128:129] op_sel_hi:[1,0]
	v_cvt_pk_bf16_f32 v72, v72, v73
	v_cvt_pk_bf16_f32 v73, v74, v75
	v_cvt_pk_bf16_f32 v74, v76, v77
	v_cvt_pk_bf16_f32 v75, v78, v79
	global_store_dwordx4 v[80:81], v[72:75], off
	v_pk_mul_f32 v[62:63], v[62:63], v[118:119] op_sel_hi:[1,0]
	v_pk_mul_f32 v[60:61], v[60:61], v[118:119] op_sel_hi:[1,0]
	v_pk_mul_f32 v[72:73], v[66:67], v[128:129] op_sel_hi:[1,0]
	v_pk_mul_f32 v[66:67], v[64:65], v[128:129] op_sel_hi:[1,0]
; DI unsigned pack2(float lo, float hi) { f32x2 v = {lo, hi}; bf16v2 r = __builtin_convertvector(v, bf16v2); return __builtin_bit_cast(unsigned, r); }
; #define PG8_WAIT_V(n) asm volatile("s_waitcnt vmcnt(" #n ")" ::: "memory")
; #define PG8_BAR __builtin_amdgcn_s_barrier()
;   DI void operator()(const f32x4 (&acc)[2][2][4][2], const Unit& u, int wr, int wc, int fr, int fq) const {
;     ...
; #pragma unroll
;     for (int ai = 0; ai < 2; ++ai)
; #pragma unroll
;       for (int m = 0; m < 4; ++m) {
;         const int row = row0 + ai * HALF + m * 16;
;         const float rs = rsv[ai][m];
;         bf16_t* rowp = O + (size_t)row * ldc + col0;
; #pragma unroll
;         for (int bj = 0; bj < 2; ++bj) {
;           const f32x4 v0 = acc[ai][bj][m][0] * rs, v1 = acc[ai][bj][m][1] * rs;
;           u32x4 w; w.x = pack2(v0[0], v0[1]); w.y = pack2(v0[2], v0[3]); w.z = pack2(v1[0], v1[1]); w.w = pack2(v1[2], v1[3]);
;           *(u32x4*)(rowp + bj * HALF) = w;
;         }
;       }
; template <class Epi, class Sched = StaticOrder>
; DI void gemm_phase(LAS unsigned char* lds, const Gemm g, const Sched& S, const Epi& E) {
;     ...
;     cur = nxt; cA = nA; cB = nB; ++ui;
;   }
;   PG8_WAIT_V(0);
;   if (wr == 0) PG8_BAR;
;   PG8_BAR;
	v_cvt_pk_bf16_f32 v64, v68, v69
	v_cvt_pk_bf16_f32 v65, v70, v71
	v_cvt_pk_bf16_f32 v66, v66, v67
	v_cvt_pk_bf16_f32 v67, v72, v73
	global_store_dwordx4 v[80:81], v[64:67], off offset:256
	v_pk_mul_f32 v[50:51], v[50:51], v[118:119] op_sel_hi:[1,0]
	v_pk_mul_f32 v[48:49], v[48:49], v[118:119] op_sel_hi:[1,0]
	v_mad_i64_i32 v[64:65], s[4:5], v164, s76, v[120:121]
	v_pk_mul_f32 v[66:67], v[58:59], v[118:119] op_sel_hi:[1,0]
	v_pk_mul_f32 v[58:59], v[56:57], v[118:119] op_sel_hi:[1,0]
	v_lshl_add_u64 v[64:65], v[64:65], 0, v[122:123]
	v_cvt_pk_bf16_f32 v56, v60, v61
	v_cvt_pk_bf16_f32 v57, v62, v63
	v_cvt_pk_bf16_f32 v58, v58, v59
	v_cvt_pk_bf16_f32 v59, v66, v67
	global_store_dwordx4 v[64:65], v[56:59], off
	v_pk_mul_f32 v[46:47], v[46:47], v[130:131] op_sel_hi:[1,0]
	v_pk_mul_f32 v[44:45], v[44:45], v[130:131] op_sel_hi:[1,0]
	v_pk_mul_f32 v[56:57], v[42:43], v[118:119] op_sel_hi:[1,0]
	v_pk_mul_f32 v[42:43], v[40:41], v[118:119] op_sel_hi:[1,0]
	v_cvt_pk_bf16_f32 v40, v48, v49
	v_cvt_pk_bf16_f32 v41, v50, v51
	v_cvt_pk_bf16_f32 v42, v42, v43
	v_cvt_pk_bf16_f32 v43, v56, v57
	global_store_dwordx4 v[64:65], v[40:43], off offset:256
	v_pk_mul_f32 v[34:35], v[34:35], v[130:131] op_sel_hi:[1,0]
	v_pk_mul_f32 v[32:33], v[32:33], v[130:131] op_sel_hi:[1,0]
	v_mad_i64_i32 v[40:41], s[4:5], v158, s76, v[120:121]
	v_lshl_add_u64 v[48:49], v[40:41], 0, v[122:123]
	v_pk_mul_f32 v[42:43], v[54:55], v[130:131] op_sel_hi:[1,0]
	v_pk_mul_f32 v[40:41], v[52:53], v[130:131] op_sel_hi:[1,0]
	v_pk_mul_f32 v[30:31], v[30:31], v[132:133] op_sel_hi:[1,0]
	v_cvt_pk_bf16_f32 v40, v40, v41
	v_cvt_pk_bf16_f32 v41, v42, v43
	v_cvt_pk_bf16_f32 v42, v44, v45
	v_cvt_pk_bf16_f32 v43, v46, v47
	global_store_dwordx4 v[48:49], v[40:43], off
	v_pk_mul_f32 v[28:29], v[28:29], v[132:133] op_sel_hi:[1,0]
	v_pk_mul_f32 v[18:19], v[18:19], v[132:133] op_sel_hi:[1,0]
	v_pk_mul_f32 v[40:41], v[26:27], v[130:131] op_sel_hi:[1,0]
	v_pk_mul_f32 v[26:27], v[24:25], v[130:131] op_sel_hi:[1,0]
	v_cvt_pk_bf16_f32 v24, v32, v33
	v_cvt_pk_bf16_f32 v25, v34, v35
	v_cvt_pk_bf16_f32 v26, v26, v27
	v_cvt_pk_bf16_f32 v27, v40, v41
	global_store_dwordx4 v[48:49], v[24:27], off offset:256
	v_pk_mul_f32 v[16:17], v[16:17], v[132:133] op_sel_hi:[1,0]
	v_pk_mul_f32 v[14:15], v[14:15], v[112:113] op_sel_hi:[1,0]
	v_mad_i64_i32 v[24:25], s[4:5], v166, s76, v[120:121]
	v_lshl_add_u64 v[32:33], v[24:25], 0, v[122:123]
	v_pk_mul_f32 v[26:27], v[38:39], v[132:133] op_sel_hi:[1,0]
	v_pk_mul_f32 v[24:25], v[36:37], v[132:133] op_sel_hi:[1,0]
	v_pk_mul_f32 v[12:13], v[12:13], v[112:113] op_sel_hi:[1,0]
	v_cvt_pk_bf16_f32 v24, v24, v25
	v_cvt_pk_bf16_f32 v25, v26, v27
	v_cvt_pk_bf16_f32 v26, v28, v29
	v_cvt_pk_bf16_f32 v27, v30, v31
	global_store_dwordx4 v[32:33], v[24:27], off
	v_pk_mul_f32 v[6:7], v[6:7], v[112:113] op_sel_hi:[1,0]
	v_pk_mul_f32 v[4:5], v[4:5], v[112:113] op_sel_hi:[1,0]
	v_pk_mul_f32 v[24:25], v[10:11], v[132:133] op_sel_hi:[1,0]
	v_pk_mul_f32 v[10:11], v[8:9], v[132:133] op_sel_hi:[1,0]
	v_cvt_pk_bf16_f32 v8, v16, v17
	v_cvt_pk_bf16_f32 v9, v18, v19
	v_cvt_pk_bf16_f32 v10, v10, v11
	v_cvt_pk_bf16_f32 v11, v24, v25
	global_store_dwordx4 v[32:33], v[8:11], off offset:256
	s_and_b64 vcc, exec, s[0:1]
	s_mov_b64 s[8:9], s[36:37]
	v_mad_i64_i32 v[8:9], s[4:5], v162, s76, v[120:121]
	v_lshl_add_u64 v[16:17], v[8:9], 0, v[122:123]
	v_pk_mul_f32 v[10:11], v[22:23], v[112:113] op_sel_hi:[1,0]
	v_pk_mul_f32 v[8:9], v[20:21], v[112:113] op_sel_hi:[1,0]
	s_mov_b32 s5, s28
	v_cvt_pk_bf16_f32 v8, v8, v9
	v_cvt_pk_bf16_f32 v9, v10, v11
	v_cvt_pk_bf16_f32 v10, v12, v13
	v_cvt_pk_bf16_f32 v11, v14, v15
	global_store_dwordx4 v[16:17], v[8:11], off
	s_mov_b32 s4, s30
	s_mov_b64 s[6:7], s[34:35]
	v_pk_mul_f32 v[8:9], v[2:3], v[112:113] op_sel_hi:[1,0]
	v_pk_mul_f32 v[2:3], v[0:1], v[112:113] op_sel_hi:[1,0]
	v_cvt_pk_bf16_f32 v0, v4, v5
	v_cvt_pk_bf16_f32 v1, v6, v7
	v_cvt_pk_bf16_f32 v2, v2, v3
	v_cvt_pk_bf16_f32 v3, v8, v9
	global_store_dwordx4 v[16:17], v[0:3], off offset:256
	s_cbranch_vccz .LBB0_343
	s_waitcnt vmcnt(0)
	s_cmpk_gt_u32 s27, 0xff
	s_cbranch_scc1 .LBB0_350
	s_barrier

; #define LAS __attribute__((address_space(3)))
; #define PG8_STAGE(bufoff, gbase, voff) do { _Pragma("unroll") for (int _i = 0; _i < 2; ++_i) \
;     __builtin_amdgcn_global_load_lds((const unsigned*)((const char*)(gbase) + (voff)[_i]), (LAS unsigned*)(lds + (bufoff) + ldsw + _i * 8192), 16, 0, 0); } while (0)
; #define PG8_BAR __builtin_amdgcn_s_barrier()
; template <class Epi, class Sched = StaticOrder>
; DI void gemm_phase(LAS unsigned char* lds, const Gemm g, const Sched& S, const Epi& E) {
;   const int tid = threadIdx.x, wid = __builtin_amdgcn_readfirstlane(tid >> 6), lane = tid & 63, wr = wid >> 2, wc = wid & 3, fr = lane & 15, fq = lane >> 4;
;   const int K = g.K, nt = K / BK;
;   unsigned voffA[2], voffB[2];
; #pragma unroll
;   for (int i = 0; i < 2; ++i) { int R, C; stage_rc(tid * 16 + i * 8192, R, C); const int Rb = Epi::PERM ? ((R & ~31) + perm32(R & 31)) : R;
;     voffA[i] = (unsigned)(R * K + C) * 2u; voffB[i] = (unsigned)(Rb * K + C) * 2u; }
;   const size_t kstep = (size_t)(BK * 2);
;   const size_t hstep = (size_t)HALF * K * 2;
;   const size_t tstep = 2 * hstep;
;   const unsigned ldsw = (unsigned)wid * 1024u;
;   const int aoff = lds_byte(wr * 64 + fr, fq * 8), boff = lds_byte(wc * 32 + fr, fq * 8);
;     ...
;   Unit cur, nxt; int ui = 0;
;   if (!S.next(0, cur)) return;
;   f32x4 acc[2][2][4][2];
; #pragma unroll
;   for (int a = 0; a < 2; ++a)
; #pragma unroll
;     for (int b = 0; b < 2; ++b)
; #pragma unroll
;       for (int m = 0; m < 4; ++m)
; #pragma unroll
;         for (int n = 0; n < 2; ++n) acc[a][b][m][n] = (f32x4){0.f, 0.f, 0.f, 0.f};
;   bf16x8 At[4][2], B0[2][2], B1[2][2];
;   const char* cA = (const char*)g.A + (size_t)cur.pm * tstep; const char* cB = (const char*)g.Bt + (size_t)cur.pn * tstep;
;   PG8_STAGE(PG8_SB(0, 0), cB, voffB); PG8_STAGE(PG8_SA(0, 0), cA, voffA); PG8_STAGE(PG8_SB(0, 1), cB + hstep, voffB); PG8_STAGE(PG8_SA(0, 1), cA + hstep, voffA);
;   if (wr == 1) PG8_BAR;
; DI void run_gemm(const Params& p, int id, unsigned char* smem) {
;     ...
;   S.init(g.M, g.N, (int)gridDim.x, __builtin_amdgcn_readfirstlane((int)((volatile LAS unsigned*)(LAS unsigned char*)(smem + 131072))[2]));
.LBB0_720:
	v_writelane_b32 v247, 1, 0
	s_add_i32 s0, 0, 0x20008
	v_mov_b32_e32 v0, s0
	ds_read_b32 v0, v0
	v_readfirstlane_b32 s29, v210
	s_waitcnt lgkmcnt(0)
	v_readfirstlane_b32 s28, v0
	s_cmpk_gt_i32 s28, 0x1ff
	s_cbranch_scc1 .LBB0_748
	v_lshrrev_b32_e32 v0, 5, v210
	v_lshrrev_b32_e32 v2, 1, v210
	v_and_b32_e32 v0, 4, v0
	v_bfe_u32 v1, v210, 2, 2
	v_and_b32_e32 v2, 24, v2
	v_or3_b32 v0, v0, v1, v2
	v_lshlrev_b32_e32 v1, 4, v210
	v_add_u32_e32 v8, 0x2000, v1
	v_lshrrev_b32_e32 v2, 7, v8
	s_movk_i32 s0, 0xe0
	v_and_b32_e32 v4, 32, v210
	s_add_u32 s30, s84, 0x22203600
	v_and_or_b32 v3, v2, s0, v0
	v_bitop3_b32 v9, v1, v4, 48 bitop3:0x6c
	v_and_b32_e32 v10, 64, v210
	v_bfe_u32 v11, v210, 2, 4
	s_movk_i32 s0, 0xf0
	s_addc_u32 s31, s85, 0
	v_or_b32_e32 v1, v9, v10
	v_and_or_b32 v2, v2, s0, v11
	s_add_u32 s33, s84, 0x1303600
	v_lshl_or_b32 v178, v2, 12, v1
	v_lshrrev_b32_e32 v2, 3, v210
	s_movk_i32 s0, 0x60
	s_addc_u32 s34, s85, 0
	v_and_or_b32 v0, v2, s0, v0
	s_movk_i32 s0, 0x70
	s_ashr_i32 s36, s28, 31
	v_lshl_or_b32 v180, v0, 12, v1
	v_and_or_b32 v0, v2, s0, v11
	s_lshr_b32 s0, s36, 29
	s_add_i32 s0, s28, s0
	s_ashr_i32 s2, s0, 3
	s_and_b32 s0, s0, -8
	s_sub_i32 s0, s28, s0
	s_lshr_b32 s3, s0, 31
	s_or_b32 s3, s3, 64
	s_mul_i32 s0, s3, s0
	s_add_i32 s0, s0, s2
	s_ashr_i32 s2, s0, 31
	s_lshr_b32 s2, s2, 26
	s_add_i32 s2, s0, s2
	s_ashr_i32 s3, s2, 6
	s_lshl_b32 s5, s3, 3
	s_sub_i32 s3, 64, s5
	s_min_u32 s8, s3, 8
	s_andn2_b32 s2, s2, 63
	v_lshl_or_b32 v176, v3, 12, v1
	s_sub_i32 s9, s0, s2
	v_cvt_f32_ubyte0_e32 v3, s8
	v_cvt_f32_i32_e32 v2, s9
	v_rcp_iflag_f32_e32 v4, v3
	v_lshl_or_b32 v182, v0, 12, v1
	s_lshr_b32 s4, s29, 6
	s_ashr_i32 s0, s9, 30
	v_mul_f32_e32 v0, v2, v4
	v_trunc_f32_e32 v0, v0
	v_fma_f32 v1, -v0, v3, v2
	v_cvt_i32_f32_e32 v0, v0
	s_lshr_b32 s1, s29, 8
	s_lshl_b32 s35, s4, 10
	s_or_b32 s0, s0, 1
	v_cmp_ge_f32_e64 s[2:3], |v1|, v3
	s_and_b64 s[2:3], s[2:3], exec
	s_cselect_b32 s0, s0, 0
	v_readfirstlane_b32 s2, v0
	s_add_i32 s0, s2, s0
	s_mul_i32 s2, s0, s8
	s_sub_i32 s2, s9, s2
	s_sext_i32_i8 s2, s2
	s_add_i32 s12, s5, s2
	s_ashr_i32 s13, s12, 31
	s_bfe_i64 s[8:9], s[0:1], 0x80000
	s_lshl_b64 s[2:3], s[12:13], 20
	s_lshl_b64 s[8:9], s[8:9], 20
	s_add_u32 s24, s33, s8
	s_addc_u32 s25, s34, s9
	s_add_i32 s37, s35, 0
	s_add_i32 m0, s37, 0x10000
	v_mov_b32_e32 v181, 0
	global_load_lds_dwordx4 v180, s[24:25]
	s_add_i32 m0, s37, 0x12000
	s_add_u32 s22, s30, s2
	global_load_lds_dwordx4 v176, s[24:25]
	s_addc_u32 s23, s31, s3
	s_mov_b32 m0, s37
	s_add_i32 s38, s37, 0x2000
	global_load_lds_dwordx4 v182, s[22:23]
	s_mov_b32 m0, s38
	s_add_u32 s2, s24, 0x80000
	global_load_lds_dwordx4 v178, s[22:23]
	s_addc_u32 s3, s25, 0
	s_add_i32 m0, s37, 0x14000
	v_mov_b32_e32 v177, v181
	global_load_lds_dwordx4 v180, s[2:3]
	s_add_i32 m0, s37, 0x16000
	v_mov_b32_e32 v183, v181
	global_load_lds_dwordx4 v176, s[2:3]
	s_add_u32 s2, s22, 0x80000
	s_addc_u32 s3, s23, 0
	s_add_i32 s39, s37, 0x4000
	s_mov_b32 m0, s39
	s_add_i32 s40, s37, 0x6000
	global_load_lds_dwordx4 v182, s[2:3]
	s_mov_b32 m0, s40
	v_mov_b32_e32 v179, v181
	global_load_lds_dwordx4 v178, s[2:3]
	v_lshl_add_u64 v[6:7], s[24:25], 0, v[180:181]
	v_lshl_add_u64 v[4:5], s[24:25], 0, v[176:177]
	v_lshl_add_u64 v[2:3], s[22:23], 0, v[182:183]
	s_cmp_lg_u32 s1, 1
	v_lshl_add_u64 v[0:1], s[22:23], 0, v[178:179]
	s_cbranch_scc1 .LBB0_723
	s_barrier

; #define PG8_STAGE(bufoff, gbase, voff) do { _Pragma("unroll") for (int _i = 0; _i < 2; ++_i) \
;     __builtin_amdgcn_global_load_lds((const unsigned*)((const char*)(gbase) + (voff)[_i]), (LAS unsigned*)(lds + (bufoff) + ldsw + _i * 8192), 16, 0, 0); } while (0)
; #define PG8_LDA(dst, b, h) do { _Pragma("unroll") for (int m = 0; m < 4; ++m) _Pragma("unroll") for (int k = 0; k < 2; ++k) dst[m][k] = *(const LAS bf16x8*)(lds + PG8_SA(b, h) + aoff + m * 2048 + k * 1024); } while (0)
; #define PG8_LDB(dst, b, h) do { _Pragma("unroll") for (int n = 0; n < 2; ++n) _Pragma("unroll") for (int k = 0; k < 2; ++k) dst[n][k] = *(const LAS bf16x8*)(lds + PG8_SB(b, h) + boff + n * 2048 + k * 1024); } while (0)
; #define PG8_MMA(ai, bj, At, Bt) do { __builtin_amdgcn_s_setprio(1); _Pragma("unroll") for (int m = 0; m < 4; ++m) _Pragma("unroll") for (int n = 0; n < 2; ++n) _Pragma("unroll") for (int k = 0; k < 2; ++k) \
;     acc[ai][bj][m][n] = __builtin_amdgcn_mfma_f32_16x16x32_bf16(Bt[n][k], At[m][k], acc[ai][bj][m][n], 0, 0, 0); __builtin_amdgcn_s_setprio(0); } while (0)
; #define PG8_WAIT_V(n) asm volatile("s_waitcnt vmcnt(" #n ")" ::: "memory")
; #define PG8_WAIT_L(n) asm volatile("s_waitcnt lgkmcnt(" #n ")" ::: "memory")
; #define PG8_BAR __builtin_amdgcn_s_barrier()
; #define PG8_SCHED __builtin_amdgcn_sched_barrier(0)
; template <class Epi, class Sched = StaticOrder>
; DI void gemm_phase(LAS unsigned char* lds, const Gemm g, const Sched& S, const Epi& E) {
;     ...
;     for (int t = 0; t < nt; t += 2) {
;       const bool last = (t == nt - 2);
;       const char* a1 = cA + (size_t)(t + 1) * kstep;
;       const char* a2 = last ? nA : cA + (size_t)(t + 2) * kstep; const char* b2 = last ? nB : cB + (size_t)(t + 2) * kstep;
;       const char* a3 = a2 + kstep; const char* b3 = b2 + kstep;
;       PG8_LDB(B0, 0, 0); PG8_SCHED; PG8_LDA(At, 0, 0); PG8_STAGE(PG8_SA(1, 1), a1 + hstep, voffA);
;       PG8_WAIT_L(8); PG8_BAR; PG8_WAIT_L(0); PG8_MMA(0, 0, At, B0); PG8_BAR; PG8_SCHED;
;       PG8_LDB(B1, 0, 1); PG8_STAGE(PG8_SB(0, 0), b2, voffB);
;       PG8_BAR; PG8_WAIT_L(0); PG8_MMA(0, 1, At, B1); PG8_BAR;
;       PG8_LDA(At, 0, 1); PG8_STAGE(PG8_SA(0, 0), a2, voffA);
;       PG8_BAR; PG8_WAIT_L(0); PG8_MMA(1, 0, At, B0); PG8_BAR; PG8_SCHED;
;       PG8_STAGE(PG8_SB(0, 1), b2 + hstep, voffB);
;       PG8_WAIT_V(6); PG8_BAR; PG8_MMA(1, 1, At, B1); PG8_BAR;
.LBB0_728:
	ds_read_b128 v[128:131], v207
	ds_read_b128 v[132:135], v207 offset:1024
	ds_read_b128 v[136:139], v207 offset:2048
	ds_read_b128 v[140:143], v207 offset:3072
	s_add_u32 s24, s22, 0xfff80080
	s_addc_u32 s25, s23, -1
	s_cmp_eq_u32 s53, 28
	s_cselect_b32 s27, s17, s25
	s_cselect_b32 s26, s43, s24
	s_cselect_b32 s25, s15, s52
	s_cselect_b32 s24, s44, s45
	s_add_i32 m0, s37, 0xc000
	ds_read_b128 v[144:147], v208
	ds_read_b128 v[148:151], v208 offset:1024
	ds_read_b128 v[152:155], v208 offset:2048
	ds_read_b128 v[156:159], v208 offset:3072
	ds_read_b128 v[160:163], v208 offset:4096
	ds_read_b128 v[164:167], v208 offset:5120
	ds_read_b128 v[168:171], v208 offset:6144
	ds_read_b128 v[172:175], v208 offset:7168
	global_load_lds_dwordx4 v184, s[22:23]
	s_add_i32 m0, s37, 0xe000
	s_nop 0
	global_load_lds_dwordx4 v186, s[22:23]
	s_waitcnt lgkmcnt(0)
	s_setprio 1
	s_barrier
	v_mfma_f32_16x16x32_bf16 v[124:127], v[128:131], v[144:147], v[124:127]
	v_mfma_f32_16x16x32_bf16 v[120:123], v[136:139], v[144:147], v[120:123]
	v_mfma_f32_16x16x32_bf16 v[108:111], v[128:131], v[152:155], v[108:111]
	v_mfma_f32_16x16x32_bf16 v[104:107], v[136:139], v[152:155], v[104:107]
	v_mfma_f32_16x16x32_bf16 v[92:95], v[128:131], v[160:163], v[92:95]
	v_mfma_f32_16x16x32_bf16 v[88:91], v[136:139], v[160:163], v[88:91]
	v_mfma_f32_16x16x32_bf16 v[76:79], v[128:131], v[168:171], v[76:79]
	v_mfma_f32_16x16x32_bf16 v[72:75], v[136:139], v[168:171], v[72:75]
	v_mfma_f32_16x16x32_bf16 v[124:127], v[132:135], v[148:151], v[124:127]
	v_mfma_f32_16x16x32_bf16 v[120:123], v[140:143], v[148:151], v[120:123]
	v_mfma_f32_16x16x32_bf16 v[108:111], v[132:135], v[156:159], v[108:111]
	v_mfma_f32_16x16x32_bf16 v[104:107], v[140:143], v[156:159], v[104:107]
	v_mfma_f32_16x16x32_bf16 v[92:95], v[132:135], v[164:167], v[92:95]
	v_mfma_f32_16x16x32_bf16 v[88:91], v[140:143], v[164:167], v[88:91]
	v_mfma_f32_16x16x32_bf16 v[76:79], v[132:135], v[172:175], v[76:79]
	v_mfma_f32_16x16x32_bf16 v[72:75], v[140:143], v[172:175], v[72:75]
	s_barrier
	s_setprio 0
	s_add_i32 s54, s50, s35
	s_add_u32 s98, s24, 0x80
	s_addc_u32 s99, s25, 0
	s_add_u32 s100, s26, 0x80
	s_addc_u32 s101, s27, 0
	s_mov_b32 m0, s54
	ds_read_b128 v[192:195], v209
	ds_read_b128 v[196:199], v209 offset:1024
	ds_read_b128 v[200:203], v209 offset:2048
	ds_read_b128 v[212:215], v209 offset:3072
	global_load_lds_dwordx4 v180, s[24:25]
	s_add_i32 m0, s54, 0x2000
	s_nop 0
	global_load_lds_dwordx4 v176, s[24:25]
	s_waitcnt lgkmcnt(0)
	s_setprio 1
	s_barrier
	v_mfma_f32_16x16x32_bf16 v[116:119], v[192:195], v[144:147], v[116:119]
	v_mfma_f32_16x16x32_bf16 v[112:115], v[200:203], v[144:147], v[112:115]
	v_mfma_f32_16x16x32_bf16 v[100:103], v[192:195], v[152:155], v[100:103]
	v_mfma_f32_16x16x32_bf16 v[96:99], v[200:203], v[152:155], v[96:99]
	v_mfma_f32_16x16x32_bf16 v[84:87], v[192:195], v[160:163], v[84:87]
	v_mfma_f32_16x16x32_bf16 v[80:83], v[200:203], v[160:163], v[80:83]
	v_mfma_f32_16x16x32_bf16 v[68:71], v[192:195], v[168:171], v[68:71]
	v_mfma_f32_16x16x32_bf16 v[64:67], v[200:203], v[168:171], v[64:67]
	v_mfma_f32_16x16x32_bf16 v[116:119], v[196:199], v[148:151], v[116:119]
	v_mfma_f32_16x16x32_bf16 v[112:115], v[212:215], v[148:151], v[112:115]
	v_mfma_f32_16x16x32_bf16 v[100:103], v[196:199], v[156:159], v[100:103]
	v_mfma_f32_16x16x32_bf16 v[96:99], v[212:215], v[156:159], v[96:99]
	v_mfma_f32_16x16x32_bf16 v[84:87], v[196:199], v[164:167], v[84:87]
	v_mfma_f32_16x16x32_bf16 v[80:83], v[212:215], v[164:167], v[80:83]
	v_mfma_f32_16x16x32_bf16 v[68:71], v[196:199], v[172:175], v[68:71]
	v_mfma_f32_16x16x32_bf16 v[64:67], v[212:215], v[172:175], v[64:67]
	s_barrier
	s_setprio 0
	s_mov_b32 m0, s37
	ds_read_b128 v[144:147], v208 offset:16384
	ds_read_b128 v[148:151], v208 offset:17408
	ds_read_b128 v[152:155], v208 offset:18432
	ds_read_b128 v[156:159], v208 offset:19456
	ds_read_b128 v[160:163], v208 offset:20480
	ds_read_b128 v[164:167], v208 offset:21504
	ds_read_b128 v[168:171], v208 offset:22528
	ds_read_b128 v[172:175], v208 offset:23552
	global_load_lds_dwordx4 v182, s[26:27]
	s_mov_b32 m0, s38
	s_nop 0
	global_load_lds_dwordx4 v178, s[26:27]
	s_waitcnt lgkmcnt(0)
	s_setprio 1
	s_barrier
	v_mfma_f32_16x16x32_bf16 v[60:63], v[128:131], v[144:147], v[60:63]
	v_mfma_f32_16x16x32_bf16 v[56:59], v[136:139], v[144:147], v[56:59]
	v_mfma_f32_16x16x32_bf16 v[44:47], v[128:131], v[152:155], v[44:47]
	v_mfma_f32_16x16x32_bf16 v[40:43], v[136:139], v[152:155], v[40:43]
	v_mfma_f32_16x16x32_bf16 v[28:31], v[128:131], v[160:163], v[28:31]
	v_mfma_f32_16x16x32_bf16 v[24:27], v[136:139], v[160:163], v[24:27]
	v_mfma_f32_16x16x32_bf16 v[12:15], v[128:131], v[168:171], v[12:15]
	v_mfma_f32_16x16x32_bf16 v[8:11], v[136:139], v[168:171], v[8:11]
	v_mfma_f32_16x16x32_bf16 v[60:63], v[132:135], v[148:151], v[60:63]
	v_mfma_f32_16x16x32_bf16 v[56:59], v[140:143], v[148:151], v[56:59]
	v_mfma_f32_16x16x32_bf16 v[44:47], v[132:135], v[156:159], v[44:47]
	v_mfma_f32_16x16x32_bf16 v[40:43], v[140:143], v[156:159], v[40:43]
	v_mfma_f32_16x16x32_bf16 v[28:31], v[132:135], v[164:167], v[28:31]
	v_mfma_f32_16x16x32_bf16 v[24:27], v[140:143], v[164:167], v[24:27]
	v_mfma_f32_16x16x32_bf16 v[12:15], v[132:135], v[172:175], v[12:15]
	v_mfma_f32_16x16x32_bf16 v[8:11], v[140:143], v[172:175], v[8:11]
	s_barrier
	s_setprio 0
	s_add_u32 s54, s24, 0x80000
	s_addc_u32 s55, s25, 0
	s_add_i32 s57, s51, s35
	s_mov_b32 m0, s57
	s_nop 0
	global_load_lds_dwordx4 v180, s[54:55]
	s_add_i32 m0, s57, 0x2000
	s_nop 0
	global_load_lds_dwordx4 v176, s[54:55]
	v_readlane_b32 vcc_lo, v247, 0
	s_cmp_eq_u32 s53, vcc_lo
	s_cbranch_scc1 .Lsw_1
	s_waitcnt vmcnt(6)
; #define PG8_STAGE(bufoff, gbase, voff) do { _Pragma("unroll") for (int _i = 0; _i < 2; ++_i) \
;     __builtin_amdgcn_global_load_lds((const unsigned*)((const char*)(gbase) + (voff)[_i]), (LAS unsigned*)(lds + (bufoff) + ldsw + _i * 8192), 16, 0, 0); } while (0)
; #define PG8_LDA(dst, b, h) do { _Pragma("unroll") for (int m = 0; m < 4; ++m) _Pragma("unroll") for (int k = 0; k < 2; ++k) dst[m][k] = *(const LAS bf16x8*)(lds + PG8_SA(b, h) + aoff + m * 2048 + k * 1024); } while (0)
; #define PG8_LDB(dst, b, h) do { _Pragma("unroll") for (int n = 0; n < 2; ++n) _Pragma("unroll") for (int k = 0; k < 2; ++k) dst[n][k] = *(const LAS bf16x8*)(lds + PG8_SB(b, h) + boff + n * 2048 + k * 1024); } while (0)
; #define PG8_MMA(ai, bj, At, Bt) do { __builtin_amdgcn_s_setprio(1); _Pragma("unroll") for (int m = 0; m < 4; ++m) _Pragma("unroll") for (int n = 0; n < 2; ++n) _Pragma("unroll") for (int k = 0; k < 2; ++k) \
;     acc[ai][bj][m][n] = __builtin_amdgcn_mfma_f32_16x16x32_bf16(Bt[n][k], At[m][k], acc[ai][bj][m][n], 0, 0, 0); __builtin_amdgcn_s_setprio(0); } while (0)
; #define PG8_WAIT_V(n) asm volatile("s_waitcnt vmcnt(" #n ")" ::: "memory")
; #define PG8_WAIT_L(n) asm volatile("s_waitcnt lgkmcnt(" #n ")" ::: "memory")
; #define PG8_BAR __builtin_amdgcn_s_barrier()
; #define PG8_SCHED __builtin_amdgcn_sched_barrier(0)
; template <class Epi, class Sched = StaticOrder>
; DI void gemm_phase(LAS unsigned char* lds, const Gemm g, const Sched& S, const Epi& E) {
;     ...
;       PG8_LDB(B0, 1, 0); PG8_SCHED; PG8_LDA(At, 1, 0); PG8_STAGE(PG8_SA(0, 1), a2 + hstep, voffA);
;       PG8_WAIT_L(8); PG8_BAR; PG8_WAIT_L(0); PG8_MMA(0, 0, At, B0); PG8_BAR; PG8_SCHED;
;       PG8_LDB(B1, 1, 1); PG8_STAGE(PG8_SB(1, 0), b3, voffB);
;       PG8_BAR; PG8_WAIT_L(0); PG8_MMA(0, 1, At, B1); PG8_BAR;
;       PG8_LDA(At, 1, 1); PG8_STAGE(PG8_SA(1, 0), a3, voffA);
;       PG8_BAR; PG8_WAIT_L(0); PG8_MMA(1, 0, At, B0); PG8_BAR; PG8_SCHED;
;       PG8_STAGE(PG8_SB(1, 1), b3 + hstep, voffB);
;       PG8_WAIT_V(6); PG8_BAR; PG8_MMA(1, 1, At, B1); PG8_BAR;
.Lsw_1:
	s_setprio 1
	s_barrier
	v_mfma_f32_16x16x32_bf16 v[52:55], v[192:195], v[144:147], v[52:55]
	v_mfma_f32_16x16x32_bf16 v[48:51], v[200:203], v[144:147], v[48:51]
	v_mfma_f32_16x16x32_bf16 v[36:39], v[192:195], v[152:155], v[36:39]
	v_mfma_f32_16x16x32_bf16 v[32:35], v[200:203], v[152:155], v[32:35]
	v_mfma_f32_16x16x32_bf16 v[20:23], v[192:195], v[160:163], v[20:23]
	v_mfma_f32_16x16x32_bf16 v[16:19], v[200:203], v[160:163], v[16:19]
	v_mfma_f32_16x16x32_bf16 v[4:7], v[192:195], v[168:171], v[4:7]
	v_mfma_f32_16x16x32_bf16 v[0:3], v[200:203], v[168:171], v[0:3]
	v_mfma_f32_16x16x32_bf16 v[52:55], v[196:199], v[148:151], v[52:55]
	v_mfma_f32_16x16x32_bf16 v[48:51], v[212:215], v[148:151], v[48:51]
	v_mfma_f32_16x16x32_bf16 v[36:39], v[196:199], v[156:159], v[36:39]
	v_mfma_f32_16x16x32_bf16 v[32:35], v[212:215], v[156:159], v[32:35]
	v_mfma_f32_16x16x32_bf16 v[20:23], v[196:199], v[164:167], v[20:23]
	v_mfma_f32_16x16x32_bf16 v[16:19], v[212:215], v[164:167], v[16:19]
	v_mfma_f32_16x16x32_bf16 v[4:7], v[196:199], v[172:175], v[4:7]
	v_mfma_f32_16x16x32_bf16 v[0:3], v[212:215], v[172:175], v[0:3]
	s_barrier
	s_setprio 0
	s_add_i32 s54, 0, 0x18000
	v_add_u32_e32 v140, s54, v205
	ds_read_b128 v[128:131], v140
	ds_read_b128 v[132:135], v140 offset:1024
	ds_read_b128 v[136:139], v140 offset:2048
	ds_read_b128 v[140:143], v140 offset:3072
	s_add_u32 s26, s26, 0x80000
	s_addc_u32 s27, s27, 0
	s_mov_b32 m0, s39
	ds_read_b128 v[144:147], v208 offset:32768
	ds_read_b128 v[148:151], v208 offset:33792
	ds_read_b128 v[152:155], v208 offset:34816
	ds_read_b128 v[156:159], v208 offset:35840
	ds_read_b128 v[160:163], v208 offset:36864
	ds_read_b128 v[164:167], v208 offset:37888
	ds_read_b128 v[168:171], v208 offset:38912
	ds_read_b128 v[172:175], v208 offset:39936
	global_load_lds_dwordx4 v182, s[26:27]
	s_mov_b32 m0, s40
	s_nop 0
	global_load_lds_dwordx4 v178, s[26:27]
	s_waitcnt lgkmcnt(0)
	s_setprio 1
	s_barrier
	v_mfma_f32_16x16x32_bf16 v[124:127], v[128:131], v[144:147], v[124:127]
	v_mfma_f32_16x16x32_bf16 v[120:123], v[136:139], v[144:147], v[120:123]
	v_mfma_f32_16x16x32_bf16 v[108:111], v[128:131], v[152:155], v[108:111]
	v_mfma_f32_16x16x32_bf16 v[104:107], v[136:139], v[152:155], v[104:107]
	v_mfma_f32_16x16x32_bf16 v[92:95], v[128:131], v[160:163], v[92:95]
	v_mfma_f32_16x16x32_bf16 v[88:91], v[136:139], v[160:163], v[88:91]
	v_mfma_f32_16x16x32_bf16 v[76:79], v[128:131], v[168:171], v[76:79]
	v_mfma_f32_16x16x32_bf16 v[72:75], v[136:139], v[168:171], v[72:75]
	v_mfma_f32_16x16x32_bf16 v[124:127], v[132:135], v[148:151], v[124:127]
	v_mfma_f32_16x16x32_bf16 v[120:123], v[140:143], v[148:151], v[120:123]
	v_mfma_f32_16x16x32_bf16 v[108:111], v[132:135], v[156:159], v[108:111]
	v_mfma_f32_16x16x32_bf16 v[104:107], v[140:143], v[156:159], v[104:107]
	v_mfma_f32_16x16x32_bf16 v[92:95], v[132:135], v[164:167], v[92:95]
	v_mfma_f32_16x16x32_bf16 v[88:91], v[140:143], v[164:167], v[88:91]
	v_mfma_f32_16x16x32_bf16 v[76:79], v[132:135], v[172:175], v[76:79]
	v_mfma_f32_16x16x32_bf16 v[72:75], v[140:143], v[172:175], v[72:75]
	s_barrier
	s_setprio 0
	s_add_i32 s26, 0, 0x1c000
	s_add_i32 s27, s54, s35
	v_add_u32_e32 v212, s26, v205
	s_mov_b32 m0, s27
	ds_read_b128 v[192:195], v212
	ds_read_b128 v[196:199], v212 offset:1024
	ds_read_b128 v[200:203], v212 offset:2048
	ds_read_b128 v[212:215], v212 offset:3072
	global_load_lds_dwordx4 v180, s[98:99]
	s_add_i32 m0, s27, 0x2000
	s_nop 0
	global_load_lds_dwordx4 v176, s[98:99]
	s_waitcnt lgkmcnt(0)
	s_setprio 1
	s_barrier
	v_mfma_f32_16x16x32_bf16 v[116:119], v[192:195], v[144:147], v[116:119]
	v_mfma_f32_16x16x32_bf16 v[112:115], v[200:203], v[144:147], v[112:115]
	v_mfma_f32_16x16x32_bf16 v[100:103], v[192:195], v[152:155], v[100:103]
	v_mfma_f32_16x16x32_bf16 v[96:99], v[200:203], v[152:155], v[96:99]
	v_mfma_f32_16x16x32_bf16 v[84:87], v[192:195], v[160:163], v[84:87]
	v_mfma_f32_16x16x32_bf16 v[80:83], v[200:203], v[160:163], v[80:83]
	v_mfma_f32_16x16x32_bf16 v[68:71], v[192:195], v[168:171], v[68:71]
	v_mfma_f32_16x16x32_bf16 v[64:67], v[200:203], v[168:171], v[64:67]
	v_mfma_f32_16x16x32_bf16 v[116:119], v[196:199], v[148:151], v[116:119]
	v_mfma_f32_16x16x32_bf16 v[112:115], v[212:215], v[148:151], v[112:115]
	v_mfma_f32_16x16x32_bf16 v[100:103], v[196:199], v[156:159], v[100:103]
	v_mfma_f32_16x16x32_bf16 v[96:99], v[212:215], v[156:159], v[96:99]
	v_mfma_f32_16x16x32_bf16 v[84:87], v[196:199], v[164:167], v[84:87]
	v_mfma_f32_16x16x32_bf16 v[80:83], v[212:215], v[164:167], v[80:83]
	v_mfma_f32_16x16x32_bf16 v[68:71], v[196:199], v[172:175], v[68:71]
	v_mfma_f32_16x16x32_bf16 v[64:67], v[212:215], v[172:175], v[64:67]
	s_barrier
	s_setprio 0
	s_mov_b32 m0, s46
	ds_read_b128 v[144:147], v208 offset:49152
	ds_read_b128 v[148:151], v208 offset:50176
	ds_read_b128 v[152:155], v208 offset:51200
	ds_read_b128 v[156:159], v208 offset:52224
	ds_read_b128 v[160:163], v208 offset:53248
	ds_read_b128 v[164:167], v208 offset:54272
	ds_read_b128 v[168:171], v208 offset:55296
	ds_read_b128 v[172:175], v208 offset:56320
	global_load_lds_dwordx4 v182, s[100:101]
	s_mov_b32 m0, s47
	s_nop 0
	global_load_lds_dwordx4 v178, s[100:101]
	s_waitcnt lgkmcnt(0)
	s_setprio 1
	s_barrier
	v_mfma_f32_16x16x32_bf16 v[60:63], v[128:131], v[144:147], v[60:63]
	v_mfma_f32_16x16x32_bf16 v[56:59], v[136:139], v[144:147], v[56:59]
	v_mfma_f32_16x16x32_bf16 v[44:47], v[128:131], v[152:155], v[44:47]
	v_mfma_f32_16x16x32_bf16 v[40:43], v[136:139], v[152:155], v[40:43]
	v_mfma_f32_16x16x32_bf16 v[28:31], v[128:131], v[160:163], v[28:31]
	v_mfma_f32_16x16x32_bf16 v[24:27], v[136:139], v[160:163], v[24:27]
	v_mfma_f32_16x16x32_bf16 v[12:15], v[128:131], v[168:171], v[12:15]
	v_mfma_f32_16x16x32_bf16 v[8:11], v[136:139], v[168:171], v[8:11]
	v_mfma_f32_16x16x32_bf16 v[60:63], v[132:135], v[148:151], v[60:63]
	v_mfma_f32_16x16x32_bf16 v[56:59], v[140:143], v[148:151], v[56:59]
	v_mfma_f32_16x16x32_bf16 v[44:47], v[132:135], v[156:159], v[44:47]
	v_mfma_f32_16x16x32_bf16 v[40:43], v[140:143], v[156:159], v[40:43]
	v_mfma_f32_16x16x32_bf16 v[28:31], v[132:135], v[164:167], v[28:31]
	v_mfma_f32_16x16x32_bf16 v[24:27], v[140:143], v[164:167], v[24:27]
	v_mfma_f32_16x16x32_bf16 v[12:15], v[132:135], v[172:175], v[12:15]
	v_mfma_f32_16x16x32_bf16 v[8:11], v[140:143], v[172:175], v[8:11]
	s_barrier
	s_setprio 0
	s_add_u32 s24, s24, 0x80080
	s_addc_u32 s25, s25, 0
	s_add_i32 s26, s26, s35
	s_mov_b32 m0, s26
	s_nop 0
	global_load_lds_dwordx4 v180, s[24:25]
	s_add_i32 m0, s26, 0x2000
	s_nop 0
	global_load_lds_dwordx4 v176, s[24:25]
	s_waitcnt vmcnt(6)
	s_cmp_eq_u32 s53, 28
	s_cbranch_scc0 .Lxs_1
	s_add_i32 m0, s37, 0xc000
	s_nop 0
	global_load_lds_dwordx4 v184, s[100:101]
	s_add_i32 m0, s37, 0xe000
	s_nop 0
	global_load_lds_dwordx4 v186, s[100:101]
; DI unsigned pack2(float lo, float hi) { f32x2 v = {lo, hi}; bf16v2 r = __builtin_convertvector(v, bf16v2); return __builtin_bit_cast(unsigned, r); }
;   DI void operator()(const f32x4 (&acc)[2][2][4][2], const Unit& u, int wr, int wc, int fr, int fq) const {
;     const int row0 = u.pm * BM + wr * 64 + fr, col0 = u.pn * BM + wc * 32 + 8 * fq;
; #pragma unroll
;     for (int ai = 0; ai < 2; ++ai) {
;       f32x4 bv[4][2][2];
; #pragma unroll
;       for (int m = 0; m < 4; ++m)
; #pragma unroll
;         for (int bj = 0; bj < 2; ++bj) {
;           const float* bp = base + (size_t)(row0 + ai * HALF + m * 16) * 2048 + col0 + bj * HALF;
;           bv[m][bj][0] = *(const f32x4*)bp; bv[m][bj][1] = *(const f32x4*)(bp + 4);
;         }
; #pragma unroll
;       for (int m = 0; m < 4; ++m) {
;         const int row = row0 + ai * HALF + m * 16;
;         const size_t off = (size_t)row * 2048 + col0;
;         float ss = 0.f;
; #pragma unroll
;         for (int bj = 0; bj < 2; ++bj) {
;           const f32x4 v0 = acc[ai][bj][m][0] + bv[m][bj][0], v1 = acc[ai][bj][m][1] + bv[m][bj][1];
;           *(f32x4*)(C + off + bj * HALF) = v0; *(f32x4*)(C + off + bj * HALF + 4) = v1;
;           if (xb) {
;             u32x4 w; w.x = pack2(v0[0], v0[1]); w.y = pack2(v0[2], v0[3]); w.z = pack2(v1[0], v1[1]); w.w = pack2(v1[2], v1[3]);
;             *(u32x4*)(xb + off + bj * HALF) = w;
;             ss += v0[0] * v0[0] + v0[1] * v0[1] + v0[2] * v0[2] + v0[3] * v0[3] + v1[0] * v1[0] + v1[1] * v1[1] + v1[2] * v1[2] + v1[3] * v1[3];
;           }
;         }
;         if (xb) {
;           ss += __shfl_xor(ss, 16); ss += __shfl_xor(ss, 32);
;           if (fq == 0) ssq[(size_t)row * 32 + u.pn * 4 + wc] = ss;
;         }
.Lxs_1:
	s_add_i32 s53, s53, 2
	s_add_u32 s22, s22, 0x100
	s_addc_u32 s23, s23, 0
	s_add_u32 s45, s45, 0x100
	s_addc_u32 s52, s52, 0
	s_cmp_gt_u32 s53, 29
	s_setprio 1
	s_barrier
	v_mfma_f32_16x16x32_bf16 v[52:55], v[192:195], v[144:147], v[52:55]
	v_mfma_f32_16x16x32_bf16 v[48:51], v[200:203], v[144:147], v[48:51]
	v_mfma_f32_16x16x32_bf16 v[36:39], v[192:195], v[152:155], v[36:39]
	v_mfma_f32_16x16x32_bf16 v[32:35], v[200:203], v[152:155], v[32:35]
	v_mfma_f32_16x16x32_bf16 v[20:23], v[192:195], v[160:163], v[20:23]
	v_mfma_f32_16x16x32_bf16 v[16:19], v[200:203], v[160:163], v[16:19]
	v_mfma_f32_16x16x32_bf16 v[4:7], v[192:195], v[168:171], v[4:7]
	v_mfma_f32_16x16x32_bf16 v[0:3], v[200:203], v[168:171], v[0:3]
	v_mfma_f32_16x16x32_bf16 v[52:55], v[196:199], v[148:151], v[52:55]
	v_mfma_f32_16x16x32_bf16 v[48:51], v[212:215], v[148:151], v[48:51]
	v_mfma_f32_16x16x32_bf16 v[36:39], v[196:199], v[156:159], v[36:39]
	v_mfma_f32_16x16x32_bf16 v[32:35], v[212:215], v[156:159], v[32:35]
	v_mfma_f32_16x16x32_bf16 v[20:23], v[196:199], v[164:167], v[20:23]
	v_mfma_f32_16x16x32_bf16 v[16:19], v[212:215], v[164:167], v[16:19]
	v_mfma_f32_16x16x32_bf16 v[4:7], v[196:199], v[172:175], v[4:7]
	v_mfma_f32_16x16x32_bf16 v[0:3], v[212:215], v[172:175], v[0:3]
	s_barrier
	s_setprio 0
	s_cbranch_scc0 .LBB0_728
	v_writelane_b32 v247, -2, 0
	v_lshl_add_u32 v196, s12, 8, v204
	v_lshl_or_b32 v192, s42, 8, v206
	v_ashrrev_i32_e32 v193, 31, v192
	v_ashrrev_i32_e32 v197, 31, v196
	v_lshl_add_u64 v[194:195], v[192:193], 2, s[60:61]
	v_lshlrev_b64 v[128:129], 13, v[196:197]
	v_lshl_add_u64 v[128:129], v[194:195], 0, v[128:129]
	global_load_dwordx4 v[214:217], v[128:129], off
	global_load_dwordx4 v[218:221], v[128:129], off offset:16
	global_load_dwordx4 v[222:225], v[128:129], off offset:512
	global_load_dwordx4 v[226:229], v[128:129], off offset:528
	v_or_b32_e32 v202, 16, v196
	v_or_b32_e32 v200, 32, v196
	v_or_b32_e32 v198, 48, v196
	v_ashrrev_i32_e32 v203, 31, v202
	v_ashrrev_i32_e32 v201, 31, v200
	v_ashrrev_i32_e32 v199, 31, v198
	v_lshlrev_b64 v[128:129], 13, v[202:203]
	v_lshlrev_b64 v[130:131], 13, v[200:201]
	v_lshlrev_b64 v[132:133], 13, v[198:199]
	v_lshl_add_u64 v[128:129], v[194:195], 0, v[128:129]
	v_lshl_add_u64 v[130:131], v[194:195], 0, v[130:131]
	v_lshl_add_u64 v[132:133], v[194:195], 0, v[132:133]
	global_load_dwordx4 v[168:171], v[128:129], off offset:16
	global_load_dwordx4 v[172:175], v[128:129], off
	global_load_dwordx4 v[160:163], v[128:129], off offset:528
	global_load_dwordx4 v[164:167], v[128:129], off offset:512
	global_load_dwordx4 v[152:155], v[130:131], off offset:16
	global_load_dwordx4 v[156:159], v[130:131], off
	global_load_dwordx4 v[144:147], v[130:131], off offset:528
	global_load_dwordx4 v[148:151], v[130:131], off offset:512
	global_load_dwordx4 v[136:139], v[132:133], off offset:16
	global_load_dwordx4 v[140:143], v[132:133], off
	s_nop 0
	global_load_dwordx4 v[128:131], v[132:133], off offset:528
	s_nop 0
	global_load_dwordx4 v[132:135], v[132:133], off offset:512
	v_and_b32_e32 v212, 64, v211
	v_xor_b32_e32 v230, 16, v211
	v_add_u32_e32 v232, 64, v212
	v_xor_b32_e32 v231, 32, v211
	v_cmp_lt_i32_e32 vcc, v230, v232
	v_lshlrev_b64 v[212:213], 11, v[196:197]
	v_readlane_b32 s64, v243, 3
	v_cndmask_b32_e32 v233, v211, v230, vcc
	v_cmp_lt_i32_e32 vcc, v231, v232
	v_readlane_b32 s78, v243, 17
	v_readlane_b32 s79, v243, 18
	v_cndmask_b32_e32 v234, v211, v231, vcc
	v_lshl_add_u64 v[230:231], v[212:213], 0, v[192:193]
	v_lshlrev_b32_e32 v212, 2, v233
	v_lshl_add_u64 v[232:233], v[230:231], 2, s[78:79]
	v_lshl_add_u64 v[230:231], v[230:231], 1, s[2:3]
	s_lshl_b32 s22, s42, 2
	s_ashr_i32 s23, s22, 31
	v_readlane_b32 s65, v243, 4
	v_readlane_b32 s66, v243, 5
	v_readlane_b32 s67, v243, 6
	v_readlane_b32 s68, v243, 7
	v_readlane_b32 s69, v243, 8
	v_readlane_b32 s70, v243, 9
	v_readlane_b32 s71, v243, 10
	v_readlane_b32 s72, v243, 11
	v_readlane_b32 s73, v243, 12
	v_readlane_b32 s74, v243, 13
	v_readlane_b32 s75, v243, 14
	v_readlane_b32 s76, v243, 15
	v_readlane_b32 s77, v243, 16
	s_waitcnt vmcnt(0)
	v_pk_add_f32 v[126:127], v[126:127], v[216:217]
	v_pk_add_f32 v[124:125], v[124:125], v[214:215]
	v_pk_add_f32 v[116:117], v[116:117], v[222:223]
	v_pk_add_f32 v[122:123], v[122:123], v[220:221]
	v_pk_add_f32 v[120:121], v[120:121], v[218:219]
	v_pk_add_f32 v[214:215], v[112:113], v[226:227]
	global_store_dwordx4 v[232:233], v[124:127], off
	global_store_dwordx4 v[232:233], v[120:123], off offset:16
	v_cvt_pk_bf16_f32 v112, v124, v125
	v_mul_f32_e32 v125, v125, v125
	v_mul_f32_e32 v213, v117, v117
	v_pk_add_f32 v[118:119], v[118:119], v[224:225]
	v_fmac_f32_e32 v125, v124, v124
	v_fmac_f32_e32 v213, v116, v116
	v_fmac_f32_e32 v125, v126, v126
	v_fmac_f32_e32 v213, v118, v118
	v_fmac_f32_e32 v125, v127, v127
	v_fmac_f32_e32 v213, v119, v119
	v_fmac_f32_e32 v125, v120, v120
	v_fmac_f32_e32 v213, v214, v214
	v_pk_add_f32 v[216:217], v[114:115], v[228:229]
	v_fmac_f32_e32 v125, v121, v121
	v_fmac_f32_e32 v213, v215, v215
	v_fmac_f32_e32 v125, v122, v122
	v_fmac_f32_e32 v213, v216, v216
	v_fmac_f32_e32 v125, v123, v123
	v_fmac_f32_e32 v213, v217, v217
	v_cvt_pk_bf16_f32 v114, v120, v121
	v_add_f32_e32 v120, v125, v213
	ds_bpermute_b32 v121, v212, v120
	v_cvt_pk_bf16_f32 v113, v126, v127
	v_cvt_pk_bf16_f32 v115, v122, v123
	global_store_dwordx4 v[230:231], v[112:115], off
	global_store_dwordx4 v[232:233], v[116:119], off offset:512
	global_store_dwordx4 v[232:233], v[214:217], off offset:528
	v_cvt_pk_bf16_f32 v122, v116, v117
	s_waitcnt lgkmcnt(0)
	v_add_f32_e32 v112, v120, v121
	v_lshlrev_b32_e32 v120, 2, v234
	ds_bpermute_b32 v113, v120, v112
	v_cvt_pk_bf16_f32 v123, v118, v119
	v_cvt_pk_bf16_f32 v124, v214, v215
	v_cvt_pk_bf16_f32 v125, v216, v217
	global_store_dwordx4 v[230:231], v[122:125], off offset:256
	s_and_saveexec_b64 s[24:25], s[0:1]
	s_cbranch_execz .LBB0_731
	s_waitcnt lgkmcnt(0)
	v_add_f32_e32 v114, v112, v113
	v_lshlrev_b64 v[112:113], 7, v[196:197]
	v_lshl_add_u64 v[112:113], s[8:9], 0, v[112:113]
	v_lshl_add_u64 v[112:113], s[22:23], 2, v[112:113]
	s_lshl_b32 s12, s41, 2
	v_lshl_add_u64 v[112:113], v[112:113], 0, s[12:13]
	global_store_dword v[112:113], v114, off

; #define LAS __attribute__((address_space(3)))
; #define PG8_STAGE(bufoff, gbase, voff) do { _Pragma("unroll") for (int _i = 0; _i < 2; ++_i) \
;     __builtin_amdgcn_global_load_lds((const unsigned*)((const char*)(gbase) + (voff)[_i]), (LAS unsigned*)(lds + (bufoff) + ldsw + _i * 8192), 16, 0, 0); } while (0)
; #define PG8_BAR __builtin_amdgcn_s_barrier()
; template <class Epi, class Sched = StaticOrder>
; DI void gemm_phase(LAS unsigned char* lds, const Gemm g, const Sched& S, const Epi& E) {
;   const int tid = threadIdx.x, wid = __builtin_amdgcn_readfirstlane(tid >> 6), lane = tid & 63, wr = wid >> 2, wc = wid & 3, fr = lane & 15, fq = lane >> 4;
;   const int K = g.K, nt = K / BK;
;   unsigned voffA[2], voffB[2];
; #pragma unroll
;   for (int i = 0; i < 2; ++i) { int R, C; stage_rc(tid * 16 + i * 8192, R, C); const int Rb = Epi::PERM ? ((R & ~31) + perm32(R & 31)) : R;
;     voffA[i] = (unsigned)(R * K + C) * 2u; voffB[i] = (unsigned)(Rb * K + C) * 2u; }
;   const size_t kstep = (size_t)(BK * 2);
;   const size_t hstep = (size_t)HALF * K * 2;
;   const size_t tstep = 2 * hstep;
;   const unsigned ldsw = (unsigned)wid * 1024u;
;   const int aoff = lds_byte(wr * 64 + fr, fq * 8), boff = lds_byte(wc * 32 + fr, fq * 8);
;     ...
;   Unit cur, nxt; int ui = 0;
;   if (!S.next(0, cur)) return;
;   f32x4 acc[2][2][4][2];
; #pragma unroll
;   for (int a = 0; a < 2; ++a)
; #pragma unroll
;     for (int b = 0; b < 2; ++b)
; #pragma unroll
;       for (int m = 0; m < 4; ++m)
; #pragma unroll
;         for (int n = 0; n < 2; ++n) acc[a][b][m][n] = (f32x4){0.f, 0.f, 0.f, 0.f};
;   bf16x8 At[4][2], B0[2][2], B1[2][2];
;   const char* cA = (const char*)g.A + (size_t)cur.pm * tstep; const char* cB = (const char*)g.Bt + (size_t)cur.pn * tstep;
;   PG8_STAGE(PG8_SB(0, 0), cB, voffB); PG8_STAGE(PG8_SA(0, 0), cA, voffA); PG8_STAGE(PG8_SB(0, 1), cB + hstep, voffB); PG8_STAGE(PG8_SA(0, 1), cA + hstep, voffA);
;   if (wr == 1) PG8_BAR;
; DI void run_gemm(const Params& p, int id, unsigned char* smem) {
;     ...
;   S.init(g.M, g.N, (int)gridDim.x, __builtin_amdgcn_readfirstlane((int)((volatile LAS unsigned*)(LAS unsigned char*)(smem + 131072))[2]));
.LBB0_803:
	v_writelane_b32 v247, 1, 0
	s_add_i32 s0, 0, 0x20008
	v_mov_b32_e32 v0, s0
	ds_read_b32 v0, v0
	v_readfirstlane_b32 s33, v210
	s_waitcnt lgkmcnt(0)
	v_readfirstlane_b32 s31, v0
	s_cmpk_gt_i32 s31, 0xaff
	s_cbranch_scc1 .LBB0_827
	v_lshrrev_b32_e32 v0, 5, v210
	v_lshrrev_b32_e32 v2, 1, v210
	v_and_b32_e32 v0, 4, v0
	v_bfe_u32 v1, v210, 2, 2
	v_and_b32_e32 v11, 24, v2
	v_or3_b32 v0, v0, v1, v11
	v_lshlrev_b32_e32 v1, 4, v210
	v_add_u32_e32 v8, 0x2000, v1
	v_lshrrev_b32_e32 v2, 7, v8
	s_movk_i32 s0, 0xe0
	v_and_b32_e32 v4, 32, v210
	s_add_u32 s77, s84, 0xc103600
	v_and_or_b32 v3, v2, s0, v0
	v_bitop3_b32 v9, v1, v4, 48 bitop3:0x6c
	v_and_b32_e32 v10, 64, v210
	v_bfe_u32 v12, v210, 2, 4
	s_movk_i32 s0, 0xf0
	s_addc_u32 s78, s85, 0
	v_or_b32_e32 v1, v9, v10
	v_and_or_b32 v2, v2, s0, v12
	s_add_u32 s79, s84, 0x1b03600
	v_lshl_or_b32 v162, v2, 12, v1
	v_lshrrev_b32_e32 v2, 3, v210
	s_movk_i32 s0, 0x60
	s_addc_u32 s80, s85, 0
	v_and_or_b32 v0, v2, s0, v0
	s_movk_i32 s0, 0x70
	s_ashr_i32 s61, s31, 31
	v_lshl_or_b32 v164, v0, 12, v1
	v_and_or_b32 v0, v2, s0, v12
	s_lshr_b32 s0, s61, 29
	s_add_i32 s0, s31, s0
	s_ashr_i32 s5, s0, 3
	s_and_b32 s0, s0, -8
	s_sub_i32 s0, s31, s0
	s_lshr_b32 s6, s0, 31
	s_or_b32 s6, s6, 0x160
	s_mul_i32 s0, s6, s0
	s_add_i32 s0, s0, s5
	s_mul_hi_i32 s5, s0, 0x2e8ba2e9
	s_lshr_b32 s6, s5, 31
	s_ashr_i32 s5, s5, 6
	s_add_i32 s5, s5, s6
	s_lshl_b32 s8, s5, 3
	s_sub_i32 s6, 64, s8
	s_min_u32 s9, s6, 8
	s_mulk_i32 s5, 0x160
	v_lshl_or_b32 v160, v3, 12, v1
	s_sub_i32 s5, s0, s5
	v_cvt_f32_ubyte0_e32 v3, s9
	v_cvt_f32_i32_e32 v2, s5
	v_rcp_iflag_f32_e32 v4, v3
	v_lshl_or_b32 v166, v0, 12, v1
	s_lshr_b32 s1, s33, 6
	s_ashr_i32 s0, s5, 30
	v_mul_f32_e32 v0, v2, v4
	v_trunc_f32_e32 v0, v0
	v_fma_f32 v1, -v0, v3, v2
	v_cvt_i32_f32_e32 v0, v0
	s_lshr_b32 s4, s33, 8
	s_lshl_b32 s60, s1, 10
	s_or_b32 s0, s0, 1
	v_cmp_ge_f32_e64 s[6:7], |v1|, v3
	s_and_b64 s[6:7], s[6:7], exec
	s_cselect_b32 s0, s0, 0
	v_readfirstlane_b32 s6, v0
	s_add_i32 s0, s6, s0
	s_mul_i32 s6, s0, s9
	s_sub_i32 s5, s5, s6
	s_sext_i32_i16 s5, s5
	s_add_i32 s12, s8, s5
	s_ashr_i32 s13, s12, 31
	s_bfe_i64 s[8:9], s[0:1], 0x100000
	s_lshl_b64 s[6:7], s[12:13], 20
	s_lshl_b64 s[8:9], s[8:9], 20
	s_add_u32 s46, s79, s8
	s_addc_u32 s47, s80, s9
	s_add_i32 s62, s60, 0
	s_add_i32 m0, s62, 0x10000
	v_mov_b32_e32 v165, 0
	global_load_lds_dwordx4 v164, s[46:47]
	s_add_i32 m0, s62, 0x12000
	s_add_u32 s14, s77, s6
	global_load_lds_dwordx4 v160, s[46:47]
	s_addc_u32 s15, s78, s7
	s_mov_b32 m0, s62
	s_add_i32 s63, s62, 0x2000
	global_load_lds_dwordx4 v166, s[14:15]
	s_mov_b32 m0, s63
	s_add_u32 s6, s46, 0x80000
	global_load_lds_dwordx4 v162, s[14:15]
	s_addc_u32 s7, s47, 0
	s_add_i32 m0, s62, 0x14000
	v_mov_b32_e32 v161, v165
	global_load_lds_dwordx4 v164, s[6:7]
	s_add_i32 m0, s62, 0x16000
	v_mov_b32_e32 v167, v165
	global_load_lds_dwordx4 v160, s[6:7]
	s_add_u32 s6, s14, 0x80000
	s_addc_u32 s7, s15, 0
	s_add_i32 s64, s62, 0x4000
	s_mov_b32 m0, s64
	s_add_i32 s65, s62, 0x6000
	global_load_lds_dwordx4 v166, s[6:7]
	s_mov_b32 m0, s65
	v_mov_b32_e32 v163, v165
	global_load_lds_dwordx4 v162, s[6:7]
	v_lshl_add_u64 v[6:7], s[46:47], 0, v[164:165]
	v_lshl_add_u64 v[4:5], s[46:47], 0, v[160:161]
	v_lshl_add_u64 v[2:3], s[14:15], 0, v[166:167]
	s_cmp_lg_u32 s4, 1
	v_lshl_add_u64 v[0:1], s[14:15], 0, v[162:163]
	s_cbranch_scc1 .LBB0_806
	s_barrier

; #define PG8_STAGE(bufoff, gbase, voff) do { _Pragma("unroll") for (int _i = 0; _i < 2; ++_i) \
;     __builtin_amdgcn_global_load_lds((const unsigned*)((const char*)(gbase) + (voff)[_i]), (LAS unsigned*)(lds + (bufoff) + ldsw + _i * 8192), 16, 0, 0); } while (0)
; #define PG8_LDA(dst, b, h) do { _Pragma("unroll") for (int m = 0; m < 4; ++m) _Pragma("unroll") for (int k = 0; k < 2; ++k) dst[m][k] = *(const LAS bf16x8*)(lds + PG8_SA(b, h) + aoff + m * 2048 + k * 1024); } while (0)
; #define PG8_LDB(dst, b, h) do { _Pragma("unroll") for (int n = 0; n < 2; ++n) _Pragma("unroll") for (int k = 0; k < 2; ++k) dst[n][k] = *(const LAS bf16x8*)(lds + PG8_SB(b, h) + boff + n * 2048 + k * 1024); } while (0)
; #define PG8_MMA(ai, bj, At, Bt) do { __builtin_amdgcn_s_setprio(1); _Pragma("unroll") for (int m = 0; m < 4; ++m) _Pragma("unroll") for (int n = 0; n < 2; ++n) _Pragma("unroll") for (int k = 0; k < 2; ++k) \
;     acc[ai][bj][m][n] = __builtin_amdgcn_mfma_f32_16x16x32_bf16(Bt[n][k], At[m][k], acc[ai][bj][m][n], 0, 0, 0); __builtin_amdgcn_s_setprio(0); } while (0)
; #define PG8_WAIT_V(n) asm volatile("s_waitcnt vmcnt(" #n ")" ::: "memory")
; #define PG8_WAIT_L(n) asm volatile("s_waitcnt lgkmcnt(" #n ")" ::: "memory")
; #define PG8_BAR __builtin_amdgcn_s_barrier()
; #define PG8_SCHED __builtin_amdgcn_sched_barrier(0)
; template <class Epi, class Sched = StaticOrder>
; DI void gemm_phase(LAS unsigned char* lds, const Gemm g, const Sched& S, const Epi& E) {
;     ...
;     for (int t = 0; t < nt; t += 2) {
;       const bool last = (t == nt - 2);
;       const char* a1 = cA + (size_t)(t + 1) * kstep;
;       const char* a2 = last ? nA : cA + (size_t)(t + 2) * kstep; const char* b2 = last ? nB : cB + (size_t)(t + 2) * kstep;
;       const char* a3 = a2 + kstep; const char* b3 = b2 + kstep;
;       PG8_LDB(B0, 0, 0); PG8_SCHED; PG8_LDA(At, 0, 0); PG8_STAGE(PG8_SA(1, 1), a1 + hstep, voffA);
;       PG8_WAIT_L(8); PG8_BAR; PG8_WAIT_L(0); PG8_MMA(0, 0, At, B0); PG8_BAR; PG8_SCHED;
;       PG8_LDB(B1, 0, 1); PG8_STAGE(PG8_SB(0, 0), b2, voffB);
;       PG8_BAR; PG8_WAIT_L(0); PG8_MMA(0, 1, At, B1); PG8_BAR;
;       PG8_LDA(At, 0, 1); PG8_STAGE(PG8_SA(0, 0), a2, voffA);
;       PG8_BAR; PG8_WAIT_L(0); PG8_MMA(1, 0, At, B0); PG8_BAR; PG8_SCHED;
;       PG8_STAGE(PG8_SB(0, 1), b2 + hstep, voffB);
;       PG8_WAIT_V(6); PG8_BAR; PG8_MMA(1, 1, At, B1); PG8_BAR;
.LBB0_811:
	ds_read_b128 v[64:67], v201
	ds_read_b128 v[68:71], v201 offset:1024
	ds_read_b128 v[72:75], v201 offset:2048
	ds_read_b128 v[76:79], v201 offset:3072
	s_add_u32 s46, s14, 0xfff80080
	s_addc_u32 s47, s15, -1
	s_cmp_eq_u32 s52, 28
	s_cselect_b32 s49, s37, s47
	s_cselect_b32 s48, s42, s46
	s_cselect_b32 s47, s35, s45
	s_cselect_b32 s46, s43, s44
	s_add_i32 m0, s62, 0xc000
	ds_read_b128 v[80:83], v202
	ds_read_b128 v[84:87], v202 offset:1024
	ds_read_b128 v[92:95], v202 offset:2048
	ds_read_b128 v[96:99], v202 offset:3072
	ds_read_b128 v[180:183], v202 offset:4096
	ds_read_b128 v[184:187], v202 offset:5120
	ds_read_b128 v[188:191], v202 offset:6144
	ds_read_b128 v[192:195], v202 offset:7168
	global_load_lds_dwordx4 v170, s[14:15]
	s_add_i32 m0, s62, 0xe000
	s_nop 0
	global_load_lds_dwordx4 v172, s[14:15]
	s_waitcnt lgkmcnt(0)
	s_setprio 1
	s_barrier
	v_mfma_f32_16x16x32_bf16 v[156:159], v[64:67], v[80:83], v[156:159]
	v_mfma_f32_16x16x32_bf16 v[144:147], v[72:75], v[80:83], v[144:147]
	v_mfma_f32_16x16x32_bf16 v[140:143], v[64:67], v[92:95], v[140:143]
	v_mfma_f32_16x16x32_bf16 v[132:135], v[72:75], v[92:95], v[132:135]
	v_mfma_f32_16x16x32_bf16 v[124:127], v[64:67], v[180:183], v[124:127]
	v_mfma_f32_16x16x32_bf16 v[116:119], v[72:75], v[180:183], v[116:119]
	v_mfma_f32_16x16x32_bf16 v[112:115], v[64:67], v[188:191], v[112:115]
	v_mfma_f32_16x16x32_bf16 v[108:111], v[72:75], v[188:191], v[108:111]
	v_mfma_f32_16x16x32_bf16 v[156:159], v[68:71], v[84:87], v[156:159]
	v_mfma_f32_16x16x32_bf16 v[144:147], v[76:79], v[84:87], v[144:147]
	v_mfma_f32_16x16x32_bf16 v[140:143], v[68:71], v[96:99], v[140:143]
	v_mfma_f32_16x16x32_bf16 v[132:135], v[76:79], v[96:99], v[132:135]
	v_mfma_f32_16x16x32_bf16 v[124:127], v[68:71], v[184:187], v[124:127]
	v_mfma_f32_16x16x32_bf16 v[116:119], v[76:79], v[184:187], v[116:119]
	v_mfma_f32_16x16x32_bf16 v[112:115], v[68:71], v[192:195], v[112:115]
	v_mfma_f32_16x16x32_bf16 v[108:111], v[76:79], v[192:195], v[108:111]
	s_barrier
	s_setprio 0
	s_add_i32 s53, s72, s60
	s_add_u32 s98, s46, 0x80
	s_addc_u32 s99, s47, 0
	s_add_u32 s100, s48, 0x80
	s_addc_u32 s101, s49, 0
	s_mov_b32 m0, s53
	ds_read_b128 v[206:209], v203
	ds_read_b128 v[212:215], v203 offset:1024
	ds_read_b128 v[216:219], v203 offset:2048
	ds_read_b128 v[220:223], v203 offset:3072
	global_load_lds_dwordx4 v164, s[46:47]
	s_add_i32 m0, s53, 0x2000
	s_nop 0
	global_load_lds_dwordx4 v160, s[46:47]
	s_waitcnt lgkmcnt(0)
	s_setprio 1
	s_barrier
	v_mfma_f32_16x16x32_bf16 v[152:155], v[206:209], v[80:83], v[152:155]
	v_mfma_f32_16x16x32_bf16 v[80:83], v[216:219], v[80:83], v[148:151]
	v_mfma_f32_16x16x32_bf16 v[152:155], v[212:215], v[84:87], v[152:155]
	v_mfma_f32_16x16x32_bf16 v[80:83], v[220:223], v[84:87], v[80:83]
	v_mfma_f32_16x16x32_bf16 v[84:87], v[206:209], v[92:95], v[136:139]
	v_mfma_f32_16x16x32_bf16 v[92:95], v[216:219], v[92:95], v[128:131]
	v_mfma_f32_16x16x32_bf16 v[104:107], v[216:219], v[180:183], v[104:107]
	v_mfma_f32_16x16x32_bf16 v[100:103], v[206:209], v[188:191], v[100:103]
	v_mfma_f32_16x16x32_bf16 v[88:91], v[216:219], v[188:191], v[88:91]
	v_mfma_f32_16x16x32_bf16 v[84:87], v[212:215], v[96:99], v[84:87]
	v_mfma_f32_16x16x32_bf16 v[92:95], v[220:223], v[96:99], v[92:95]
	v_mfma_f32_16x16x32_bf16 v[96:99], v[206:209], v[180:183], v[120:123]
	v_mfma_f32_16x16x32_bf16 v[104:107], v[220:223], v[184:187], v[104:107]
	v_mfma_f32_16x16x32_bf16 v[100:103], v[212:215], v[192:195], v[100:103]
	v_mfma_f32_16x16x32_bf16 v[88:91], v[220:223], v[192:195], v[88:91]
	v_mfma_f32_16x16x32_bf16 v[96:99], v[212:215], v[184:187], v[96:99]
	s_barrier
	s_setprio 0
	s_mov_b32 m0, s62
	ds_read_b128 v[120:123], v202 offset:16384
	ds_read_b128 v[128:131], v202 offset:17408
	ds_read_b128 v[136:139], v202 offset:18432
	ds_read_b128 v[148:151], v202 offset:19456
	ds_read_b128 v[180:183], v202 offset:20480
	ds_read_b128 v[184:187], v202 offset:21504
	ds_read_b128 v[188:191], v202 offset:22528
	ds_read_b128 v[192:195], v202 offset:23552
	global_load_lds_dwordx4 v166, s[48:49]
	s_mov_b32 m0, s63
	s_nop 0
	global_load_lds_dwordx4 v162, s[48:49]
	s_waitcnt lgkmcnt(0)
	s_setprio 1
	s_barrier
	v_mfma_f32_16x16x32_bf16 v[60:63], v[64:67], v[120:123], v[60:63]
	v_mfma_f32_16x16x32_bf16 v[48:51], v[72:75], v[120:123], v[48:51]
	v_mfma_f32_16x16x32_bf16 v[44:47], v[64:67], v[136:139], v[44:47]
	v_mfma_f32_16x16x32_bf16 v[36:39], v[72:75], v[136:139], v[36:39]
	v_mfma_f32_16x16x32_bf16 v[28:31], v[64:67], v[180:183], v[28:31]
	v_mfma_f32_16x16x32_bf16 v[20:23], v[72:75], v[180:183], v[20:23]
	v_mfma_f32_16x16x32_bf16 v[16:19], v[64:67], v[188:191], v[16:19]
	v_mfma_f32_16x16x32_bf16 v[12:15], v[72:75], v[188:191], v[12:15]
	v_mfma_f32_16x16x32_bf16 v[60:63], v[68:71], v[128:131], v[60:63]
	v_mfma_f32_16x16x32_bf16 v[48:51], v[76:79], v[128:131], v[48:51]
	v_mfma_f32_16x16x32_bf16 v[44:47], v[68:71], v[148:151], v[44:47]
	v_mfma_f32_16x16x32_bf16 v[36:39], v[76:79], v[148:151], v[36:39]
	v_mfma_f32_16x16x32_bf16 v[28:31], v[68:71], v[184:187], v[28:31]
	v_mfma_f32_16x16x32_bf16 v[20:23], v[76:79], v[184:187], v[20:23]
	v_mfma_f32_16x16x32_bf16 v[16:19], v[68:71], v[192:195], v[16:19]
	v_mfma_f32_16x16x32_bf16 v[12:15], v[76:79], v[192:195], v[12:15]
	s_barrier
	s_setprio 0
	s_add_u32 s54, s46, 0x80000
	s_addc_u32 s55, s47, 0
	s_add_i32 s53, s73, s60
	s_mov_b32 m0, s53
	s_nop 0
	global_load_lds_dwordx4 v164, s[54:55]
	s_add_i32 m0, s53, 0x2000
	s_nop 0
	global_load_lds_dwordx4 v160, s[54:55]
	v_readlane_b32 vcc_lo, v247, 0
	s_cmp_eq_u32 s52, vcc_lo
	s_cbranch_scc1 .Lsw_2
	s_waitcnt vmcnt(6)
; #define PG8_STAGE(bufoff, gbase, voff) do { _Pragma("unroll") for (int _i = 0; _i < 2; ++_i) \
;     __builtin_amdgcn_global_load_lds((const unsigned*)((const char*)(gbase) + (voff)[_i]), (LAS unsigned*)(lds + (bufoff) + ldsw + _i * 8192), 16, 0, 0); } while (0)
; #define PG8_LDA(dst, b, h) do { _Pragma("unroll") for (int m = 0; m < 4; ++m) _Pragma("unroll") for (int k = 0; k < 2; ++k) dst[m][k] = *(const LAS bf16x8*)(lds + PG8_SA(b, h) + aoff + m * 2048 + k * 1024); } while (0)
; #define PG8_LDB(dst, b, h) do { _Pragma("unroll") for (int n = 0; n < 2; ++n) _Pragma("unroll") for (int k = 0; k < 2; ++k) dst[n][k] = *(const LAS bf16x8*)(lds + PG8_SB(b, h) + boff + n * 2048 + k * 1024); } while (0)
; #define PG8_MMA(ai, bj, At, Bt) do { __builtin_amdgcn_s_setprio(1); _Pragma("unroll") for (int m = 0; m < 4; ++m) _Pragma("unroll") for (int n = 0; n < 2; ++n) _Pragma("unroll") for (int k = 0; k < 2; ++k) \
;     acc[ai][bj][m][n] = __builtin_amdgcn_mfma_f32_16x16x32_bf16(Bt[n][k], At[m][k], acc[ai][bj][m][n], 0, 0, 0); __builtin_amdgcn_s_setprio(0); } while (0)
; #define PG8_WAIT_V(n) asm volatile("s_waitcnt vmcnt(" #n ")" ::: "memory")
; #define PG8_WAIT_L(n) asm volatile("s_waitcnt lgkmcnt(" #n ")" ::: "memory")
; #define PG8_BAR __builtin_amdgcn_s_barrier()
; #define PG8_SCHED __builtin_amdgcn_sched_barrier(0)
; template <class Epi, class Sched = StaticOrder>
; DI void gemm_phase(LAS unsigned char* lds, const Gemm g, const Sched& S, const Epi& E) {
;     ...
;       PG8_LDB(B0, 1, 0); PG8_SCHED; PG8_LDA(At, 1, 0); PG8_STAGE(PG8_SA(0, 1), a2 + hstep, voffA);
;       PG8_WAIT_L(8); PG8_BAR; PG8_WAIT_L(0); PG8_MMA(0, 0, At, B0); PG8_BAR; PG8_SCHED;
;       PG8_LDB(B1, 1, 1); PG8_STAGE(PG8_SB(1, 0), b3, voffB);
;       PG8_BAR; PG8_WAIT_L(0); PG8_MMA(0, 1, At, B1); PG8_BAR;
;       PG8_LDA(At, 1, 1); PG8_STAGE(PG8_SA(1, 0), a3, voffA);
;       PG8_BAR; PG8_WAIT_L(0); PG8_MMA(1, 0, At, B0); PG8_BAR; PG8_SCHED;
;       PG8_STAGE(PG8_SB(1, 1), b3 + hstep, voffB);
;       PG8_WAIT_V(6); PG8_BAR; PG8_MMA(1, 1, At, B1); PG8_BAR;
.Lsw_2:
	s_setprio 1
	s_barrier
	v_mfma_f32_16x16x32_bf16 v[56:59], v[206:209], v[120:123], v[56:59]
	v_mfma_f32_16x16x32_bf16 v[52:55], v[216:219], v[120:123], v[52:55]
	v_mfma_f32_16x16x32_bf16 v[40:43], v[206:209], v[136:139], v[40:43]
	v_mfma_f32_16x16x32_bf16 v[32:35], v[216:219], v[136:139], v[32:35]
	v_mfma_f32_16x16x32_bf16 v[24:27], v[206:209], v[180:183], v[24:27]
	v_mfma_f32_16x16x32_bf16 v[8:11], v[216:219], v[180:183], v[8:11]
	v_mfma_f32_16x16x32_bf16 v[4:7], v[206:209], v[188:191], v[4:7]
	v_mfma_f32_16x16x32_bf16 v[0:3], v[216:219], v[188:191], v[0:3]
	v_mfma_f32_16x16x32_bf16 v[56:59], v[212:215], v[128:131], v[56:59]
	v_mfma_f32_16x16x32_bf16 v[52:55], v[220:223], v[128:131], v[52:55]
	v_mfma_f32_16x16x32_bf16 v[40:43], v[212:215], v[148:151], v[40:43]
	v_mfma_f32_16x16x32_bf16 v[32:35], v[220:223], v[148:151], v[32:35]
	v_mfma_f32_16x16x32_bf16 v[24:27], v[212:215], v[184:187], v[24:27]
	v_mfma_f32_16x16x32_bf16 v[8:11], v[220:223], v[184:187], v[8:11]
	v_mfma_f32_16x16x32_bf16 v[4:7], v[212:215], v[192:195], v[4:7]
	v_mfma_f32_16x16x32_bf16 v[0:3], v[220:223], v[192:195], v[0:3]
	s_barrier
	s_setprio 0
	s_add_i32 s53, 0, 0x18000
	v_add_u32_e32 v76, s53, v198
	ds_read_b128 v[64:67], v76
	ds_read_b128 v[68:71], v76 offset:1024
	ds_read_b128 v[72:75], v76 offset:2048
	ds_read_b128 v[76:79], v76 offset:3072
	s_add_u32 s48, s48, 0x80000
	s_addc_u32 s49, s49, 0
	s_mov_b32 m0, s64
	ds_read_b128 v[120:123], v202 offset:32768
	ds_read_b128 v[128:131], v202 offset:33792
	ds_read_b128 v[180:183], v202 offset:34816
	ds_read_b128 v[184:187], v202 offset:35840
	ds_read_b128 v[188:191], v202 offset:36864
	ds_read_b128 v[192:195], v202 offset:37888
	ds_read_b128 v[206:209], v202 offset:38912
	ds_read_b128 v[212:215], v202 offset:39936
	global_load_lds_dwordx4 v166, s[48:49]
	s_mov_b32 m0, s65
	s_nop 0
	global_load_lds_dwordx4 v162, s[48:49]
	s_waitcnt lgkmcnt(0)
	s_setprio 1
	s_barrier
	v_mfma_f32_16x16x32_bf16 v[136:139], v[64:67], v[120:123], v[156:159]
	v_mfma_f32_16x16x32_bf16 v[156:159], v[68:71], v[128:131], v[136:139]
	v_mfma_f32_16x16x32_bf16 v[136:139], v[72:75], v[120:123], v[144:147]
	v_mfma_f32_16x16x32_bf16 v[144:147], v[76:79], v[128:131], v[136:139]
	v_mfma_f32_16x16x32_bf16 v[136:139], v[64:67], v[180:183], v[140:143]
	v_mfma_f32_16x16x32_bf16 v[132:135], v[72:75], v[180:183], v[132:135]
	v_mfma_f32_16x16x32_bf16 v[124:127], v[64:67], v[188:191], v[124:127]
	v_mfma_f32_16x16x32_bf16 v[116:119], v[72:75], v[188:191], v[116:119]
	v_mfma_f32_16x16x32_bf16 v[112:115], v[64:67], v[206:209], v[112:115]
	v_mfma_f32_16x16x32_bf16 v[108:111], v[72:75], v[206:209], v[108:111]
	v_mfma_f32_16x16x32_bf16 v[140:143], v[68:71], v[184:187], v[136:139]
	v_mfma_f32_16x16x32_bf16 v[132:135], v[76:79], v[184:187], v[132:135]
	v_mfma_f32_16x16x32_bf16 v[124:127], v[68:71], v[192:195], v[124:127]
	v_mfma_f32_16x16x32_bf16 v[116:119], v[76:79], v[192:195], v[116:119]
	v_mfma_f32_16x16x32_bf16 v[112:115], v[68:71], v[212:215], v[112:115]
	v_mfma_f32_16x16x32_bf16 v[108:111], v[76:79], v[212:215], v[108:111]
	s_barrier
	s_setprio 0
	s_add_i32 s48, 0, 0x1c000
	v_add_u32_e32 v136, s48, v198
	s_add_i32 s49, s53, s60
	ds_read_b128 v[216:219], v136
	ds_read_b128 v[220:223], v136 offset:1024
	ds_read_b128 v[224:227], v136 offset:2048
	ds_read_b128 v[228:231], v136 offset:3072
	s_mov_b32 m0, s49
	s_nop 0
	global_load_lds_dwordx4 v164, s[98:99]
	s_add_i32 m0, s49, 0x2000
	s_nop 0
	global_load_lds_dwordx4 v160, s[98:99]
	s_waitcnt lgkmcnt(0)
	s_setprio 1
	s_barrier
	v_mfma_f32_16x16x32_bf16 v[80:83], v[224:227], v[120:123], v[80:83]
	v_mfma_f32_16x16x32_bf16 v[136:139], v[216:219], v[120:123], v[152:155]
	v_mfma_f32_16x16x32_bf16 v[148:151], v[228:231], v[128:131], v[80:83]
	v_mfma_f32_16x16x32_bf16 v[80:83], v[216:219], v[180:183], v[84:87]
	v_mfma_f32_16x16x32_bf16 v[152:155], v[220:223], v[128:131], v[136:139]
	v_mfma_f32_16x16x32_bf16 v[136:139], v[220:223], v[184:187], v[80:83]
	v_mfma_f32_16x16x32_bf16 v[80:83], v[224:227], v[180:183], v[92:95]
	v_mfma_f32_16x16x32_bf16 v[128:131], v[228:231], v[184:187], v[80:83]
	v_mfma_f32_16x16x32_bf16 v[80:83], v[216:219], v[188:191], v[96:99]
	v_mfma_f32_16x16x32_bf16 v[120:123], v[220:223], v[192:195], v[80:83]
	v_mfma_f32_16x16x32_bf16 v[80:83], v[224:227], v[188:191], v[104:107]
	v_mfma_f32_16x16x32_bf16 v[104:107], v[228:231], v[192:195], v[80:83]
	v_mfma_f32_16x16x32_bf16 v[80:83], v[216:219], v[206:209], v[100:103]
	v_mfma_f32_16x16x32_bf16 v[100:103], v[220:223], v[212:215], v[80:83]
	v_mfma_f32_16x16x32_bf16 v[80:83], v[224:227], v[206:209], v[88:91]
	v_mfma_f32_16x16x32_bf16 v[88:91], v[228:231], v[212:215], v[80:83]
	s_barrier
	s_setprio 0
	s_mov_b32 m0, s67
	s_nop 2
	ds_read_b128 v[80:83], v202 offset:49152
	ds_read_b128 v[84:87], v202 offset:50176
	ds_read_b128 v[92:95], v202 offset:51200
	ds_read_b128 v[96:99], v202 offset:52224
	ds_read_b128 v[180:183], v202 offset:53248
	ds_read_b128 v[184:187], v202 offset:54272
	ds_read_b128 v[188:191], v202 offset:55296
	ds_read_b128 v[192:195], v202 offset:56320
	global_load_lds_dwordx4 v166, s[100:101]
	s_mov_b32 m0, s68
	s_nop 0
	global_load_lds_dwordx4 v162, s[100:101]
	s_waitcnt lgkmcnt(0)
	s_setprio 1
	s_barrier
	v_mfma_f32_16x16x32_bf16 v[60:63], v[64:67], v[80:83], v[60:63]
	v_mfma_f32_16x16x32_bf16 v[48:51], v[72:75], v[80:83], v[48:51]
	v_mfma_f32_16x16x32_bf16 v[44:47], v[64:67], v[92:95], v[44:47]
	v_mfma_f32_16x16x32_bf16 v[36:39], v[72:75], v[92:95], v[36:39]
	v_mfma_f32_16x16x32_bf16 v[28:31], v[64:67], v[180:183], v[28:31]
	v_mfma_f32_16x16x32_bf16 v[20:23], v[72:75], v[180:183], v[20:23]
	v_mfma_f32_16x16x32_bf16 v[16:19], v[64:67], v[188:191], v[16:19]
	v_mfma_f32_16x16x32_bf16 v[12:15], v[72:75], v[188:191], v[12:15]
	v_mfma_f32_16x16x32_bf16 v[60:63], v[68:71], v[84:87], v[60:63]
	v_mfma_f32_16x16x32_bf16 v[48:51], v[76:79], v[84:87], v[48:51]
	v_mfma_f32_16x16x32_bf16 v[44:47], v[68:71], v[96:99], v[44:47]
	v_mfma_f32_16x16x32_bf16 v[36:39], v[76:79], v[96:99], v[36:39]
	v_mfma_f32_16x16x32_bf16 v[28:31], v[68:71], v[184:187], v[28:31]
	v_mfma_f32_16x16x32_bf16 v[20:23], v[76:79], v[184:187], v[20:23]
	v_mfma_f32_16x16x32_bf16 v[16:19], v[68:71], v[192:195], v[16:19]
	v_mfma_f32_16x16x32_bf16 v[12:15], v[76:79], v[192:195], v[12:15]
	s_barrier
	s_setprio 0
	s_add_u32 s46, s46, 0x80080
	s_addc_u32 s47, s47, 0
	s_add_i32 s48, s48, s60
	s_mov_b32 m0, s48
	s_nop 0
	global_load_lds_dwordx4 v164, s[46:47]
	s_add_i32 m0, s48, 0x2000
	s_nop 0
	global_load_lds_dwordx4 v160, s[46:47]
	s_waitcnt vmcnt(6)
	s_cmp_eq_u32 s52, 28
	s_cbranch_scc0 .Lxs_2
	s_add_i32 m0, s62, 0xc000
	s_nop 0
	global_load_lds_dwordx4 v170, s[100:101]
	s_add_i32 m0, s62, 0xe000
	s_nop 0
	global_load_lds_dwordx4 v172, s[100:101]
; DI float row_rstd(const float* ssq, int row, int fq) {
;   const f32x4 a = *(const f32x4*)(ssq + (size_t)row * 32 + fq * 8), b = *(const f32x4*)(ssq + (size_t)row * 32 + fq * 8 + 4);
;   float sm = ((a[0] + a[1]) + (a[2] + a[3])) + ((b[0] + b[1]) + (b[2] + b[3]));
;   sm += __shfl_xor(sm, 16); sm += __shfl_xor(sm, 32);
;   return rsqrtf(sm * (1.0f / 2048.f) + 1e-6f);
;   DI void operator()(const f32x4 (&acc)[2][2][4][2], const Unit& u, int wr, int wc, int fr, int fq) const {
;     const int col = u.pn * 128 + wc * 32 + 8 * fq;
;     float w0[8], w1[8], w2[8], bb[8];
; #pragma unroll
;     for (int e = 0; e < 8; ++e) { w0[e] = cw[col + e]; w1[e] = cw[5632 + col + e]; w2[e] = cw[2 * 5632 + col + e]; bb[e] = cb[col + e]; }
; #pragma unroll
;     for (int ai = 0; ai < 2; ++ai) {
;       const int row0 = u.pm * BM + ai * HALF + wr * 64, span = row0 >> 6;
;       float rsv[4];
; #pragma unroll
;       for (int m = 0; m < 4; ++m) rsv[m] = row_rstd(ssq, row0 + 16 * m + fr, fq);
.Lxs_2:
	s_add_i32 s52, s52, 2
	s_add_u32 s14, s14, 0x100
	s_addc_u32 s15, s15, 0
	s_add_u32 s44, s44, 0x100
	s_addc_u32 s45, s45, 0
	s_cmp_gt_u32 s52, 29
	s_setprio 1
	s_barrier
	v_mfma_f32_16x16x32_bf16 v[56:59], v[216:219], v[80:83], v[56:59]
	v_mfma_f32_16x16x32_bf16 v[52:55], v[224:227], v[80:83], v[52:55]
	v_mfma_f32_16x16x32_bf16 v[40:43], v[216:219], v[92:95], v[40:43]
	v_mfma_f32_16x16x32_bf16 v[32:35], v[224:227], v[92:95], v[32:35]
	v_mfma_f32_16x16x32_bf16 v[24:27], v[216:219], v[180:183], v[24:27]
	v_mfma_f32_16x16x32_bf16 v[8:11], v[224:227], v[180:183], v[8:11]
	v_mfma_f32_16x16x32_bf16 v[4:7], v[216:219], v[188:191], v[4:7]
	v_mfma_f32_16x16x32_bf16 v[0:3], v[224:227], v[188:191], v[0:3]
	v_mfma_f32_16x16x32_bf16 v[56:59], v[220:223], v[84:87], v[56:59]
	v_mfma_f32_16x16x32_bf16 v[52:55], v[228:231], v[84:87], v[52:55]
	v_mfma_f32_16x16x32_bf16 v[40:43], v[220:223], v[96:99], v[40:43]
	v_mfma_f32_16x16x32_bf16 v[32:35], v[228:231], v[96:99], v[32:35]
	v_mfma_f32_16x16x32_bf16 v[24:27], v[220:223], v[184:187], v[24:27]
	v_mfma_f32_16x16x32_bf16 v[8:11], v[228:231], v[184:187], v[8:11]
	v_mfma_f32_16x16x32_bf16 v[4:7], v[220:223], v[192:195], v[4:7]
	v_mfma_f32_16x16x32_bf16 v[0:3], v[228:231], v[192:195], v[0:3]
	s_barrier
	s_setprio 0
	s_cbranch_scc0 .LBB0_811
	v_writelane_b32 v247, -2, 0
	s_lshl_b32 s35, s12, 8
	s_add_i32 s35, s35, s66
	v_or_b32_e32 v190, s35, v179
	v_ashrrev_i32_e32 v191, 31, v190
	v_lshlrev_b64 v[64:65], 7, v[190:191]
	v_or_b32_e32 v188, 16, v190
	v_lshl_add_u64 v[64:65], v[168:169], 0, v[64:65]
	v_ashrrev_i32_e32 v189, 31, v188
	global_load_dwordx4 v[192:195], v[64:65], off
	global_load_dwordx4 v[206:209], v[64:65], off offset:16
	v_lshlrev_b64 v[64:65], 7, v[188:189]
	v_lshl_add_u64 v[64:65], v[168:169], 0, v[64:65]
	global_load_dwordx4 v[212:215], v[64:65], off
	global_load_dwordx4 v[216:219], v[64:65], off offset:16
	v_or_b32_e32 v186, 32, v190
	v_ashrrev_i32_e32 v187, 31, v186
	v_lshlrev_b64 v[64:65], 7, v[186:187]
	v_or_b32_e32 v184, 48, v190
	v_lshl_add_u64 v[64:65], v[168:169], 0, v[64:65]
	v_ashrrev_i32_e32 v185, 31, v184
	global_load_dwordx4 v[220:223], v[64:65], off
	global_load_dwordx4 v[224:227], v[64:65], off offset:16
	v_lshlrev_b64 v[64:65], 7, v[184:185]
	v_lshl_add_u64 v[64:65], v[168:169], 0, v[64:65]
	global_load_dwordx4 v[228:231], v[64:65], off
	global_load_dwordx4 v[232:235], v[64:65], off offset:16
	v_lshl_or_b32 v180, s13, 7, v200
	v_and_b32_e32 v65, 64, v204
	v_xor_b32_e32 v64, 16, v204
	v_ashrrev_i32_e32 v181, 31, v180
	v_add_u32_e32 v65, 64, v65
	v_readlane_b32 s44, v243, 3
	v_xor_b32_e32 v66, 32, v204
	v_lshlrev_b64 v[182:183], 2, v[180:181]
	v_cmp_lt_i32_e32 vcc, v64, v65
	v_readlane_b32 s52, v243, 11
	v_readlane_b32 s53, v243, 12
	v_cndmask_b32_e32 v64, v204, v64, vcc
	v_cmp_lt_i32_e32 vcc, v66, v65
	v_lshl_add_u64 v[92:93], s[52:53], 0, v[182:183]
	v_readlane_b32 s54, v243, 13
	v_cndmask_b32_e32 v65, v204, v66, vcc
	v_add_co_u32_e32 v94, vcc, 0x5000, v92
	v_readlane_b32 s55, v243, 14
	s_nop 0
	v_addc_co_u32_e32 v95, vcc, 0, v93, vcc
	v_add_co_u32_e32 v96, vcc, 0xb000, v92
	v_lshl_add_u64 v[72:73], s[54:55], 0, v[182:183]
	v_lshl_add_u64 v[74:75], v[92:93], 0, s[26:27]
	v_lshl_add_u64 v[76:77], v[92:93], 0, s[28:29]
	v_addc_co_u32_e32 v97, vcc, 0, v93, vcc
	v_lshlrev_b32_e32 v187, 2, v64
	v_lshlrev_b32_e32 v185, 2, v65
	global_load_dwordx4 v[64:67], v[92:93], off offset:16
	global_load_dwordx4 v[80:83], v[92:93], off
	global_load_dwordx4 v[68:71], v[72:73], off offset:16
	global_load_dwordx4 v[84:87], v[72:73], off
	s_nop 0
	global_load_dwordx4 v[72:75], v[74:75], off offset:16
	s_nop 0
	global_load_dwordx4 v[76:79], v[76:77], off offset:16
	s_nop 0
	global_load_dwordx4 v[92:95], v[94:95], off offset:2048
	s_nop 0
	global_load_dwordx4 v[96:99], v[96:97], off
	v_mov_b32_e32 v211, 0
	v_mov_b32_e32 v205, 0
	v_readlane_b32 s45, v243, 4
	v_readlane_b32 s46, v243, 5
	v_readlane_b32 s47, v243, 6
	v_readlane_b32 s48, v243, 7
	v_readlane_b32 s49, v243, 8
	v_readlane_b32 s50, v243, 9
	v_readlane_b32 s51, v243, 10
	v_readlane_b32 s56, v243, 15
	v_readlane_b32 s57, v243, 16
	v_readlane_b32 s58, v243, 17
	v_readlane_b32 s59, v243, 18
	s_waitcnt vmcnt(0)
	v_mov_b32_e32 v196, v192
	v_mov_b32_e32 v197, v206
	v_mov_b32_e32 v206, v193
	v_mov_b32_e32 v192, v194
	v_mov_b32_e32 v193, v208
	v_mov_b32_e32 v208, v195
	v_pk_add_f32 v[194:195], v[196:197], v[206:207]
	v_pk_add_f32 v[192:193], v[192:193], v[208:209]
	v_mov_b32_e32 v196, v212
	v_mov_b32_e32 v197, v216
	v_mov_b32_e32 v216, v213
	v_mov_b32_e32 v206, v214
	v_mov_b32_e32 v207, v218
	v_mov_b32_e32 v218, v215
	v_pk_add_f32 v[192:193], v[194:195], v[192:193]
	v_pk_add_f32 v[194:195], v[196:197], v[216:217]
	v_pk_add_f32 v[196:197], v[206:207], v[218:219]
	v_mov_b32_e32 v208, v220
	v_pk_add_f32 v[194:195], v[194:195], v[196:197]
	v_mov_b32_e32 v197, v192
	v_mov_b32_e32 v196, v194
	v_mov_b32_e32 v192, v195
	v_pk_add_f32 v[192:193], v[196:197], v[192:193]
	ds_bpermute_b32 v195, v187, v193
	ds_bpermute_b32 v194, v187, v192
	v_mov_b32_e32 v209, v224
	v_mov_b32_e32 v224, v221
	v_mov_b32_e32 v212, v222
	v_mov_b32_e32 v213, v226
	s_waitcnt lgkmcnt(0)
	v_pk_add_f32 v[192:193], v[192:193], v[194:195]
	ds_bpermute_b32 v195, v185, v193
	ds_bpermute_b32 v194, v185, v192
	v_mov_b32_e32 v226, v223
	v_mov_b32_e32 v196, v228
	v_mov_b32_e32 v197, v232
	v_mov_b32_e32 v232, v229
	s_waitcnt lgkmcnt(0)
; DI unsigned pack2(float lo, float hi) { f32x2 v = {lo, hi}; bf16v2 r = __builtin_convertvector(v, bf16v2); return __builtin_bit_cast(unsigned, r); }
; DI float silu_f(float x) { return x * sigmoid_f(x); }
; DI float dpp_ror1(float v) { return __int_as_float(__builtin_amdgcn_update_dpp(0, __float_as_int(v), 0x121, 0xf, 0xf, false)); }
; DI float dpp_ror2(float v) { return __int_as_float(__builtin_amdgcn_update_dpp(0, __float_as_int(v), 0x122, 0xf, 0xf, false)); }
;   DI void operator()(const f32x4 (&acc)[2][2][4][2], const Unit& u, int wr, int wc, int fr, int fq) const {
;     ...
;       float p1[8], p2[8];
; #pragma unroll
;       for (int e = 0; e < 8; ++e) { p1[e] = 0.f; p2[e] = 0.f; }
; #pragma unroll
;       for (int m = 0; m < 4; ++m) {
;         float g[8], uu[8], a[8];
;         const float rs = rsv[m];
; #pragma unroll
;         for (int e = 0; e < 4; ++e) { g[e] = acc[ai][0][m][0][e] * rs; g[4 + e] = acc[ai][0][m][1][e] * rs; uu[e] = acc[ai][1][m][0][e] * rs; uu[4 + e] = acc[ai][1][m][1][e] * rs; }
; #pragma unroll
;         for (int e = 0; e < 8; ++e) {
;           const float x1 = dpp_ror1(g[e]), x2 = dpp_ror2(g[e]);
;           const float pr1 = (fr == 0) ? p1[e] : x1, pr2 = (fr < 2) ? p2[e] : x2;
;           a[e] = w2[e] * g[e] + w1[e] * pr1 + w0[e] * pr2 + bb[e];
;           p1[e] = x1; p2[e] = x2;
;         }
;         if (m == 0 && fr < 2) {
;           float* ha = headA + (size_t)(span * 2 + fr) * 5632 + col; float* hu = headU + (size_t)(span * 2 + fr) * 5632 + col;
;           *(f32x4*)ha = (f32x4){a[0], a[1], a[2], a[3]}; *(f32x4*)(ha + 4) = (f32x4){a[4], a[5], a[6], a[7]};
;           *(f32x4*)hu = (f32x4){uu[0], uu[1], uu[2], uu[3]}; *(f32x4*)(hu + 4) = (f32x4){uu[4], uu[5], uu[6], uu[7]};
;         } else {
;           u32x4 w;
;           w.x = pack2(silu_f(a[0]) * uu[0], silu_f(a[1]) * uu[1]);
;           w.y = pack2(silu_f(a[2]) * uu[2], silu_f(a[3]) * uu[3]);
;           w.z = pack2(silu_f(a[4]) * uu[4], silu_f(a[5]) * uu[5]);
;           w.w = pack2(silu_f(a[6]) * uu[6], silu_f(a[7]) * uu[7]);
;           *(u32x4*)(H + (size_t)(row0 + 16 * m + fr) * 5632 + col) = w;
	v_pk_add_f32 v[192:193], v[192:193], v[194:195]
	v_mov_b32_e32 v206, v230
	v_pk_fma_f32 v[192:193], v[192:193], s[30:31], v[178:179] op_sel_hi:[1,0,0]
	v_mov_b32_e32 v207, v234
	v_mul_f32_e32 v189, 0x4b800000, v193
	v_cmp_gt_f32_e64 s[12:13], s74, v193
	v_mov_b32_e32 v234, v231
	v_pk_add_f32 v[208:209], v[208:209], v[224:225]
	v_cndmask_b32_e64 v189, v193, v189, s[12:13]
	v_rsq_f32_e32 v189, v189
	v_pk_add_f32 v[212:213], v[212:213], v[226:227]
	v_pk_add_f32 v[196:197], v[196:197], v[232:233]
	v_pk_add_f32 v[194:195], v[206:207], v[234:235]
	v_mul_f32_e32 v191, 0x45800000, v189
	v_cndmask_b32_e64 v220, v189, v191, s[12:13]
	v_pk_add_f32 v[208:209], v[208:209], v[212:213]
	v_pk_add_f32 v[194:195], v[196:197], v[194:195]
	v_pk_mul_f32 v[156:157], v[156:157], v[220:221] op_sel_hi:[1,0]
	v_mov_b32_e32 v216, 0
	v_mov_b32_e32 v218, 0
	v_mov_b32_e32 v196, v194
	v_mov_b32_e32 v197, v208
	v_mov_b32_e32 v208, v195
	v_mov_b32_dpp v216, v156 row_ror:1 row_mask:0xf bank_mask:0xf
	v_mov_b32_dpp v218, v157 row_ror:1 row_mask:0xf bank_mask:0xf
	v_pk_add_f32 v[194:195], v[196:197], v[208:209]
	v_cndmask_b32_e64 v207, v218, 0, s[0:1]
	v_cndmask_b32_e64 v206, v216, 0, s[0:1]
	v_pk_mul_f32 v[158:159], v[158:159], v[220:221] op_sel_hi:[1,0]
	v_mov_b32_e32 v212, 0
	v_mov_b32_e32 v214, 0
	ds_bpermute_b32 v197, v187, v195
	ds_bpermute_b32 v196, v187, v194
	v_mov_b32_e32 v215, 0
	v_mov_b32_e32 v217, 0
	v_pk_mul_f32 v[206:207], v[92:93], v[206:207]
	v_mov_b32_dpp v212, v158 row_ror:1 row_mask:0xf bank_mask:0xf
	v_mov_b32_dpp v214, v159 row_ror:1 row_mask:0xf bank_mask:0xf
	v_mov_b32_dpp v215, v156 row_ror:2 row_mask:0xf bank_mask:0xf
	v_mov_b32_dpp v217, v157 row_ror:2 row_mask:0xf bank_mask:0xf
	v_pk_fma_f32 v[156:157], v[96:97], v[156:157], v[206:207]
	v_mov_b32_e32 v213, 0
	v_cndmask_b32_e64 v207, v214, 0, s[0:1]
	v_cndmask_b32_e64 v206, v212, 0, s[0:1]
	v_cndmask_b32_e64 v209, v217, 0, s[4:5]
	v_cndmask_b32_e64 v208, v215, 0, s[4:5]
	v_mov_b32_dpp v211, v158 row_ror:2 row_mask:0xf bank_mask:0xf
	v_mov_b32_dpp v213, v159 row_ror:2 row_mask:0xf bank_mask:0xf
	v_pk_mul_f32 v[206:207], v[94:95], v[206:207]
	v_pk_fma_f32 v[156:157], v[80:81], v[208:209], v[156:157]
	v_cndmask_b32_e64 v209, v213, 0, s[4:5]
	v_cndmask_b32_e64 v208, v211, 0, s[4:5]
	v_pk_fma_f32 v[158:159], v[98:99], v[158:159], v[206:207]
	v_pk_mul_f32 v[144:145], v[144:145], v[220:221] op_sel_hi:[1,0]
	v_pk_fma_f32 v[158:159], v[82:83], v[208:209], v[158:159]
	v_mov_b32_e32 v207, 0
	v_mov_b32_e32 v209, 0
	v_pk_mul_f32 v[146:147], v[146:147], v[220:221] op_sel_hi:[1,0]
	v_mov_b32_e32 v191, 0
	s_waitcnt lgkmcnt(0)
	v_pk_add_f32 v[194:195], v[194:195], v[196:197]
	v_mov_b32_dpp v207, v144 row_ror:1 row_mask:0xf bank_mask:0xf
	v_mov_b32_dpp v209, v145 row_ror:1 row_mask:0xf bank_mask:0xf
	v_mov_b32_dpp v191, v146 row_ror:1 row_mask:0xf bank_mask:0xf
	v_mov_b32_dpp v205, v147 row_ror:1 row_mask:0xf bank_mask:0xf
	ds_bpermute_b32 v197, v185, v195
	ds_bpermute_b32 v196, v185, v194
	v_pk_mul_f32 v[152:153], v[152:153], v[220:221] op_sel_hi:[1,0]
	v_pk_mul_f32 v[148:149], v[148:149], v[220:221] op_sel_hi:[1,0]
	v_pk_mul_f32 v[154:155], v[154:155], v[220:221] op_sel_hi:[1,0]
	v_pk_mul_f32 v[150:151], v[150:151], v[220:221] op_sel_hi:[1,0]
	v_mov_b32_e32 v206, 0
	v_mov_b32_e32 v208, 0
	v_cndmask_b32_e64 v223, v209, 0, s[0:1]
	v_cndmask_b32_e64 v222, v207, 0, s[0:1]
	v_mov_b32_e32 v189, 0
	v_mov_b32_e32 v193, 0
	v_cndmask_b32_e64 v221, v205, 0, s[0:1]
	v_cndmask_b32_e64 v220, v191, 0, s[0:1]
	v_mov_b32_dpp v206, v144 row_ror:2 row_mask:0xf bank_mask:0xf
	v_mov_b32_dpp v208, v145 row_ror:2 row_mask:0xf bank_mask:0xf
	v_pk_mul_f32 v[222:223], v[72:73], v[222:223]
	v_mov_b32_dpp v189, v146 row_ror:2 row_mask:0xf bank_mask:0xf
	v_mov_b32_dpp v193, v147 row_ror:2 row_mask:0xf bank_mask:0xf
	v_pk_mul_f32 v[220:221], v[74:75], v[220:221]
	v_cndmask_b32_e64 v225, v208, 0, s[4:5]
	v_cndmask_b32_e64 v224, v206, 0, s[4:5]
	v_pk_fma_f32 v[144:145], v[76:77], v[144:145], v[222:223]
	v_cndmask_b32_e64 v223, v193, 0, s[4:5]
	v_cndmask_b32_e64 v222, v189, 0, s[4:5]
	v_pk_fma_f32 v[146:147], v[78:79], v[146:147], v[220:221]
	v_pk_fma_f32 v[144:145], v[64:65], v[224:225], v[144:145]
	v_pk_fma_f32 v[146:147], v[66:67], v[222:223], v[146:147]
	v_cmp_gt_f32_e32 vcc, s74, v192
	v_pk_add_f32 v[156:157], v[84:85], v[156:157]
	v_pk_add_f32 v[158:159], v[86:87], v[158:159]
	v_pk_add_f32 v[144:145], v[68:69], v[144:145]
	v_pk_add_f32 v[146:147], v[70:71], v[146:147]
	s_and_saveexec_b64 s[12:13], s[10:11]
	s_xor_b64 s[12:13], exec, s[12:13]
	s_cbranch_execz .LBB0_814
	v_mul_f32_e32 v219, 0xbfb8aa3b, v156
	v_exp_f32_e32 v219, v219
	v_mul_f32_e32 v220, 0xbfb8aa3b, v157
	v_exp_f32_e32 v220, v220
	v_mul_f32_e32 v222, 0xbfb8aa3b, v159
	v_add_f32_e32 v219, 1.0, v219
	v_exp_f32_e32 v223, v222
	v_add_f32_e32 v221, 1.0, v220
	v_rcp_f32_e32 v220, v219
	v_mul_f32_e32 v219, 0xbfb8aa3b, v158
	v_exp_f32_e32 v219, v219
	v_rcp_f32_e32 v221, v221
	v_add_f32_e32 v219, 1.0, v219
	v_rcp_f32_e32 v222, v219
	v_add_f32_e32 v219, 1.0, v223
	v_rcp_f32_e32 v223, v219
	v_pk_mul_f32 v[156:157], v[156:157], v[220:221]
	s_nop 0
	v_pk_mul_f32 v[152:153], v[152:153], v[156:157]
	v_pk_mul_f32 v[156:157], v[158:159], v[222:223]
	v_cvt_pk_bf16_f32 v152, v152, v153
	v_mul_f32_e32 v153, 0xbfb8aa3b, v144
	v_pk_mul_f32 v[154:155], v[154:155], v[156:157]
	v_exp_f32_e32 v156, v153
	v_mul_f32_e32 v153, 0xbfb8aa3b, v145
	v_exp_f32_e32 v157, v153
	v_cvt_pk_bf16_f32 v153, v154, v155
	v_add_f32_e32 v154, 1.0, v156
	v_mul_f32_e32 v156, 0xbfb8aa3b, v146
	v_add_f32_e32 v155, 1.0, v157
	v_mul_f32_e32 v157, 0xbfb8aa3b, v147
	v_exp_f32_e32 v156, v156
	v_exp_f32_e32 v157, v157
	v_rcp_f32_e32 v154, v154
	v_rcp_f32_e32 v155, v155
	v_add_f32_e32 v156, 1.0, v156
	v_add_f32_e32 v157, 1.0, v157
	v_rcp_f32_e32 v156, v156
	v_rcp_f32_e32 v157, v157
	v_pk_mul_f32 v[144:145], v[144:145], v[154:155]
	s_nop 0
	v_pk_mul_f32 v[144:145], v[148:149], v[144:145]
	s_nop 0
	v_cvt_pk_bf16_f32 v154, v144, v145
	v_pk_mul_f32 v[144:145], v[146:147], v[156:157]
	s_nop 0
	v_pk_mul_f32 v[144:145], v[150:151], v[144:145]
	s_nop 0
	v_cvt_pk_bf16_f32 v155, v144, v145
	v_mov_b64_e32 v[144:145], s[16:17]
	v_mad_i64_i32 v[144:145], s[14:15], v190, s75, v[144:145]
	v_lshl_add_u64 v[144:145], v[180:181], 1, v[144:145]
	global_store_dwordx4 v[144:145], v[152:155], off

; #define LAS __attribute__((address_space(3)))
;   DI bool next(int i, Unit& u) const {
;     const long L = (long)i * G + c; if (L >= nwg) return false;
;     int wgid = (int)L; { const int q = nwg / NXCD, r = nwg % NXCD, xcd = wgid % NXCD, off = wgid / NXCD; wgid = (xcd < r ? xcd * (q + 1) : r * (q + 1) + (xcd - r) * q) + off; }
;     const int nig = WGM * nN, gid = wgid / nig, fm = gid * WGM, gsz = (nM - fm) < WGM ? (nM - fm) : WGM;
;     u.pm = fm + ((wgid % nig) % gsz); u.pn = (wgid % nig) / gsz; return true;
;   }
; DI void run_gemm(const Params& p, int id, unsigned char* smem) {
;     ...
;   S.init(g.M, g.N, (int)gridDim.x, __builtin_amdgcn_readfirstlane((int)((volatile LAS unsigned*)(LAS unsigned char*)(smem + 131072))[2]));
.LBB0_947:
	v_writelane_b32 v247, 1, 0
	s_add_i32 s0, 0, 0x20008
	v_mov_b32_e32 v0, s0
	ds_read_b32 v0, v0
	v_readfirstlane_b32 s25, v210
	s_waitcnt lgkmcnt(0)
	v_readfirstlane_b32 s24, v0
	s_cmpk_lt_i32 s24, 0x200
	s_cselect_b64 s[0:1], -1, 0
	s_cmpk_gt_i32 s24, 0x1ff
	s_cbranch_scc1 .LBB0_949
	s_ashr_i32 s2, s24, 31
	s_lshr_b32 s2, s2, 29
	s_add_i32 s2, s24, s2
	s_ashr_i32 s3, s2, 3
	s_and_b32 s2, s2, -8
	s_sub_i32 s2, s24, s2
	s_lshr_b32 s4, s2, 31
	s_or_b32 s4, s4, 64
	s_mul_i32 s2, s4, s2
	s_add_i32 s2, s2, s3
	s_ashr_i32 s3, s2, 31
	s_lshr_b32 s3, s3, 26
	s_add_i32 s3, s2, s3
	s_ashr_i32 s4, s3, 6
	s_lshl_b32 s4, s4, 3
	s_sub_i32 s5, 64, s4
	s_min_u32 s5, s5, 8
	s_andn2_b32 s3, s3, 63
	s_sub_i32 s6, s2, s3
	v_cvt_f32_ubyte0_e32 v1, s5
	v_cvt_f32_i32_e32 v0, s6
	v_rcp_iflag_f32_e32 v2, v1
	s_ashr_i32 s2, s6, 30
	s_or_b32 s7, s2, 1
	v_mul_f32_e32 v2, v0, v2
	v_trunc_f32_e32 v2, v2
	v_fma_f32 v0, -v2, v1, v0
	v_cvt_i32_f32_e32 v2, v2
	v_cmp_ge_f32_e64 s[2:3], |v0|, v1
	s_and_b64 s[2:3], s[2:3], exec
	s_cselect_b32 s2, s7, 0
	v_readfirstlane_b32 s3, v2
	s_add_i32 s3, s3, s2
	s_sext_i32_i8 s2, s3
	s_mul_i32 s3, s3, s5
	s_sub_i32 s3, s6, s3
	s_sext_i32_i8 s3, s3
	s_add_i32 s51, s4, s3

; #define PG8_STAGE(bufoff, gbase, voff) do { _Pragma("unroll") for (int _i = 0; _i < 2; ++_i) \
;     __builtin_amdgcn_global_load_lds((const unsigned*)((const char*)(gbase) + (voff)[_i]), (LAS unsigned*)(lds + (bufoff) + ldsw + _i * 8192), 16, 0, 0); } while (0)
; #define PG8_LDA(dst, b, h) do { _Pragma("unroll") for (int m = 0; m < 4; ++m) _Pragma("unroll") for (int k = 0; k < 2; ++k) dst[m][k] = *(const LAS bf16x8*)(lds + PG8_SA(b, h) + aoff + m * 2048 + k * 1024); } while (0)
; #define PG8_LDB(dst, b, h) do { _Pragma("unroll") for (int n = 0; n < 2; ++n) _Pragma("unroll") for (int k = 0; k < 2; ++k) dst[n][k] = *(const LAS bf16x8*)(lds + PG8_SB(b, h) + boff + n * 2048 + k * 1024); } while (0)
; #define PG8_MMA(ai, bj, At, Bt) do { __builtin_amdgcn_s_setprio(1); _Pragma("unroll") for (int m = 0; m < 4; ++m) _Pragma("unroll") for (int n = 0; n < 2; ++n) _Pragma("unroll") for (int k = 0; k < 2; ++k) \
;     acc[ai][bj][m][n] = __builtin_amdgcn_mfma_f32_16x16x32_bf16(Bt[n][k], At[m][k], acc[ai][bj][m][n], 0, 0, 0); __builtin_amdgcn_s_setprio(0); } while (0)
; #define PG8_WAIT_V(n) asm volatile("s_waitcnt vmcnt(" #n ")" ::: "memory")
; #define PG8_WAIT_L(n) asm volatile("s_waitcnt lgkmcnt(" #n ")" ::: "memory")
; #define PG8_BAR __builtin_amdgcn_s_barrier()
; #define PG8_SCHED __builtin_amdgcn_sched_barrier(0)
; template <class Epi, class Sched = StaticOrder>
; DI void gemm_phase(LAS unsigned char* lds, const Gemm g, const Sched& S, const Epi& E) {
;     ...
;     for (int t = 0; t < nt; t += 2) {
;       const bool last = (t == nt - 2);
;       const char* a1 = cA + (size_t)(t + 1) * kstep;
;       const char* a2 = last ? nA : cA + (size_t)(t + 2) * kstep; const char* b2 = last ? nB : cB + (size_t)(t + 2) * kstep;
;       const char* a3 = a2 + kstep; const char* b3 = b2 + kstep;
;       PG8_LDB(B0, 0, 0); PG8_SCHED; PG8_LDA(At, 0, 0); PG8_STAGE(PG8_SA(1, 1), a1 + hstep, voffA);
;       PG8_WAIT_L(8); PG8_BAR; PG8_WAIT_L(0); PG8_MMA(0, 0, At, B0); PG8_BAR; PG8_SCHED;
;       PG8_LDB(B1, 0, 1); PG8_STAGE(PG8_SB(0, 0), b2, voffB);
;       PG8_BAR; PG8_WAIT_L(0); PG8_MMA(0, 1, At, B1); PG8_BAR;
;       PG8_LDA(At, 0, 1); PG8_STAGE(PG8_SA(0, 0), a2, voffA);
;       PG8_BAR; PG8_WAIT_L(0); PG8_MMA(1, 0, At, B0); PG8_BAR; PG8_SCHED;
;       PG8_STAGE(PG8_SB(0, 1), b2 + hstep, voffB);
;       PG8_WAIT_V(6); PG8_BAR; PG8_MMA(1, 1, At, B1); PG8_BAR;
.LBB0_961:
	ds_read_b128 v[128:131], v214
	ds_read_b128 v[132:135], v214 offset:1024
	ds_read_b128 v[136:139], v214 offset:2048
	ds_read_b128 v[140:143], v214 offset:3072
	s_add_u32 s20, s18, 0xffea0080
	s_addc_u32 s21, s19, -1
	s_cmpk_eq_i32 s44, 0x54
	s_cselect_b32 s23, s5, s21
	s_cselect_b32 s22, s4, s20
	s_cselect_b32 s21, s7, s43
	s_cselect_b32 s20, s6, s42
	s_add_i32 m0, s31, 0xc000
	ds_read_b128 v[144:147], v215
	ds_read_b128 v[148:151], v215 offset:1024
	ds_read_b128 v[152:155], v215 offset:2048
	ds_read_b128 v[156:159], v215 offset:3072
	ds_read_b128 v[160:163], v215 offset:4096
	ds_read_b128 v[164:167], v215 offset:5120
	ds_read_b128 v[168:171], v215 offset:6144
	ds_read_b128 v[172:175], v215 offset:7168
	global_load_lds_dwordx4 v184, s[18:19]
	s_add_i32 m0, s31, 0xe000
	s_nop 0
	global_load_lds_dwordx4 v186, s[18:19]
	s_waitcnt lgkmcnt(0)
	s_setprio 1
	s_barrier
	v_mfma_f32_16x16x32_bf16 v[124:127], v[128:131], v[144:147], v[124:127]
	v_mfma_f32_16x16x32_bf16 v[120:123], v[136:139], v[144:147], v[120:123]
	v_mfma_f32_16x16x32_bf16 v[108:111], v[128:131], v[152:155], v[108:111]
	v_mfma_f32_16x16x32_bf16 v[104:107], v[136:139], v[152:155], v[104:107]
	v_mfma_f32_16x16x32_bf16 v[92:95], v[128:131], v[160:163], v[92:95]
	v_mfma_f32_16x16x32_bf16 v[88:91], v[136:139], v[160:163], v[88:91]
	v_mfma_f32_16x16x32_bf16 v[76:79], v[128:131], v[168:171], v[76:79]
	v_mfma_f32_16x16x32_bf16 v[72:75], v[136:139], v[168:171], v[72:75]
	v_mfma_f32_16x16x32_bf16 v[124:127], v[132:135], v[148:151], v[124:127]
	v_mfma_f32_16x16x32_bf16 v[120:123], v[140:143], v[148:151], v[120:123]
	v_mfma_f32_16x16x32_bf16 v[108:111], v[132:135], v[156:159], v[108:111]
	v_mfma_f32_16x16x32_bf16 v[104:107], v[140:143], v[156:159], v[104:107]
	v_mfma_f32_16x16x32_bf16 v[92:95], v[132:135], v[164:167], v[92:95]
	v_mfma_f32_16x16x32_bf16 v[88:91], v[140:143], v[164:167], v[88:91]
	v_mfma_f32_16x16x32_bf16 v[76:79], v[132:135], v[172:175], v[76:79]
	v_mfma_f32_16x16x32_bf16 v[72:75], v[140:143], v[172:175], v[72:75]
	s_barrier
	s_setprio 0
	s_add_i32 s45, s46, s30
	s_add_u32 s98, s20, 0x80
	s_addc_u32 s99, s21, 0
	s_add_u32 s100, s22, 0x80
	s_addc_u32 s101, s23, 0
	s_mov_b32 m0, s45
	ds_read_b128 v[192:195], v216
	ds_read_b128 v[196:199], v216 offset:1024
	ds_read_b128 v[200:203], v216 offset:2048
	ds_read_b128 v[204:207], v216 offset:3072
	global_load_lds_dwordx4 v178, s[20:21]
	s_add_i32 m0, s45, 0x2000
	s_nop 0
	global_load_lds_dwordx4 v182, s[20:21]
	s_waitcnt lgkmcnt(0)
	s_setprio 1
	s_barrier
	v_mfma_f32_16x16x32_bf16 v[116:119], v[192:195], v[144:147], v[116:119]
	v_mfma_f32_16x16x32_bf16 v[112:115], v[200:203], v[144:147], v[112:115]
	v_mfma_f32_16x16x32_bf16 v[100:103], v[192:195], v[152:155], v[100:103]
	v_mfma_f32_16x16x32_bf16 v[96:99], v[200:203], v[152:155], v[96:99]
	v_mfma_f32_16x16x32_bf16 v[84:87], v[192:195], v[160:163], v[84:87]
	v_mfma_f32_16x16x32_bf16 v[80:83], v[200:203], v[160:163], v[80:83]
	v_mfma_f32_16x16x32_bf16 v[68:71], v[192:195], v[168:171], v[68:71]
	v_mfma_f32_16x16x32_bf16 v[64:67], v[200:203], v[168:171], v[64:67]
	v_mfma_f32_16x16x32_bf16 v[116:119], v[196:199], v[148:151], v[116:119]
	v_mfma_f32_16x16x32_bf16 v[112:115], v[204:207], v[148:151], v[112:115]
	v_mfma_f32_16x16x32_bf16 v[100:103], v[196:199], v[156:159], v[100:103]
	v_mfma_f32_16x16x32_bf16 v[96:99], v[204:207], v[156:159], v[96:99]
	v_mfma_f32_16x16x32_bf16 v[84:87], v[196:199], v[164:167], v[84:87]
	v_mfma_f32_16x16x32_bf16 v[80:83], v[204:207], v[164:167], v[80:83]
	v_mfma_f32_16x16x32_bf16 v[68:71], v[196:199], v[172:175], v[68:71]
	v_mfma_f32_16x16x32_bf16 v[64:67], v[204:207], v[172:175], v[64:67]
	s_barrier
	s_setprio 0
	s_mov_b32 m0, s31
	ds_read_b128 v[144:147], v215 offset:16384
	ds_read_b128 v[148:151], v215 offset:17408
	ds_read_b128 v[152:155], v215 offset:18432
	ds_read_b128 v[156:159], v215 offset:19456
	ds_read_b128 v[160:163], v215 offset:20480
	ds_read_b128 v[164:167], v215 offset:21504
	ds_read_b128 v[168:171], v215 offset:22528
	ds_read_b128 v[172:175], v215 offset:23552
	global_load_lds_dwordx4 v176, s[22:23]
	s_mov_b32 m0, s33
	s_nop 0
	global_load_lds_dwordx4 v180, s[22:23]
	s_waitcnt lgkmcnt(0)
	s_setprio 1
	s_barrier
	v_mfma_f32_16x16x32_bf16 v[60:63], v[128:131], v[144:147], v[60:63]
	v_mfma_f32_16x16x32_bf16 v[56:59], v[136:139], v[144:147], v[56:59]
	v_mfma_f32_16x16x32_bf16 v[44:47], v[128:131], v[152:155], v[44:47]
	v_mfma_f32_16x16x32_bf16 v[40:43], v[136:139], v[152:155], v[40:43]
	v_mfma_f32_16x16x32_bf16 v[28:31], v[128:131], v[160:163], v[28:31]
	v_mfma_f32_16x16x32_bf16 v[24:27], v[136:139], v[160:163], v[24:27]
	v_mfma_f32_16x16x32_bf16 v[12:15], v[128:131], v[168:171], v[12:15]
	v_mfma_f32_16x16x32_bf16 v[8:11], v[136:139], v[168:171], v[8:11]
	v_mfma_f32_16x16x32_bf16 v[60:63], v[132:135], v[148:151], v[60:63]
	v_mfma_f32_16x16x32_bf16 v[56:59], v[140:143], v[148:151], v[56:59]
	v_mfma_f32_16x16x32_bf16 v[44:47], v[132:135], v[156:159], v[44:47]
	v_mfma_f32_16x16x32_bf16 v[40:43], v[140:143], v[156:159], v[40:43]
	v_mfma_f32_16x16x32_bf16 v[28:31], v[132:135], v[164:167], v[28:31]
	v_mfma_f32_16x16x32_bf16 v[24:27], v[140:143], v[164:167], v[24:27]
	v_mfma_f32_16x16x32_bf16 v[12:15], v[132:135], v[172:175], v[12:15]
	v_mfma_f32_16x16x32_bf16 v[8:11], v[140:143], v[172:175], v[8:11]
	s_barrier
	s_setprio 0
	s_add_u32 s52, s20, 0x160000
	s_addc_u32 s53, s21, 0
	s_add_i32 s45, s47, s30
	s_mov_b32 m0, s45
	s_nop 0
	global_load_lds_dwordx4 v178, s[52:53]
	s_add_i32 m0, s45, 0x2000
	s_nop 0
	global_load_lds_dwordx4 v182, s[52:53]
	v_readlane_b32 vcc_lo, v247, 0
	s_cmp_eq_u32 s44, vcc_lo
	s_cbranch_scc1 .Lsw_3
	s_waitcnt vmcnt(6)
; #define PG8_STAGE(bufoff, gbase, voff) do { _Pragma("unroll") for (int _i = 0; _i < 2; ++_i) \
;     __builtin_amdgcn_global_load_lds((const unsigned*)((const char*)(gbase) + (voff)[_i]), (LAS unsigned*)(lds + (bufoff) + ldsw + _i * 8192), 16, 0, 0); } while (0)
; #define PG8_LDA(dst, b, h) do { _Pragma("unroll") for (int m = 0; m < 4; ++m) _Pragma("unroll") for (int k = 0; k < 2; ++k) dst[m][k] = *(const LAS bf16x8*)(lds + PG8_SA(b, h) + aoff + m * 2048 + k * 1024); } while (0)
; #define PG8_LDB(dst, b, h) do { _Pragma("unroll") for (int n = 0; n < 2; ++n) _Pragma("unroll") for (int k = 0; k < 2; ++k) dst[n][k] = *(const LAS bf16x8*)(lds + PG8_SB(b, h) + boff + n * 2048 + k * 1024); } while (0)
; #define PG8_MMA(ai, bj, At, Bt) do { __builtin_amdgcn_s_setprio(1); _Pragma("unroll") for (int m = 0; m < 4; ++m) _Pragma("unroll") for (int n = 0; n < 2; ++n) _Pragma("unroll") for (int k = 0; k < 2; ++k) \
;     acc[ai][bj][m][n] = __builtin_amdgcn_mfma_f32_16x16x32_bf16(Bt[n][k], At[m][k], acc[ai][bj][m][n], 0, 0, 0); __builtin_amdgcn_s_setprio(0); } while (0)
; #define PG8_WAIT_V(n) asm volatile("s_waitcnt vmcnt(" #n ")" ::: "memory")
; #define PG8_WAIT_L(n) asm volatile("s_waitcnt lgkmcnt(" #n ")" ::: "memory")
; #define PG8_BAR __builtin_amdgcn_s_barrier()
; #define PG8_SCHED __builtin_amdgcn_sched_barrier(0)
; template <class Epi, class Sched = StaticOrder>
; DI void gemm_phase(LAS unsigned char* lds, const Gemm g, const Sched& S, const Epi& E) {
;     ...
;       PG8_LDB(B0, 1, 0); PG8_SCHED; PG8_LDA(At, 1, 0); PG8_STAGE(PG8_SA(0, 1), a2 + hstep, voffA);
;       PG8_WAIT_L(8); PG8_BAR; PG8_WAIT_L(0); PG8_MMA(0, 0, At, B0); PG8_BAR; PG8_SCHED;
;       PG8_LDB(B1, 1, 1); PG8_STAGE(PG8_SB(1, 0), b3, voffB);
;       PG8_BAR; PG8_WAIT_L(0); PG8_MMA(0, 1, At, B1); PG8_BAR;
;       PG8_LDA(At, 1, 1); PG8_STAGE(PG8_SA(1, 0), a3, voffA);
;       PG8_BAR; PG8_WAIT_L(0); PG8_MMA(1, 0, At, B0); PG8_BAR; PG8_SCHED;
;       PG8_STAGE(PG8_SB(1, 1), b3 + hstep, voffB);
;       PG8_WAIT_V(6); PG8_BAR; PG8_MMA(1, 1, At, B1); PG8_BAR;
.Lsw_3:
	s_setprio 1
	s_barrier
	v_mfma_f32_16x16x32_bf16 v[52:55], v[192:195], v[144:147], v[52:55]
	v_mfma_f32_16x16x32_bf16 v[48:51], v[200:203], v[144:147], v[48:51]
	v_mfma_f32_16x16x32_bf16 v[36:39], v[192:195], v[152:155], v[36:39]
	v_mfma_f32_16x16x32_bf16 v[32:35], v[200:203], v[152:155], v[32:35]
	v_mfma_f32_16x16x32_bf16 v[20:23], v[192:195], v[160:163], v[20:23]
	v_mfma_f32_16x16x32_bf16 v[16:19], v[200:203], v[160:163], v[16:19]
	v_mfma_f32_16x16x32_bf16 v[4:7], v[192:195], v[168:171], v[4:7]
	v_mfma_f32_16x16x32_bf16 v[0:3], v[200:203], v[168:171], v[0:3]
	v_mfma_f32_16x16x32_bf16 v[52:55], v[196:199], v[148:151], v[52:55]
	v_mfma_f32_16x16x32_bf16 v[48:51], v[204:207], v[148:151], v[48:51]
	v_mfma_f32_16x16x32_bf16 v[36:39], v[196:199], v[156:159], v[36:39]
	v_mfma_f32_16x16x32_bf16 v[32:35], v[204:207], v[156:159], v[32:35]
	v_mfma_f32_16x16x32_bf16 v[20:23], v[196:199], v[164:167], v[20:23]
	v_mfma_f32_16x16x32_bf16 v[16:19], v[204:207], v[164:167], v[16:19]
	v_mfma_f32_16x16x32_bf16 v[4:7], v[196:199], v[172:175], v[4:7]
	v_mfma_f32_16x16x32_bf16 v[0:3], v[204:207], v[172:175], v[0:3]
	s_barrier
	s_setprio 0
	s_add_i32 s45, 0, 0x18000
	v_add_u32_e32 v140, s45, v212
	ds_read_b128 v[128:131], v140
	ds_read_b128 v[132:135], v140 offset:1024
	ds_read_b128 v[136:139], v140 offset:2048
	ds_read_b128 v[140:143], v140 offset:3072
	s_add_u32 s22, s22, 0x160000
	s_addc_u32 s23, s23, 0
	s_mov_b32 m0, s34
	ds_read_b128 v[144:147], v215 offset:32768
	ds_read_b128 v[148:151], v215 offset:33792
	ds_read_b128 v[152:155], v215 offset:34816
	ds_read_b128 v[156:159], v215 offset:35840
	ds_read_b128 v[160:163], v215 offset:36864
	ds_read_b128 v[164:167], v215 offset:37888
	ds_read_b128 v[168:171], v215 offset:38912
	ds_read_b128 v[172:175], v215 offset:39936
	global_load_lds_dwordx4 v176, s[22:23]
	s_mov_b32 m0, s35
	s_nop 0
	global_load_lds_dwordx4 v180, s[22:23]
	s_waitcnt lgkmcnt(0)
	s_setprio 1
	s_barrier
	v_mfma_f32_16x16x32_bf16 v[124:127], v[128:131], v[144:147], v[124:127]
	v_mfma_f32_16x16x32_bf16 v[120:123], v[136:139], v[144:147], v[120:123]
	v_mfma_f32_16x16x32_bf16 v[108:111], v[128:131], v[152:155], v[108:111]
	v_mfma_f32_16x16x32_bf16 v[104:107], v[136:139], v[152:155], v[104:107]
	v_mfma_f32_16x16x32_bf16 v[92:95], v[128:131], v[160:163], v[92:95]
	v_mfma_f32_16x16x32_bf16 v[88:91], v[136:139], v[160:163], v[88:91]
	v_mfma_f32_16x16x32_bf16 v[76:79], v[128:131], v[168:171], v[76:79]
	v_mfma_f32_16x16x32_bf16 v[72:75], v[136:139], v[168:171], v[72:75]
	v_mfma_f32_16x16x32_bf16 v[124:127], v[132:135], v[148:151], v[124:127]
	v_mfma_f32_16x16x32_bf16 v[120:123], v[140:143], v[148:151], v[120:123]
	v_mfma_f32_16x16x32_bf16 v[108:111], v[132:135], v[156:159], v[108:111]
	v_mfma_f32_16x16x32_bf16 v[104:107], v[140:143], v[156:159], v[104:107]
	v_mfma_f32_16x16x32_bf16 v[92:95], v[132:135], v[164:167], v[92:95]
	v_mfma_f32_16x16x32_bf16 v[88:91], v[140:143], v[164:167], v[88:91]
	v_mfma_f32_16x16x32_bf16 v[76:79], v[132:135], v[172:175], v[76:79]
	v_mfma_f32_16x16x32_bf16 v[72:75], v[140:143], v[172:175], v[72:75]
	s_barrier
	s_setprio 0
	s_add_i32 s22, 0, 0x1c000
	s_add_i32 s23, s45, s30
	v_add_u32_e32 v204, s22, v212
	s_mov_b32 m0, s23
	ds_read_b128 v[192:195], v204
	ds_read_b128 v[196:199], v204 offset:1024
	ds_read_b128 v[200:203], v204 offset:2048
	ds_read_b128 v[204:207], v204 offset:3072
	global_load_lds_dwordx4 v178, s[98:99]
	s_add_i32 m0, s23, 0x2000
	s_nop 0
	global_load_lds_dwordx4 v182, s[98:99]
	s_waitcnt lgkmcnt(0)
	s_setprio 1
	s_barrier
	v_mfma_f32_16x16x32_bf16 v[116:119], v[192:195], v[144:147], v[116:119]
	v_mfma_f32_16x16x32_bf16 v[112:115], v[200:203], v[144:147], v[112:115]
	v_mfma_f32_16x16x32_bf16 v[100:103], v[192:195], v[152:155], v[100:103]
	v_mfma_f32_16x16x32_bf16 v[96:99], v[200:203], v[152:155], v[96:99]
	v_mfma_f32_16x16x32_bf16 v[84:87], v[192:195], v[160:163], v[84:87]
	v_mfma_f32_16x16x32_bf16 v[80:83], v[200:203], v[160:163], v[80:83]
	v_mfma_f32_16x16x32_bf16 v[68:71], v[192:195], v[168:171], v[68:71]
	v_mfma_f32_16x16x32_bf16 v[64:67], v[200:203], v[168:171], v[64:67]
	v_mfma_f32_16x16x32_bf16 v[116:119], v[196:199], v[148:151], v[116:119]
	v_mfma_f32_16x16x32_bf16 v[112:115], v[204:207], v[148:151], v[112:115]
	v_mfma_f32_16x16x32_bf16 v[100:103], v[196:199], v[156:159], v[100:103]
	v_mfma_f32_16x16x32_bf16 v[96:99], v[204:207], v[156:159], v[96:99]
	v_mfma_f32_16x16x32_bf16 v[84:87], v[196:199], v[164:167], v[84:87]
	v_mfma_f32_16x16x32_bf16 v[80:83], v[204:207], v[164:167], v[80:83]
	v_mfma_f32_16x16x32_bf16 v[68:71], v[196:199], v[172:175], v[68:71]
	v_mfma_f32_16x16x32_bf16 v[64:67], v[204:207], v[172:175], v[64:67]
	s_barrier
	s_setprio 0
	s_mov_b32 m0, s37
	ds_read_b128 v[144:147], v215 offset:49152
	ds_read_b128 v[148:151], v215 offset:50176
	ds_read_b128 v[152:155], v215 offset:51200
	ds_read_b128 v[156:159], v215 offset:52224
	ds_read_b128 v[160:163], v215 offset:53248
	ds_read_b128 v[164:167], v215 offset:54272
	ds_read_b128 v[168:171], v215 offset:55296
	ds_read_b128 v[172:175], v215 offset:56320
	global_load_lds_dwordx4 v176, s[100:101]
	s_mov_b32 m0, s38
	s_nop 0
	global_load_lds_dwordx4 v180, s[100:101]
	s_waitcnt lgkmcnt(0)
	s_setprio 1
	s_barrier
	v_mfma_f32_16x16x32_bf16 v[60:63], v[128:131], v[144:147], v[60:63]
	v_mfma_f32_16x16x32_bf16 v[56:59], v[136:139], v[144:147], v[56:59]
	v_mfma_f32_16x16x32_bf16 v[44:47], v[128:131], v[152:155], v[44:47]
	v_mfma_f32_16x16x32_bf16 v[40:43], v[136:139], v[152:155], v[40:43]
	v_mfma_f32_16x16x32_bf16 v[28:31], v[128:131], v[160:163], v[28:31]
	v_mfma_f32_16x16x32_bf16 v[24:27], v[136:139], v[160:163], v[24:27]
	v_mfma_f32_16x16x32_bf16 v[12:15], v[128:131], v[168:171], v[12:15]
	v_mfma_f32_16x16x32_bf16 v[8:11], v[136:139], v[168:171], v[8:11]
	v_mfma_f32_16x16x32_bf16 v[60:63], v[132:135], v[148:151], v[60:63]
	v_mfma_f32_16x16x32_bf16 v[56:59], v[140:143], v[148:151], v[56:59]
	v_mfma_f32_16x16x32_bf16 v[44:47], v[132:135], v[156:159], v[44:47]
	v_mfma_f32_16x16x32_bf16 v[40:43], v[140:143], v[156:159], v[40:43]
	v_mfma_f32_16x16x32_bf16 v[28:31], v[132:135], v[164:167], v[28:31]
	v_mfma_f32_16x16x32_bf16 v[24:27], v[140:143], v[164:167], v[24:27]
	v_mfma_f32_16x16x32_bf16 v[12:15], v[132:135], v[172:175], v[12:15]
	v_mfma_f32_16x16x32_bf16 v[8:11], v[140:143], v[172:175], v[8:11]
	s_barrier
	s_setprio 0
	s_add_u32 s20, s20, 0x160080
	s_addc_u32 s21, s21, 0
	s_add_i32 s22, s22, s30
	s_mov_b32 m0, s22
	s_nop 0
	global_load_lds_dwordx4 v178, s[20:21]
	s_add_i32 m0, s22, 0x2000
	s_nop 0
	global_load_lds_dwordx4 v182, s[20:21]
	s_waitcnt vmcnt(6)
	s_cmpk_eq_i32 s44, 0x54
	s_cbranch_scc0 .Lxs_3
	s_add_i32 m0, s31, 0xc000
	s_nop 0
	global_load_lds_dwordx4 v184, s[100:101]
	s_add_i32 m0, s31, 0xe000
	s_nop 0
	global_load_lds_dwordx4 v186, s[100:101]
; DI unsigned pack2(float lo, float hi) { f32x2 v = {lo, hi}; bf16v2 r = __builtin_convertvector(v, bf16v2); return __builtin_bit_cast(unsigned, r); }
;   DI void operator()(const f32x4 (&acc)[2][2][4][2], const Unit& u, int wr, int wc, int fr, int fq) const {
;     const int row0 = u.pm * BM + wr * 64 + fr, col0 = u.pn * BM + wc * 32 + 8 * fq;
; #pragma unroll
;     for (int ai = 0; ai < 2; ++ai) {
;       f32x4 bv[4][2][2];
; #pragma unroll
;       for (int m = 0; m < 4; ++m)
; #pragma unroll
;         for (int bj = 0; bj < 2; ++bj) {
;           const float* bp = base + (size_t)(row0 + ai * HALF + m * 16) * 2048 + col0 + bj * HALF;
;           bv[m][bj][0] = *(const f32x4*)bp; bv[m][bj][1] = *(const f32x4*)(bp + 4);
;         }
; #pragma unroll
;       for (int m = 0; m < 4; ++m) {
;         const int row = row0 + ai * HALF + m * 16;
;         const size_t off = (size_t)row * 2048 + col0;
;         float ss = 0.f;
; #pragma unroll
;         for (int bj = 0; bj < 2; ++bj) {
;           const f32x4 v0 = acc[ai][bj][m][0] + bv[m][bj][0], v1 = acc[ai][bj][m][1] + bv[m][bj][1];
;           *(f32x4*)(C + off + bj * HALF) = v0; *(f32x4*)(C + off + bj * HALF + 4) = v1;
;           if (xb) {
;             u32x4 w; w.x = pack2(v0[0], v0[1]); w.y = pack2(v0[2], v0[3]); w.z = pack2(v1[0], v1[1]); w.w = pack2(v1[2], v1[3]);
;             *(u32x4*)(xb + off + bj * HALF) = w;
;             ss += v0[0] * v0[0] + v0[1] * v0[1] + v0[2] * v0[2] + v0[3] * v0[3] + v1[0] * v1[0] + v1[1] * v1[1] + v1[2] * v1[2] + v1[3] * v1[3];
;           }
;         }
;         if (xb) {
;           ss += __shfl_xor(ss, 16); ss += __shfl_xor(ss, 32);
;           if (fq == 0) ssq[(size_t)row * 32 + u.pn * 4 + wc] = ss;
;         }
.Lxs_3:
	s_add_i32 s44, s44, 2
	s_add_u32 s18, s18, 0x100
	s_addc_u32 s19, s19, 0
	s_add_u32 s42, s42, 0x100
	s_addc_u32 s43, s43, 0
	s_cmpk_gt_u32 s44, 0x55
	s_setprio 1
	s_barrier
	v_mfma_f32_16x16x32_bf16 v[52:55], v[192:195], v[144:147], v[52:55]
	v_mfma_f32_16x16x32_bf16 v[48:51], v[200:203], v[144:147], v[48:51]
	v_mfma_f32_16x16x32_bf16 v[36:39], v[192:195], v[152:155], v[36:39]
	v_mfma_f32_16x16x32_bf16 v[32:35], v[200:203], v[152:155], v[32:35]
	v_mfma_f32_16x16x32_bf16 v[20:23], v[192:195], v[160:163], v[20:23]
	v_mfma_f32_16x16x32_bf16 v[16:19], v[200:203], v[160:163], v[16:19]
	v_mfma_f32_16x16x32_bf16 v[4:7], v[192:195], v[168:171], v[4:7]
	v_mfma_f32_16x16x32_bf16 v[0:3], v[200:203], v[168:171], v[0:3]
	v_mfma_f32_16x16x32_bf16 v[52:55], v[196:199], v[148:151], v[52:55]
	v_mfma_f32_16x16x32_bf16 v[48:51], v[204:207], v[148:151], v[48:51]
	v_mfma_f32_16x16x32_bf16 v[36:39], v[196:199], v[156:159], v[36:39]
	v_mfma_f32_16x16x32_bf16 v[32:35], v[204:207], v[156:159], v[32:35]
	v_mfma_f32_16x16x32_bf16 v[20:23], v[196:199], v[164:167], v[20:23]
	v_mfma_f32_16x16x32_bf16 v[16:19], v[204:207], v[164:167], v[16:19]
	v_mfma_f32_16x16x32_bf16 v[4:7], v[196:199], v[172:175], v[4:7]
	v_mfma_f32_16x16x32_bf16 v[0:3], v[204:207], v[172:175], v[0:3]
	s_barrier
	s_setprio 0
	s_cbranch_scc0 .LBB0_961
	v_writelane_b32 v247, -2, 0
	v_lshl_add_u32 v194, s51, 8, v211
	v_lshl_or_b32 v192, s2, 8, v213
	v_readlane_b32 s52, v243, 3
	v_ashrrev_i32_e32 v193, 31, v192
	v_readlane_b32 s66, v243, 17
	v_readlane_b32 s67, v243, 18
	v_ashrrev_i32_e32 v195, 31, v194
	v_lshlrev_b64 v[128:129], 13, v[194:195]
	v_lshl_add_u64 v[196:197], v[192:193], 2, s[66:67]
	v_lshl_add_u64 v[236:237], v[196:197], 0, v[128:129]
	global_load_dwordx4 v[220:223], v[236:237], off
	global_load_dwordx4 v[224:227], v[236:237], off offset:16
	global_load_dwordx4 v[228:231], v[236:237], off offset:512
	global_load_dwordx4 v[232:235], v[236:237], off offset:528
	v_or_b32_e32 v206, 16, v194
	v_or_b32_e32 v202, 32, v194
	v_or_b32_e32 v198, 48, v194
	v_ashrrev_i32_e32 v207, 31, v206
	v_ashrrev_i32_e32 v203, 31, v202
	v_ashrrev_i32_e32 v199, 31, v198
	v_lshlrev_b64 v[128:129], 13, v[206:207]
	v_lshlrev_b64 v[130:131], 13, v[202:203]
	v_lshlrev_b64 v[132:133], 13, v[198:199]
	v_lshl_add_u64 v[208:209], v[196:197], 0, v[128:129]
	v_lshl_add_u64 v[204:205], v[196:197], 0, v[130:131]
	v_lshl_add_u64 v[200:201], v[196:197], 0, v[132:133]
	global_load_dwordx4 v[168:171], v[208:209], off offset:16
	global_load_dwordx4 v[172:175], v[208:209], off
	global_load_dwordx4 v[160:163], v[208:209], off offset:528
	global_load_dwordx4 v[164:167], v[208:209], off offset:512
	global_load_dwordx4 v[152:155], v[204:205], off offset:16
	global_load_dwordx4 v[156:159], v[204:205], off
	global_load_dwordx4 v[144:147], v[204:205], off offset:528
	global_load_dwordx4 v[148:151], v[204:205], off offset:512
	global_load_dwordx4 v[136:139], v[200:201], off offset:16
	global_load_dwordx4 v[140:143], v[200:201], off
	global_load_dwordx4 v[128:131], v[200:201], off offset:528
	global_load_dwordx4 v[132:135], v[200:201], off offset:512
	v_and_b32_e32 v218, 64, v217
	v_xor_b32_e32 v238, 16, v217
	v_add_u32_e32 v240, 64, v218
	v_xor_b32_e32 v239, 32, v217
	v_cmp_lt_i32_e32 vcc, v238, v240
	v_lshlrev_b64 v[218:219], 11, v[194:195]
	s_lshl_b32 s18, s2, 2
	v_cndmask_b32_e32 v241, v217, v238, vcc
	v_cmp_lt_i32_e32 vcc, v239, v240
	s_ashr_i32 s19, s18, 31
	v_readlane_b32 s53, v243, 4
	v_cndmask_b32_e32 v240, v217, v239, vcc
	v_lshl_add_u64 v[238:239], v[218:219], 0, v[192:193]
	v_lshlrev_b32_e32 v218, 2, v241
	v_lshl_add_u64 v[238:239], v[238:239], 1, s[12:13]
	v_readlane_b32 s54, v243, 5
	v_readlane_b32 s55, v243, 6
	v_readlane_b32 s56, v243, 7
	v_readlane_b32 s57, v243, 8
	v_readlane_b32 s58, v243, 9
	v_readlane_b32 s59, v243, 10
	v_readlane_b32 s60, v243, 11
	v_readlane_b32 s61, v243, 12
	v_readlane_b32 s62, v243, 13
	v_readlane_b32 s63, v243, 14
	v_readlane_b32 s64, v243, 15
	v_readlane_b32 s65, v243, 16
	s_waitcnt vmcnt(0)
	v_pk_add_f32 v[126:127], v[126:127], v[222:223]
	v_pk_add_f32 v[124:125], v[124:125], v[220:221]
	v_pk_add_f32 v[116:117], v[116:117], v[228:229]
	v_pk_add_f32 v[122:123], v[122:123], v[226:227]
	v_pk_add_f32 v[120:121], v[120:121], v[224:225]
	v_pk_add_f32 v[220:221], v[112:113], v[232:233]
	global_store_dwordx4 v[236:237], v[124:127], off
	global_store_dwordx4 v[236:237], v[120:123], off offset:16
	v_cvt_pk_bf16_f32 v112, v124, v125
	v_mul_f32_e32 v125, v125, v125
	v_mul_f32_e32 v219, v117, v117
	v_pk_add_f32 v[118:119], v[118:119], v[230:231]
	v_fmac_f32_e32 v125, v124, v124
	v_fmac_f32_e32 v219, v116, v116
	v_fmac_f32_e32 v125, v126, v126
	v_fmac_f32_e32 v219, v118, v118
	v_fmac_f32_e32 v125, v127, v127
	v_fmac_f32_e32 v219, v119, v119
	v_fmac_f32_e32 v125, v120, v120
	v_fmac_f32_e32 v219, v220, v220
	v_pk_add_f32 v[222:223], v[114:115], v[234:235]
	v_fmac_f32_e32 v125, v121, v121
	v_fmac_f32_e32 v219, v221, v221
	v_fmac_f32_e32 v125, v122, v122
	v_fmac_f32_e32 v219, v222, v222
	v_fmac_f32_e32 v125, v123, v123
	v_fmac_f32_e32 v219, v223, v223
	v_cvt_pk_bf16_f32 v114, v120, v121
	v_add_f32_e32 v121, v125, v219
	v_cvt_pk_bf16_f32 v115, v122, v123
	ds_bpermute_b32 v122, v218, v121
	v_cvt_pk_bf16_f32 v113, v126, v127
	global_store_dwordx4 v[238:239], v[112:115], off
	global_store_dwordx4 v[236:237], v[116:119], off offset:512
	global_store_dwordx4 v[236:237], v[220:223], off offset:528
	v_lshlrev_b32_e32 v126, 2, v240
	v_cvt_pk_bf16_f32 v120, v116, v117
	s_waitcnt lgkmcnt(0)
	v_add_f32_e32 v112, v121, v122
	ds_bpermute_b32 v113, v126, v112
	v_cvt_pk_bf16_f32 v121, v118, v119
	v_cvt_pk_bf16_f32 v122, v220, v221
	v_cvt_pk_bf16_f32 v123, v222, v223
	global_store_dwordx4 v[238:239], v[120:123], off offset:256
	s_and_saveexec_b64 s[20:21], s[0:1]
	s_cbranch_execz .LBB0_964
	s_waitcnt lgkmcnt(0)
	v_add_f32_e32 v114, v112, v113
	v_lshlrev_b64 v[112:113], 7, v[194:195]
	v_lshl_add_u64 v[112:113], s[14:15], 0, v[112:113]
	v_lshl_add_u64 v[112:113], s[18:19], 2, v[112:113]
	s_lshl_b32 s2, s36, 2
	v_lshl_add_u64 v[112:113], v[112:113], 0, s[2:3]
	global_store_dword v[112:113], v114, off

; #define LAS __attribute__((address_space(3)))
;   DI bool next(int i, Unit& u) const {
;     const int rd = i / 3, k = i - 3 * rd;
;     const int tr = c + G * rd; if (tr >= 512) return false;
;     int pm, t;
;     if (G == 256) { const int x = c & 7, q = (c >> 3) + 32 * rd; pm = 8 * x + (q & 7); t = q >> 3; }
;     else { pm = tr >> 3; t = tr & 7; }
;     u.pm = pm; u.pn = k < 2 ? 2 * t + k : 16 + t; return true;
; DI void run_gemm(const Params& p, int id, unsigned char* smem) {
;     ...
;   else if (kind == 3) { pg8::EpiOdd E; E.BG = ((bf16_t*)(p.ws + OFF_A6)); E.C = ((bf16_t*)(p.ws + OFF_Cc)); E.cw = p.od_conv_w; E.tailM = ((float*)(p.ws + OFF_tailM)); E.headC = ((float*)(p.ws + OFF_headC)); E.ssq = ssq_in; pg8::TripletOrder T; T.init((int)gridDim.x, S.c); pg8::gemm_phase<pg8::EpiOdd, pg8::TripletOrder>((LAS unsigned char*)smem, g, T, E); }
.LBB0_1036:
	v_writelane_b32 v247, 1, 0
	s_add_i32 s0, 0, 0x20008
	v_mov_b32_e32 v0, s0
	ds_read_b32 v0, v0
	v_readfirstlane_b32 s33, v210
	s_waitcnt lgkmcnt(0)
	v_readfirstlane_b32 s31, v0
	s_cmpk_gt_i32 s31, 0x1ff
	s_cbranch_scc1 .LBB0_1072
	v_readlane_b32 s0, v243, 1
	v_readlane_b32 s1, v243, 2
	s_and_b64 vcc, exec, s[0:1]
	s_cbranch_vccz .LBB0_1039
	s_ashr_i32 s60, s31, 3
	s_and_b32 s4, s31, 7
	s_cbranch_execz .LBB0_1040
	s_branch .LBB0_1041

; #define PG8_STAGE(bufoff, gbase, voff) do { _Pragma("unroll") for (int _i = 0; _i < 2; ++_i) \
;     __builtin_amdgcn_global_load_lds((const unsigned*)((const char*)(gbase) + (voff)[_i]), (LAS unsigned*)(lds + (bufoff) + ldsw + _i * 8192), 16, 0, 0); } while (0)
; #define PG8_LDA(dst, b, h) do { _Pragma("unroll") for (int m = 0; m < 4; ++m) _Pragma("unroll") for (int k = 0; k < 2; ++k) dst[m][k] = *(const LAS bf16x8*)(lds + PG8_SA(b, h) + aoff + m * 2048 + k * 1024); } while (0)
; #define PG8_LDB(dst, b, h) do { _Pragma("unroll") for (int n = 0; n < 2; ++n) _Pragma("unroll") for (int k = 0; k < 2; ++k) dst[n][k] = *(const LAS bf16x8*)(lds + PG8_SB(b, h) + boff + n * 2048 + k * 1024); } while (0)
; #define PG8_MMA(ai, bj, At, Bt) do { __builtin_amdgcn_s_setprio(1); _Pragma("unroll") for (int m = 0; m < 4; ++m) _Pragma("unroll") for (int n = 0; n < 2; ++n) _Pragma("unroll") for (int k = 0; k < 2; ++k) \
;     acc[ai][bj][m][n] = __builtin_amdgcn_mfma_f32_16x16x32_bf16(Bt[n][k], At[m][k], acc[ai][bj][m][n], 0, 0, 0); __builtin_amdgcn_s_setprio(0); } while (0)
; #define PG8_WAIT_V(n) asm volatile("s_waitcnt vmcnt(" #n ")" ::: "memory")
; #define PG8_WAIT_L(n) asm volatile("s_waitcnt lgkmcnt(" #n ")" ::: "memory")
; #define PG8_BAR __builtin_amdgcn_s_barrier()
; #define PG8_SCHED __builtin_amdgcn_sched_barrier(0)
; template <class Epi, class Sched = StaticOrder>
; DI void gemm_phase(LAS unsigned char* lds, const Gemm g, const Sched& S, const Epi& E) {
;     ...
;     for (int t = 0; t < nt; t += 2) {
;       const bool last = (t == nt - 2);
;       const char* a1 = cA + (size_t)(t + 1) * kstep;
;       const char* a2 = last ? nA : cA + (size_t)(t + 2) * kstep; const char* b2 = last ? nB : cB + (size_t)(t + 2) * kstep;
;       const char* a3 = a2 + kstep; const char* b3 = b2 + kstep;
;       PG8_LDB(B0, 0, 0); PG8_SCHED; PG8_LDA(At, 0, 0); PG8_STAGE(PG8_SA(1, 1), a1 + hstep, voffA);
;       PG8_WAIT_L(8); PG8_BAR; PG8_WAIT_L(0); PG8_MMA(0, 0, At, B0); PG8_BAR; PG8_SCHED;
;       PG8_LDB(B1, 0, 1); PG8_STAGE(PG8_SB(0, 0), b2, voffB);
;       PG8_BAR; PG8_WAIT_L(0); PG8_MMA(0, 1, At, B1); PG8_BAR;
;       PG8_LDA(At, 0, 1); PG8_STAGE(PG8_SA(0, 0), a2, voffA);
;       PG8_BAR; PG8_WAIT_L(0); PG8_MMA(1, 0, At, B0); PG8_BAR; PG8_SCHED;
;       PG8_STAGE(PG8_SB(0, 1), b2 + hstep, voffB);
;       PG8_WAIT_V(6); PG8_BAR; PG8_MMA(1, 1, At, B1); PG8_BAR;
.LBB0_1052:
	ds_read_b128 v[128:131], v203
	ds_read_b128 v[132:135], v203 offset:1024
	ds_read_b128 v[136:139], v203 offset:2048
	ds_read_b128 v[140:143], v203 offset:3072
	s_add_u32 s12, s10, 0xfff80080
	s_addc_u32 s13, s11, -1
	s_cmp_eq_u32 s52, 28
	s_cselect_b32 s65, s41, s13
	s_cselect_b32 s64, s42, s12
	s_cselect_b32 s13, s43, s49
	s_cselect_b32 s12, s44, s45
	s_add_i32 m0, s61, 0xc000
	ds_read_b128 v[144:147], v204
	ds_read_b128 v[148:151], v204 offset:1024
	ds_read_b128 v[152:155], v204 offset:2048
	ds_read_b128 v[156:159], v204 offset:3072
	ds_read_b128 v[178:181], v204 offset:4096
	ds_read_b128 v[182:185], v204 offset:5120
	ds_read_b128 v[186:189], v204 offset:6144
	ds_read_b128 v[190:193], v204 offset:7168
	global_load_lds_dwordx4 v172, s[10:11]
	s_add_i32 m0, s61, 0xe000
	s_nop 0
	global_load_lds_dwordx4 v174, s[10:11]
	s_waitcnt lgkmcnt(0)
	s_setprio 1
	s_barrier
	v_mfma_f32_16x16x32_bf16 v[124:127], v[128:131], v[144:147], v[124:127]
	v_mfma_f32_16x16x32_bf16 v[120:123], v[136:139], v[144:147], v[120:123]
	v_mfma_f32_16x16x32_bf16 v[116:119], v[128:131], v[152:155], v[116:119]
	v_mfma_f32_16x16x32_bf16 v[104:107], v[136:139], v[152:155], v[104:107]
	v_mfma_f32_16x16x32_bf16 v[92:95], v[128:131], v[178:181], v[92:95]
	v_mfma_f32_16x16x32_bf16 v[88:91], v[136:139], v[178:181], v[88:91]
	v_mfma_f32_16x16x32_bf16 v[84:87], v[128:131], v[186:189], v[84:87]
	v_mfma_f32_16x16x32_bf16 v[72:75], v[136:139], v[186:189], v[72:75]
	v_mfma_f32_16x16x32_bf16 v[124:127], v[132:135], v[148:151], v[124:127]
	v_mfma_f32_16x16x32_bf16 v[120:123], v[140:143], v[148:151], v[120:123]
	v_mfma_f32_16x16x32_bf16 v[116:119], v[132:135], v[156:159], v[116:119]
	v_mfma_f32_16x16x32_bf16 v[104:107], v[140:143], v[156:159], v[104:107]
	v_mfma_f32_16x16x32_bf16 v[92:95], v[132:135], v[182:185], v[92:95]
	v_mfma_f32_16x16x32_bf16 v[88:91], v[140:143], v[182:185], v[88:91]
	v_mfma_f32_16x16x32_bf16 v[84:87], v[132:135], v[190:193], v[84:87]
	v_mfma_f32_16x16x32_bf16 v[72:75], v[140:143], v[190:193], v[72:75]
	s_barrier
	s_setprio 0
	s_add_i32 s53, s80, s70
	s_add_u32 s98, s12, 0x80
	s_addc_u32 s99, s13, 0
	s_add_u32 s100, s64, 0x80
	s_addc_u32 s101, s65, 0
	s_mov_b32 m0, s53
	ds_read_b128 v[194:197], v205
	ds_read_b128 v[212:215], v205 offset:1024
	ds_read_b128 v[216:219], v205 offset:2048
	ds_read_b128 v[220:223], v205 offset:3072
	global_load_lds_dwordx4 v162, s[12:13]
	s_add_i32 m0, s53, 0x2000
	s_nop 0
	global_load_lds_dwordx4 v166, s[12:13]
	s_waitcnt lgkmcnt(0)
	s_setprio 1
	s_barrier
	v_mfma_f32_16x16x32_bf16 v[112:115], v[194:197], v[144:147], v[112:115]
	v_mfma_f32_16x16x32_bf16 v[108:111], v[216:219], v[144:147], v[108:111]
	v_mfma_f32_16x16x32_bf16 v[100:103], v[194:197], v[152:155], v[100:103]
	v_mfma_f32_16x16x32_bf16 v[96:99], v[216:219], v[152:155], v[96:99]
	v_mfma_f32_16x16x32_bf16 v[80:83], v[194:197], v[178:181], v[80:83]
	v_mfma_f32_16x16x32_bf16 v[76:79], v[216:219], v[178:181], v[76:79]
	v_mfma_f32_16x16x32_bf16 v[68:71], v[194:197], v[186:189], v[68:71]
	v_mfma_f32_16x16x32_bf16 v[64:67], v[216:219], v[186:189], v[64:67]
	v_mfma_f32_16x16x32_bf16 v[112:115], v[212:215], v[148:151], v[112:115]
	v_mfma_f32_16x16x32_bf16 v[108:111], v[220:223], v[148:151], v[108:111]
	v_mfma_f32_16x16x32_bf16 v[100:103], v[212:215], v[156:159], v[100:103]
	v_mfma_f32_16x16x32_bf16 v[96:99], v[220:223], v[156:159], v[96:99]
	v_mfma_f32_16x16x32_bf16 v[80:83], v[212:215], v[182:185], v[80:83]
	v_mfma_f32_16x16x32_bf16 v[76:79], v[220:223], v[182:185], v[76:79]
	v_mfma_f32_16x16x32_bf16 v[68:71], v[212:215], v[190:193], v[68:71]
	v_mfma_f32_16x16x32_bf16 v[64:67], v[220:223], v[190:193], v[64:67]
	s_barrier
	s_setprio 0
	s_mov_b32 m0, s61
	ds_read_b128 v[144:147], v204 offset:16384
	ds_read_b128 v[148:151], v204 offset:17408
	ds_read_b128 v[152:155], v204 offset:18432
	ds_read_b128 v[156:159], v204 offset:19456
	ds_read_b128 v[178:181], v204 offset:20480
	ds_read_b128 v[182:185], v204 offset:21504
	ds_read_b128 v[186:189], v204 offset:22528
	ds_read_b128 v[190:193], v204 offset:23552
	global_load_lds_dwordx4 v160, s[64:65]
	s_mov_b32 m0, s63
	s_nop 0
	global_load_lds_dwordx4 v164, s[64:65]
	s_waitcnt lgkmcnt(0)
	s_setprio 1
	s_barrier
	v_mfma_f32_16x16x32_bf16 v[60:63], v[128:131], v[144:147], v[60:63]
	v_mfma_f32_16x16x32_bf16 v[56:59], v[136:139], v[144:147], v[56:59]
	v_mfma_f32_16x16x32_bf16 v[48:51], v[128:131], v[152:155], v[48:51]
	v_mfma_f32_16x16x32_bf16 v[40:43], v[136:139], v[152:155], v[40:43]
	v_mfma_f32_16x16x32_bf16 v[28:31], v[128:131], v[178:181], v[28:31]
	v_mfma_f32_16x16x32_bf16 v[24:27], v[136:139], v[178:181], v[24:27]
	v_mfma_f32_16x16x32_bf16 v[12:15], v[128:131], v[186:189], v[12:15]
	v_mfma_f32_16x16x32_bf16 v[8:11], v[136:139], v[186:189], v[8:11]
	v_mfma_f32_16x16x32_bf16 v[60:63], v[132:135], v[148:151], v[60:63]
	v_mfma_f32_16x16x32_bf16 v[56:59], v[140:143], v[148:151], v[56:59]
	v_mfma_f32_16x16x32_bf16 v[48:51], v[132:135], v[156:159], v[48:51]
	v_mfma_f32_16x16x32_bf16 v[40:43], v[140:143], v[156:159], v[40:43]
	v_mfma_f32_16x16x32_bf16 v[28:31], v[132:135], v[182:185], v[28:31]
	v_mfma_f32_16x16x32_bf16 v[24:27], v[140:143], v[182:185], v[24:27]
	v_mfma_f32_16x16x32_bf16 v[12:15], v[132:135], v[190:193], v[12:15]
	v_mfma_f32_16x16x32_bf16 v[8:11], v[140:143], v[190:193], v[8:11]
	s_barrier
	s_setprio 0
	s_add_u32 s54, s12, 0x80000
	s_addc_u32 s55, s13, 0
	s_add_i32 s53, s81, s70
	s_mov_b32 m0, s53
	s_nop 0
	global_load_lds_dwordx4 v162, s[54:55]
	s_add_i32 m0, s53, 0x2000
	s_nop 0
	global_load_lds_dwordx4 v166, s[54:55]
	v_readlane_b32 vcc_lo, v247, 0
	s_cmp_eq_u32 s52, vcc_lo
	s_cbranch_scc1 .Lsw_4
	s_waitcnt vmcnt(6)
; #define PG8_STAGE(bufoff, gbase, voff) do { _Pragma("unroll") for (int _i = 0; _i < 2; ++_i) \
;     __builtin_amdgcn_global_load_lds((const unsigned*)((const char*)(gbase) + (voff)[_i]), (LAS unsigned*)(lds + (bufoff) + ldsw + _i * 8192), 16, 0, 0); } while (0)
; #define PG8_LDA(dst, b, h) do { _Pragma("unroll") for (int m = 0; m < 4; ++m) _Pragma("unroll") for (int k = 0; k < 2; ++k) dst[m][k] = *(const LAS bf16x8*)(lds + PG8_SA(b, h) + aoff + m * 2048 + k * 1024); } while (0)
; #define PG8_LDB(dst, b, h) do { _Pragma("unroll") for (int n = 0; n < 2; ++n) _Pragma("unroll") for (int k = 0; k < 2; ++k) dst[n][k] = *(const LAS bf16x8*)(lds + PG8_SB(b, h) + boff + n * 2048 + k * 1024); } while (0)
; #define PG8_MMA(ai, bj, At, Bt) do { __builtin_amdgcn_s_setprio(1); _Pragma("unroll") for (int m = 0; m < 4; ++m) _Pragma("unroll") for (int n = 0; n < 2; ++n) _Pragma("unroll") for (int k = 0; k < 2; ++k) \
;     acc[ai][bj][m][n] = __builtin_amdgcn_mfma_f32_16x16x32_bf16(Bt[n][k], At[m][k], acc[ai][bj][m][n], 0, 0, 0); __builtin_amdgcn_s_setprio(0); } while (0)
; #define PG8_WAIT_V(n) asm volatile("s_waitcnt vmcnt(" #n ")" ::: "memory")
; #define PG8_WAIT_L(n) asm volatile("s_waitcnt lgkmcnt(" #n ")" ::: "memory")
; #define PG8_BAR __builtin_amdgcn_s_barrier()
; #define PG8_SCHED __builtin_amdgcn_sched_barrier(0)
; template <class Epi, class Sched = StaticOrder>
; DI void gemm_phase(LAS unsigned char* lds, const Gemm g, const Sched& S, const Epi& E) {
;     ...
;       PG8_LDB(B0, 1, 0); PG8_SCHED; PG8_LDA(At, 1, 0); PG8_STAGE(PG8_SA(0, 1), a2 + hstep, voffA);
;       PG8_WAIT_L(8); PG8_BAR; PG8_WAIT_L(0); PG8_MMA(0, 0, At, B0); PG8_BAR; PG8_SCHED;
;       PG8_LDB(B1, 1, 1); PG8_STAGE(PG8_SB(1, 0), b3, voffB);
;       PG8_BAR; PG8_WAIT_L(0); PG8_MMA(0, 1, At, B1); PG8_BAR;
;       PG8_LDA(At, 1, 1); PG8_STAGE(PG8_SA(1, 0), a3, voffA);
;       PG8_BAR; PG8_WAIT_L(0); PG8_MMA(1, 0, At, B0); PG8_BAR; PG8_SCHED;
;       PG8_STAGE(PG8_SB(1, 1), b3 + hstep, voffB);
;       PG8_WAIT_V(6); PG8_BAR; PG8_MMA(1, 1, At, B1); PG8_BAR;
.Lsw_4:
	s_setprio 1
	s_barrier
	v_mfma_f32_16x16x32_bf16 v[52:55], v[194:197], v[144:147], v[52:55]
	v_mfma_f32_16x16x32_bf16 v[44:47], v[216:219], v[144:147], v[44:47]
	v_mfma_f32_16x16x32_bf16 v[36:39], v[194:197], v[152:155], v[36:39]
	v_mfma_f32_16x16x32_bf16 v[32:35], v[216:219], v[152:155], v[32:35]
	v_mfma_f32_16x16x32_bf16 v[20:23], v[194:197], v[178:181], v[20:23]
	v_mfma_f32_16x16x32_bf16 v[16:19], v[216:219], v[178:181], v[16:19]
	v_mfma_f32_16x16x32_bf16 v[4:7], v[194:197], v[186:189], v[4:7]
	v_mfma_f32_16x16x32_bf16 v[0:3], v[216:219], v[186:189], v[0:3]
	v_mfma_f32_16x16x32_bf16 v[52:55], v[212:215], v[148:151], v[52:55]
	v_mfma_f32_16x16x32_bf16 v[44:47], v[220:223], v[148:151], v[44:47]
	v_mfma_f32_16x16x32_bf16 v[36:39], v[212:215], v[156:159], v[36:39]
	v_mfma_f32_16x16x32_bf16 v[32:35], v[220:223], v[156:159], v[32:35]
	v_mfma_f32_16x16x32_bf16 v[20:23], v[212:215], v[182:185], v[20:23]
	v_mfma_f32_16x16x32_bf16 v[16:19], v[220:223], v[182:185], v[16:19]
	v_mfma_f32_16x16x32_bf16 v[4:7], v[212:215], v[190:193], v[4:7]
	v_mfma_f32_16x16x32_bf16 v[0:3], v[220:223], v[190:193], v[0:3]
	s_barrier
	s_setprio 0
	s_add_i32 s53, 0, 0x18000
	v_add_u32_e32 v140, s53, v199
	ds_read_b128 v[128:131], v140
	ds_read_b128 v[132:135], v140 offset:1024
	ds_read_b128 v[136:139], v140 offset:2048
	ds_read_b128 v[140:143], v140 offset:3072
	s_add_u32 s54, s64, 0x80000
	s_addc_u32 s55, s65, 0
	s_mov_b32 m0, s71
	ds_read_b128 v[144:147], v204 offset:32768
	ds_read_b128 v[148:151], v204 offset:33792
	ds_read_b128 v[152:155], v204 offset:34816
	ds_read_b128 v[156:159], v204 offset:35840
	ds_read_b128 v[178:181], v204 offset:36864
	ds_read_b128 v[182:185], v204 offset:37888
	ds_read_b128 v[186:189], v204 offset:38912
	ds_read_b128 v[190:193], v204 offset:39936
	global_load_lds_dwordx4 v160, s[54:55]
	s_mov_b32 m0, s72
	s_nop 0
	global_load_lds_dwordx4 v164, s[54:55]
	s_waitcnt lgkmcnt(0)
	s_setprio 1
	s_barrier
	v_mfma_f32_16x16x32_bf16 v[124:127], v[128:131], v[144:147], v[124:127]
	v_mfma_f32_16x16x32_bf16 v[120:123], v[136:139], v[144:147], v[120:123]
	v_mfma_f32_16x16x32_bf16 v[116:119], v[128:131], v[152:155], v[116:119]
	v_mfma_f32_16x16x32_bf16 v[104:107], v[136:139], v[152:155], v[104:107]
	v_mfma_f32_16x16x32_bf16 v[92:95], v[128:131], v[178:181], v[92:95]
	v_mfma_f32_16x16x32_bf16 v[88:91], v[136:139], v[178:181], v[88:91]
	v_mfma_f32_16x16x32_bf16 v[84:87], v[128:131], v[186:189], v[84:87]
	v_mfma_f32_16x16x32_bf16 v[72:75], v[136:139], v[186:189], v[72:75]
	v_mfma_f32_16x16x32_bf16 v[124:127], v[132:135], v[148:151], v[124:127]
	v_mfma_f32_16x16x32_bf16 v[120:123], v[140:143], v[148:151], v[120:123]
	v_mfma_f32_16x16x32_bf16 v[116:119], v[132:135], v[156:159], v[116:119]
	v_mfma_f32_16x16x32_bf16 v[104:107], v[140:143], v[156:159], v[104:107]
	v_mfma_f32_16x16x32_bf16 v[92:95], v[132:135], v[182:185], v[92:95]
	v_mfma_f32_16x16x32_bf16 v[88:91], v[140:143], v[182:185], v[88:91]
	v_mfma_f32_16x16x32_bf16 v[84:87], v[132:135], v[190:193], v[84:87]
	v_mfma_f32_16x16x32_bf16 v[72:75], v[140:143], v[190:193], v[72:75]
	s_barrier
	s_setprio 0
	s_add_i32 s54, 0, 0x1c000
	s_add_i32 s53, s53, s70
	v_add_u32_e32 v168, s54, v199
	s_mov_b32 m0, s53
	ds_read_b128 v[194:197], v168
	ds_read_b128 v[212:215], v168 offset:1024
	ds_read_b128 v[216:219], v168 offset:2048
	ds_read_b128 v[220:223], v168 offset:3072
	global_load_lds_dwordx4 v162, s[98:99]
	s_add_i32 m0, s53, 0x2000
	s_nop 0
	global_load_lds_dwordx4 v166, s[98:99]
	s_waitcnt lgkmcnt(0)
	s_setprio 1
	s_barrier
	v_mfma_f32_16x16x32_bf16 v[112:115], v[194:197], v[144:147], v[112:115]
	v_mfma_f32_16x16x32_bf16 v[108:111], v[216:219], v[144:147], v[108:111]
	v_mfma_f32_16x16x32_bf16 v[100:103], v[194:197], v[152:155], v[100:103]
	v_mfma_f32_16x16x32_bf16 v[96:99], v[216:219], v[152:155], v[96:99]
	v_mfma_f32_16x16x32_bf16 v[80:83], v[194:197], v[178:181], v[80:83]
	v_mfma_f32_16x16x32_bf16 v[76:79], v[216:219], v[178:181], v[76:79]
	v_mfma_f32_16x16x32_bf16 v[68:71], v[194:197], v[186:189], v[68:71]
	v_mfma_f32_16x16x32_bf16 v[64:67], v[216:219], v[186:189], v[64:67]
	v_mfma_f32_16x16x32_bf16 v[112:115], v[212:215], v[148:151], v[112:115]
	v_mfma_f32_16x16x32_bf16 v[108:111], v[220:223], v[148:151], v[108:111]
	v_mfma_f32_16x16x32_bf16 v[100:103], v[212:215], v[156:159], v[100:103]
	v_mfma_f32_16x16x32_bf16 v[96:99], v[220:223], v[156:159], v[96:99]
	v_mfma_f32_16x16x32_bf16 v[80:83], v[212:215], v[182:185], v[80:83]
	v_mfma_f32_16x16x32_bf16 v[76:79], v[220:223], v[182:185], v[76:79]
	v_mfma_f32_16x16x32_bf16 v[68:71], v[212:215], v[190:193], v[68:71]
	v_mfma_f32_16x16x32_bf16 v[64:67], v[220:223], v[190:193], v[64:67]
	s_barrier
	s_setprio 0
	s_mov_b32 m0, s76
	ds_read_b128 v[144:147], v204 offset:49152
	ds_read_b128 v[148:151], v204 offset:50176
	ds_read_b128 v[152:155], v204 offset:51200
	ds_read_b128 v[156:159], v204 offset:52224
	ds_read_b128 v[178:181], v204 offset:53248
	ds_read_b128 v[182:185], v204 offset:54272
	ds_read_b128 v[186:189], v204 offset:55296
	ds_read_b128 v[190:193], v204 offset:56320
	global_load_lds_dwordx4 v160, s[100:101]
	s_mov_b32 m0, s77
	s_nop 0
	global_load_lds_dwordx4 v164, s[100:101]
	s_waitcnt lgkmcnt(0)
	s_setprio 1
	s_barrier
	v_mfma_f32_16x16x32_bf16 v[60:63], v[128:131], v[144:147], v[60:63]
	v_mfma_f32_16x16x32_bf16 v[56:59], v[136:139], v[144:147], v[56:59]
	v_mfma_f32_16x16x32_bf16 v[48:51], v[128:131], v[152:155], v[48:51]
	v_mfma_f32_16x16x32_bf16 v[40:43], v[136:139], v[152:155], v[40:43]
	v_mfma_f32_16x16x32_bf16 v[28:31], v[128:131], v[178:181], v[28:31]
	v_mfma_f32_16x16x32_bf16 v[24:27], v[136:139], v[178:181], v[24:27]
	v_mfma_f32_16x16x32_bf16 v[12:15], v[128:131], v[186:189], v[12:15]
	v_mfma_f32_16x16x32_bf16 v[8:11], v[136:139], v[186:189], v[8:11]
	v_mfma_f32_16x16x32_bf16 v[60:63], v[132:135], v[148:151], v[60:63]
	v_mfma_f32_16x16x32_bf16 v[56:59], v[140:143], v[148:151], v[56:59]
	v_mfma_f32_16x16x32_bf16 v[48:51], v[132:135], v[156:159], v[48:51]
	v_mfma_f32_16x16x32_bf16 v[40:43], v[140:143], v[156:159], v[40:43]
	v_mfma_f32_16x16x32_bf16 v[28:31], v[132:135], v[182:185], v[28:31]
	v_mfma_f32_16x16x32_bf16 v[24:27], v[140:143], v[182:185], v[24:27]
	v_mfma_f32_16x16x32_bf16 v[12:15], v[132:135], v[190:193], v[12:15]
	v_mfma_f32_16x16x32_bf16 v[8:11], v[140:143], v[190:193], v[8:11]
	s_barrier
	s_setprio 0
	s_add_u32 s12, s12, 0x80080
	s_addc_u32 s13, s13, 0
	s_add_i32 s53, s54, s70
	s_mov_b32 m0, s53
	s_nop 0
	global_load_lds_dwordx4 v162, s[12:13]
	s_add_i32 m0, s53, 0x2000
	s_nop 0
	global_load_lds_dwordx4 v166, s[12:13]
	s_waitcnt vmcnt(6)
	s_cmp_eq_u32 s52, 28
	s_cbranch_scc0 .Lxs_4
	s_add_i32 m0, s61, 0xc000
	s_nop 0
	global_load_lds_dwordx4 v172, s[100:101]
	s_add_i32 m0, s61, 0xe000
	s_nop 0
	global_load_lds_dwordx4 v174, s[100:101]
; #define PG8_STAGE(bufoff, gbase, voff) do { _Pragma("unroll") for (int _i = 0; _i < 2; ++_i) \
;     __builtin_amdgcn_global_load_lds((const unsigned*)((const char*)(gbase) + (voff)[_i]), (LAS unsigned*)(lds + (bufoff) + ldsw + _i * 8192), 16, 0, 0); } while (0)
; #define PG8_MMA(ai, bj, At, Bt) do { __builtin_amdgcn_s_setprio(1); _Pragma("unroll") for (int m = 0; m < 4; ++m) _Pragma("unroll") for (int n = 0; n < 2; ++n) _Pragma("unroll") for (int k = 0; k < 2; ++k) \
;     acc[ai][bj][m][n] = __builtin_amdgcn_mfma_f32_16x16x32_bf16(Bt[n][k], At[m][k], acc[ai][bj][m][n], 0, 0, 0); __builtin_amdgcn_s_setprio(0); } while (0)
; #define PG8_WAIT_V(n) asm volatile("s_waitcnt vmcnt(" #n ")" ::: "memory")
; #define PG8_WAIT_L(n) asm volatile("s_waitcnt lgkmcnt(" #n ")" ::: "memory")
; #define PG8_BAR __builtin_amdgcn_s_barrier()
; #define PG8_SCHED __builtin_amdgcn_sched_barrier(0)
;   DI void operator()(const f32x4 (&acc)[2][2][4][2], const Unit& u, int wr, int wc, int fr, int fq) const {
;     ...
;     const int col = u.pn * 128 + wc * 32 + 8 * fq;
;     float w0[8], w1[8], w2[8];
; #pragma unroll
;     for (int e = 0; e < 8; ++e) { w0[e] = cw[col + e]; w1[e] = cw[2048 + col + e]; w2[e] = cw[4096 + col + e]; }
; #pragma unroll
;     for (int ai = 0; ai < 2; ++ai) {
;       const int row0 = u.pm * BM + ai * HALF + wr * 64, span = row0 >> 6;
;       float rsv[4];
; #pragma unroll
;       for (int m = 0; m < 4; ++m) rsv[m] = row_rstd(ssq, row0 + 16 * m + fr, fq);
; template <class Epi, class Sched = StaticOrder>
; DI void gemm_phase(LAS unsigned char* lds, const Gemm g, const Sched& S, const Epi& E) {
;     ...
;       PG8_BAR; PG8_WAIT_L(0); PG8_MMA(1, 0, At, B0); PG8_BAR; PG8_SCHED;
;       PG8_STAGE(PG8_SB(1, 1), b3 + hstep, voffB);
;       PG8_WAIT_V(6); PG8_BAR; PG8_MMA(1, 1, At, B1); PG8_BAR;
;     }
;     E(acc, cur, wr, wc, fr, fq);
.Lxs_4:
	s_add_i32 s52, s52, 2
	s_add_u32 s10, s10, 0x100
	s_addc_u32 s11, s11, 0
	s_add_u32 s45, s45, 0x100
	s_addc_u32 s49, s49, 0
	s_cmp_gt_u32 s52, 29
	s_setprio 1
	s_barrier
	v_mfma_f32_16x16x32_bf16 v[52:55], v[194:197], v[144:147], v[52:55]
	v_mfma_f32_16x16x32_bf16 v[44:47], v[216:219], v[144:147], v[44:47]
	v_mfma_f32_16x16x32_bf16 v[36:39], v[194:197], v[152:155], v[36:39]
	v_mfma_f32_16x16x32_bf16 v[32:35], v[216:219], v[152:155], v[32:35]
	v_mfma_f32_16x16x32_bf16 v[20:23], v[194:197], v[178:181], v[20:23]
	v_mfma_f32_16x16x32_bf16 v[16:19], v[216:219], v[178:181], v[16:19]
	v_mfma_f32_16x16x32_bf16 v[4:7], v[194:197], v[186:189], v[4:7]
	v_mfma_f32_16x16x32_bf16 v[0:3], v[216:219], v[186:189], v[0:3]
	v_mfma_f32_16x16x32_bf16 v[52:55], v[212:215], v[148:151], v[52:55]
	v_mfma_f32_16x16x32_bf16 v[44:47], v[220:223], v[148:151], v[44:47]
	v_mfma_f32_16x16x32_bf16 v[36:39], v[212:215], v[156:159], v[36:39]
	v_mfma_f32_16x16x32_bf16 v[32:35], v[220:223], v[156:159], v[32:35]
	v_mfma_f32_16x16x32_bf16 v[20:23], v[212:215], v[182:185], v[20:23]
	v_mfma_f32_16x16x32_bf16 v[16:19], v[220:223], v[182:185], v[16:19]
	v_mfma_f32_16x16x32_bf16 v[4:7], v[212:215], v[190:193], v[4:7]
	v_mfma_f32_16x16x32_bf16 v[0:3], v[220:223], v[190:193], v[0:3]
	s_barrier
	s_setprio 0
	s_cbranch_scc0 .LBB0_1052
	v_writelane_b32 v247, -2, 0
	s_cmp_lt_i32 s62, 16
	s_mov_b64 s[10:11], -1
	s_cbranch_scc0 .LBB0_1067
	s_lshl_b32 s41, s60, 8
	s_add_i32 s41, s41, s75
	v_or_b32_e32 v186, s41, v177
	v_ashrrev_i32_e32 v187, 31, v186
	v_lshlrev_b64 v[128:129], 7, v[186:187]
	v_or_b32_e32 v180, 16, v186
	v_lshl_add_u64 v[128:129], v[170:171], 0, v[128:129]
	v_ashrrev_i32_e32 v181, 31, v180
	global_load_dwordx4 v[152:155], v[128:129], off
	global_load_dwordx4 v[156:159], v[128:129], off offset:16
	v_lshlrev_b64 v[128:129], 7, v[180:181]
	v_lshl_add_u64 v[128:129], v[170:171], 0, v[128:129]
	global_load_dwordx4 v[188:191], v[128:129], off
	global_load_dwordx4 v[192:195], v[128:129], off offset:16
	v_or_b32_e32 v184, 32, v186
	v_ashrrev_i32_e32 v185, 31, v184
	v_lshlrev_b64 v[128:129], 7, v[184:185]
	v_or_b32_e32 v182, 48, v186
	v_lshl_add_u64 v[128:129], v[170:171], 0, v[128:129]
	v_ashrrev_i32_e32 v183, 31, v182
	global_load_dwordx4 v[212:215], v[128:129], off
	global_load_dwordx4 v[216:219], v[128:129], off offset:16
	v_lshlrev_b64 v[128:129], 7, v[182:183]
	v_lshl_add_u64 v[128:129], v[170:171], 0, v[128:129]
	global_load_dwordx4 v[220:223], v[128:129], off
	global_load_dwordx4 v[224:227], v[128:129], off offset:16
	v_and_b32_e32 v129, 64, v206
	v_lshl_or_b32 v178, s62, 7, v200
	v_xor_b32_e32 v128, 16, v206
	v_add_u32_e32 v129, 64, v129
	v_readlane_b32 s44, v243, 3
	v_xor_b32_e32 v130, 32, v206
	v_ashrrev_i32_e32 v179, 31, v178
	v_readlane_b32 s45, v243, 4
	v_cmp_lt_i32_e32 vcc, v128, v129
	s_movk_i32 s10, 0x2000
	v_lshl_add_u64 v[144:145], v[178:179], 2, s[44:45]
	v_cndmask_b32_e32 v134, v206, v128, vcc
	v_cmp_lt_i32_e32 vcc, v130, v129
	v_lshl_add_u64 v[132:133], v[144:145], 0, s[26:27]
	v_lshl_add_u64 v[136:137], v[144:145], 0, s[28:29]
	v_cndmask_b32_e32 v135, v206, v130, vcc
	v_add_co_u32_e32 v146, vcc, s10, v144
	global_load_dwordx4 v[128:131], v[144:145], off offset:16
	global_load_dwordx4 v[140:143], v[144:145], off
	v_addc_co_u32_e32 v147, vcc, 0, v145, vcc
	v_add_co_u32_e32 v148, vcc, s74, v144
	v_lshlrev_b32_e32 v196, 2, v134
	s_nop 0
	v_addc_co_u32_e32 v149, vcc, 0, v145, vcc
	v_lshlrev_b32_e32 v207, 2, v135
	global_load_dwordx4 v[132:135], v[132:133], off offset:16
	s_nop 0
	global_load_dwordx4 v[136:139], v[136:137], off offset:16
	s_nop 0
	global_load_dwordx4 v[144:147], v[146:147], off
	s_nop 0
	global_load_dwordx4 v[148:151], v[148:149], off
	v_mov_b32_e32 v197, 0
	v_mov_b32_e32 v211, 0
	v_readlane_b32 s46, v243, 5
	v_readlane_b32 s47, v243, 6
	v_readlane_b32 s48, v243, 7
	v_readlane_b32 s49, v243, 8
	v_readlane_b32 s50, v243, 9
	v_readlane_b32 s51, v243, 10
	v_readlane_b32 s52, v243, 11
	v_readlane_b32 s53, v243, 12
	v_readlane_b32 s54, v243, 13
	v_readlane_b32 s55, v243, 14
	v_readlane_b32 s56, v243, 15
	v_readlane_b32 s57, v243, 16
	v_readlane_b32 s58, v243, 17
	v_readlane_b32 s59, v243, 18
	s_waitcnt vmcnt(0)
	v_mov_b32_e32 v208, v152
	v_mov_b32_e32 v209, v156
	v_mov_b32_e32 v156, v153
	v_mov_b32_e32 v152, v154
	v_mov_b32_e32 v153, v158
	v_mov_b32_e32 v158, v155
	v_pk_add_f32 v[154:155], v[208:209], v[156:157]
	v_pk_add_f32 v[152:153], v[152:153], v[158:159]
	v_mov_b32_e32 v156, v188
	v_mov_b32_e32 v157, v192
	v_mov_b32_e32 v192, v189
	v_mov_b32_e32 v158, v190
	v_mov_b32_e32 v159, v194
	v_mov_b32_e32 v194, v191
	v_pk_add_f32 v[152:153], v[154:155], v[152:153]
	v_pk_add_f32 v[154:155], v[156:157], v[192:193]
	v_pk_add_f32 v[156:157], v[158:159], v[194:195]
	v_mov_b32_e32 v188, v212
	v_pk_add_f32 v[154:155], v[154:155], v[156:157]
	v_mov_b32_e32 v157, v152
	v_mov_b32_e32 v156, v154
	v_mov_b32_e32 v152, v155
	v_pk_add_f32 v[152:153], v[156:157], v[152:153]
	ds_bpermute_b32 v155, v196, v153
	ds_bpermute_b32 v154, v196, v152
	v_mov_b32_e32 v189, v216
	v_mov_b32_e32 v216, v213
	v_mov_b32_e32 v190, v214
	v_mov_b32_e32 v191, v218
	s_waitcnt lgkmcnt(0)
; DI unsigned pack2(float lo, float hi) { f32x2 v = {lo, hi}; bf16v2 r = __builtin_convertvector(v, bf16v2); return __builtin_bit_cast(unsigned, r); }
; DI float dpp_ror1(float v) { return __int_as_float(__builtin_amdgcn_update_dpp(0, __float_as_int(v), 0x121, 0xf, 0xf, false)); }
; DI float dpp_ror2(float v) { return __int_as_float(__builtin_amdgcn_update_dpp(0, __float_as_int(v), 0x122, 0xf, 0xf, false)); }
; DI float row_rstd(const float* ssq, int row, int fq) {
;   const f32x4 a = *(const f32x4*)(ssq + (size_t)row * 32 + fq * 8), b = *(const f32x4*)(ssq + (size_t)row * 32 + fq * 8 + 4);
;   float sm = ((a[0] + a[1]) + (a[2] + a[3])) + ((b[0] + b[1]) + (b[2] + b[3]));
;   sm += __shfl_xor(sm, 16); sm += __shfl_xor(sm, 32);
;   return rsqrtf(sm * (1.0f / 2048.f) + 1e-6f);
; }
;   DI void operator()(const f32x4 (&acc)[2][2][4][2], const Unit& u, int wr, int wc, int fr, int fq) const {
;     ...
;       for (int m = 0; m < 4; ++m) rsv[m] = row_rstd(ssq, row0 + 16 * m + fr, fq);
;       float p1[8], p2[8];
; #pragma unroll
;       for (int e = 0; e < 8; ++e) { p1[e] = 0.f; p2[e] = 0.f; }
; #pragma unroll
;       for (int m = 0; m < 4; ++m) {
;         float g[8], a[8];
;         const float rs1 = rsv[m], rs2 = rs1 * rs1;
; #pragma unroll
;         for (int e = 0; e < 4; ++e) { g[e] = acc[ai][0][m][0][e] * acc[ai][1][m][0][e] * rs2; g[4 + e] = acc[ai][0][m][1][e] * acc[ai][1][m][1][e] * rs2; }
; #pragma unroll
;         for (int e = 0; e < 8; ++e) {
;           const float x1 = dpp_ror1(g[e]), x2 = dpp_ror2(g[e]);
;           const float pr1 = (fr == 0) ? p1[e] : x1, pr2 = (fr < 2) ? p2[e] : x2;
;           a[e] = w2[e] * g[e] + w1[e] * pr1 + w0[e] * pr2;
;           p1[e] = x1; p2[e] = x2;
;         }
;         if (m == 0 && fr < 2) {
;           float* hc = headC + (size_t)(span * 2 + fr) * 2048 + col;
;           *(f32x4*)hc = (f32x4){a[0], a[1], a[2], a[3]}; *(f32x4*)(hc + 4) = (f32x4){a[4], a[5], a[6], a[7]};
;         } else {
;           u32x4 w; w.x = pack2(a[0] * rs1, a[1] * rs1); w.y = pack2(a[2] * rs1, a[3] * rs1); w.z = pack2(a[4] * rs1, a[5] * rs1); w.w = pack2(a[6] * rs1, a[7] * rs1);
;           *(u32x4*)(C + (size_t)(row0 + 16 * m + fr) * 2048 + col) = w;
	v_pk_add_f32 v[152:153], v[152:153], v[154:155]
	ds_bpermute_b32 v155, v207, v153
	ds_bpermute_b32 v154, v207, v152
	v_mov_b32_e32 v218, v215
	v_mov_b32_e32 v208, v220
	v_mov_b32_e32 v209, v224
	v_mov_b32_e32 v224, v221
	v_mov_b32_e32 v212, v222
	v_mov_b32_e32 v213, v226
	v_mov_b32_e32 v226, v223
	v_pk_add_f32 v[156:157], v[188:189], v[216:217]
	v_pk_add_f32 v[158:159], v[190:191], v[218:219]
	v_pk_add_f32 v[188:189], v[208:209], v[224:225]
	v_pk_add_f32 v[190:191], v[212:213], v[226:227]
	s_waitcnt lgkmcnt(0)
	v_pk_add_f32 v[152:153], v[152:153], v[154:155]
	v_pk_add_f32 v[156:157], v[156:157], v[158:159]
	v_pk_add_f32 v[158:159], v[188:189], v[190:191]
	v_pk_fma_f32 v[188:189], v[152:153], s[30:31], v[176:177] op_sel_hi:[1,0,0]
	v_mov_b32_e32 v153, v156
	v_mul_f32_e32 v152, 0x4b800000, v189
	v_cmp_gt_f32_e64 s[10:11], s84, v189
	v_mov_b32_e32 v156, v159
	v_mov_b32_e32 v194, v123
	v_cndmask_b32_e64 v152, v189, v152, s[10:11]
	v_rsq_f32_e32 v168, v152
	v_mov_b32_e32 v152, v158
	v_pk_add_f32 v[152:153], v[152:153], v[156:157]
	ds_bpermute_b32 v155, v196, v153
	ds_bpermute_b32 v154, v196, v152
	v_mul_f32_e32 v156, 0x45800000, v168
	v_cndmask_b32_e64 v195, v168, v156, s[10:11]
	v_mov_b32_e32 v217, 0
	v_mul_f32_e32 v156, v125, v113
	s_waitcnt lgkmcnt(0)
	v_pk_add_f32 v[190:191], v[152:153], v[154:155]
	v_mov_b32_e32 v152, v111
	v_mov_b32_e32 v153, v195
	v_mul_f32_e32 v154, v124, v112
	v_pk_mul_f32 v[152:153], v[194:195], v[152:153]
	v_mul_f32_e32 v155, v120, v108
	v_mul_f32_e32 v154, v154, v153
	v_pk_mul_f32 v[222:223], v[152:153], v[152:153] op_sel:[0,1] op_sel_hi:[1,0]
	v_mov_b32_e32 v213, 0
	v_mov_b32_dpp v217, v154 row_ror:1 row_mask:0xf bank_mask:0xf
	v_cndmask_b32_e64 v152, v217, 0, s[0:1]
	v_mul_f32_e32 v157, v121, v109
	v_mul_f32_e32 v158, v126, v114
	v_mul_f32_e32 v159, v122, v110
	v_mul_f32_e32 v168, v127, v115
	v_mul_f32_e32 v194, v155, v153
	v_mul_f32_e32 v155, v156, v153
	v_mov_b32_dpp v213, v154 row_ror:2 row_mask:0xf bank_mask:0xf
	v_mov_b32_e32 v221, 0
	v_mul_f32_e32 v152, v144, v152
	v_mul_f32_e32 v208, v157, v153
	v_mul_f32_e32 v156, v158, v153
	v_mul_f32_e32 v159, v159, v153
	v_mul_f32_e32 v157, v168, v153
	v_mov_b32_dpp v221, v155 row_ror:1 row_mask:0xf bank_mask:0xf
	v_cndmask_b32_e64 v153, v213, 0, s[8:9]
	v_fmac_f32_e32 v152, v148, v154
	v_mov_b32_e32 v219, 0
	v_fmac_f32_e32 v152, v140, v153
	v_cndmask_b32_e64 v153, v221, 0, s[0:1]
	v_mov_b32_dpp v219, v155 row_ror:2 row_mask:0xf bank_mask:0xf
	v_mul_f32_e32 v153, v145, v153
	v_mov_b32_e32 v216, 0
	v_cndmask_b32_e64 v154, v219, 0, s[8:9]
	v_fmac_f32_e32 v153, v149, v155
	v_mov_b32_dpp v216, v156 row_ror:1 row_mask:0xf bank_mask:0xf
	v_fmac_f32_e32 v153, v141, v154
	v_mov_b32_e32 v212, 0
	v_cndmask_b32_e64 v154, v216, 0, s[0:1]
	v_mov_b32_e32 v220, 0
	v_mov_b32_dpp v212, v156 row_ror:2 row_mask:0xf bank_mask:0xf
	v_mul_f32_e32 v154, v146, v154
	v_mov_b32_dpp v220, v157 row_ror:1 row_mask:0xf bank_mask:0xf
	v_cndmask_b32_e64 v155, v212, 0, s[8:9]
	v_fmac_f32_e32 v154, v150, v156
	v_mov_b32_e32 v218, 0
	v_fmac_f32_e32 v154, v142, v155
	v_cndmask_b32_e64 v155, v220, 0, s[0:1]
	v_mov_b32_dpp v218, v157 row_ror:2 row_mask:0xf bank_mask:0xf
	v_mul_f32_e32 v155, v147, v155
	v_cndmask_b32_e64 v156, v218, 0, s[8:9]
	v_fmac_f32_e32 v155, v151, v157
	v_mov_b32_dpp v197, v194 row_ror:1 row_mask:0xf bank_mask:0xf
	v_fmac_f32_e32 v155, v143, v156
	v_mov_b32_e32 v189, 0
	v_cndmask_b32_e64 v156, v197, 0, s[0:1]
	v_mov_b32_e32 v214, 0
	v_mov_b32_dpp v189, v194 row_ror:2 row_mask:0xf bank_mask:0xf
	v_mul_f32_e32 v156, v132, v156
	v_mov_b32_dpp v214, v208 row_ror:1 row_mask:0xf bank_mask:0xf
	v_cndmask_b32_e64 v157, v189, 0, s[8:9]
	v_fmac_f32_e32 v156, v136, v194
	v_fmac_f32_e32 v156, v128, v157
	v_cndmask_b32_e64 v157, v214, 0, s[0:1]
	v_mov_b32_e32 v209, 0
	v_mul_f32_e32 v157, v133, v157
	v_fmac_f32_e32 v157, v137, v208
	v_mov_b32_dpp v209, v208 row_ror:2 row_mask:0xf bank_mask:0xf
	v_mov_b32_e32 v208, 0
	v_cndmask_b32_e64 v158, v209, 0, s[8:9]
	v_fmac_f32_e32 v157, v129, v158
	v_mov_b32_dpp v208, v159 row_ror:1 row_mask:0xf bank_mask:0xf
	v_mov_b32_e32 v194, 0
	v_cndmask_b32_e64 v158, v208, 0, s[0:1]
	ds_bpermute_b32 v193, v207, v191
	ds_bpermute_b32 v192, v207, v190
	v_mov_b32_dpp v194, v159 row_ror:2 row_mask:0xf bank_mask:0xf
	v_mov_b32_e32 v215, 0
	v_mul_f32_e32 v158, v134, v158
	v_cndmask_b32_e64 v168, v194, 0, s[8:9]
	v_mov_b32_dpp v215, v222 row_ror:1 row_mask:0xf bank_mask:0xf
	v_fmac_f32_e32 v158, v138, v159
	v_mov_b32_dpp v211, v222 row_ror:2 row_mask:0xf bank_mask:0xf
	v_fmac_f32_e32 v158, v130, v168
	v_cndmask_b32_e64 v168, v215, 0, s[0:1]
	v_mul_f32_e32 v159, v139, v222
	v_cndmask_b32_e64 v223, v211, 0, s[8:9]
	v_fmac_f32_e32 v159, v135, v168
	v_cmp_gt_f32_e32 vcc, s84, v188
	v_fmac_f32_e32 v159, v131, v223
	s_and_saveexec_b64 s[10:11], s[4:5]
	s_xor_b64 s[10:11], exec, s[10:11]
	s_cbranch_execz .LBB0_1056
	v_mul_f32_e32 v152, v195, v152
	v_mul_f32_e32 v153, v195, v153
	v_cvt_pk_bf16_f32 v152, v152, v153
	v_mul_f32_e32 v153, v195, v154
	v_mul_f32_e32 v154, v195, v155
	v_cvt_pk_bf16_f32 v153, v153, v154
	v_mul_f32_e32 v154, v195, v156
	v_mul_f32_e32 v155, v195, v157
	v_cvt_pk_bf16_f32 v154, v154, v155
	v_mul_f32_e32 v155, v195, v158
	v_mul_f32_e32 v156, v195, v159
	v_cvt_pk_bf16_f32 v155, v155, v156
	v_lshlrev_b64 v[156:157], 12, v[186:187]
	v_lshl_add_u64 v[156:157], s[18:19], 0, v[156:157]
	v_lshl_add_u64 v[156:157], v[178:179], 1, v[156:157]
	global_store_dwordx4 v[156:157], v[152:155], off

; #define PG8_WAIT_V(n) asm volatile("s_waitcnt vmcnt(" #n ")" ::: "memory")
; #define PG8_BAR __builtin_amdgcn_s_barrier()
;   DI bool next(int i, Unit& u) const {
;     const long L = (long)i * G + c; if (L >= nwg) return false;
;     int wgid = (int)L; { const int q = nwg / NXCD, r = nwg % NXCD, xcd = wgid % NXCD, off = wgid / NXCD; wgid = (xcd < r ? xcd * (q + 1) : r * (q + 1) + (xcd - r) * q) + off; }
;     const int nig = WGM * nN, gid = wgid / nig, fm = gid * WGM, gsz = (nM - fm) < WGM ? (nM - fm) : WGM;
;     u.pm = fm + ((wgid % nig) % gsz); u.pn = (wgid % nig) / gsz; return true;
; template <class Epi, class Sched = StaticOrder>
; DI void gemm_phase(LAS unsigned char* lds, const Gemm g, const Sched& S, const Epi& E) {
;   const int tid = threadIdx.x, wid = __builtin_amdgcn_readfirstlane(tid >> 6), lane = tid & 63, wr = wid >> 2, wc = wid & 3, fr = lane & 15, fq = lane >> 4;
;   const int K = g.K, nt = K / BK;
;   unsigned voffA[2], voffB[2];
; #pragma unroll
;   for (int i = 0; i < 2; ++i) { int R, C; stage_rc(tid * 16 + i * 8192, R, C); const int Rb = Epi::PERM ? ((R & ~31) + perm32(R & 31)) : R;
;     voffA[i] = (unsigned)(R * K + C) * 2u; voffB[i] = (unsigned)(Rb * K + C) * 2u; }
;   const size_t kstep = (size_t)(BK * 2);
;   const size_t hstep = (size_t)HALF * K * 2;
;   const size_t tstep = 2 * hstep;
;   const unsigned ldsw = (unsigned)wid * 1024u;
;   const int aoff = lds_byte(wr * 64 + fr, fq * 8), boff = lds_byte(wc * 32 + fr, fq * 8);
;     ...
;   Unit cur, nxt; int ui = 0;
;   if (!S.next(0, cur)) return;
;   f32x4 acc[2][2][4][2];
; #pragma unroll
;   for (int a = 0; a < 2; ++a)
; #pragma unroll
;     for (int b = 0; b < 2; ++b)
; #pragma unroll
;       for (int m = 0; m < 4; ++m)
; #pragma unroll
;         for (int n = 0; n < 2; ++n) acc[a][b][m][n] = (f32x4){0.f, 0.f, 0.f, 0.f};
;   bf16x8 At[4][2], B0[2][2], B1[2][2];
;   const char* cA = (const char*)g.A + (size_t)cur.pm * tstep; const char* cB = (const char*)g.Bt + (size_t)cur.pn * tstep;
;   PG8_STAGE(PG8_SB(0, 0), cB, voffB); PG8_STAGE(PG8_SA(0, 0), cA, voffA); PG8_STAGE(PG8_SB(0, 1), cB + hstep, voffB); PG8_STAGE(PG8_SA(0, 1), cA + hstep, voffA);
;   if (wr == 1) PG8_BAR;
;   PG8_WAIT_V(4); PG8_BAR;
;   PG8_STAGE(PG8_SB(1, 0), cB + kstep, voffB); PG8_STAGE(PG8_SA(1, 0), cA + kstep, voffA); PG8_STAGE(PG8_SB(1, 1), cB + hstep + kstep, voffB);
;   PG8_WAIT_V(6); PG8_BAR;
.LBB0_1186:
	v_writelane_b32 v247, 1, 0
	s_add_i32 s0, 0, 0x20008
	v_mov_b32_e32 v0, s0
	ds_read_b32 v0, v0
	v_readfirstlane_b32 s29, v210
	s_waitcnt lgkmcnt(0)
	v_readfirstlane_b32 s28, v0
	s_cmpk_gt_i32 s28, 0x1ff
	s_cbranch_scc1 .LBB0_1214
	v_lshrrev_b32_e32 v0, 5, v210
	v_lshrrev_b32_e32 v2, 1, v210
	v_and_b32_e32 v0, 4, v0
	v_bfe_u32 v1, v210, 2, 2
	v_and_b32_e32 v2, 24, v2
	v_or3_b32 v0, v0, v1, v2
	v_lshlrev_b32_e32 v1, 4, v210
	v_add_u32_e32 v8, 0x2000, v1
	v_lshrrev_b32_e32 v2, 7, v8
	s_movk_i32 s0, 0xe0
	v_and_b32_e32 v4, 32, v210
	s_add_u32 s30, s84, 0x18903600
	v_and_or_b32 v3, v2, s0, v0
	v_bitop3_b32 v9, v1, v4, 48 bitop3:0x6c
	v_and_b32_e32 v10, 64, v210
	v_bfe_u32 v11, v210, 2, 4
	s_movk_i32 s0, 0xf0
	s_addc_u32 s31, s85, 0
	v_or_b32_e32 v1, v9, v10
	v_and_or_b32 v2, v2, s0, v11
	s_add_u32 s33, s84, 0xb703600
	v_lshl_or_b32 v178, v2, 12, v1
	v_lshrrev_b32_e32 v2, 3, v210
	s_movk_i32 s0, 0x60
	s_addc_u32 s34, s85, 0
	v_and_or_b32 v0, v2, s0, v0
	s_movk_i32 s0, 0x70
	s_ashr_i32 s36, s28, 31
	v_lshl_or_b32 v180, v0, 12, v1
	v_and_or_b32 v0, v2, s0, v11
	s_lshr_b32 s0, s36, 29
	s_add_i32 s0, s28, s0
	s_ashr_i32 s2, s0, 3
	s_and_b32 s0, s0, -8
	s_sub_i32 s0, s28, s0
	s_lshr_b32 s3, s0, 31
	s_or_b32 s3, s3, 64
	s_mul_i32 s0, s3, s0
	s_add_i32 s0, s0, s2
	s_ashr_i32 s2, s0, 31
	s_lshr_b32 s2, s2, 26
	s_add_i32 s2, s0, s2
	s_ashr_i32 s3, s2, 6
	s_lshl_b32 s5, s3, 3
	s_sub_i32 s3, 64, s5
	s_min_u32 s8, s3, 8
	s_andn2_b32 s2, s2, 63
	v_lshl_or_b32 v176, v3, 12, v1
	s_sub_i32 s9, s0, s2
	v_cvt_f32_ubyte0_e32 v3, s8
	v_cvt_f32_i32_e32 v2, s9
	v_rcp_iflag_f32_e32 v4, v3
	v_lshl_or_b32 v182, v0, 12, v1
	s_lshr_b32 s4, s29, 6
	s_ashr_i32 s0, s9, 30
	v_mul_f32_e32 v0, v2, v4
	v_trunc_f32_e32 v0, v0
	v_fma_f32 v1, -v0, v3, v2
	v_cvt_i32_f32_e32 v0, v0
	s_lshr_b32 s1, s29, 8
	s_lshl_b32 s35, s4, 10
	s_or_b32 s0, s0, 1
	v_cmp_ge_f32_e64 s[2:3], |v1|, v3
	s_and_b64 s[2:3], s[2:3], exec
	s_cselect_b32 s0, s0, 0
	v_readfirstlane_b32 s2, v0
	s_add_i32 s0, s2, s0
	s_mul_i32 s2, s0, s8
	s_sub_i32 s2, s9, s2
	s_sext_i32_i8 s2, s2
	s_add_i32 s12, s5, s2
	s_ashr_i32 s13, s12, 31
	s_bfe_i64 s[8:9], s[0:1], 0x80000
	s_lshl_b64 s[2:3], s[12:13], 20
	s_lshl_b64 s[8:9], s[8:9], 20
	s_add_u32 s24, s33, s8
	s_addc_u32 s25, s34, s9
	s_add_i32 s37, s35, 0
	s_add_i32 m0, s37, 0x10000
	v_mov_b32_e32 v181, 0
	global_load_lds_dwordx4 v180, s[24:25]
	s_add_i32 m0, s37, 0x12000
	s_add_u32 s22, s30, s2
	global_load_lds_dwordx4 v176, s[24:25]
	s_addc_u32 s23, s31, s3
	s_mov_b32 m0, s37
	s_add_i32 s38, s37, 0x2000
	global_load_lds_dwordx4 v182, s[22:23]
	s_mov_b32 m0, s38
	s_add_u32 s2, s24, 0x80000
	global_load_lds_dwordx4 v178, s[22:23]
	s_addc_u32 s3, s25, 0
	s_add_i32 m0, s37, 0x14000
	v_mov_b32_e32 v177, v181
	global_load_lds_dwordx4 v180, s[2:3]
	s_add_i32 m0, s37, 0x16000
	v_mov_b32_e32 v183, v181
	global_load_lds_dwordx4 v176, s[2:3]
	s_add_u32 s2, s22, 0x80000
	s_addc_u32 s3, s23, 0
	s_add_i32 s39, s37, 0x4000
	s_mov_b32 m0, s39
	s_add_i32 s40, s37, 0x6000
	global_load_lds_dwordx4 v182, s[2:3]
	s_mov_b32 m0, s40
	v_mov_b32_e32 v179, v181
	global_load_lds_dwordx4 v178, s[2:3]
	v_lshl_add_u64 v[6:7], s[24:25], 0, v[180:181]
	v_lshl_add_u64 v[4:5], s[24:25], 0, v[176:177]
	v_lshl_add_u64 v[2:3], s[22:23], 0, v[182:183]
	s_cmp_lg_u32 s1, 1
	v_lshl_add_u64 v[0:1], s[22:23], 0, v[178:179]
	s_cbranch_scc1 .LBB0_1189
	s_barrier

; #define PG8_STAGE(bufoff, gbase, voff) do { _Pragma("unroll") for (int _i = 0; _i < 2; ++_i) \
;     __builtin_amdgcn_global_load_lds((const unsigned*)((const char*)(gbase) + (voff)[_i]), (LAS unsigned*)(lds + (bufoff) + ldsw + _i * 8192), 16, 0, 0); } while (0)
; #define PG8_LDA(dst, b, h) do { _Pragma("unroll") for (int m = 0; m < 4; ++m) _Pragma("unroll") for (int k = 0; k < 2; ++k) dst[m][k] = *(const LAS bf16x8*)(lds + PG8_SA(b, h) + aoff + m * 2048 + k * 1024); } while (0)
; #define PG8_LDB(dst, b, h) do { _Pragma("unroll") for (int n = 0; n < 2; ++n) _Pragma("unroll") for (int k = 0; k < 2; ++k) dst[n][k] = *(const LAS bf16x8*)(lds + PG8_SB(b, h) + boff + n * 2048 + k * 1024); } while (0)
; #define PG8_MMA(ai, bj, At, Bt) do { __builtin_amdgcn_s_setprio(1); _Pragma("unroll") for (int m = 0; m < 4; ++m) _Pragma("unroll") for (int n = 0; n < 2; ++n) _Pragma("unroll") for (int k = 0; k < 2; ++k) \
;     acc[ai][bj][m][n] = __builtin_amdgcn_mfma_f32_16x16x32_bf16(Bt[n][k], At[m][k], acc[ai][bj][m][n], 0, 0, 0); __builtin_amdgcn_s_setprio(0); } while (0)
; #define PG8_WAIT_V(n) asm volatile("s_waitcnt vmcnt(" #n ")" ::: "memory")
; #define PG8_WAIT_L(n) asm volatile("s_waitcnt lgkmcnt(" #n ")" ::: "memory")
; #define PG8_BAR __builtin_amdgcn_s_barrier()
; #define PG8_SCHED __builtin_amdgcn_sched_barrier(0)
; template <class Epi, class Sched = StaticOrder>
; DI void gemm_phase(LAS unsigned char* lds, const Gemm g, const Sched& S, const Epi& E) {
;     ...
;     for (int t = 0; t < nt; t += 2) {
;       const bool last = (t == nt - 2);
;       const char* a1 = cA + (size_t)(t + 1) * kstep;
;       const char* a2 = last ? nA : cA + (size_t)(t + 2) * kstep; const char* b2 = last ? nB : cB + (size_t)(t + 2) * kstep;
;       const char* a3 = a2 + kstep; const char* b3 = b2 + kstep;
;       PG8_LDB(B0, 0, 0); PG8_SCHED; PG8_LDA(At, 0, 0); PG8_STAGE(PG8_SA(1, 1), a1 + hstep, voffA);
;       PG8_WAIT_L(8); PG8_BAR; PG8_WAIT_L(0); PG8_MMA(0, 0, At, B0); PG8_BAR; PG8_SCHED;
;       PG8_LDB(B1, 0, 1); PG8_STAGE(PG8_SB(0, 0), b2, voffB);
;       PG8_BAR; PG8_WAIT_L(0); PG8_MMA(0, 1, At, B1); PG8_BAR;
;       PG8_LDA(At, 0, 1); PG8_STAGE(PG8_SA(0, 0), a2, voffA);
;       PG8_BAR; PG8_WAIT_L(0); PG8_MMA(1, 0, At, B0); PG8_BAR; PG8_SCHED;
;       PG8_STAGE(PG8_SB(0, 1), b2 + hstep, voffB);
;       PG8_WAIT_V(6); PG8_BAR; PG8_MMA(1, 1, At, B1); PG8_BAR;
.LBB0_1194:
	ds_read_b128 v[128:131], v214
	ds_read_b128 v[132:135], v214 offset:1024
	ds_read_b128 v[136:139], v214 offset:2048
	ds_read_b128 v[140:143], v214 offset:3072
	s_add_u32 s24, s22, 0xfff80080
	s_addc_u32 s25, s23, -1
	s_cmp_eq_u32 s54, 28
	s_cselect_b32 s27, s17, s25
	s_cselect_b32 s26, s43, s24
	s_cselect_b32 s25, s15, s53
	s_cselect_b32 s24, s51, s52
	s_add_i32 m0, s37, 0xc000
	ds_read_b128 v[144:147], v215
	ds_read_b128 v[148:151], v215 offset:1024
	ds_read_b128 v[152:155], v215 offset:2048
	ds_read_b128 v[156:159], v215 offset:3072
	ds_read_b128 v[160:163], v215 offset:4096
	ds_read_b128 v[164:167], v215 offset:5120
	ds_read_b128 v[168:171], v215 offset:6144
	ds_read_b128 v[172:175], v215 offset:7168
	global_load_lds_dwordx4 v184, s[22:23]
	s_add_i32 m0, s37, 0xe000
	s_nop 0
	global_load_lds_dwordx4 v186, s[22:23]
	s_waitcnt lgkmcnt(0)
	s_setprio 1
	s_barrier
	v_mfma_f32_16x16x32_bf16 v[124:127], v[128:131], v[144:147], v[124:127]
	v_mfma_f32_16x16x32_bf16 v[120:123], v[136:139], v[144:147], v[120:123]
	v_mfma_f32_16x16x32_bf16 v[108:111], v[128:131], v[152:155], v[108:111]
	v_mfma_f32_16x16x32_bf16 v[104:107], v[136:139], v[152:155], v[104:107]
	v_mfma_f32_16x16x32_bf16 v[92:95], v[128:131], v[160:163], v[92:95]
	v_mfma_f32_16x16x32_bf16 v[88:91], v[136:139], v[160:163], v[88:91]
	v_mfma_f32_16x16x32_bf16 v[76:79], v[128:131], v[168:171], v[76:79]
	v_mfma_f32_16x16x32_bf16 v[72:75], v[136:139], v[168:171], v[72:75]
	v_mfma_f32_16x16x32_bf16 v[124:127], v[132:135], v[148:151], v[124:127]
	v_mfma_f32_16x16x32_bf16 v[120:123], v[140:143], v[148:151], v[120:123]
	v_mfma_f32_16x16x32_bf16 v[108:111], v[132:135], v[156:159], v[108:111]
	v_mfma_f32_16x16x32_bf16 v[104:107], v[140:143], v[156:159], v[104:107]
	v_mfma_f32_16x16x32_bf16 v[92:95], v[132:135], v[164:167], v[92:95]
	v_mfma_f32_16x16x32_bf16 v[88:91], v[140:143], v[164:167], v[88:91]
	v_mfma_f32_16x16x32_bf16 v[76:79], v[132:135], v[172:175], v[76:79]
	v_mfma_f32_16x16x32_bf16 v[72:75], v[140:143], v[172:175], v[72:75]
	s_barrier
	s_setprio 0
	s_add_i32 s55, s48, s35
	s_add_u32 s98, s24, 0x80
	s_addc_u32 s99, s25, 0
	s_add_u32 s100, s26, 0x80
	s_addc_u32 s101, s27, 0
	s_mov_b32 m0, s55
	ds_read_b128 v[192:195], v216
	ds_read_b128 v[196:199], v216 offset:1024
	ds_read_b128 v[200:203], v216 offset:2048
	ds_read_b128 v[204:207], v216 offset:3072
	global_load_lds_dwordx4 v180, s[24:25]
	s_add_i32 m0, s55, 0x2000
	s_nop 0
	global_load_lds_dwordx4 v176, s[24:25]
	s_waitcnt lgkmcnt(0)
	s_setprio 1
	s_barrier
	v_mfma_f32_16x16x32_bf16 v[116:119], v[192:195], v[144:147], v[116:119]
	v_mfma_f32_16x16x32_bf16 v[112:115], v[200:203], v[144:147], v[112:115]
	v_mfma_f32_16x16x32_bf16 v[100:103], v[192:195], v[152:155], v[100:103]
	v_mfma_f32_16x16x32_bf16 v[96:99], v[200:203], v[152:155], v[96:99]
	v_mfma_f32_16x16x32_bf16 v[84:87], v[192:195], v[160:163], v[84:87]
	v_mfma_f32_16x16x32_bf16 v[80:83], v[200:203], v[160:163], v[80:83]
	v_mfma_f32_16x16x32_bf16 v[68:71], v[192:195], v[168:171], v[68:71]
	v_mfma_f32_16x16x32_bf16 v[64:67], v[200:203], v[168:171], v[64:67]
	v_mfma_f32_16x16x32_bf16 v[116:119], v[196:199], v[148:151], v[116:119]
	v_mfma_f32_16x16x32_bf16 v[112:115], v[204:207], v[148:151], v[112:115]
	v_mfma_f32_16x16x32_bf16 v[100:103], v[196:199], v[156:159], v[100:103]
	v_mfma_f32_16x16x32_bf16 v[96:99], v[204:207], v[156:159], v[96:99]
	v_mfma_f32_16x16x32_bf16 v[84:87], v[196:199], v[164:167], v[84:87]
	v_mfma_f32_16x16x32_bf16 v[80:83], v[204:207], v[164:167], v[80:83]
	v_mfma_f32_16x16x32_bf16 v[68:71], v[196:199], v[172:175], v[68:71]
	v_mfma_f32_16x16x32_bf16 v[64:67], v[204:207], v[172:175], v[64:67]
	s_barrier
	s_setprio 0
	s_mov_b32 m0, s37
	ds_read_b128 v[144:147], v215 offset:16384
	ds_read_b128 v[148:151], v215 offset:17408
	ds_read_b128 v[152:155], v215 offset:18432
	ds_read_b128 v[156:159], v215 offset:19456
	ds_read_b128 v[160:163], v215 offset:20480
	ds_read_b128 v[164:167], v215 offset:21504
	ds_read_b128 v[168:171], v215 offset:22528
	ds_read_b128 v[172:175], v215 offset:23552
	global_load_lds_dwordx4 v182, s[26:27]
	s_mov_b32 m0, s38
	s_nop 0
	global_load_lds_dwordx4 v178, s[26:27]
	s_waitcnt lgkmcnt(0)
	s_setprio 1
	s_barrier
	v_mfma_f32_16x16x32_bf16 v[60:63], v[128:131], v[144:147], v[60:63]
	v_mfma_f32_16x16x32_bf16 v[56:59], v[136:139], v[144:147], v[56:59]
	v_mfma_f32_16x16x32_bf16 v[44:47], v[128:131], v[152:155], v[44:47]
	v_mfma_f32_16x16x32_bf16 v[40:43], v[136:139], v[152:155], v[40:43]
	v_mfma_f32_16x16x32_bf16 v[28:31], v[128:131], v[160:163], v[28:31]
	v_mfma_f32_16x16x32_bf16 v[24:27], v[136:139], v[160:163], v[24:27]
	v_mfma_f32_16x16x32_bf16 v[12:15], v[128:131], v[168:171], v[12:15]
	v_mfma_f32_16x16x32_bf16 v[8:11], v[136:139], v[168:171], v[8:11]
	v_mfma_f32_16x16x32_bf16 v[60:63], v[132:135], v[148:151], v[60:63]
	v_mfma_f32_16x16x32_bf16 v[56:59], v[140:143], v[148:151], v[56:59]
	v_mfma_f32_16x16x32_bf16 v[44:47], v[132:135], v[156:159], v[44:47]
	v_mfma_f32_16x16x32_bf16 v[40:43], v[140:143], v[156:159], v[40:43]
	v_mfma_f32_16x16x32_bf16 v[28:31], v[132:135], v[164:167], v[28:31]
	v_mfma_f32_16x16x32_bf16 v[24:27], v[140:143], v[164:167], v[24:27]
	v_mfma_f32_16x16x32_bf16 v[12:15], v[132:135], v[172:175], v[12:15]
	v_mfma_f32_16x16x32_bf16 v[8:11], v[140:143], v[172:175], v[8:11]
	s_barrier
	s_setprio 0
	s_add_u32 s56, s24, 0x80000
	s_addc_u32 s57, s25, 0
	s_add_i32 s55, s49, s35
	s_mov_b32 m0, s55
	s_nop 0
	global_load_lds_dwordx4 v180, s[56:57]
	s_add_i32 m0, s55, 0x2000
	s_nop 0
	global_load_lds_dwordx4 v176, s[56:57]
	v_readlane_b32 vcc_lo, v247, 0
	s_cmp_eq_u32 s54, vcc_lo
	s_cbranch_scc1 .Lsw_5
	s_waitcnt vmcnt(6)
; #define PG8_STAGE(bufoff, gbase, voff) do { _Pragma("unroll") for (int _i = 0; _i < 2; ++_i) \
;     __builtin_amdgcn_global_load_lds((const unsigned*)((const char*)(gbase) + (voff)[_i]), (LAS unsigned*)(lds + (bufoff) + ldsw + _i * 8192), 16, 0, 0); } while (0)
; #define PG8_LDA(dst, b, h) do { _Pragma("unroll") for (int m = 0; m < 4; ++m) _Pragma("unroll") for (int k = 0; k < 2; ++k) dst[m][k] = *(const LAS bf16x8*)(lds + PG8_SA(b, h) + aoff + m * 2048 + k * 1024); } while (0)
; #define PG8_LDB(dst, b, h) do { _Pragma("unroll") for (int n = 0; n < 2; ++n) _Pragma("unroll") for (int k = 0; k < 2; ++k) dst[n][k] = *(const LAS bf16x8*)(lds + PG8_SB(b, h) + boff + n * 2048 + k * 1024); } while (0)
; #define PG8_MMA(ai, bj, At, Bt) do { __builtin_amdgcn_s_setprio(1); _Pragma("unroll") for (int m = 0; m < 4; ++m) _Pragma("unroll") for (int n = 0; n < 2; ++n) _Pragma("unroll") for (int k = 0; k < 2; ++k) \
;     acc[ai][bj][m][n] = __builtin_amdgcn_mfma_f32_16x16x32_bf16(Bt[n][k], At[m][k], acc[ai][bj][m][n], 0, 0, 0); __builtin_amdgcn_s_setprio(0); } while (0)
; #define PG8_WAIT_V(n) asm volatile("s_waitcnt vmcnt(" #n ")" ::: "memory")
; #define PG8_WAIT_L(n) asm volatile("s_waitcnt lgkmcnt(" #n ")" ::: "memory")
; #define PG8_BAR __builtin_amdgcn_s_barrier()
; #define PG8_SCHED __builtin_amdgcn_sched_barrier(0)
; template <class Epi, class Sched = StaticOrder>
; DI void gemm_phase(LAS unsigned char* lds, const Gemm g, const Sched& S, const Epi& E) {
;     ...
;       PG8_WAIT_V(6); PG8_BAR; PG8_MMA(1, 1, At, B1); PG8_BAR;
;       PG8_LDB(B0, 1, 0); PG8_SCHED; PG8_LDA(At, 1, 0); PG8_STAGE(PG8_SA(0, 1), a2 + hstep, voffA);
;       PG8_WAIT_L(8); PG8_BAR; PG8_WAIT_L(0); PG8_MMA(0, 0, At, B0); PG8_BAR; PG8_SCHED;
;       PG8_LDB(B1, 1, 1); PG8_STAGE(PG8_SB(1, 0), b3, voffB);
;       PG8_BAR; PG8_WAIT_L(0); PG8_MMA(0, 1, At, B1); PG8_BAR;
;       PG8_LDA(At, 1, 1); PG8_STAGE(PG8_SA(1, 0), a3, voffA);
;       PG8_BAR; PG8_WAIT_L(0); PG8_MMA(1, 0, At, B0); PG8_BAR; PG8_SCHED;
;       PG8_STAGE(PG8_SB(1, 1), b3 + hstep, voffB);
;       PG8_WAIT_V(6); PG8_BAR; PG8_MMA(1, 1, At, B1); PG8_BAR;
.Lsw_5:
	s_setprio 1
	s_barrier
	v_mfma_f32_16x16x32_bf16 v[52:55], v[192:195], v[144:147], v[52:55]
	v_mfma_f32_16x16x32_bf16 v[48:51], v[200:203], v[144:147], v[48:51]
	v_mfma_f32_16x16x32_bf16 v[36:39], v[192:195], v[152:155], v[36:39]
	v_mfma_f32_16x16x32_bf16 v[32:35], v[200:203], v[152:155], v[32:35]
	v_mfma_f32_16x16x32_bf16 v[20:23], v[192:195], v[160:163], v[20:23]
	v_mfma_f32_16x16x32_bf16 v[16:19], v[200:203], v[160:163], v[16:19]
	v_mfma_f32_16x16x32_bf16 v[4:7], v[192:195], v[168:171], v[4:7]
	v_mfma_f32_16x16x32_bf16 v[0:3], v[200:203], v[168:171], v[0:3]
	v_mfma_f32_16x16x32_bf16 v[52:55], v[196:199], v[148:151], v[52:55]
	v_mfma_f32_16x16x32_bf16 v[48:51], v[204:207], v[148:151], v[48:51]
	v_mfma_f32_16x16x32_bf16 v[36:39], v[196:199], v[156:159], v[36:39]
	v_mfma_f32_16x16x32_bf16 v[32:35], v[204:207], v[156:159], v[32:35]
	v_mfma_f32_16x16x32_bf16 v[20:23], v[196:199], v[164:167], v[20:23]
	v_mfma_f32_16x16x32_bf16 v[16:19], v[204:207], v[164:167], v[16:19]
	v_mfma_f32_16x16x32_bf16 v[4:7], v[196:199], v[172:175], v[4:7]
	v_mfma_f32_16x16x32_bf16 v[0:3], v[204:207], v[172:175], v[0:3]
	s_barrier
	s_setprio 0
	s_add_i32 s55, 0, 0x18000
	v_add_u32_e32 v140, s55, v212
	ds_read_b128 v[128:131], v140
	ds_read_b128 v[132:135], v140 offset:1024
	ds_read_b128 v[136:139], v140 offset:2048
	ds_read_b128 v[140:143], v140 offset:3072
	s_add_u32 s26, s26, 0x80000
	s_addc_u32 s27, s27, 0
	s_mov_b32 m0, s39
	ds_read_b128 v[144:147], v215 offset:32768
	ds_read_b128 v[148:151], v215 offset:33792
	ds_read_b128 v[152:155], v215 offset:34816
	ds_read_b128 v[156:159], v215 offset:35840
	ds_read_b128 v[160:163], v215 offset:36864
	ds_read_b128 v[164:167], v215 offset:37888
	ds_read_b128 v[168:171], v215 offset:38912
	ds_read_b128 v[172:175], v215 offset:39936
	global_load_lds_dwordx4 v182, s[26:27]
	s_mov_b32 m0, s40
	s_nop 0
	global_load_lds_dwordx4 v178, s[26:27]
	s_waitcnt lgkmcnt(0)
	s_setprio 1
	s_barrier
	v_mfma_f32_16x16x32_bf16 v[124:127], v[128:131], v[144:147], v[124:127]
	v_mfma_f32_16x16x32_bf16 v[120:123], v[136:139], v[144:147], v[120:123]
	v_mfma_f32_16x16x32_bf16 v[108:111], v[128:131], v[152:155], v[108:111]
	v_mfma_f32_16x16x32_bf16 v[104:107], v[136:139], v[152:155], v[104:107]
	v_mfma_f32_16x16x32_bf16 v[92:95], v[128:131], v[160:163], v[92:95]
	v_mfma_f32_16x16x32_bf16 v[88:91], v[136:139], v[160:163], v[88:91]
	v_mfma_f32_16x16x32_bf16 v[76:79], v[128:131], v[168:171], v[76:79]
	v_mfma_f32_16x16x32_bf16 v[72:75], v[136:139], v[168:171], v[72:75]
	v_mfma_f32_16x16x32_bf16 v[124:127], v[132:135], v[148:151], v[124:127]
	v_mfma_f32_16x16x32_bf16 v[120:123], v[140:143], v[148:151], v[120:123]
	v_mfma_f32_16x16x32_bf16 v[108:111], v[132:135], v[156:159], v[108:111]
	v_mfma_f32_16x16x32_bf16 v[104:107], v[140:143], v[156:159], v[104:107]
	v_mfma_f32_16x16x32_bf16 v[92:95], v[132:135], v[164:167], v[92:95]
	v_mfma_f32_16x16x32_bf16 v[88:91], v[140:143], v[164:167], v[88:91]
	v_mfma_f32_16x16x32_bf16 v[76:79], v[132:135], v[172:175], v[76:79]
	v_mfma_f32_16x16x32_bf16 v[72:75], v[140:143], v[172:175], v[72:75]
	s_barrier
	s_setprio 0
	s_add_i32 s26, 0, 0x1c000
	s_add_i32 s27, s55, s35
	v_add_u32_e32 v204, s26, v212
	s_mov_b32 m0, s27
	ds_read_b128 v[192:195], v204
	ds_read_b128 v[196:199], v204 offset:1024
	ds_read_b128 v[200:203], v204 offset:2048
	ds_read_b128 v[204:207], v204 offset:3072
	global_load_lds_dwordx4 v180, s[98:99]
	s_add_i32 m0, s27, 0x2000
	s_nop 0
	global_load_lds_dwordx4 v176, s[98:99]
	s_waitcnt lgkmcnt(0)
	s_setprio 1
	s_barrier
	v_mfma_f32_16x16x32_bf16 v[116:119], v[192:195], v[144:147], v[116:119]
	v_mfma_f32_16x16x32_bf16 v[112:115], v[200:203], v[144:147], v[112:115]
	v_mfma_f32_16x16x32_bf16 v[100:103], v[192:195], v[152:155], v[100:103]
	v_mfma_f32_16x16x32_bf16 v[96:99], v[200:203], v[152:155], v[96:99]
	v_mfma_f32_16x16x32_bf16 v[84:87], v[192:195], v[160:163], v[84:87]
	v_mfma_f32_16x16x32_bf16 v[80:83], v[200:203], v[160:163], v[80:83]
	v_mfma_f32_16x16x32_bf16 v[68:71], v[192:195], v[168:171], v[68:71]
	v_mfma_f32_16x16x32_bf16 v[64:67], v[200:203], v[168:171], v[64:67]
	v_mfma_f32_16x16x32_bf16 v[116:119], v[196:199], v[148:151], v[116:119]
	v_mfma_f32_16x16x32_bf16 v[112:115], v[204:207], v[148:151], v[112:115]
	v_mfma_f32_16x16x32_bf16 v[100:103], v[196:199], v[156:159], v[100:103]
	v_mfma_f32_16x16x32_bf16 v[96:99], v[204:207], v[156:159], v[96:99]
	v_mfma_f32_16x16x32_bf16 v[84:87], v[196:199], v[164:167], v[84:87]
	v_mfma_f32_16x16x32_bf16 v[80:83], v[204:207], v[164:167], v[80:83]
	v_mfma_f32_16x16x32_bf16 v[68:71], v[196:199], v[172:175], v[68:71]
	v_mfma_f32_16x16x32_bf16 v[64:67], v[204:207], v[172:175], v[64:67]
	s_barrier
	s_setprio 0
	s_mov_b32 m0, s44
	ds_read_b128 v[144:147], v215 offset:49152
	ds_read_b128 v[148:151], v215 offset:50176
	ds_read_b128 v[152:155], v215 offset:51200
	ds_read_b128 v[156:159], v215 offset:52224
	ds_read_b128 v[160:163], v215 offset:53248
	ds_read_b128 v[164:167], v215 offset:54272
	ds_read_b128 v[168:171], v215 offset:55296
	ds_read_b128 v[172:175], v215 offset:56320
	global_load_lds_dwordx4 v182, s[100:101]
	s_mov_b32 m0, s45
	s_nop 0
	global_load_lds_dwordx4 v178, s[100:101]
	s_waitcnt lgkmcnt(0)
	s_setprio 1
	s_barrier
	v_mfma_f32_16x16x32_bf16 v[60:63], v[128:131], v[144:147], v[60:63]
	v_mfma_f32_16x16x32_bf16 v[56:59], v[136:139], v[144:147], v[56:59]
	v_mfma_f32_16x16x32_bf16 v[44:47], v[128:131], v[152:155], v[44:47]
	v_mfma_f32_16x16x32_bf16 v[40:43], v[136:139], v[152:155], v[40:43]
	v_mfma_f32_16x16x32_bf16 v[28:31], v[128:131], v[160:163], v[28:31]
	v_mfma_f32_16x16x32_bf16 v[24:27], v[136:139], v[160:163], v[24:27]
	v_mfma_f32_16x16x32_bf16 v[12:15], v[128:131], v[168:171], v[12:15]
	v_mfma_f32_16x16x32_bf16 v[8:11], v[136:139], v[168:171], v[8:11]
	v_mfma_f32_16x16x32_bf16 v[60:63], v[132:135], v[148:151], v[60:63]
	v_mfma_f32_16x16x32_bf16 v[56:59], v[140:143], v[148:151], v[56:59]
	v_mfma_f32_16x16x32_bf16 v[44:47], v[132:135], v[156:159], v[44:47]
	v_mfma_f32_16x16x32_bf16 v[40:43], v[140:143], v[156:159], v[40:43]
	v_mfma_f32_16x16x32_bf16 v[28:31], v[132:135], v[164:167], v[28:31]
	v_mfma_f32_16x16x32_bf16 v[24:27], v[140:143], v[164:167], v[24:27]
	v_mfma_f32_16x16x32_bf16 v[12:15], v[132:135], v[172:175], v[12:15]
	v_mfma_f32_16x16x32_bf16 v[8:11], v[140:143], v[172:175], v[8:11]
	s_barrier
	s_setprio 0
	s_add_u32 s24, s24, 0x80080
	s_addc_u32 s25, s25, 0
	s_add_i32 s26, s26, s35
	s_mov_b32 m0, s26
	s_nop 0
	global_load_lds_dwordx4 v180, s[24:25]
	s_add_i32 m0, s26, 0x2000
	s_nop 0
	global_load_lds_dwordx4 v176, s[24:25]
	s_waitcnt vmcnt(6)
	s_cmp_eq_u32 s54, 28
	s_cbranch_scc0 .Lxs_5
	s_add_i32 m0, s37, 0xc000
	s_nop 0
	global_load_lds_dwordx4 v184, s[100:101]
	s_add_i32 m0, s37, 0xe000
	s_nop 0
	global_load_lds_dwordx4 v186, s[100:101]
; DI unsigned pack2(float lo, float hi) { f32x2 v = {lo, hi}; bf16v2 r = __builtin_convertvector(v, bf16v2); return __builtin_bit_cast(unsigned, r); }
; #define PG8_STAGE(bufoff, gbase, voff) do { _Pragma("unroll") for (int _i = 0; _i < 2; ++_i) \
;     __builtin_amdgcn_global_load_lds((const unsigned*)((const char*)(gbase) + (voff)[_i]), (LAS unsigned*)(lds + (bufoff) + ldsw + _i * 8192), 16, 0, 0); } while (0)
;   DI void operator()(const f32x4 (&acc)[2][2][4][2], const Unit& u, int wr, int wc, int fr, int fq) const {
;     const int row0 = u.pm * BM + wr * 64 + fr, col0 = u.pn * BM + wc * 32 + 8 * fq;
; #pragma unroll
;     for (int ai = 0; ai < 2; ++ai) {
;       f32x4 bv[4][2][2];
; #pragma unroll
;       for (int m = 0; m < 4; ++m)
; #pragma unroll
;         for (int bj = 0; bj < 2; ++bj) {
;           const float* bp = base + (size_t)(row0 + ai * HALF + m * 16) * 2048 + col0 + bj * HALF;
;           bv[m][bj][0] = *(const f32x4*)bp; bv[m][bj][1] = *(const f32x4*)(bp + 4);
;         }
; #pragma unroll
;       for (int m = 0; m < 4; ++m) {
;         const int row = row0 + ai * HALF + m * 16;
;         const size_t off = (size_t)row * 2048 + col0;
;         float ss = 0.f;
; #pragma unroll
;         for (int bj = 0; bj < 2; ++bj) {
;           const f32x4 v0 = acc[ai][bj][m][0] + bv[m][bj][0], v1 = acc[ai][bj][m][1] + bv[m][bj][1];
;           *(f32x4*)(C + off + bj * HALF) = v0; *(f32x4*)(C + off + bj * HALF + 4) = v1;
;           if (xb) {
;             u32x4 w; w.x = pack2(v0[0], v0[1]); w.y = pack2(v0[2], v0[3]); w.z = pack2(v1[0], v1[1]); w.w = pack2(v1[2], v1[3]);
;             *(u32x4*)(xb + off + bj * HALF) = w;
;             ss += v0[0] * v0[0] + v0[1] * v0[1] + v0[2] * v0[2] + v0[3] * v0[3] + v1[0] * v1[0] + v1[1] * v1[1] + v1[2] * v1[2] + v1[3] * v1[3];
;           }
;         }
;         if (xb) {
;           ss += __shfl_xor(ss, 16); ss += __shfl_xor(ss, 32);
;           if (fq == 0) ssq[(size_t)row * 32 + u.pn * 4 + wc] = ss;
;         }
; template <class Epi, class Sched = StaticOrder>
; DI void gemm_phase(LAS unsigned char* lds, const Gemm g, const Sched& S, const Epi& E) {
;     ...
;       PG8_BAR; PG8_WAIT_L(0); PG8_MMA(1, 0, At, B0); PG8_BAR; PG8_SCHED;
;       PG8_STAGE(PG8_SB(1, 1), b3 + hstep, voffB);
;       PG8_WAIT_V(6); PG8_BAR; PG8_MMA(1, 1, At, B1); PG8_BAR;
;     }
;     E(acc, cur, wr, wc, fr, fq);
;     if (!has_next) break;
.Lxs_5:
	s_add_i32 s54, s54, 2
	s_add_u32 s22, s22, 0x100
	s_addc_u32 s23, s23, 0
	s_add_u32 s52, s52, 0x100
	s_addc_u32 s53, s53, 0
	s_cmp_gt_u32 s54, 29
	s_setprio 1
	s_barrier
	v_mfma_f32_16x16x32_bf16 v[52:55], v[192:195], v[144:147], v[52:55]
	v_mfma_f32_16x16x32_bf16 v[48:51], v[200:203], v[144:147], v[48:51]
	v_mfma_f32_16x16x32_bf16 v[36:39], v[192:195], v[152:155], v[36:39]
	v_mfma_f32_16x16x32_bf16 v[32:35], v[200:203], v[152:155], v[32:35]
	v_mfma_f32_16x16x32_bf16 v[20:23], v[192:195], v[160:163], v[20:23]
	v_mfma_f32_16x16x32_bf16 v[16:19], v[200:203], v[160:163], v[16:19]
	v_mfma_f32_16x16x32_bf16 v[4:7], v[192:195], v[168:171], v[4:7]
	v_mfma_f32_16x16x32_bf16 v[0:3], v[200:203], v[168:171], v[0:3]
	v_mfma_f32_16x16x32_bf16 v[52:55], v[196:199], v[148:151], v[52:55]
	v_mfma_f32_16x16x32_bf16 v[48:51], v[204:207], v[148:151], v[48:51]
	v_mfma_f32_16x16x32_bf16 v[36:39], v[196:199], v[156:159], v[36:39]
	v_mfma_f32_16x16x32_bf16 v[32:35], v[204:207], v[156:159], v[32:35]
	v_mfma_f32_16x16x32_bf16 v[20:23], v[196:199], v[164:167], v[20:23]
	v_mfma_f32_16x16x32_bf16 v[16:19], v[204:207], v[164:167], v[16:19]
	v_mfma_f32_16x16x32_bf16 v[4:7], v[196:199], v[172:175], v[4:7]
	v_mfma_f32_16x16x32_bf16 v[0:3], v[204:207], v[172:175], v[0:3]
	s_barrier
	s_setprio 0
	s_cbranch_scc0 .LBB0_1194
	v_writelane_b32 v247, -2, 0
	v_lshl_add_u32 v194, s12, 8, v211
	v_lshl_or_b32 v192, s42, 8, v213
	v_readlane_b32 s52, v243, 3
	v_ashrrev_i32_e32 v193, 31, v192
	v_readlane_b32 s66, v243, 17
	v_readlane_b32 s67, v243, 18
	v_ashrrev_i32_e32 v195, 31, v194
	v_lshlrev_b64 v[128:129], 13, v[194:195]
	v_lshl_add_u64 v[196:197], v[192:193], 2, s[66:67]
	v_lshl_add_u64 v[236:237], v[196:197], 0, v[128:129]
	global_load_dwordx4 v[220:223], v[236:237], off
	global_load_dwordx4 v[224:227], v[236:237], off offset:16
	global_load_dwordx4 v[228:231], v[236:237], off offset:512
	global_load_dwordx4 v[232:235], v[236:237], off offset:528
	v_or_b32_e32 v206, 16, v194
	v_or_b32_e32 v202, 32, v194
	v_or_b32_e32 v198, 48, v194
	v_ashrrev_i32_e32 v207, 31, v206
	v_ashrrev_i32_e32 v203, 31, v202
	v_ashrrev_i32_e32 v199, 31, v198
	v_lshlrev_b64 v[128:129], 13, v[206:207]
	v_lshlrev_b64 v[130:131], 13, v[202:203]
	v_lshlrev_b64 v[132:133], 13, v[198:199]
	v_lshl_add_u64 v[208:209], v[196:197], 0, v[128:129]
	v_lshl_add_u64 v[204:205], v[196:197], 0, v[130:131]
	v_lshl_add_u64 v[200:201], v[196:197], 0, v[132:133]
	global_load_dwordx4 v[168:171], v[208:209], off offset:16
	global_load_dwordx4 v[172:175], v[208:209], off
	global_load_dwordx4 v[160:163], v[208:209], off offset:528
	global_load_dwordx4 v[164:167], v[208:209], off offset:512
	global_load_dwordx4 v[152:155], v[204:205], off offset:16
	global_load_dwordx4 v[156:159], v[204:205], off
	global_load_dwordx4 v[144:147], v[204:205], off offset:528
	global_load_dwordx4 v[148:151], v[204:205], off offset:512
	global_load_dwordx4 v[136:139], v[200:201], off offset:16
	global_load_dwordx4 v[140:143], v[200:201], off
	global_load_dwordx4 v[128:131], v[200:201], off offset:528
	global_load_dwordx4 v[132:135], v[200:201], off offset:512
	v_and_b32_e32 v218, 64, v217
	v_xor_b32_e32 v238, 16, v217
	v_add_u32_e32 v240, 64, v218
	v_xor_b32_e32 v239, 32, v217
	v_cmp_lt_i32_e32 vcc, v238, v240
	v_lshlrev_b64 v[218:219], 11, v[194:195]
	s_lshl_b32 s22, s42, 2
	v_cndmask_b32_e32 v241, v217, v238, vcc
	v_cmp_lt_i32_e32 vcc, v239, v240
	s_ashr_i32 s23, s22, 31
	v_readlane_b32 s53, v243, 4
	v_cndmask_b32_e32 v240, v217, v239, vcc
	v_lshl_add_u64 v[238:239], v[218:219], 0, v[192:193]
	v_lshlrev_b32_e32 v218, 2, v241
	v_lshl_add_u64 v[238:239], v[238:239], 1, s[2:3]
	v_readlane_b32 s54, v243, 5
	v_readlane_b32 s55, v243, 6
	v_readlane_b32 s56, v243, 7
	v_readlane_b32 s57, v243, 8
	v_readlane_b32 s58, v243, 9
	v_readlane_b32 s59, v243, 10
	v_readlane_b32 s60, v243, 11
	v_readlane_b32 s61, v243, 12
	v_readlane_b32 s62, v243, 13
	v_readlane_b32 s63, v243, 14
	v_readlane_b32 s64, v243, 15
	v_readlane_b32 s65, v243, 16
	s_waitcnt vmcnt(0)
	v_pk_add_f32 v[126:127], v[126:127], v[222:223]
	v_pk_add_f32 v[124:125], v[124:125], v[220:221]
	v_pk_add_f32 v[116:117], v[116:117], v[228:229]
	v_pk_add_f32 v[122:123], v[122:123], v[226:227]
	v_pk_add_f32 v[120:121], v[120:121], v[224:225]
	v_pk_add_f32 v[220:221], v[112:113], v[232:233]
	global_store_dwordx4 v[236:237], v[124:127], off
	global_store_dwordx4 v[236:237], v[120:123], off offset:16
	v_cvt_pk_bf16_f32 v112, v124, v125
	v_mul_f32_e32 v125, v125, v125
	v_mul_f32_e32 v219, v117, v117
	v_pk_add_f32 v[118:119], v[118:119], v[230:231]
	v_fmac_f32_e32 v125, v124, v124
	v_fmac_f32_e32 v219, v116, v116
	v_fmac_f32_e32 v125, v126, v126
	v_fmac_f32_e32 v219, v118, v118
	v_fmac_f32_e32 v125, v127, v127
	v_fmac_f32_e32 v219, v119, v119
	v_fmac_f32_e32 v125, v120, v120
	v_fmac_f32_e32 v219, v220, v220
	v_pk_add_f32 v[222:223], v[114:115], v[234:235]
	v_fmac_f32_e32 v125, v121, v121
	v_fmac_f32_e32 v219, v221, v221
	v_fmac_f32_e32 v125, v122, v122
	v_fmac_f32_e32 v219, v222, v222
	v_fmac_f32_e32 v125, v123, v123
	v_fmac_f32_e32 v219, v223, v223
	v_cvt_pk_bf16_f32 v114, v120, v121
	v_add_f32_e32 v121, v125, v219
	v_cvt_pk_bf16_f32 v115, v122, v123
	ds_bpermute_b32 v122, v218, v121
	v_cvt_pk_bf16_f32 v113, v126, v127
	global_store_dwordx4 v[238:239], v[112:115], off
	global_store_dwordx4 v[236:237], v[116:119], off offset:512
	global_store_dwordx4 v[236:237], v[220:223], off offset:528
	v_lshlrev_b32_e32 v126, 2, v240
	v_cvt_pk_bf16_f32 v120, v116, v117
	s_waitcnt lgkmcnt(0)
	v_add_f32_e32 v112, v121, v122
	ds_bpermute_b32 v113, v126, v112
	v_cvt_pk_bf16_f32 v121, v118, v119
	v_cvt_pk_bf16_f32 v122, v220, v221
	v_cvt_pk_bf16_f32 v123, v222, v223
	global_store_dwordx4 v[238:239], v[120:123], off offset:256
	s_and_saveexec_b64 s[24:25], s[0:1]
	s_cbranch_execz .LBB0_1197
	s_waitcnt lgkmcnt(0)
	v_add_f32_e32 v114, v112, v113
	v_lshlrev_b64 v[112:113], 7, v[194:195]
	v_lshl_add_u64 v[112:113], s[8:9], 0, v[112:113]
	v_lshl_add_u64 v[112:113], s[22:23], 2, v[112:113]
	s_lshl_b32 s12, s41, 2
	v_lshl_add_u64 v[112:113], v[112:113], 0, s[12:13]
	global_store_dword v[112:113], v114, off

; #define PG8_WAIT_V(n) asm volatile("s_waitcnt vmcnt(" #n ")" ::: "memory")
; #define PG8_BAR __builtin_amdgcn_s_barrier()
;   DI bool next(int i, Unit& u) const {
;     const long L = (long)i * G + c; if (L >= nwg) return false;
;     int wgid = (int)L; { const int q = nwg / NXCD, r = nwg % NXCD, xcd = wgid % NXCD, off = wgid / NXCD; wgid = (xcd < r ? xcd * (q + 1) : r * (q + 1) + (xcd - r) * q) + off; }
;     const int nig = WGM * nN, gid = wgid / nig, fm = gid * WGM, gsz = (nM - fm) < WGM ? (nM - fm) : WGM;
;     u.pm = fm + ((wgid % nig) % gsz); u.pn = (wgid % nig) / gsz; return true;
; template <class Epi, class Sched = StaticOrder>
; DI void gemm_phase(LAS unsigned char* lds, const Gemm g, const Sched& S, const Epi& E) {
;   const int tid = threadIdx.x, wid = __builtin_amdgcn_readfirstlane(tid >> 6), lane = tid & 63, wr = wid >> 2, wc = wid & 3, fr = lane & 15, fq = lane >> 4;
;   const int K = g.K, nt = K / BK;
;   unsigned voffA[2], voffB[2];
; #pragma unroll
;   for (int i = 0; i < 2; ++i) { int R, C; stage_rc(tid * 16 + i * 8192, R, C); const int Rb = Epi::PERM ? ((R & ~31) + perm32(R & 31)) : R;
;     voffA[i] = (unsigned)(R * K + C) * 2u; voffB[i] = (unsigned)(Rb * K + C) * 2u; }
;   const size_t kstep = (size_t)(BK * 2);
;   const size_t hstep = (size_t)HALF * K * 2;
;   const size_t tstep = 2 * hstep;
;   const unsigned ldsw = (unsigned)wid * 1024u;
;   const int aoff = lds_byte(wr * 64 + fr, fq * 8), boff = lds_byte(wc * 32 + fr, fq * 8);
;     ...
;   Unit cur, nxt; int ui = 0;
;   if (!S.next(0, cur)) return;
;   f32x4 acc[2][2][4][2];
; #pragma unroll
;   for (int a = 0; a < 2; ++a)
; #pragma unroll
;     for (int b = 0; b < 2; ++b)
; #pragma unroll
;       for (int m = 0; m < 4; ++m)
; #pragma unroll
;         for (int n = 0; n < 2; ++n) acc[a][b][m][n] = (f32x4){0.f, 0.f, 0.f, 0.f};
;   bf16x8 At[4][2], B0[2][2], B1[2][2];
;   const char* cA = (const char*)g.A + (size_t)cur.pm * tstep; const char* cB = (const char*)g.Bt + (size_t)cur.pn * tstep;
;   PG8_STAGE(PG8_SB(0, 0), cB, voffB); PG8_STAGE(PG8_SA(0, 0), cA, voffA); PG8_STAGE(PG8_SB(0, 1), cB + hstep, voffB); PG8_STAGE(PG8_SA(0, 1), cA + hstep, voffA);
;   if (wr == 1) PG8_BAR;
;   PG8_WAIT_V(4); PG8_BAR;
;   PG8_STAGE(PG8_SB(1, 0), cB + kstep, voffB); PG8_STAGE(PG8_SA(1, 0), cA + kstep, voffA); PG8_STAGE(PG8_SB(1, 1), cB + hstep + kstep, voffB);
;   PG8_WAIT_V(6); PG8_BAR;
.LBB0_1269:
	v_writelane_b32 v247, 1, 0
	s_add_i32 s0, 0, 0x20008
	v_mov_b32_e32 v0, s0
	ds_read_b32 v0, v0
	v_readfirstlane_b32 s37, v210
	s_waitcnt lgkmcnt(0)
	v_readfirstlane_b32 s33, v0
	s_cmpk_gt_i32 s33, 0xaff
	s_cbranch_scc1 .LBB0_1293
	v_lshrrev_b32_e32 v0, 5, v210
	v_lshrrev_b32_e32 v2, 1, v210
	v_and_b32_e32 v0, 4, v0
	v_bfe_u32 v1, v210, 2, 2
	v_and_b32_e32 v11, 24, v2
	v_or3_b32 v0, v0, v1, v11
	v_lshlrev_b32_e32 v1, 4, v210
	v_add_u32_e32 v8, 0x2000, v1
	v_lshrrev_b32_e32 v2, 7, v8
	s_movk_i32 s0, 0xe0
	v_and_b32_e32 v4, 32, v210
	s_add_u32 s56, s84, 0xc103600
	v_and_or_b32 v3, v2, s0, v0
	v_bitop3_b32 v9, v1, v4, 48 bitop3:0x6c
	v_and_b32_e32 v10, 64, v210
	v_bfe_u32 v12, v210, 2, 4
	s_movk_i32 s0, 0xf0
	s_addc_u32 s57, s85, 0
	v_or_b32_e32 v1, v9, v10
	v_and_or_b32 v2, v2, s0, v12
	s_add_u32 s60, s84, 0x4703600
	v_lshl_or_b32 v162, v2, 12, v1
	v_lshrrev_b32_e32 v2, 3, v210
	s_movk_i32 s0, 0x60
	s_addc_u32 s61, s85, 0
	v_and_or_b32 v0, v2, s0, v0
	s_movk_i32 s0, 0x70
	s_ashr_i32 s63, s33, 31
	v_lshl_or_b32 v164, v0, 12, v1
	v_and_or_b32 v0, v2, s0, v12
	s_lshr_b32 s0, s63, 29
	s_add_i32 s0, s33, s0
	s_ashr_i32 s5, s0, 3
	s_and_b32 s0, s0, -8
	s_sub_i32 s0, s33, s0
	s_lshr_b32 s6, s0, 31
	s_or_b32 s6, s6, 0x160
	s_mul_i32 s0, s6, s0
	s_add_i32 s0, s0, s5
	s_mul_hi_i32 s5, s0, 0x2e8ba2e9
	s_lshr_b32 s6, s5, 31
	s_ashr_i32 s5, s5, 6
	s_add_i32 s5, s5, s6
	s_lshl_b32 s8, s5, 3
	s_sub_i32 s6, 64, s8
	s_min_u32 s9, s6, 8
	s_mulk_i32 s5, 0x160
	v_lshl_or_b32 v160, v3, 12, v1
	s_sub_i32 s5, s0, s5
	v_cvt_f32_ubyte0_e32 v3, s9
	v_cvt_f32_i32_e32 v2, s5
	v_rcp_iflag_f32_e32 v4, v3
	v_lshl_or_b32 v166, v0, 12, v1
	s_lshr_b32 s1, s37, 6
	s_ashr_i32 s0, s5, 30
	v_mul_f32_e32 v0, v2, v4
	v_trunc_f32_e32 v0, v0
	v_fma_f32 v1, -v0, v3, v2
	v_cvt_i32_f32_e32 v0, v0
	s_lshr_b32 s4, s37, 8
	s_lshl_b32 s62, s1, 10
	s_or_b32 s0, s0, 1
	v_cmp_ge_f32_e64 s[6:7], |v1|, v3
	s_and_b64 s[6:7], s[6:7], exec
	s_cselect_b32 s0, s0, 0
	v_readfirstlane_b32 s6, v0
	s_add_i32 s0, s6, s0
	s_mul_i32 s6, s0, s9
	s_sub_i32 s5, s5, s6
	s_sext_i32_i16 s5, s5
	s_add_i32 s12, s8, s5
	s_ashr_i32 s13, s12, 31
	s_bfe_i64 s[8:9], s[0:1], 0x100000
	s_lshl_b64 s[6:7], s[12:13], 20
	s_lshl_b64 s[8:9], s[8:9], 20
	s_add_u32 s48, s60, s8
	s_addc_u32 s49, s61, s9
	s_add_i32 s64, s62, 0
	s_add_i32 m0, s64, 0x10000
	v_mov_b32_e32 v165, 0
	global_load_lds_dwordx4 v164, s[48:49]
	s_add_i32 m0, s64, 0x12000
	s_add_u32 s14, s56, s6
	global_load_lds_dwordx4 v160, s[48:49]
	s_addc_u32 s15, s57, s7
	s_mov_b32 m0, s64
	s_add_i32 s65, s64, 0x2000
	global_load_lds_dwordx4 v166, s[14:15]
	s_mov_b32 m0, s65
	s_add_u32 s6, s48, 0x80000
	global_load_lds_dwordx4 v162, s[14:15]
	s_addc_u32 s7, s49, 0
	s_add_i32 m0, s64, 0x14000
	v_mov_b32_e32 v161, v165
	global_load_lds_dwordx4 v164, s[6:7]
	s_add_i32 m0, s64, 0x16000
	v_mov_b32_e32 v167, v165
	global_load_lds_dwordx4 v160, s[6:7]
	s_add_u32 s6, s14, 0x80000
	s_addc_u32 s7, s15, 0
	s_add_i32 s66, s64, 0x4000
	s_mov_b32 m0, s66
	s_add_i32 s67, s64, 0x6000
	global_load_lds_dwordx4 v166, s[6:7]
	s_mov_b32 m0, s67
	v_mov_b32_e32 v163, v165
	global_load_lds_dwordx4 v162, s[6:7]
	v_lshl_add_u64 v[6:7], s[48:49], 0, v[164:165]
	v_lshl_add_u64 v[4:5], s[48:49], 0, v[160:161]
	v_lshl_add_u64 v[2:3], s[14:15], 0, v[166:167]
	s_cmp_lg_u32 s4, 1
	v_lshl_add_u64 v[0:1], s[14:15], 0, v[162:163]
	s_cbranch_scc1 .LBB0_1272
	s_barrier

; #define PG8_STAGE(bufoff, gbase, voff) do { _Pragma("unroll") for (int _i = 0; _i < 2; ++_i) \
;     __builtin_amdgcn_global_load_lds((const unsigned*)((const char*)(gbase) + (voff)[_i]), (LAS unsigned*)(lds + (bufoff) + ldsw + _i * 8192), 16, 0, 0); } while (0)
; #define PG8_LDA(dst, b, h) do { _Pragma("unroll") for (int m = 0; m < 4; ++m) _Pragma("unroll") for (int k = 0; k < 2; ++k) dst[m][k] = *(const LAS bf16x8*)(lds + PG8_SA(b, h) + aoff + m * 2048 + k * 1024); } while (0)
; #define PG8_LDB(dst, b, h) do { _Pragma("unroll") for (int n = 0; n < 2; ++n) _Pragma("unroll") for (int k = 0; k < 2; ++k) dst[n][k] = *(const LAS bf16x8*)(lds + PG8_SB(b, h) + boff + n * 2048 + k * 1024); } while (0)
; #define PG8_MMA(ai, bj, At, Bt) do { __builtin_amdgcn_s_setprio(1); _Pragma("unroll") for (int m = 0; m < 4; ++m) _Pragma("unroll") for (int n = 0; n < 2; ++n) _Pragma("unroll") for (int k = 0; k < 2; ++k) \
;     acc[ai][bj][m][n] = __builtin_amdgcn_mfma_f32_16x16x32_bf16(Bt[n][k], At[m][k], acc[ai][bj][m][n], 0, 0, 0); __builtin_amdgcn_s_setprio(0); } while (0)
; #define PG8_WAIT_V(n) asm volatile("s_waitcnt vmcnt(" #n ")" ::: "memory")
; #define PG8_WAIT_L(n) asm volatile("s_waitcnt lgkmcnt(" #n ")" ::: "memory")
; #define PG8_BAR __builtin_amdgcn_s_barrier()
; #define PG8_SCHED __builtin_amdgcn_sched_barrier(0)
; template <class Epi, class Sched = StaticOrder>
; DI void gemm_phase(LAS unsigned char* lds, const Gemm g, const Sched& S, const Epi& E) {
;     ...
;     for (int t = 0; t < nt; t += 2) {
;       const bool last = (t == nt - 2);
;       const char* a1 = cA + (size_t)(t + 1) * kstep;
;       const char* a2 = last ? nA : cA + (size_t)(t + 2) * kstep; const char* b2 = last ? nB : cB + (size_t)(t + 2) * kstep;
;       const char* a3 = a2 + kstep; const char* b3 = b2 + kstep;
;       PG8_LDB(B0, 0, 0); PG8_SCHED; PG8_LDA(At, 0, 0); PG8_STAGE(PG8_SA(1, 1), a1 + hstep, voffA);
;       PG8_WAIT_L(8); PG8_BAR; PG8_WAIT_L(0); PG8_MMA(0, 0, At, B0); PG8_BAR; PG8_SCHED;
;       PG8_LDB(B1, 0, 1); PG8_STAGE(PG8_SB(0, 0), b2, voffB);
;       PG8_BAR; PG8_WAIT_L(0); PG8_MMA(0, 1, At, B1); PG8_BAR;
;       PG8_LDA(At, 0, 1); PG8_STAGE(PG8_SA(0, 0), a2, voffA);
;       PG8_BAR; PG8_WAIT_L(0); PG8_MMA(1, 0, At, B0); PG8_BAR; PG8_SCHED;
;       PG8_STAGE(PG8_SB(0, 1), b2 + hstep, voffB);
;       PG8_WAIT_V(6); PG8_BAR; PG8_MMA(1, 1, At, B1); PG8_BAR;
.LBB0_1277:
	ds_read_b128 v[64:67], v201
	ds_read_b128 v[68:71], v201 offset:1024
	ds_read_b128 v[72:75], v201 offset:2048
	ds_read_b128 v[76:79], v201 offset:3072
	s_add_u32 s48, s14, 0xfff80080
	s_addc_u32 s49, s15, -1
	s_cmp_eq_u32 s58, 28
	s_cselect_b32 s51, s41, s49
	s_cselect_b32 s50, s42, s48
	s_cselect_b32 s49, s39, s53
	s_cselect_b32 s48, s43, s52
	s_add_i32 m0, s64, 0xc000
	ds_read_b128 v[80:83], v202
	ds_read_b128 v[84:87], v202 offset:1024
	ds_read_b128 v[88:91], v202 offset:2048
	ds_read_b128 v[92:95], v202 offset:3072
	ds_read_b128 v[180:183], v202 offset:4096
	ds_read_b128 v[184:187], v202 offset:5120
	ds_read_b128 v[188:191], v202 offset:6144
	ds_read_b128 v[192:195], v202 offset:7168
	global_load_lds_dwordx4 v170, s[14:15]
	s_add_i32 m0, s64, 0xe000
	s_nop 0
	global_load_lds_dwordx4 v172, s[14:15]
	s_waitcnt lgkmcnt(0)
	s_setprio 1
	s_barrier
	v_mfma_f32_16x16x32_bf16 v[156:159], v[64:67], v[80:83], v[156:159]
	v_mfma_f32_16x16x32_bf16 v[144:147], v[72:75], v[80:83], v[144:147]
	v_mfma_f32_16x16x32_bf16 v[140:143], v[64:67], v[88:91], v[140:143]
	v_mfma_f32_16x16x32_bf16 v[132:135], v[72:75], v[88:91], v[132:135]
	v_mfma_f32_16x16x32_bf16 v[124:127], v[64:67], v[180:183], v[124:127]
	v_mfma_f32_16x16x32_bf16 v[116:119], v[72:75], v[180:183], v[116:119]
	v_mfma_f32_16x16x32_bf16 v[112:115], v[64:67], v[188:191], v[112:115]
	v_mfma_f32_16x16x32_bf16 v[108:111], v[72:75], v[188:191], v[108:111]
	v_mfma_f32_16x16x32_bf16 v[156:159], v[68:71], v[84:87], v[156:159]
	v_mfma_f32_16x16x32_bf16 v[144:147], v[76:79], v[84:87], v[144:147]
	v_mfma_f32_16x16x32_bf16 v[140:143], v[68:71], v[92:95], v[140:143]
	v_mfma_f32_16x16x32_bf16 v[132:135], v[76:79], v[92:95], v[132:135]
	v_mfma_f32_16x16x32_bf16 v[124:127], v[68:71], v[184:187], v[124:127]
	v_mfma_f32_16x16x32_bf16 v[116:119], v[76:79], v[184:187], v[116:119]
	v_mfma_f32_16x16x32_bf16 v[112:115], v[68:71], v[192:195], v[112:115]
	v_mfma_f32_16x16x32_bf16 v[108:111], v[76:79], v[192:195], v[108:111]
	s_barrier
	s_setprio 0
	s_add_i32 s59, s72, s62
	s_add_u32 s98, s48, 0x80
	s_addc_u32 s99, s49, 0
	s_add_u32 s100, s50, 0x80
	s_addc_u32 s101, s51, 0
	s_mov_b32 m0, s59
	ds_read_b128 v[206:209], v203
	ds_read_b128 v[212:215], v203 offset:1024
	ds_read_b128 v[216:219], v203 offset:2048
	ds_read_b128 v[220:223], v203 offset:3072
	global_load_lds_dwordx4 v164, s[48:49]
	s_add_i32 m0, s59, 0x2000
	s_nop 0
	global_load_lds_dwordx4 v160, s[48:49]
	s_waitcnt lgkmcnt(0)
	s_setprio 1
	s_barrier
	v_mfma_f32_16x16x32_bf16 v[152:155], v[206:209], v[80:83], v[152:155]
	v_mfma_f32_16x16x32_bf16 v[80:83], v[216:219], v[80:83], v[148:151]
	v_mfma_f32_16x16x32_bf16 v[152:155], v[212:215], v[84:87], v[152:155]
	v_mfma_f32_16x16x32_bf16 v[80:83], v[220:223], v[84:87], v[80:83]
	v_mfma_f32_16x16x32_bf16 v[84:87], v[206:209], v[88:91], v[136:139]
	v_mfma_f32_16x16x32_bf16 v[88:91], v[216:219], v[88:91], v[128:131]
	v_mfma_f32_16x16x32_bf16 v[104:107], v[216:219], v[180:183], v[104:107]
	v_mfma_f32_16x16x32_bf16 v[100:103], v[206:209], v[188:191], v[100:103]
	v_mfma_f32_16x16x32_bf16 v[96:99], v[216:219], v[188:191], v[96:99]
	v_mfma_f32_16x16x32_bf16 v[84:87], v[212:215], v[92:95], v[84:87]
	v_mfma_f32_16x16x32_bf16 v[88:91], v[220:223], v[92:95], v[88:91]
	v_mfma_f32_16x16x32_bf16 v[92:95], v[206:209], v[180:183], v[120:123]
	v_mfma_f32_16x16x32_bf16 v[104:107], v[220:223], v[184:187], v[104:107]
	v_mfma_f32_16x16x32_bf16 v[100:103], v[212:215], v[192:195], v[100:103]
	v_mfma_f32_16x16x32_bf16 v[96:99], v[220:223], v[192:195], v[96:99]
	v_mfma_f32_16x16x32_bf16 v[92:95], v[212:215], v[184:187], v[92:95]
	s_barrier
	s_setprio 0
	s_mov_b32 m0, s64
	ds_read_b128 v[120:123], v202 offset:16384
	ds_read_b128 v[128:131], v202 offset:17408
	ds_read_b128 v[136:139], v202 offset:18432
	ds_read_b128 v[148:151], v202 offset:19456
	ds_read_b128 v[180:183], v202 offset:20480
	ds_read_b128 v[184:187], v202 offset:21504
	ds_read_b128 v[188:191], v202 offset:22528
	ds_read_b128 v[192:195], v202 offset:23552
	global_load_lds_dwordx4 v166, s[50:51]
	s_mov_b32 m0, s65
	s_nop 0
	global_load_lds_dwordx4 v162, s[50:51]
	s_waitcnt lgkmcnt(0)
	s_setprio 1
	s_barrier
	v_mfma_f32_16x16x32_bf16 v[60:63], v[64:67], v[120:123], v[60:63]
	v_mfma_f32_16x16x32_bf16 v[48:51], v[72:75], v[120:123], v[48:51]
	v_mfma_f32_16x16x32_bf16 v[44:47], v[64:67], v[136:139], v[44:47]
	v_mfma_f32_16x16x32_bf16 v[36:39], v[72:75], v[136:139], v[36:39]
	v_mfma_f32_16x16x32_bf16 v[28:31], v[64:67], v[180:183], v[28:31]
	v_mfma_f32_16x16x32_bf16 v[20:23], v[72:75], v[180:183], v[20:23]
	v_mfma_f32_16x16x32_bf16 v[16:19], v[64:67], v[188:191], v[16:19]
	v_mfma_f32_16x16x32_bf16 v[12:15], v[72:75], v[188:191], v[12:15]
	v_mfma_f32_16x16x32_bf16 v[60:63], v[68:71], v[128:131], v[60:63]
	v_mfma_f32_16x16x32_bf16 v[48:51], v[76:79], v[128:131], v[48:51]
	v_mfma_f32_16x16x32_bf16 v[44:47], v[68:71], v[148:151], v[44:47]
	v_mfma_f32_16x16x32_bf16 v[36:39], v[76:79], v[148:151], v[36:39]
	v_mfma_f32_16x16x32_bf16 v[28:31], v[68:71], v[184:187], v[28:31]
	v_mfma_f32_16x16x32_bf16 v[20:23], v[76:79], v[184:187], v[20:23]
	v_mfma_f32_16x16x32_bf16 v[16:19], v[68:71], v[192:195], v[16:19]
	v_mfma_f32_16x16x32_bf16 v[12:15], v[76:79], v[192:195], v[12:15]
	s_barrier
	s_setprio 0
	s_add_u32 s78, s48, 0x80000
	s_addc_u32 s79, s49, 0
	s_add_i32 s59, s73, s62
	s_mov_b32 m0, s59
	s_nop 0
	global_load_lds_dwordx4 v164, s[78:79]
	s_add_i32 m0, s59, 0x2000
	s_nop 0
	global_load_lds_dwordx4 v160, s[78:79]
	v_readlane_b32 vcc_lo, v247, 0
	s_cmp_eq_u32 s58, vcc_lo
	s_cbranch_scc1 .Lsw_6
	s_waitcnt vmcnt(6)
; #define PG8_STAGE(bufoff, gbase, voff) do { _Pragma("unroll") for (int _i = 0; _i < 2; ++_i) \
;     __builtin_amdgcn_global_load_lds((const unsigned*)((const char*)(gbase) + (voff)[_i]), (LAS unsigned*)(lds + (bufoff) + ldsw + _i * 8192), 16, 0, 0); } while (0)
; #define PG8_LDA(dst, b, h) do { _Pragma("unroll") for (int m = 0; m < 4; ++m) _Pragma("unroll") for (int k = 0; k < 2; ++k) dst[m][k] = *(const LAS bf16x8*)(lds + PG8_SA(b, h) + aoff + m * 2048 + k * 1024); } while (0)
; #define PG8_LDB(dst, b, h) do { _Pragma("unroll") for (int n = 0; n < 2; ++n) _Pragma("unroll") for (int k = 0; k < 2; ++k) dst[n][k] = *(const LAS bf16x8*)(lds + PG8_SB(b, h) + boff + n * 2048 + k * 1024); } while (0)
; #define PG8_MMA(ai, bj, At, Bt) do { __builtin_amdgcn_s_setprio(1); _Pragma("unroll") for (int m = 0; m < 4; ++m) _Pragma("unroll") for (int n = 0; n < 2; ++n) _Pragma("unroll") for (int k = 0; k < 2; ++k) \
;     acc[ai][bj][m][n] = __builtin_amdgcn_mfma_f32_16x16x32_bf16(Bt[n][k], At[m][k], acc[ai][bj][m][n], 0, 0, 0); __builtin_amdgcn_s_setprio(0); } while (0)
; #define PG8_WAIT_V(n) asm volatile("s_waitcnt vmcnt(" #n ")" ::: "memory")
; #define PG8_WAIT_L(n) asm volatile("s_waitcnt lgkmcnt(" #n ")" ::: "memory")
; #define PG8_BAR __builtin_amdgcn_s_barrier()
; #define PG8_SCHED __builtin_amdgcn_sched_barrier(0)
; template <class Epi, class Sched = StaticOrder>
; DI void gemm_phase(LAS unsigned char* lds, const Gemm g, const Sched& S, const Epi& E) {
;     ...
;       PG8_WAIT_V(6); PG8_BAR; PG8_MMA(1, 1, At, B1); PG8_BAR;
;       PG8_LDB(B0, 1, 0); PG8_SCHED; PG8_LDA(At, 1, 0); PG8_STAGE(PG8_SA(0, 1), a2 + hstep, voffA);
;       PG8_WAIT_L(8); PG8_BAR; PG8_WAIT_L(0); PG8_MMA(0, 0, At, B0); PG8_BAR; PG8_SCHED;
;       PG8_LDB(B1, 1, 1); PG8_STAGE(PG8_SB(1, 0), b3, voffB);
;       PG8_BAR; PG8_WAIT_L(0); PG8_MMA(0, 1, At, B1); PG8_BAR;
;       PG8_LDA(At, 1, 1); PG8_STAGE(PG8_SA(1, 0), a3, voffA);
;       PG8_BAR; PG8_WAIT_L(0); PG8_MMA(1, 0, At, B0); PG8_BAR; PG8_SCHED;
;       PG8_STAGE(PG8_SB(1, 1), b3 + hstep, voffB);
;       PG8_WAIT_V(6); PG8_BAR; PG8_MMA(1, 1, At, B1); PG8_BAR;
.Lsw_6:
	s_setprio 1
	s_barrier
	v_mfma_f32_16x16x32_bf16 v[56:59], v[206:209], v[120:123], v[56:59]
	v_mfma_f32_16x16x32_bf16 v[52:55], v[216:219], v[120:123], v[52:55]
	v_mfma_f32_16x16x32_bf16 v[40:43], v[206:209], v[136:139], v[40:43]
	v_mfma_f32_16x16x32_bf16 v[32:35], v[216:219], v[136:139], v[32:35]
	v_mfma_f32_16x16x32_bf16 v[24:27], v[206:209], v[180:183], v[24:27]
	v_mfma_f32_16x16x32_bf16 v[8:11], v[216:219], v[180:183], v[8:11]
	v_mfma_f32_16x16x32_bf16 v[4:7], v[206:209], v[188:191], v[4:7]
	v_mfma_f32_16x16x32_bf16 v[0:3], v[216:219], v[188:191], v[0:3]
	v_mfma_f32_16x16x32_bf16 v[56:59], v[212:215], v[128:131], v[56:59]
	v_mfma_f32_16x16x32_bf16 v[52:55], v[220:223], v[128:131], v[52:55]
	v_mfma_f32_16x16x32_bf16 v[40:43], v[212:215], v[148:151], v[40:43]
	v_mfma_f32_16x16x32_bf16 v[32:35], v[220:223], v[148:151], v[32:35]
	v_mfma_f32_16x16x32_bf16 v[24:27], v[212:215], v[184:187], v[24:27]
	v_mfma_f32_16x16x32_bf16 v[8:11], v[220:223], v[184:187], v[8:11]
	v_mfma_f32_16x16x32_bf16 v[4:7], v[212:215], v[192:195], v[4:7]
	v_mfma_f32_16x16x32_bf16 v[0:3], v[220:223], v[192:195], v[0:3]
	s_barrier
	s_setprio 0
	s_add_i32 s59, 0, 0x18000
	v_add_u32_e32 v76, s59, v198
	ds_read_b128 v[64:67], v76
	ds_read_b128 v[68:71], v76 offset:1024
	ds_read_b128 v[72:75], v76 offset:2048
	ds_read_b128 v[76:79], v76 offset:3072
	s_add_u32 s50, s50, 0x80000
	s_addc_u32 s51, s51, 0
	s_mov_b32 m0, s66
	ds_read_b128 v[120:123], v202 offset:32768
	ds_read_b128 v[128:131], v202 offset:33792
	ds_read_b128 v[180:183], v202 offset:34816
	ds_read_b128 v[184:187], v202 offset:35840
	ds_read_b128 v[188:191], v202 offset:36864
	ds_read_b128 v[192:195], v202 offset:37888
	ds_read_b128 v[206:209], v202 offset:38912
	ds_read_b128 v[212:215], v202 offset:39936
	global_load_lds_dwordx4 v166, s[50:51]
	s_mov_b32 m0, s67
	s_nop 0
	global_load_lds_dwordx4 v162, s[50:51]
	s_waitcnt lgkmcnt(0)
	s_setprio 1
	s_barrier
	v_mfma_f32_16x16x32_bf16 v[136:139], v[64:67], v[120:123], v[156:159]
	v_mfma_f32_16x16x32_bf16 v[156:159], v[68:71], v[128:131], v[136:139]
	v_mfma_f32_16x16x32_bf16 v[136:139], v[72:75], v[120:123], v[144:147]
	v_mfma_f32_16x16x32_bf16 v[144:147], v[76:79], v[128:131], v[136:139]
	v_mfma_f32_16x16x32_bf16 v[136:139], v[64:67], v[180:183], v[140:143]
	v_mfma_f32_16x16x32_bf16 v[132:135], v[72:75], v[180:183], v[132:135]
	v_mfma_f32_16x16x32_bf16 v[124:127], v[64:67], v[188:191], v[124:127]
	v_mfma_f32_16x16x32_bf16 v[116:119], v[72:75], v[188:191], v[116:119]
	v_mfma_f32_16x16x32_bf16 v[112:115], v[64:67], v[206:209], v[112:115]
	v_mfma_f32_16x16x32_bf16 v[108:111], v[72:75], v[206:209], v[108:111]
	v_mfma_f32_16x16x32_bf16 v[140:143], v[68:71], v[184:187], v[136:139]
	v_mfma_f32_16x16x32_bf16 v[132:135], v[76:79], v[184:187], v[132:135]
	v_mfma_f32_16x16x32_bf16 v[124:127], v[68:71], v[192:195], v[124:127]
	v_mfma_f32_16x16x32_bf16 v[116:119], v[76:79], v[192:195], v[116:119]
	v_mfma_f32_16x16x32_bf16 v[112:115], v[68:71], v[212:215], v[112:115]
	v_mfma_f32_16x16x32_bf16 v[108:111], v[76:79], v[212:215], v[108:111]
	s_barrier
	s_setprio 0
	s_add_i32 s50, 0, 0x1c000
	v_add_u32_e32 v136, s50, v198
	s_add_i32 s51, s59, s62
	ds_read_b128 v[216:219], v136
	ds_read_b128 v[220:223], v136 offset:1024
	ds_read_b128 v[224:227], v136 offset:2048
	ds_read_b128 v[228:231], v136 offset:3072
	s_mov_b32 m0, s51
	s_nop 0
	global_load_lds_dwordx4 v164, s[98:99]
	s_add_i32 m0, s51, 0x2000
	s_nop 0
	global_load_lds_dwordx4 v160, s[98:99]
	s_waitcnt lgkmcnt(0)
	s_setprio 1
	s_barrier
	v_mfma_f32_16x16x32_bf16 v[80:83], v[224:227], v[120:123], v[80:83]
	v_mfma_f32_16x16x32_bf16 v[136:139], v[216:219], v[120:123], v[152:155]
	v_mfma_f32_16x16x32_bf16 v[148:151], v[228:231], v[128:131], v[80:83]
	v_mfma_f32_16x16x32_bf16 v[80:83], v[216:219], v[180:183], v[84:87]
	v_mfma_f32_16x16x32_bf16 v[152:155], v[220:223], v[128:131], v[136:139]
	v_mfma_f32_16x16x32_bf16 v[136:139], v[220:223], v[184:187], v[80:83]
	v_mfma_f32_16x16x32_bf16 v[80:83], v[224:227], v[180:183], v[88:91]
	v_mfma_f32_16x16x32_bf16 v[128:131], v[228:231], v[184:187], v[80:83]
	v_mfma_f32_16x16x32_bf16 v[80:83], v[216:219], v[188:191], v[92:95]
	v_mfma_f32_16x16x32_bf16 v[120:123], v[220:223], v[192:195], v[80:83]
	v_mfma_f32_16x16x32_bf16 v[80:83], v[224:227], v[188:191], v[104:107]
	v_mfma_f32_16x16x32_bf16 v[104:107], v[228:231], v[192:195], v[80:83]
	v_mfma_f32_16x16x32_bf16 v[80:83], v[216:219], v[206:209], v[100:103]
	v_mfma_f32_16x16x32_bf16 v[100:103], v[220:223], v[212:215], v[80:83]
	v_mfma_f32_16x16x32_bf16 v[80:83], v[224:227], v[206:209], v[96:99]
	v_mfma_f32_16x16x32_bf16 v[96:99], v[228:231], v[212:215], v[80:83]
	s_barrier
	s_setprio 0
	s_mov_b32 m0, s55
	s_nop 2
	ds_read_b128 v[80:83], v202 offset:49152
	ds_read_b128 v[84:87], v202 offset:50176
	ds_read_b128 v[88:91], v202 offset:51200
	ds_read_b128 v[92:95], v202 offset:52224
	ds_read_b128 v[180:183], v202 offset:53248
	ds_read_b128 v[184:187], v202 offset:54272
	ds_read_b128 v[188:191], v202 offset:55296
	ds_read_b128 v[192:195], v202 offset:56320
	global_load_lds_dwordx4 v166, s[100:101]
	s_mov_b32 m0, s68
	s_nop 0
	global_load_lds_dwordx4 v162, s[100:101]
	s_waitcnt lgkmcnt(0)
	s_setprio 1
	s_barrier
	v_mfma_f32_16x16x32_bf16 v[60:63], v[64:67], v[80:83], v[60:63]
	v_mfma_f32_16x16x32_bf16 v[48:51], v[72:75], v[80:83], v[48:51]
	v_mfma_f32_16x16x32_bf16 v[44:47], v[64:67], v[88:91], v[44:47]
	v_mfma_f32_16x16x32_bf16 v[36:39], v[72:75], v[88:91], v[36:39]
	v_mfma_f32_16x16x32_bf16 v[28:31], v[64:67], v[180:183], v[28:31]
	v_mfma_f32_16x16x32_bf16 v[20:23], v[72:75], v[180:183], v[20:23]
	v_mfma_f32_16x16x32_bf16 v[16:19], v[64:67], v[188:191], v[16:19]
	v_mfma_f32_16x16x32_bf16 v[12:15], v[72:75], v[188:191], v[12:15]
	v_mfma_f32_16x16x32_bf16 v[60:63], v[68:71], v[84:87], v[60:63]
	v_mfma_f32_16x16x32_bf16 v[48:51], v[76:79], v[84:87], v[48:51]
	v_mfma_f32_16x16x32_bf16 v[44:47], v[68:71], v[92:95], v[44:47]
	v_mfma_f32_16x16x32_bf16 v[36:39], v[76:79], v[92:95], v[36:39]
	v_mfma_f32_16x16x32_bf16 v[28:31], v[68:71], v[184:187], v[28:31]
	v_mfma_f32_16x16x32_bf16 v[20:23], v[76:79], v[184:187], v[20:23]
	v_mfma_f32_16x16x32_bf16 v[16:19], v[68:71], v[192:195], v[16:19]
	v_mfma_f32_16x16x32_bf16 v[12:15], v[76:79], v[192:195], v[12:15]
	s_barrier
	s_setprio 0
	s_add_u32 s48, s48, 0x80080
	s_addc_u32 s49, s49, 0
	s_add_i32 s50, s50, s62
	s_mov_b32 m0, s50
	s_nop 0
	global_load_lds_dwordx4 v164, s[48:49]
	s_add_i32 m0, s50, 0x2000
	s_nop 0
	global_load_lds_dwordx4 v160, s[48:49]
	s_waitcnt vmcnt(6)
	s_cmp_eq_u32 s58, 28
	s_cbranch_scc0 .Lxs_6
	s_add_i32 m0, s64, 0xc000
	s_nop 0
	global_load_lds_dwordx4 v170, s[100:101]
	s_add_i32 m0, s64, 0xe000
	s_nop 0
	global_load_lds_dwordx4 v172, s[100:101]
; #define PG8_STAGE(bufoff, gbase, voff) do { _Pragma("unroll") for (int _i = 0; _i < 2; ++_i) \
;     __builtin_amdgcn_global_load_lds((const unsigned*)((const char*)(gbase) + (voff)[_i]), (LAS unsigned*)(lds + (bufoff) + ldsw + _i * 8192), 16, 0, 0); } while (0)
; #define PG8_MMA(ai, bj, At, Bt) do { __builtin_amdgcn_s_setprio(1); _Pragma("unroll") for (int m = 0; m < 4; ++m) _Pragma("unroll") for (int n = 0; n < 2; ++n) _Pragma("unroll") for (int k = 0; k < 2; ++k) \
;     acc[ai][bj][m][n] = __builtin_amdgcn_mfma_f32_16x16x32_bf16(Bt[n][k], At[m][k], acc[ai][bj][m][n], 0, 0, 0); __builtin_amdgcn_s_setprio(0); } while (0)
; #define PG8_WAIT_V(n) asm volatile("s_waitcnt vmcnt(" #n ")" ::: "memory")
; #define PG8_WAIT_L(n) asm volatile("s_waitcnt lgkmcnt(" #n ")" ::: "memory")
; #define PG8_BAR __builtin_amdgcn_s_barrier()
; #define PG8_SCHED __builtin_amdgcn_sched_barrier(0)
;   DI void operator()(const f32x4 (&acc)[2][2][4][2], const Unit& u, int wr, int wc, int fr, int fq) const {
;     const int col = u.pn * 128 + wc * 32 + 8 * fq;
;     float w0[8], w1[8], w2[8], bb[8];
; #pragma unroll
;     for (int e = 0; e < 8; ++e) { w0[e] = cw[col + e]; w1[e] = cw[5632 + col + e]; w2[e] = cw[2 * 5632 + col + e]; bb[e] = cb[col + e]; }
; #pragma unroll
;     for (int ai = 0; ai < 2; ++ai) {
;       const int row0 = u.pm * BM + ai * HALF + wr * 64, span = row0 >> 6;
;       float rsv[4];
; #pragma unroll
;       for (int m = 0; m < 4; ++m) rsv[m] = row_rstd(ssq, row0 + 16 * m + fr, fq);
; template <class Epi, class Sched = StaticOrder>
; DI void gemm_phase(LAS unsigned char* lds, const Gemm g, const Sched& S, const Epi& E) {
;     ...
;       PG8_BAR; PG8_WAIT_L(0); PG8_MMA(1, 0, At, B0); PG8_BAR; PG8_SCHED;
;       PG8_STAGE(PG8_SB(1, 1), b3 + hstep, voffB);
;       PG8_WAIT_V(6); PG8_BAR; PG8_MMA(1, 1, At, B1); PG8_BAR;
;     }
;     E(acc, cur, wr, wc, fr, fq);
.Lxs_6:
	s_add_i32 s58, s58, 2
	s_add_u32 s14, s14, 0x100
	s_addc_u32 s15, s15, 0
	s_add_u32 s52, s52, 0x100
	s_addc_u32 s53, s53, 0
	s_cmp_gt_u32 s58, 29
	s_setprio 1
	s_barrier
	v_mfma_f32_16x16x32_bf16 v[56:59], v[216:219], v[80:83], v[56:59]
	v_mfma_f32_16x16x32_bf16 v[52:55], v[224:227], v[80:83], v[52:55]
	v_mfma_f32_16x16x32_bf16 v[40:43], v[216:219], v[88:91], v[40:43]
	v_mfma_f32_16x16x32_bf16 v[32:35], v[224:227], v[88:91], v[32:35]
	v_mfma_f32_16x16x32_bf16 v[24:27], v[216:219], v[180:183], v[24:27]
	v_mfma_f32_16x16x32_bf16 v[8:11], v[224:227], v[180:183], v[8:11]
	v_mfma_f32_16x16x32_bf16 v[4:7], v[216:219], v[188:191], v[4:7]
	v_mfma_f32_16x16x32_bf16 v[0:3], v[224:227], v[188:191], v[0:3]
	v_mfma_f32_16x16x32_bf16 v[56:59], v[220:223], v[84:87], v[56:59]
	v_mfma_f32_16x16x32_bf16 v[52:55], v[228:231], v[84:87], v[52:55]
	v_mfma_f32_16x16x32_bf16 v[40:43], v[220:223], v[92:95], v[40:43]
	v_mfma_f32_16x16x32_bf16 v[32:35], v[228:231], v[92:95], v[32:35]
	v_mfma_f32_16x16x32_bf16 v[24:27], v[220:223], v[184:187], v[24:27]
	v_mfma_f32_16x16x32_bf16 v[8:11], v[228:231], v[184:187], v[8:11]
	v_mfma_f32_16x16x32_bf16 v[4:7], v[220:223], v[192:195], v[4:7]
	v_mfma_f32_16x16x32_bf16 v[0:3], v[228:231], v[192:195], v[0:3]
	s_barrier
	s_setprio 0
	s_cbranch_scc0 .LBB0_1277
	v_writelane_b32 v247, -2, 0
	s_lshl_b32 s39, s12, 8
	s_add_i32 s39, s39, s54
	v_or_b32_e32 v190, s39, v179
	v_ashrrev_i32_e32 v191, 31, v190
	v_lshlrev_b64 v[64:65], 7, v[190:191]
	v_or_b32_e32 v188, 16, v190
	v_lshl_add_u64 v[64:65], v[168:169], 0, v[64:65]
	v_ashrrev_i32_e32 v189, 31, v188
	global_load_dwordx4 v[192:195], v[64:65], off
	global_load_dwordx4 v[206:209], v[64:65], off offset:16
	v_lshlrev_b64 v[64:65], 7, v[188:189]
	v_lshl_add_u64 v[64:65], v[168:169], 0, v[64:65]
	global_load_dwordx4 v[212:215], v[64:65], off
	global_load_dwordx4 v[216:219], v[64:65], off offset:16
	v_or_b32_e32 v186, 32, v190
	v_ashrrev_i32_e32 v187, 31, v186
	v_lshlrev_b64 v[64:65], 7, v[186:187]
	v_or_b32_e32 v184, 48, v190
	v_lshl_add_u64 v[64:65], v[168:169], 0, v[64:65]
	v_ashrrev_i32_e32 v185, 31, v184
	global_load_dwordx4 v[220:223], v[64:65], off
	global_load_dwordx4 v[224:227], v[64:65], off offset:16
	v_lshlrev_b64 v[64:65], 7, v[184:185]
	v_lshl_add_u64 v[64:65], v[168:169], 0, v[64:65]
	global_load_dwordx4 v[228:231], v[64:65], off
	global_load_dwordx4 v[232:235], v[64:65], off offset:16
	v_lshl_or_b32 v180, s13, 7, v200
	v_and_b32_e32 v65, 64, v204
	v_xor_b32_e32 v64, 16, v204
	v_ashrrev_i32_e32 v181, 31, v180
	v_add_u32_e32 v65, 64, v65
	v_xor_b32_e32 v66, 32, v204
	v_lshlrev_b64 v[182:183], 2, v[180:181]
	v_cmp_lt_i32_e32 vcc, v64, v65
	v_lshl_add_u64 v[88:89], s[16:17], 0, v[182:183]
	v_lshl_add_u64 v[72:73], s[18:19], 0, v[182:183]
	v_cndmask_b32_e32 v64, v204, v64, vcc
	v_cmp_lt_i32_e32 vcc, v66, v65
	v_lshl_add_u64 v[74:75], v[88:89], 0, s[30:31]
	v_lshl_add_u64 v[76:77], v[88:89], 0, s[34:35]
	v_cndmask_b32_e32 v65, v204, v66, vcc
	v_add_co_u32_e32 v90, vcc, 0x5000, v88
	v_lshlrev_b32_e32 v187, 2, v64
	s_nop 0
	v_addc_co_u32_e32 v91, vcc, 0, v89, vcc
	v_add_co_u32_e32 v92, vcc, 0xb000, v88
	v_lshlrev_b32_e32 v185, 2, v65
	s_nop 0
	v_addc_co_u32_e32 v93, vcc, 0, v89, vcc
	global_load_dwordx4 v[64:67], v[88:89], off offset:16
	global_load_dwordx4 v[80:83], v[88:89], off
	global_load_dwordx4 v[68:71], v[72:73], off offset:16
	global_load_dwordx4 v[84:87], v[72:73], off
	s_nop 0
	global_load_dwordx4 v[72:75], v[74:75], off offset:16
	s_nop 0
	global_load_dwordx4 v[76:79], v[76:77], off offset:16
	s_nop 0
	global_load_dwordx4 v[88:91], v[90:91], off offset:2048
	s_nop 0
	global_load_dwordx4 v[92:95], v[92:93], off
	v_mov_b32_e32 v211, 0
	v_mov_b32_e32 v205, 0
	s_waitcnt vmcnt(0)
	v_mov_b32_e32 v196, v192
	v_mov_b32_e32 v197, v206
	v_mov_b32_e32 v206, v193
	v_mov_b32_e32 v192, v194
	v_mov_b32_e32 v193, v208
	v_mov_b32_e32 v208, v195
	v_pk_add_f32 v[194:195], v[196:197], v[206:207]
	v_pk_add_f32 v[192:193], v[192:193], v[208:209]
	v_mov_b32_e32 v196, v212
	v_mov_b32_e32 v197, v216
	v_mov_b32_e32 v216, v213
	v_mov_b32_e32 v206, v214
	v_mov_b32_e32 v207, v218
	v_mov_b32_e32 v218, v215
	v_pk_add_f32 v[192:193], v[194:195], v[192:193]
	v_pk_add_f32 v[194:195], v[196:197], v[216:217]
	v_pk_add_f32 v[196:197], v[206:207], v[218:219]
	v_mov_b32_e32 v208, v220
	v_pk_add_f32 v[194:195], v[194:195], v[196:197]
	v_mov_b32_e32 v197, v192
	v_mov_b32_e32 v196, v194
	v_mov_b32_e32 v192, v195
	v_pk_add_f32 v[192:193], v[196:197], v[192:193]
	ds_bpermute_b32 v195, v187, v193
	ds_bpermute_b32 v194, v187, v192
	v_mov_b32_e32 v209, v224
	v_mov_b32_e32 v224, v221
	v_mov_b32_e32 v212, v222
	v_mov_b32_e32 v213, v226
	s_waitcnt lgkmcnt(0)
	v_pk_add_f32 v[192:193], v[192:193], v[194:195]
	ds_bpermute_b32 v195, v185, v193
	ds_bpermute_b32 v194, v185, v192
	v_mov_b32_e32 v226, v223
	v_mov_b32_e32 v196, v228
	v_mov_b32_e32 v197, v232
	v_mov_b32_e32 v232, v229
	s_waitcnt lgkmcnt(0)
; DI unsigned pack2(float lo, float hi) { f32x2 v = {lo, hi}; bf16v2 r = __builtin_convertvector(v, bf16v2); return __builtin_bit_cast(unsigned, r); }
; DI float silu_f(float x) { return x * sigmoid_f(x); }
; DI float dpp_ror1(float v) { return __int_as_float(__builtin_amdgcn_update_dpp(0, __float_as_int(v), 0x121, 0xf, 0xf, false)); }
; DI float dpp_ror2(float v) { return __int_as_float(__builtin_amdgcn_update_dpp(0, __float_as_int(v), 0x122, 0xf, 0xf, false)); }
;   DI void operator()(const f32x4 (&acc)[2][2][4][2], const Unit& u, int wr, int wc, int fr, int fq) const {
;     ...
;       for (int m = 0; m < 4; ++m) rsv[m] = row_rstd(ssq, row0 + 16 * m + fr, fq);
;       float p1[8], p2[8];
; #pragma unroll
;       for (int e = 0; e < 8; ++e) { p1[e] = 0.f; p2[e] = 0.f; }
; #pragma unroll
;       for (int m = 0; m < 4; ++m) {
;         float g[8], uu[8], a[8];
;         const float rs = rsv[m];
; #pragma unroll
;         for (int e = 0; e < 4; ++e) { g[e] = acc[ai][0][m][0][e] * rs; g[4 + e] = acc[ai][0][m][1][e] * rs; uu[e] = acc[ai][1][m][0][e] * rs; uu[4 + e] = acc[ai][1][m][1][e] * rs; }
; #pragma unroll
;         for (int e = 0; e < 8; ++e) {
;           const float x1 = dpp_ror1(g[e]), x2 = dpp_ror2(g[e]);
;           const float pr1 = (fr == 0) ? p1[e] : x1, pr2 = (fr < 2) ? p2[e] : x2;
;           a[e] = w2[e] * g[e] + w1[e] * pr1 + w0[e] * pr2 + bb[e];
;           p1[e] = x1; p2[e] = x2;
;         }
;         if (m == 0 && fr < 2) {
;           float* ha = headA + (size_t)(span * 2 + fr) * 5632 + col; float* hu = headU + (size_t)(span * 2 + fr) * 5632 + col;
;           *(f32x4*)ha = (f32x4){a[0], a[1], a[2], a[3]}; *(f32x4*)(ha + 4) = (f32x4){a[4], a[5], a[6], a[7]};
;           *(f32x4*)hu = (f32x4){uu[0], uu[1], uu[2], uu[3]}; *(f32x4*)(hu + 4) = (f32x4){uu[4], uu[5], uu[6], uu[7]};
;         } else {
;           u32x4 w;
;           w.x = pack2(silu_f(a[0]) * uu[0], silu_f(a[1]) * uu[1]);
;           w.y = pack2(silu_f(a[2]) * uu[2], silu_f(a[3]) * uu[3]);
;           w.z = pack2(silu_f(a[4]) * uu[4], silu_f(a[5]) * uu[5]);
;           w.w = pack2(silu_f(a[6]) * uu[6], silu_f(a[7]) * uu[7]);
;           *(u32x4*)(H + (size_t)(row0 + 16 * m + fr) * 5632 + col) = w;
	v_pk_add_f32 v[192:193], v[192:193], v[194:195]
	v_mov_b32_e32 v206, v230
	v_pk_fma_f32 v[192:193], v[192:193], s[36:37], v[178:179] op_sel_hi:[1,0,0]
	v_mov_b32_e32 v207, v234
	v_mul_f32_e32 v189, 0x4b800000, v193
	v_cmp_gt_f32_e64 s[12:13], s74, v193
	v_mov_b32_e32 v234, v231
	v_pk_add_f32 v[208:209], v[208:209], v[224:225]
	v_cndmask_b32_e64 v189, v193, v189, s[12:13]
	v_rsq_f32_e32 v189, v189
	v_pk_add_f32 v[212:213], v[212:213], v[226:227]
	v_pk_add_f32 v[196:197], v[196:197], v[232:233]
	v_pk_add_f32 v[194:195], v[206:207], v[234:235]
	v_mul_f32_e32 v191, 0x45800000, v189
	v_cndmask_b32_e64 v220, v189, v191, s[12:13]
	v_pk_add_f32 v[208:209], v[208:209], v[212:213]
	v_pk_add_f32 v[194:195], v[196:197], v[194:195]
	v_pk_mul_f32 v[156:157], v[156:157], v[220:221] op_sel_hi:[1,0]
	v_mov_b32_e32 v216, 0
	v_mov_b32_e32 v218, 0
	v_mov_b32_e32 v196, v194
	v_mov_b32_e32 v197, v208
	v_mov_b32_e32 v208, v195
	v_mov_b32_dpp v216, v156 row_ror:1 row_mask:0xf bank_mask:0xf
	v_mov_b32_dpp v218, v157 row_ror:1 row_mask:0xf bank_mask:0xf
	v_pk_add_f32 v[194:195], v[196:197], v[208:209]
	v_cndmask_b32_e64 v207, v218, 0, s[0:1]
	v_cndmask_b32_e64 v206, v216, 0, s[0:1]
	v_pk_mul_f32 v[158:159], v[158:159], v[220:221] op_sel_hi:[1,0]
	v_mov_b32_e32 v212, 0
	v_mov_b32_e32 v214, 0
	ds_bpermute_b32 v197, v187, v195
	ds_bpermute_b32 v196, v187, v194
	v_mov_b32_e32 v215, 0
	v_mov_b32_e32 v217, 0
	v_pk_mul_f32 v[206:207], v[88:89], v[206:207]
	v_mov_b32_dpp v212, v158 row_ror:1 row_mask:0xf bank_mask:0xf
	v_mov_b32_dpp v214, v159 row_ror:1 row_mask:0xf bank_mask:0xf
	v_mov_b32_dpp v215, v156 row_ror:2 row_mask:0xf bank_mask:0xf
	v_mov_b32_dpp v217, v157 row_ror:2 row_mask:0xf bank_mask:0xf
	v_pk_fma_f32 v[156:157], v[92:93], v[156:157], v[206:207]
	v_mov_b32_e32 v213, 0
	v_cndmask_b32_e64 v207, v214, 0, s[0:1]
	v_cndmask_b32_e64 v206, v212, 0, s[0:1]
	v_cndmask_b32_e64 v209, v217, 0, s[4:5]
	v_cndmask_b32_e64 v208, v215, 0, s[4:5]
	v_mov_b32_dpp v211, v158 row_ror:2 row_mask:0xf bank_mask:0xf
	v_mov_b32_dpp v213, v159 row_ror:2 row_mask:0xf bank_mask:0xf
	v_pk_mul_f32 v[206:207], v[90:91], v[206:207]
	v_pk_fma_f32 v[156:157], v[80:81], v[208:209], v[156:157]
	v_cndmask_b32_e64 v209, v213, 0, s[4:5]
	v_cndmask_b32_e64 v208, v211, 0, s[4:5]
	v_pk_fma_f32 v[158:159], v[94:95], v[158:159], v[206:207]
	v_pk_mul_f32 v[144:145], v[144:145], v[220:221] op_sel_hi:[1,0]
	v_pk_fma_f32 v[158:159], v[82:83], v[208:209], v[158:159]
	v_mov_b32_e32 v207, 0
	v_mov_b32_e32 v209, 0
	v_pk_mul_f32 v[146:147], v[146:147], v[220:221] op_sel_hi:[1,0]
	v_mov_b32_e32 v191, 0
	s_waitcnt lgkmcnt(0)
	v_pk_add_f32 v[194:195], v[194:195], v[196:197]
	v_mov_b32_dpp v207, v144 row_ror:1 row_mask:0xf bank_mask:0xf
	v_mov_b32_dpp v209, v145 row_ror:1 row_mask:0xf bank_mask:0xf
	v_mov_b32_dpp v191, v146 row_ror:1 row_mask:0xf bank_mask:0xf
	v_mov_b32_dpp v205, v147 row_ror:1 row_mask:0xf bank_mask:0xf
	ds_bpermute_b32 v197, v185, v195
	ds_bpermute_b32 v196, v185, v194
	v_pk_mul_f32 v[152:153], v[152:153], v[220:221] op_sel_hi:[1,0]
	v_pk_mul_f32 v[148:149], v[148:149], v[220:221] op_sel_hi:[1,0]
	v_pk_mul_f32 v[154:155], v[154:155], v[220:221] op_sel_hi:[1,0]
	v_pk_mul_f32 v[150:151], v[150:151], v[220:221] op_sel_hi:[1,0]
	v_mov_b32_e32 v206, 0
	v_mov_b32_e32 v208, 0
	v_cndmask_b32_e64 v223, v209, 0, s[0:1]
	v_cndmask_b32_e64 v222, v207, 0, s[0:1]
	v_mov_b32_e32 v189, 0
	v_mov_b32_e32 v193, 0
	v_cndmask_b32_e64 v221, v205, 0, s[0:1]
	v_cndmask_b32_e64 v220, v191, 0, s[0:1]
	v_mov_b32_dpp v206, v144 row_ror:2 row_mask:0xf bank_mask:0xf
	v_mov_b32_dpp v208, v145 row_ror:2 row_mask:0xf bank_mask:0xf
	v_pk_mul_f32 v[222:223], v[72:73], v[222:223]
	v_mov_b32_dpp v189, v146 row_ror:2 row_mask:0xf bank_mask:0xf
	v_mov_b32_dpp v193, v147 row_ror:2 row_mask:0xf bank_mask:0xf
	v_pk_mul_f32 v[220:221], v[74:75], v[220:221]
	v_cndmask_b32_e64 v225, v208, 0, s[4:5]
	v_cndmask_b32_e64 v224, v206, 0, s[4:5]
	v_pk_fma_f32 v[144:145], v[76:77], v[144:145], v[222:223]
	v_cndmask_b32_e64 v223, v193, 0, s[4:5]
	v_cndmask_b32_e64 v222, v189, 0, s[4:5]
	v_pk_fma_f32 v[146:147], v[78:79], v[146:147], v[220:221]
	v_pk_fma_f32 v[144:145], v[64:65], v[224:225], v[144:145]
	v_pk_fma_f32 v[146:147], v[66:67], v[222:223], v[146:147]
	v_cmp_gt_f32_e32 vcc, s74, v192
	v_pk_add_f32 v[156:157], v[84:85], v[156:157]
	v_pk_add_f32 v[158:159], v[86:87], v[158:159]
	v_pk_add_f32 v[144:145], v[68:69], v[144:145]
	v_pk_add_f32 v[146:147], v[70:71], v[146:147]
	s_and_saveexec_b64 s[12:13], s[10:11]
	s_xor_b64 s[12:13], exec, s[12:13]
	s_cbranch_execz .LBB0_1280
	v_mul_f32_e32 v219, 0xbfb8aa3b, v156
	v_exp_f32_e32 v219, v219
	v_mul_f32_e32 v220, 0xbfb8aa3b, v157
	v_exp_f32_e32 v220, v220
	v_mul_f32_e32 v222, 0xbfb8aa3b, v159
	v_add_f32_e32 v219, 1.0, v219
	v_exp_f32_e32 v223, v222
	v_add_f32_e32 v221, 1.0, v220
	v_rcp_f32_e32 v220, v219
	v_mul_f32_e32 v219, 0xbfb8aa3b, v158
	v_exp_f32_e32 v219, v219
	v_rcp_f32_e32 v221, v221
	v_add_f32_e32 v219, 1.0, v219
	v_rcp_f32_e32 v222, v219
	v_add_f32_e32 v219, 1.0, v223
	v_rcp_f32_e32 v223, v219
	v_pk_mul_f32 v[156:157], v[156:157], v[220:221]
	s_nop 0
	v_pk_mul_f32 v[152:153], v[152:153], v[156:157]
	v_pk_mul_f32 v[156:157], v[158:159], v[222:223]
	v_cvt_pk_bf16_f32 v152, v152, v153
	v_mul_f32_e32 v153, 0xbfb8aa3b, v144
	v_pk_mul_f32 v[154:155], v[154:155], v[156:157]
	v_exp_f32_e32 v156, v153
	v_mul_f32_e32 v153, 0xbfb8aa3b, v145
	v_exp_f32_e32 v157, v153
	v_cvt_pk_bf16_f32 v153, v154, v155
	v_add_f32_e32 v154, 1.0, v156
	v_mul_f32_e32 v156, 0xbfb8aa3b, v146
	v_add_f32_e32 v155, 1.0, v157
	v_mul_f32_e32 v157, 0xbfb8aa3b, v147
	v_exp_f32_e32 v156, v156
	v_exp_f32_e32 v157, v157
	v_rcp_f32_e32 v154, v154
	v_rcp_f32_e32 v155, v155
	v_add_f32_e32 v156, 1.0, v156
	v_add_f32_e32 v157, 1.0, v157
	v_rcp_f32_e32 v156, v156
	v_rcp_f32_e32 v157, v157
	v_pk_mul_f32 v[144:145], v[144:145], v[154:155]
	s_nop 0
	v_pk_mul_f32 v[144:145], v[148:149], v[144:145]
	s_nop 0
	v_cvt_pk_bf16_f32 v154, v144, v145
	v_pk_mul_f32 v[144:145], v[146:147], v[156:157]
	s_nop 0
	v_pk_mul_f32 v[144:145], v[150:151], v[144:145]
	s_nop 0
	v_cvt_pk_bf16_f32 v155, v144, v145
	v_mov_b64_e32 v[144:145], s[20:21]
	v_mad_i64_i32 v[144:145], s[14:15], v190, s75, v[144:145]
	v_lshl_add_u64 v[144:145], v[180:181], 1, v[144:145]
	global_store_dwordx4 v[144:145], v[152:155], off

; #define PG8_WAIT_V(n) asm volatile("s_waitcnt vmcnt(" #n ")" ::: "memory")
; #define PG8_BAR __builtin_amdgcn_s_barrier()
;   DI bool next(int i, Unit& u) const {
;     const long L = (long)i * G + c; if (L >= nwg) return false;
;     int wgid = (int)L; { const int q = nwg / NXCD, r = nwg % NXCD, xcd = wgid % NXCD, off = wgid / NXCD; wgid = (xcd < r ? xcd * (q + 1) : r * (q + 1) + (xcd - r) * q) + off; }
;     const int nig = WGM * nN, gid = wgid / nig, fm = gid * WGM, gsz = (nM - fm) < WGM ? (nM - fm) : WGM;
;     u.pm = fm + ((wgid % nig) % gsz); u.pn = (wgid % nig) / gsz; return true;
; template <class Epi, class Sched = StaticOrder>
; DI void gemm_phase(LAS unsigned char* lds, const Gemm g, const Sched& S, const Epi& E) {
;   const int tid = threadIdx.x, wid = __builtin_amdgcn_readfirstlane(tid >> 6), lane = tid & 63, wr = wid >> 2, wc = wid & 3, fr = lane & 15, fq = lane >> 4;
;   const int K = g.K, nt = K / BK;
;   unsigned voffA[2], voffB[2];
; #pragma unroll
;   for (int i = 0; i < 2; ++i) { int R, C; stage_rc(tid * 16 + i * 8192, R, C); const int Rb = Epi::PERM ? ((R & ~31) + perm32(R & 31)) : R;
;     voffA[i] = (unsigned)(R * K + C) * 2u; voffB[i] = (unsigned)(Rb * K + C) * 2u; }
;   const size_t kstep = (size_t)(BK * 2);
;   const size_t hstep = (size_t)HALF * K * 2;
;   const size_t tstep = 2 * hstep;
;   const unsigned ldsw = (unsigned)wid * 1024u;
;   const int aoff = lds_byte(wr * 64 + fr, fq * 8), boff = lds_byte(wc * 32 + fr, fq * 8);
;     ...
;   Unit cur, nxt; int ui = 0;
;   if (!S.next(0, cur)) return;
;   f32x4 acc[2][2][4][2];
; #pragma unroll
;   for (int a = 0; a < 2; ++a)
; #pragma unroll
;     for (int b = 0; b < 2; ++b)
; #pragma unroll
;       for (int m = 0; m < 4; ++m)
; #pragma unroll
;         for (int n = 0; n < 2; ++n) acc[a][b][m][n] = (f32x4){0.f, 0.f, 0.f, 0.f};
;   bf16x8 At[4][2], B0[2][2], B1[2][2];
;   const char* cA = (const char*)g.A + (size_t)cur.pm * tstep; const char* cB = (const char*)g.Bt + (size_t)cur.pn * tstep;
;   PG8_STAGE(PG8_SB(0, 0), cB, voffB); PG8_STAGE(PG8_SA(0, 0), cA, voffA); PG8_STAGE(PG8_SB(0, 1), cB + hstep, voffB); PG8_STAGE(PG8_SA(0, 1), cA + hstep, voffA);
;   if (wr == 1) PG8_BAR;
;   PG8_WAIT_V(4); PG8_BAR;
;   PG8_STAGE(PG8_SB(1, 0), cB + kstep, voffB); PG8_STAGE(PG8_SA(1, 0), cA + kstep, voffA); PG8_STAGE(PG8_SB(1, 1), cB + hstep + kstep, voffB);
;   PG8_WAIT_V(6); PG8_BAR;
.LBB0_1413:
	v_writelane_b32 v247, 1, 0
	s_add_i32 s0, 0, 0x20008
	v_mov_b32_e32 v0, s0
	ds_read_b32 v0, v0
	v_readfirstlane_b32 s23, v210
	s_waitcnt lgkmcnt(0)
	v_readfirstlane_b32 s22, v0
	s_cmpk_gt_i32 s22, 0x1ff
	s_cbranch_scc1 .LBB0_1429
	v_lshrrev_b32_e32 v0, 5, v210
	v_lshrrev_b32_e32 v2, 1, v210
	v_and_b32_e32 v0, 4, v0
	v_bfe_u32 v1, v210, 2, 2
	v_and_b32_e32 v2, 24, v2
	v_or3_b32 v0, v0, v1, v2
	v_lshlrev_b32_e32 v1, 4, v210
	v_add_u32_e32 v2, 0x2000, v1
	v_and_b32_e32 v4, 32, v210
	v_lshrrev_b32_e32 v2, 7, v2
	s_movk_i32 s0, 0xe0
	v_bitop3_b32 v8, v1, v4, 48 bitop3:0x6c
	v_and_b32_e32 v9, 64, v210
	v_and_or_b32 v3, v2, s0, v0
	v_or_b32_e32 v1, v8, v9
	v_mul_u32_u24_e32 v3, 0x1600, v3
	v_lshrrev_b32_e32 v1, 1, v1
	v_or_b32_e32 v3, v3, v1
	v_lshlrev_b32_e32 v128, 1, v3
	v_bfe_u32 v3, v210, 2, 4
	s_movk_i32 s0, 0xf0
	v_and_or_b32 v2, v2, s0, v3
	v_mul_u32_u24_e32 v10, 0x1600, v2
	v_or_b32_e32 v2, v10, v1
	s_add_u32 s24, s84, 0x10903600
	v_lshlrev_b32_e32 v130, 1, v2
	v_lshrrev_b32_e32 v2, 3, v210
	s_movk_i32 s0, 0x60
	s_addc_u32 s25, s85, 0
	v_and_or_b32 v0, v2, s0, v0
	s_add_u32 s26, s84, 0x8903600
	v_mul_u32_u24_e32 v0, 0x1600, v0
	s_addc_u32 s27, s85, 0
	v_or_b32_e32 v0, v0, v1
	s_movk_i32 s0, 0x70
	s_ashr_i32 s29, s22, 31
	v_lshlrev_b32_e32 v132, 1, v0
	v_and_or_b32 v0, v2, s0, v3
	s_lshr_b32 s0, s29, 29
	s_add_i32 s0, s22, s0
	s_ashr_i32 s3, s0, 3
	s_and_b32 s0, s0, -8
	s_sub_i32 s0, s22, s0
	s_lshr_b32 s4, s0, 31
	s_or_b32 s4, s4, 64
	s_mul_i32 s0, s4, s0
	s_add_i32 s0, s0, s3
	s_ashr_i32 s3, s0, 31
	s_lshr_b32 s3, s3, 26
	s_add_i32 s3, s0, s3
	s_ashr_i32 s4, s3, 6
	s_lshl_b32 s6, s4, 3
	s_sub_i32 s4, 64, s6
	s_min_u32 s7, s4, 8
	s_andn2_b32 s3, s3, 63
	v_mul_u32_u24_e32 v11, 0x1600, v0
	s_sub_i32 s3, s0, s3
	v_cvt_f32_ubyte0_e32 v2, s7
	v_or_b32_e32 v0, v1, v11
	v_cvt_f32_i32_e32 v1, s3
	v_rcp_iflag_f32_e32 v3, v2
	v_lshlrev_b32_e32 v134, 1, v0
	s_lshr_b32 s2, s23, 6
	s_ashr_i32 s0, s3, 30
	v_mul_f32_e32 v0, v1, v3
	v_trunc_f32_e32 v0, v0
	v_fma_f32 v1, -v0, v2, v1
	v_cvt_i32_f32_e32 v0, v0
	s_lshr_b32 s1, s23, 8
	s_lshl_b32 s28, s2, 10
	s_or_b32 s0, s0, 1
	v_cmp_ge_f32_e64 s[4:5], |v1|, v2
	s_and_b64 s[4:5], s[4:5], exec
	s_cselect_b32 s0, s0, 0
	v_readfirstlane_b32 s4, v0
	s_add_i32 s0, s4, s0
	s_mul_i32 s4, s0, s7
	s_sub_i32 s3, s3, s4
	s_sext_i32_i8 s3, s3
	s_bfe_i64 s[4:5], s[0:1], 0x80000
	s_add_i32 s43, s6, s3
	s_mul_hi_i32 s5, s4, 0x2c0000
	s_mul_i32 s4, s4, 0x2c0000
	s_add_u32 s18, s26, s4
	s_addc_u32 s19, s27, s5
	s_add_i32 s30, s28, 0
	s_add_i32 m0, s30, 0x10000
	s_mul_i32 s6, s43, 0x2c0000
	global_load_lds_dwordx4 v132, s[18:19]
	s_add_i32 m0, s30, 0x12000
	s_mul_hi_i32 s3, s43, 0x2c0000
	s_add_u32 s16, s24, s6
	global_load_lds_dwordx4 v128, s[18:19]
	s_addc_u32 s17, s25, s3
	s_mov_b32 m0, s30
	s_add_i32 s31, s30, 0x2000
	global_load_lds_dwordx4 v134, s[16:17]
	s_mov_b32 m0, s31
	s_add_u32 s4, s18, 0x160000
	global_load_lds_dwordx4 v130, s[16:17]
	s_addc_u32 s5, s19, 0
	s_add_i32 m0, s30, 0x14000
	v_mov_b32_e32 v133, 0
	global_load_lds_dwordx4 v132, s[4:5]
	s_add_i32 m0, s30, 0x16000
	v_mov_b32_e32 v129, v133
	global_load_lds_dwordx4 v128, s[4:5]
	s_add_u32 s4, s16, 0x160000
	s_addc_u32 s5, s17, 0
	s_add_i32 s33, s30, 0x4000
	s_mov_b32 m0, s33
	s_add_i32 s34, s30, 0x6000
	global_load_lds_dwordx4 v134, s[4:5]
	s_mov_b32 m0, s34
	v_mov_b32_e32 v135, v133
	global_load_lds_dwordx4 v130, s[4:5]
	v_mov_b32_e32 v131, v133
	v_lshl_add_u64 v[6:7], s[18:19], 0, v[132:133]
	v_lshl_add_u64 v[4:5], s[18:19], 0, v[128:129]
	v_lshl_add_u64 v[2:3], s[16:17], 0, v[134:135]
	v_lshl_add_u64 v[0:1], s[16:17], 0, v[130:131]
	s_cmp_lg_u32 s1, 1
	s_mov_b64 s[6:7], 0x160000
	s_cbranch_scc1 .LBB0_1416
	s_barrier

; #define PG8_STAGE(bufoff, gbase, voff) do { _Pragma("unroll") for (int _i = 0; _i < 2; ++_i) \
;     __builtin_amdgcn_global_load_lds((const unsigned*)((const char*)(gbase) + (voff)[_i]), (LAS unsigned*)(lds + (bufoff) + ldsw + _i * 8192), 16, 0, 0); } while (0)
; #define PG8_LDA(dst, b, h) do { _Pragma("unroll") for (int m = 0; m < 4; ++m) _Pragma("unroll") for (int k = 0; k < 2; ++k) dst[m][k] = *(const LAS bf16x8*)(lds + PG8_SA(b, h) + aoff + m * 2048 + k * 1024); } while (0)
; #define PG8_LDB(dst, b, h) do { _Pragma("unroll") for (int n = 0; n < 2; ++n) _Pragma("unroll") for (int k = 0; k < 2; ++k) dst[n][k] = *(const LAS bf16x8*)(lds + PG8_SB(b, h) + boff + n * 2048 + k * 1024); } while (0)
; #define PG8_MMA(ai, bj, At, Bt) do { __builtin_amdgcn_s_setprio(1); _Pragma("unroll") for (int m = 0; m < 4; ++m) _Pragma("unroll") for (int n = 0; n < 2; ++n) _Pragma("unroll") for (int k = 0; k < 2; ++k) \
;     acc[ai][bj][m][n] = __builtin_amdgcn_mfma_f32_16x16x32_bf16(Bt[n][k], At[m][k], acc[ai][bj][m][n], 0, 0, 0); __builtin_amdgcn_s_setprio(0); } while (0)
; #define PG8_WAIT_V(n) asm volatile("s_waitcnt vmcnt(" #n ")" ::: "memory")
; #define PG8_WAIT_L(n) asm volatile("s_waitcnt lgkmcnt(" #n ")" ::: "memory")
; #define PG8_BAR __builtin_amdgcn_s_barrier()
; #define PG8_SCHED __builtin_amdgcn_sched_barrier(0)
; template <class Epi, class Sched = StaticOrder>
; DI void gemm_phase(LAS unsigned char* lds, const Gemm g, const Sched& S, const Epi& E) {
;     ...
;     for (int t = 0; t < nt; t += 2) {
;       const bool last = (t == nt - 2);
;       const char* a1 = cA + (size_t)(t + 1) * kstep;
;       const char* a2 = last ? nA : cA + (size_t)(t + 2) * kstep; const char* b2 = last ? nB : cB + (size_t)(t + 2) * kstep;
;       const char* a3 = a2 + kstep; const char* b3 = b2 + kstep;
;       PG8_LDB(B0, 0, 0); PG8_SCHED; PG8_LDA(At, 0, 0); PG8_STAGE(PG8_SA(1, 1), a1 + hstep, voffA);
;       PG8_WAIT_L(8); PG8_BAR; PG8_WAIT_L(0); PG8_MMA(0, 0, At, B0); PG8_BAR; PG8_SCHED;
;       PG8_LDB(B1, 0, 1); PG8_STAGE(PG8_SB(0, 0), b2, voffB);
;       PG8_BAR; PG8_WAIT_L(0); PG8_MMA(0, 1, At, B1); PG8_BAR;
;       PG8_LDA(At, 0, 1); PG8_STAGE(PG8_SA(0, 0), a2, voffA);
;       PG8_BAR; PG8_WAIT_L(0); PG8_MMA(1, 0, At, B0); PG8_BAR; PG8_SCHED;
;       PG8_STAGE(PG8_SB(0, 1), b2 + hstep, voffB);
;       PG8_WAIT_V(6); PG8_BAR; PG8_MMA(1, 1, At, B1); PG8_BAR;
.LBB0_1424:
	ds_read_b128 v[144:147], v159
	ds_read_b128 v[148:151], v159 offset:1024
	ds_read_b128 v[152:155], v159 offset:2048
	ds_read_b128 v[162:165], v159 offset:3072
	s_add_u32 s18, s16, 0xffea0080
	s_addc_u32 s19, s17, -1
	s_cmpk_eq_i32 s47, 0x54
	s_cselect_b32 s21, s3, s19
	s_cselect_b32 s20, s2, s18
	s_cselect_b32 s19, s5, s46
	s_cselect_b32 s18, s4, s45
	s_add_i32 m0, s30, 0xc000
	ds_read_b128 v[166:169], v160
	ds_read_b128 v[170:173], v160 offset:1024
	ds_read_b128 v[174:177], v160 offset:2048
	ds_read_b128 v[178:181], v160 offset:3072
	ds_read_b128 v[182:185], v160 offset:4096
	ds_read_b128 v[186:189], v160 offset:5120
	ds_read_b128 v[190:193], v160 offset:6144
	ds_read_b128 v[194:197], v160 offset:7168
	global_load_lds_dwordx4 v136, s[16:17]
	s_add_i32 m0, s30, 0xe000
	s_nop 0
	global_load_lds_dwordx4 v138, s[16:17]
	s_waitcnt lgkmcnt(0)
	s_setprio 1
	s_barrier
	v_mfma_f32_16x16x32_bf16 v[124:127], v[144:147], v[166:169], v[124:127]
	v_mfma_f32_16x16x32_bf16 v[120:123], v[152:155], v[166:169], v[120:123]
	v_mfma_f32_16x16x32_bf16 v[116:119], v[144:147], v[174:177], v[116:119]
	v_mfma_f32_16x16x32_bf16 v[112:115], v[152:155], v[174:177], v[112:115]
	v_mfma_f32_16x16x32_bf16 v[104:107], v[144:147], v[182:185], v[104:107]
	v_mfma_f32_16x16x32_bf16 v[96:99], v[152:155], v[182:185], v[96:99]
	v_mfma_f32_16x16x32_bf16 v[88:91], v[144:147], v[190:193], v[88:91]
	v_mfma_f32_16x16x32_bf16 v[80:83], v[152:155], v[190:193], v[80:83]
	v_mfma_f32_16x16x32_bf16 v[124:127], v[148:151], v[170:173], v[124:127]
	v_mfma_f32_16x16x32_bf16 v[120:123], v[162:165], v[170:173], v[120:123]
	v_mfma_f32_16x16x32_bf16 v[116:119], v[148:151], v[178:181], v[116:119]
	v_mfma_f32_16x16x32_bf16 v[112:115], v[162:165], v[178:181], v[112:115]
	v_mfma_f32_16x16x32_bf16 v[104:107], v[148:151], v[186:189], v[104:107]
	v_mfma_f32_16x16x32_bf16 v[96:99], v[162:165], v[186:189], v[96:99]
	v_mfma_f32_16x16x32_bf16 v[88:91], v[148:151], v[194:197], v[88:91]
	v_mfma_f32_16x16x32_bf16 v[80:83], v[162:165], v[194:197], v[80:83]
	s_barrier
	s_setprio 0
	s_add_i32 s48, s39, s28
	s_add_u32 s98, s18, 0x80
	s_addc_u32 s99, s19, 0
	s_add_u32 s100, s20, 0x80
	s_addc_u32 s101, s21, 0
	s_mov_b32 m0, s48
	ds_read_b128 v[198:201], v161
	ds_read_b128 v[202:205], v161 offset:1024
	ds_read_b128 v[206:209], v161 offset:2048
	ds_read_b128 v[210:213], v161 offset:3072
	global_load_lds_dwordx4 v132, s[18:19]
	s_add_i32 m0, s48, 0x2000
	s_nop 0
	global_load_lds_dwordx4 v128, s[18:19]
	s_waitcnt lgkmcnt(0)
	s_setprio 1
	s_barrier
	v_mfma_f32_16x16x32_bf16 v[108:111], v[198:201], v[166:169], v[108:111]
	v_mfma_f32_16x16x32_bf16 v[100:103], v[206:209], v[166:169], v[100:103]
	v_mfma_f32_16x16x32_bf16 v[92:95], v[198:201], v[174:177], v[92:95]
	v_mfma_f32_16x16x32_bf16 v[84:87], v[206:209], v[174:177], v[84:87]
	v_mfma_f32_16x16x32_bf16 v[76:79], v[198:201], v[182:185], v[76:79]
	v_mfma_f32_16x16x32_bf16 v[72:75], v[206:209], v[182:185], v[72:75]
	v_mfma_f32_16x16x32_bf16 v[68:71], v[198:201], v[190:193], v[68:71]
	v_mfma_f32_16x16x32_bf16 v[64:67], v[206:209], v[190:193], v[64:67]
	v_mfma_f32_16x16x32_bf16 v[108:111], v[202:205], v[170:173], v[108:111]
	v_mfma_f32_16x16x32_bf16 v[100:103], v[210:213], v[170:173], v[100:103]
	v_mfma_f32_16x16x32_bf16 v[92:95], v[202:205], v[178:181], v[92:95]
	v_mfma_f32_16x16x32_bf16 v[84:87], v[210:213], v[178:181], v[84:87]
	v_mfma_f32_16x16x32_bf16 v[76:79], v[202:205], v[186:189], v[76:79]
	v_mfma_f32_16x16x32_bf16 v[72:75], v[210:213], v[186:189], v[72:75]
	v_mfma_f32_16x16x32_bf16 v[68:71], v[202:205], v[194:197], v[68:71]
	v_mfma_f32_16x16x32_bf16 v[64:67], v[210:213], v[194:197], v[64:67]
	s_barrier
	s_setprio 0
	s_mov_b32 m0, s30
	ds_read_b128 v[166:169], v160 offset:16384
	ds_read_b128 v[170:173], v160 offset:17408
	ds_read_b128 v[174:177], v160 offset:18432
	ds_read_b128 v[178:181], v160 offset:19456
	ds_read_b128 v[182:185], v160 offset:20480
	ds_read_b128 v[186:189], v160 offset:21504
	ds_read_b128 v[190:193], v160 offset:22528
	ds_read_b128 v[194:197], v160 offset:23552
	global_load_lds_dwordx4 v134, s[20:21]
	s_mov_b32 m0, s31
	s_nop 0
	global_load_lds_dwordx4 v130, s[20:21]
	s_waitcnt lgkmcnt(0)
	s_setprio 1
	s_barrier
	v_mfma_f32_16x16x32_bf16 v[60:63], v[144:147], v[166:169], v[60:63]
	v_mfma_f32_16x16x32_bf16 v[56:59], v[152:155], v[166:169], v[56:59]
	v_mfma_f32_16x16x32_bf16 v[52:55], v[144:147], v[174:177], v[52:55]
	v_mfma_f32_16x16x32_bf16 v[44:47], v[152:155], v[174:177], v[44:47]
	v_mfma_f32_16x16x32_bf16 v[36:39], v[144:147], v[182:185], v[36:39]
	v_mfma_f32_16x16x32_bf16 v[28:31], v[152:155], v[182:185], v[28:31]
	v_mfma_f32_16x16x32_bf16 v[20:23], v[144:147], v[190:193], v[20:23]
	v_mfma_f32_16x16x32_bf16 v[12:15], v[152:155], v[190:193], v[12:15]
	v_mfma_f32_16x16x32_bf16 v[60:63], v[148:151], v[170:173], v[60:63]
	v_mfma_f32_16x16x32_bf16 v[56:59], v[162:165], v[170:173], v[56:59]
	v_mfma_f32_16x16x32_bf16 v[52:55], v[148:151], v[178:181], v[52:55]
	v_mfma_f32_16x16x32_bf16 v[44:47], v[162:165], v[178:181], v[44:47]
	v_mfma_f32_16x16x32_bf16 v[36:39], v[148:151], v[186:189], v[36:39]
	v_mfma_f32_16x16x32_bf16 v[28:31], v[162:165], v[186:189], v[28:31]
	v_mfma_f32_16x16x32_bf16 v[20:23], v[148:151], v[194:197], v[20:23]
	v_mfma_f32_16x16x32_bf16 v[12:15], v[162:165], v[194:197], v[12:15]
	s_barrier
	s_setprio 0
	s_add_u32 s48, s18, 0x160000
	s_addc_u32 s49, s19, 0
	s_add_i32 s50, s40, s28
	s_mov_b32 m0, s50
	s_nop 0
	global_load_lds_dwordx4 v132, s[48:49]
	s_add_i32 m0, s50, 0x2000
	s_nop 0
	global_load_lds_dwordx4 v128, s[48:49]
	v_readlane_b32 vcc_lo, v247, 0
	s_cmp_eq_u32 s47, vcc_lo
	s_cbranch_scc1 .Lsw_7
	s_waitcnt vmcnt(6)
; #define PG8_STAGE(bufoff, gbase, voff) do { _Pragma("unroll") for (int _i = 0; _i < 2; ++_i) \
;     __builtin_amdgcn_global_load_lds((const unsigned*)((const char*)(gbase) + (voff)[_i]), (LAS unsigned*)(lds + (bufoff) + ldsw + _i * 8192), 16, 0, 0); } while (0)
; #define PG8_LDA(dst, b, h) do { _Pragma("unroll") for (int m = 0; m < 4; ++m) _Pragma("unroll") for (int k = 0; k < 2; ++k) dst[m][k] = *(const LAS bf16x8*)(lds + PG8_SA(b, h) + aoff + m * 2048 + k * 1024); } while (0)
; #define PG8_LDB(dst, b, h) do { _Pragma("unroll") for (int n = 0; n < 2; ++n) _Pragma("unroll") for (int k = 0; k < 2; ++k) dst[n][k] = *(const LAS bf16x8*)(lds + PG8_SB(b, h) + boff + n * 2048 + k * 1024); } while (0)
; #define PG8_MMA(ai, bj, At, Bt) do { __builtin_amdgcn_s_setprio(1); _Pragma("unroll") for (int m = 0; m < 4; ++m) _Pragma("unroll") for (int n = 0; n < 2; ++n) _Pragma("unroll") for (int k = 0; k < 2; ++k) \
;     acc[ai][bj][m][n] = __builtin_amdgcn_mfma_f32_16x16x32_bf16(Bt[n][k], At[m][k], acc[ai][bj][m][n], 0, 0, 0); __builtin_amdgcn_s_setprio(0); } while (0)
; #define PG8_WAIT_V(n) asm volatile("s_waitcnt vmcnt(" #n ")" ::: "memory")
; #define PG8_WAIT_L(n) asm volatile("s_waitcnt lgkmcnt(" #n ")" ::: "memory")
; #define PG8_BAR __builtin_amdgcn_s_barrier()
; #define PG8_SCHED __builtin_amdgcn_sched_barrier(0)
; template <class Epi, class Sched = StaticOrder>
; DI void gemm_phase(LAS unsigned char* lds, const Gemm g, const Sched& S, const Epi& E) {
;     ...
;       PG8_WAIT_V(6); PG8_BAR; PG8_MMA(1, 1, At, B1); PG8_BAR;
;       PG8_LDB(B0, 1, 0); PG8_SCHED; PG8_LDA(At, 1, 0); PG8_STAGE(PG8_SA(0, 1), a2 + hstep, voffA);
;       PG8_WAIT_L(8); PG8_BAR; PG8_WAIT_L(0); PG8_MMA(0, 0, At, B0); PG8_BAR; PG8_SCHED;
;       PG8_LDB(B1, 1, 1); PG8_STAGE(PG8_SB(1, 0), b3, voffB);
;       PG8_BAR; PG8_WAIT_L(0); PG8_MMA(0, 1, At, B1); PG8_BAR;
;       PG8_LDA(At, 1, 1); PG8_STAGE(PG8_SA(1, 0), a3, voffA);
;       PG8_BAR; PG8_WAIT_L(0); PG8_MMA(1, 0, At, B0); PG8_BAR; PG8_SCHED;
;       PG8_STAGE(PG8_SB(1, 1), b3 + hstep, voffB);
;       PG8_WAIT_V(6); PG8_BAR; PG8_MMA(1, 1, At, B1); PG8_BAR;
.Lsw_7:
	s_setprio 1
	s_barrier
	v_mfma_f32_16x16x32_bf16 v[48:51], v[198:201], v[166:169], v[48:51]
	v_mfma_f32_16x16x32_bf16 v[40:43], v[206:209], v[166:169], v[40:43]
	v_mfma_f32_16x16x32_bf16 v[32:35], v[198:201], v[174:177], v[32:35]
	v_mfma_f32_16x16x32_bf16 v[24:27], v[206:209], v[174:177], v[24:27]
	v_mfma_f32_16x16x32_bf16 v[16:19], v[198:201], v[182:185], v[16:19]
	v_mfma_f32_16x16x32_bf16 v[8:11], v[206:209], v[182:185], v[8:11]
	v_mfma_f32_16x16x32_bf16 v[4:7], v[198:201], v[190:193], v[4:7]
	v_mfma_f32_16x16x32_bf16 v[0:3], v[206:209], v[190:193], v[0:3]
	v_mfma_f32_16x16x32_bf16 v[48:51], v[202:205], v[170:173], v[48:51]
	v_mfma_f32_16x16x32_bf16 v[40:43], v[210:213], v[170:173], v[40:43]
	v_mfma_f32_16x16x32_bf16 v[32:35], v[202:205], v[178:181], v[32:35]
	v_mfma_f32_16x16x32_bf16 v[24:27], v[210:213], v[178:181], v[24:27]
	v_mfma_f32_16x16x32_bf16 v[16:19], v[202:205], v[186:189], v[16:19]
	v_mfma_f32_16x16x32_bf16 v[8:11], v[210:213], v[186:189], v[8:11]
	v_mfma_f32_16x16x32_bf16 v[4:7], v[202:205], v[194:197], v[4:7]
	v_mfma_f32_16x16x32_bf16 v[0:3], v[210:213], v[194:197], v[0:3]
	s_barrier
	s_setprio 0
	s_add_i32 s48, 0, 0x18000
	v_add_u32_e32 v162, s48, v157
	ds_read_b128 v[144:147], v162
	ds_read_b128 v[148:151], v162 offset:1024
	ds_read_b128 v[152:155], v162 offset:2048
	ds_read_b128 v[162:165], v162 offset:3072
	s_add_u32 s20, s20, 0x160000
	s_addc_u32 s21, s21, 0
	s_mov_b32 m0, s33
	ds_read_b128 v[166:169], v160 offset:32768
	ds_read_b128 v[170:173], v160 offset:33792
	ds_read_b128 v[174:177], v160 offset:34816
	ds_read_b128 v[178:181], v160 offset:35840
	ds_read_b128 v[182:185], v160 offset:36864
	ds_read_b128 v[186:189], v160 offset:37888
	ds_read_b128 v[190:193], v160 offset:38912
	ds_read_b128 v[194:197], v160 offset:39936
	global_load_lds_dwordx4 v134, s[20:21]
	s_mov_b32 m0, s34
	s_nop 0
	global_load_lds_dwordx4 v130, s[20:21]
	s_waitcnt lgkmcnt(0)
	s_setprio 1
	s_barrier
	v_mfma_f32_16x16x32_bf16 v[124:127], v[144:147], v[166:169], v[124:127]
	v_mfma_f32_16x16x32_bf16 v[120:123], v[152:155], v[166:169], v[120:123]
	v_mfma_f32_16x16x32_bf16 v[116:119], v[144:147], v[174:177], v[116:119]
	v_mfma_f32_16x16x32_bf16 v[112:115], v[152:155], v[174:177], v[112:115]
	v_mfma_f32_16x16x32_bf16 v[104:107], v[144:147], v[182:185], v[104:107]
	v_mfma_f32_16x16x32_bf16 v[96:99], v[152:155], v[182:185], v[96:99]
	v_mfma_f32_16x16x32_bf16 v[88:91], v[144:147], v[190:193], v[88:91]
	v_mfma_f32_16x16x32_bf16 v[80:83], v[152:155], v[190:193], v[80:83]
	v_mfma_f32_16x16x32_bf16 v[124:127], v[148:151], v[170:173], v[124:127]
	v_mfma_f32_16x16x32_bf16 v[120:123], v[162:165], v[170:173], v[120:123]
	v_mfma_f32_16x16x32_bf16 v[116:119], v[148:151], v[178:181], v[116:119]
	v_mfma_f32_16x16x32_bf16 v[112:115], v[162:165], v[178:181], v[112:115]
	v_mfma_f32_16x16x32_bf16 v[104:107], v[148:151], v[186:189], v[104:107]
	v_mfma_f32_16x16x32_bf16 v[96:99], v[162:165], v[186:189], v[96:99]
	v_mfma_f32_16x16x32_bf16 v[88:91], v[148:151], v[194:197], v[88:91]
	v_mfma_f32_16x16x32_bf16 v[80:83], v[162:165], v[194:197], v[80:83]
	s_barrier
	s_setprio 0
	s_add_i32 s20, 0, 0x1c000
	s_add_i32 s21, s48, s28
	v_add_u32_e32 v210, s20, v157
	s_mov_b32 m0, s21
	ds_read_b128 v[198:201], v210
	ds_read_b128 v[202:205], v210 offset:1024
	ds_read_b128 v[206:209], v210 offset:2048
	ds_read_b128 v[210:213], v210 offset:3072
	global_load_lds_dwordx4 v132, s[98:99]
	s_add_i32 m0, s21, 0x2000
	s_nop 0
	global_load_lds_dwordx4 v128, s[98:99]
	s_waitcnt lgkmcnt(0)
	s_setprio 1
	s_barrier
	v_mfma_f32_16x16x32_bf16 v[108:111], v[198:201], v[166:169], v[108:111]
	v_mfma_f32_16x16x32_bf16 v[100:103], v[206:209], v[166:169], v[100:103]
	v_mfma_f32_16x16x32_bf16 v[92:95], v[198:201], v[174:177], v[92:95]
	v_mfma_f32_16x16x32_bf16 v[84:87], v[206:209], v[174:177], v[84:87]
	v_mfma_f32_16x16x32_bf16 v[76:79], v[198:201], v[182:185], v[76:79]
	v_mfma_f32_16x16x32_bf16 v[72:75], v[206:209], v[182:185], v[72:75]
	v_mfma_f32_16x16x32_bf16 v[68:71], v[198:201], v[190:193], v[68:71]
	v_mfma_f32_16x16x32_bf16 v[64:67], v[206:209], v[190:193], v[64:67]
	v_mfma_f32_16x16x32_bf16 v[108:111], v[202:205], v[170:173], v[108:111]
	v_mfma_f32_16x16x32_bf16 v[100:103], v[210:213], v[170:173], v[100:103]
	v_mfma_f32_16x16x32_bf16 v[92:95], v[202:205], v[178:181], v[92:95]
	v_mfma_f32_16x16x32_bf16 v[84:87], v[210:213], v[178:181], v[84:87]
	v_mfma_f32_16x16x32_bf16 v[76:79], v[202:205], v[186:189], v[76:79]
	v_mfma_f32_16x16x32_bf16 v[72:75], v[210:213], v[186:189], v[72:75]
	v_mfma_f32_16x16x32_bf16 v[68:71], v[202:205], v[194:197], v[68:71]
	v_mfma_f32_16x16x32_bf16 v[64:67], v[210:213], v[194:197], v[64:67]
	s_barrier
	s_setprio 0
	s_mov_b32 m0, s35
	ds_read_b128 v[166:169], v160 offset:49152
	ds_read_b128 v[170:173], v160 offset:50176
	ds_read_b128 v[174:177], v160 offset:51200
	ds_read_b128 v[178:181], v160 offset:52224
	ds_read_b128 v[182:185], v160 offset:53248
	ds_read_b128 v[186:189], v160 offset:54272
	ds_read_b128 v[190:193], v160 offset:55296
	ds_read_b128 v[194:197], v160 offset:56320
	global_load_lds_dwordx4 v134, s[100:101]
	s_mov_b32 m0, s36
	s_nop 0
	global_load_lds_dwordx4 v130, s[100:101]
	s_waitcnt lgkmcnt(0)
	s_setprio 1
	s_barrier
	v_mfma_f32_16x16x32_bf16 v[60:63], v[144:147], v[166:169], v[60:63]
	v_mfma_f32_16x16x32_bf16 v[56:59], v[152:155], v[166:169], v[56:59]
	v_mfma_f32_16x16x32_bf16 v[52:55], v[144:147], v[174:177], v[52:55]
	v_mfma_f32_16x16x32_bf16 v[44:47], v[152:155], v[174:177], v[44:47]
	v_mfma_f32_16x16x32_bf16 v[36:39], v[144:147], v[182:185], v[36:39]
	v_mfma_f32_16x16x32_bf16 v[28:31], v[152:155], v[182:185], v[28:31]
	v_mfma_f32_16x16x32_bf16 v[20:23], v[144:147], v[190:193], v[20:23]
	v_mfma_f32_16x16x32_bf16 v[12:15], v[152:155], v[190:193], v[12:15]
	v_mfma_f32_16x16x32_bf16 v[60:63], v[148:151], v[170:173], v[60:63]
	v_mfma_f32_16x16x32_bf16 v[56:59], v[162:165], v[170:173], v[56:59]
	v_mfma_f32_16x16x32_bf16 v[52:55], v[148:151], v[178:181], v[52:55]
	v_mfma_f32_16x16x32_bf16 v[44:47], v[162:165], v[178:181], v[44:47]
	v_mfma_f32_16x16x32_bf16 v[36:39], v[148:151], v[186:189], v[36:39]
	v_mfma_f32_16x16x32_bf16 v[28:31], v[162:165], v[186:189], v[28:31]
	v_mfma_f32_16x16x32_bf16 v[20:23], v[148:151], v[194:197], v[20:23]
	v_mfma_f32_16x16x32_bf16 v[12:15], v[162:165], v[194:197], v[12:15]
	s_barrier
	s_setprio 0
	s_add_u32 s18, s18, 0x160080
	s_addc_u32 s19, s19, 0
	s_add_i32 s20, s20, s28
	s_mov_b32 m0, s20
	s_nop 0
	global_load_lds_dwordx4 v132, s[18:19]
	s_add_i32 m0, s20, 0x2000
	s_nop 0
	global_load_lds_dwordx4 v128, s[18:19]
	s_waitcnt vmcnt(6)
	s_cmpk_eq_i32 s47, 0x54
	s_cbranch_scc0 .Lxs_7
	s_add_i32 m0, s30, 0xc000
	s_nop 0
	global_load_lds_dwordx4 v136, s[100:101]
	s_add_i32 m0, s30, 0xe000
	s_nop 0
	global_load_lds_dwordx4 v138, s[100:101]
; #define PG8_STAGE(bufoff, gbase, voff) do { _Pragma("unroll") for (int _i = 0; _i < 2; ++_i) \
;     __builtin_amdgcn_global_load_lds((const unsigned*)((const char*)(gbase) + (voff)[_i]), (LAS unsigned*)(lds + (bufoff) + ldsw + _i * 8192), 16, 0, 0); } while (0)
; #define PG8_MMA(ai, bj, At, Bt) do { __builtin_amdgcn_s_setprio(1); _Pragma("unroll") for (int m = 0; m < 4; ++m) _Pragma("unroll") for (int n = 0; n < 2; ++n) _Pragma("unroll") for (int k = 0; k < 2; ++k) \
;     acc[ai][bj][m][n] = __builtin_amdgcn_mfma_f32_16x16x32_bf16(Bt[n][k], At[m][k], acc[ai][bj][m][n], 0, 0, 0); __builtin_amdgcn_s_setprio(0); } while (0)
; #define PG8_WAIT_V(n) asm volatile("s_waitcnt vmcnt(" #n ")" ::: "memory")
; #define PG8_WAIT_L(n) asm volatile("s_waitcnt lgkmcnt(" #n ")" ::: "memory")
; #define PG8_BAR __builtin_amdgcn_s_barrier()
; #define PG8_SCHED __builtin_amdgcn_sched_barrier(0)
;   DI void operator()(const f32x4 (&acc)[2][2][4][2], const Unit& u, int wr, int wc, int fr, int fq) const {
;     const int row0 = u.pm * BM + wr * 64 + fr, col0 = u.pn * BM + wc * 32 + 8 * fq;
; #pragma unroll
;     for (int ai = 0; ai < 2; ++ai) {
;       f32x4 bv[4][2][2];
; #pragma unroll
;       for (int m = 0; m < 4; ++m)
; #pragma unroll
;         for (int bj = 0; bj < 2; ++bj) {
;           const float* bp = base + (size_t)(row0 + ai * HALF + m * 16) * 2048 + col0 + bj * HALF;
;           bv[m][bj][0] = *(const f32x4*)bp; bv[m][bj][1] = *(const f32x4*)(bp + 4);
;         }
; #pragma unroll
;       for (int m = 0; m < 4; ++m) {
;         const int row = row0 + ai * HALF + m * 16;
;         const size_t off = (size_t)row * 2048 + col0;
;         float ss = 0.f;
; #pragma unroll
;         for (int bj = 0; bj < 2; ++bj) {
;           const f32x4 v0 = acc[ai][bj][m][0] + bv[m][bj][0], v1 = acc[ai][bj][m][1] + bv[m][bj][1];
;           *(f32x4*)(C + off + bj * HALF) = v0; *(f32x4*)(C + off + bj * HALF + 4) = v1;
; template <class Epi, class Sched = StaticOrder>
; DI void gemm_phase(LAS unsigned char* lds, const Gemm g, const Sched& S, const Epi& E) {
;     ...
;       PG8_BAR; PG8_WAIT_L(0); PG8_MMA(1, 0, At, B0); PG8_BAR; PG8_SCHED;
;       PG8_STAGE(PG8_SB(1, 1), b3 + hstep, voffB);
;       PG8_WAIT_V(6); PG8_BAR; PG8_MMA(1, 1, At, B1); PG8_BAR;
;     }
;     E(acc, cur, wr, wc, fr, fq);
;     if (!has_next) break;
.Lxs_7:
	s_add_i32 s47, s47, 2
	s_add_u32 s16, s16, 0x100
	s_addc_u32 s17, s17, 0
	s_add_u32 s45, s45, 0x100
	s_addc_u32 s46, s46, 0
	s_cmpk_gt_u32 s47, 0x55
	s_setprio 1
	s_barrier
	v_mfma_f32_16x16x32_bf16 v[48:51], v[198:201], v[166:169], v[48:51]
	v_mfma_f32_16x16x32_bf16 v[40:43], v[206:209], v[166:169], v[40:43]
	v_mfma_f32_16x16x32_bf16 v[32:35], v[198:201], v[174:177], v[32:35]
	v_mfma_f32_16x16x32_bf16 v[24:27], v[206:209], v[174:177], v[24:27]
	v_mfma_f32_16x16x32_bf16 v[16:19], v[198:201], v[182:185], v[16:19]
	v_mfma_f32_16x16x32_bf16 v[8:11], v[206:209], v[182:185], v[8:11]
	v_mfma_f32_16x16x32_bf16 v[4:7], v[198:201], v[190:193], v[4:7]
	v_mfma_f32_16x16x32_bf16 v[0:3], v[206:209], v[190:193], v[0:3]
	v_mfma_f32_16x16x32_bf16 v[48:51], v[202:205], v[170:173], v[48:51]
	v_mfma_f32_16x16x32_bf16 v[40:43], v[210:213], v[170:173], v[40:43]
	v_mfma_f32_16x16x32_bf16 v[32:35], v[202:205], v[178:181], v[32:35]
	v_mfma_f32_16x16x32_bf16 v[24:27], v[210:213], v[178:181], v[24:27]
	v_mfma_f32_16x16x32_bf16 v[16:19], v[202:205], v[186:189], v[16:19]
	v_mfma_f32_16x16x32_bf16 v[8:11], v[210:213], v[186:189], v[8:11]
	v_mfma_f32_16x16x32_bf16 v[4:7], v[202:205], v[194:197], v[4:7]
	v_mfma_f32_16x16x32_bf16 v[0:3], v[210:213], v[194:197], v[0:3]
	s_barrier
	s_setprio 0
	s_cbranch_scc0 .LBB0_1424
	v_writelane_b32 v247, -2, 0
	v_lshl_or_b32 v144, s44, 8, v158
	v_lshl_add_u32 v154, s43, 8, v156
	v_ashrrev_i32_e32 v145, 31, v144
	v_lshlrev_b64 v[144:145], 2, v[144:145]
	v_ashrrev_i32_e32 v155, 31, v154
	v_lshl_add_u64 v[146:147], s[54:55], 0, v[144:145]
	v_lshlrev_b64 v[148:149], 13, v[154:155]
	v_or_b32_e32 v174, 16, v154
	v_lshl_add_u64 v[170:171], v[146:147], 0, v[148:149]
	v_ashrrev_i32_e32 v175, 31, v174
	global_load_dwordx4 v[150:153], v[170:171], off offset:16
	global_load_dwordx4 v[162:165], v[170:171], off
	global_load_dwordx4 v[166:169], v[170:171], off offset:528
	s_nop 0
	global_load_dwordx4 v[170:173], v[170:171], off offset:512
	v_lshlrev_b64 v[222:223], 13, v[174:175]
	v_or_b32_e32 v190, 32, v154
	v_lshl_add_u64 v[186:187], v[146:147], 0, v[222:223]
	v_ashrrev_i32_e32 v191, 31, v190
	global_load_dwordx4 v[174:177], v[186:187], off offset:16
	global_load_dwordx4 v[178:181], v[186:187], off
	global_load_dwordx4 v[182:185], v[186:187], off offset:528
	s_nop 0
	global_load_dwordx4 v[186:189], v[186:187], off offset:512
	v_lshlrev_b64 v[224:225], 13, v[190:191]
	v_or_b32_e32 v154, 48, v154
	v_lshl_add_u64 v[202:203], v[146:147], 0, v[224:225]
	v_ashrrev_i32_e32 v155, 31, v154
	global_load_dwordx4 v[190:193], v[202:203], off offset:16
	global_load_dwordx4 v[194:197], v[202:203], off
	global_load_dwordx4 v[198:201], v[202:203], off offset:528
	s_nop 0
	global_load_dwordx4 v[202:205], v[202:203], off offset:512
	v_lshlrev_b64 v[154:155], 13, v[154:155]
	v_lshl_add_u64 v[218:219], v[146:147], 0, v[154:155]
	global_load_dwordx4 v[206:209], v[218:219], off offset:16
	global_load_dwordx4 v[210:213], v[218:219], off
	global_load_dwordx4 v[214:217], v[218:219], off offset:528
	s_nop 0
	global_load_dwordx4 v[218:221], v[218:219], off offset:512
	s_and_b64 vcc, exec, s[0:1]
	s_mov_b32 s44, s41
	s_mov_b32 s43, s42
	s_mov_b64 s[18:19], s[4:5]
	s_mov_b64 s[16:17], s[2:3]
	s_waitcnt vmcnt(0)
; DI unsigned pack2(float lo, float hi) { f32x2 v = {lo, hi}; bf16v2 r = __builtin_convertvector(v, bf16v2); return __builtin_bit_cast(unsigned, r); }
; #define PG8_WAIT_V(n) asm volatile("s_waitcnt vmcnt(" #n ")" ::: "memory")
; #define PG8_BAR __builtin_amdgcn_s_barrier()
;   DI void operator()(const f32x4 (&acc)[2][2][4][2], const Unit& u, int wr, int wc, int fr, int fq) const {
;     ...
;       for (int m = 0; m < 4; ++m) {
;         const int row = row0 + ai * HALF + m * 16;
;         const size_t off = (size_t)row * 2048 + col0;
;         float ss = 0.f;
; #pragma unroll
;         for (int bj = 0; bj < 2; ++bj) {
;           const f32x4 v0 = acc[ai][bj][m][0] + bv[m][bj][0], v1 = acc[ai][bj][m][1] + bv[m][bj][1];
;           *(f32x4*)(C + off + bj * HALF) = v0; *(f32x4*)(C + off + bj * HALF + 4) = v1;
;           if (xb) {
;             u32x4 w; w.x = pack2(v0[0], v0[1]); w.y = pack2(v0[2], v0[3]); w.z = pack2(v1[0], v1[1]); w.w = pack2(v1[2], v1[3]);
;             *(u32x4*)(xb + off + bj * HALF) = w;
; template <class Epi, class Sched = StaticOrder>
; DI void gemm_phase(LAS unsigned char* lds, const Gemm g, const Sched& S, const Epi& E) {
;     ...
;     E(acc, cur, wr, wc, fr, fq);
;     if (!has_next) break;
; #pragma unroll
;     for (int a = 0; a < 2; ++a)
; #pragma unroll
;       for (int b = 0; b < 2; ++b)
; #pragma unroll
;         for (int m = 0; m < 4; ++m)
; #pragma unroll
;           for (int n = 0; n < 2; ++n) acc[a][b][m][n] = (f32x4){0.f, 0.f, 0.f, 0.f};
;     cur = nxt; cA = nA; cB = nB; ++ui;
;   }
;   PG8_WAIT_V(0);
;   if (wr == 0) PG8_BAR;
;   PG8_BAR;
	v_pk_add_f32 v[120:121], v[120:121], v[150:151]
	v_lshl_add_u64 v[150:151], s[54:55], 0, v[148:149]
	v_pk_add_f32 v[126:127], v[126:127], v[164:165]
	v_pk_add_f32 v[124:125], v[124:125], v[162:163]
	v_lshl_add_u64 v[150:151], v[150:151], 0, v[144:145]
	v_pk_add_f32 v[110:111], v[110:111], v[172:173]
	v_pk_add_f32 v[108:109], v[108:109], v[170:171]
	v_pk_add_f32 v[122:123], v[122:123], v[152:153]
	global_store_dwordx4 v[150:151], v[124:127], off
	global_store_dwordx4 v[150:151], v[120:123], off offset:16
	v_pk_add_f32 v[102:103], v[102:103], v[168:169]
	v_pk_add_f32 v[100:101], v[100:101], v[166:167]
	global_store_dwordx4 v[150:151], v[108:111], off offset:512
	global_store_dwordx4 v[150:151], v[100:103], off offset:528
	v_pk_add_f32 v[94:95], v[94:95], v[188:189]
	v_pk_add_f32 v[108:109], v[112:113], v[174:175]
	v_lshl_add_u64 v[112:113], s[54:55], 0, v[222:223]
	v_pk_add_f32 v[102:103], v[118:119], v[180:181]
	v_pk_add_f32 v[100:101], v[116:117], v[178:179]
	v_lshl_add_u64 v[112:113], v[112:113], 0, v[144:145]
	v_pk_add_f32 v[92:93], v[92:93], v[186:187]
	v_pk_add_f32 v[110:111], v[114:115], v[176:177]
	global_store_dwordx4 v[112:113], v[100:103], off
	global_store_dwordx4 v[112:113], v[108:111], off offset:16
	v_pk_add_f32 v[86:87], v[86:87], v[184:185]
	v_pk_add_f32 v[84:85], v[84:85], v[182:183]
	global_store_dwordx4 v[112:113], v[92:95], off offset:512
	global_store_dwordx4 v[112:113], v[84:87], off offset:528
	v_pk_add_f32 v[78:79], v[78:79], v[204:205]
	v_pk_add_f32 v[92:93], v[96:97], v[190:191]
	v_lshl_add_u64 v[96:97], s[54:55], 0, v[224:225]
	v_pk_add_f32 v[86:87], v[106:107], v[196:197]
	v_pk_add_f32 v[84:85], v[104:105], v[194:195]
	v_lshl_add_u64 v[96:97], v[96:97], 0, v[144:145]
	v_pk_add_f32 v[76:77], v[76:77], v[202:203]
	v_pk_add_f32 v[94:95], v[98:99], v[192:193]
	global_store_dwordx4 v[96:97], v[84:87], off
	global_store_dwordx4 v[96:97], v[92:95], off offset:16
	v_pk_add_f32 v[74:75], v[74:75], v[200:201]
	v_pk_add_f32 v[72:73], v[72:73], v[198:199]
	global_store_dwordx4 v[96:97], v[76:79], off offset:512
	global_store_dwordx4 v[96:97], v[72:75], off offset:528
	v_pk_add_f32 v[70:71], v[70:71], v[220:221]
	v_pk_add_f32 v[76:77], v[80:81], v[206:207]
	v_lshl_add_u64 v[80:81], s[54:55], 0, v[154:155]
	v_pk_add_f32 v[74:75], v[90:91], v[212:213]
	v_pk_add_f32 v[72:73], v[88:89], v[210:211]
	v_lshl_add_u64 v[80:81], v[80:81], 0, v[144:145]
	v_pk_add_f32 v[68:69], v[68:69], v[218:219]
	v_pk_add_f32 v[64:65], v[64:65], v[214:215]
	v_lshl_add_u64 v[154:155], v[148:149], 0, s[10:11]
	v_pk_add_f32 v[78:79], v[82:83], v[208:209]
	global_store_dwordx4 v[80:81], v[72:75], off
	global_store_dwordx4 v[80:81], v[76:79], off offset:16
	v_pk_add_f32 v[66:67], v[66:67], v[216:217]
	global_store_dwordx4 v[80:81], v[68:71], off offset:512
	global_store_dwordx4 v[80:81], v[64:67], off offset:528
	v_lshl_add_u64 v[152:153], v[148:149], 0, s[12:13]
	v_lshl_add_u64 v[150:151], v[148:149], 0, s[14:15]
	v_lshl_add_u64 v[64:65], v[146:147], 0, v[154:155]
	global_load_dwordx4 v[108:111], v[64:65], off offset:16
	global_load_dwordx4 v[120:123], v[64:65], off
	global_load_dwordx4 v[92:95], v[64:65], off offset:528
	global_load_dwordx4 v[100:103], v[64:65], off offset:512
	v_lshl_add_u64 v[64:65], v[146:147], 0, v[152:153]
	global_load_dwordx4 v[88:91], v[64:65], off offset:16
	global_load_dwordx4 v[96:99], v[64:65], off
	global_load_dwordx4 v[76:79], v[64:65], off offset:528
	global_load_dwordx4 v[84:87], v[64:65], off offset:512
	v_lshl_add_u64 v[68:69], v[146:147], 0, v[150:151]
	global_load_dwordx4 v[72:75], v[68:69], off offset:16
	global_load_dwordx4 v[80:83], v[68:69], off
	global_load_dwordx4 v[64:67], v[68:69], off offset:528
	s_nop 0
	global_load_dwordx4 v[68:71], v[68:69], off offset:512
	v_lshl_add_u64 v[148:149], v[148:149], 0, s[6:7]
	v_lshl_add_u64 v[112:113], v[146:147], 0, v[148:149]
	global_load_dwordx4 v[116:119], v[112:113], off offset:16
	global_load_dwordx4 v[124:127], v[112:113], off
	global_load_dwordx4 v[104:107], v[112:113], off offset:528
	s_nop 0
	global_load_dwordx4 v[112:115], v[112:113], off offset:512
	s_waitcnt vmcnt(0)
	v_pk_add_f32 v[56:57], v[56:57], v[108:109]
	v_lshl_add_u64 v[108:109], s[54:55], 0, v[154:155]
	v_pk_add_f32 v[62:63], v[62:63], v[122:123]
	v_pk_add_f32 v[60:61], v[60:61], v[120:121]
	v_lshl_add_u64 v[108:109], v[108:109], 0, v[144:145]
	v_pk_add_f32 v[50:51], v[50:51], v[102:103]
	v_pk_add_f32 v[48:49], v[48:49], v[100:101]
	v_pk_add_f32 v[58:59], v[58:59], v[110:111]
	global_store_dwordx4 v[108:109], v[60:63], off
	global_store_dwordx4 v[108:109], v[56:59], off offset:16
	v_pk_add_f32 v[42:43], v[42:43], v[94:95]
	v_pk_add_f32 v[40:41], v[40:41], v[92:93]
	global_store_dwordx4 v[108:109], v[48:51], off offset:512
	global_store_dwordx4 v[108:109], v[40:43], off offset:528
	v_pk_add_f32 v[34:35], v[34:35], v[86:87]
	v_lshl_add_u64 v[48:49], s[54:55], 0, v[152:153]
	v_pk_add_f32 v[42:43], v[54:55], v[98:99]
	v_pk_add_f32 v[40:41], v[52:53], v[96:97]
	v_lshl_add_u64 v[48:49], v[48:49], 0, v[144:145]
	v_pk_add_f32 v[32:33], v[32:33], v[84:85]
	v_pk_add_f32 v[46:47], v[46:47], v[90:91]
	v_pk_add_f32 v[44:45], v[44:45], v[88:89]
	global_store_dwordx4 v[48:49], v[40:43], off
	global_store_dwordx4 v[48:49], v[44:47], off offset:16
	v_pk_add_f32 v[26:27], v[26:27], v[78:79]
	v_pk_add_f32 v[24:25], v[24:25], v[76:77]
	global_store_dwordx4 v[48:49], v[32:35], off offset:512
	global_store_dwordx4 v[48:49], v[24:27], off offset:528
	v_pk_add_f32 v[18:19], v[18:19], v[70:71]
	v_lshl_add_u64 v[32:33], s[54:55], 0, v[150:151]
	v_pk_add_f32 v[26:27], v[38:39], v[82:83]
	v_pk_add_f32 v[24:25], v[36:37], v[80:81]
	v_lshl_add_u64 v[32:33], v[32:33], 0, v[144:145]
	v_pk_add_f32 v[16:17], v[16:17], v[68:69]
	v_pk_add_f32 v[30:31], v[30:31], v[74:75]
	v_pk_add_f32 v[28:29], v[28:29], v[72:73]
	global_store_dwordx4 v[32:33], v[24:27], off
	global_store_dwordx4 v[32:33], v[28:31], off offset:16
	v_pk_add_f32 v[10:11], v[10:11], v[66:67]
	v_pk_add_f32 v[8:9], v[8:9], v[64:65]
	global_store_dwordx4 v[32:33], v[16:19], off offset:512
	global_store_dwordx4 v[32:33], v[8:11], off offset:528
	v_pk_add_f32 v[6:7], v[6:7], v[114:115]
	v_lshl_add_u64 v[16:17], s[54:55], 0, v[148:149]
	v_pk_add_f32 v[10:11], v[22:23], v[126:127]
	v_pk_add_f32 v[8:9], v[20:21], v[124:125]
	v_lshl_add_u64 v[16:17], v[16:17], 0, v[144:145]
	v_pk_add_f32 v[4:5], v[4:5], v[112:113]
	v_pk_add_f32 v[14:15], v[14:15], v[118:119]
	v_pk_add_f32 v[12:13], v[12:13], v[116:117]
	global_store_dwordx4 v[16:17], v[8:11], off
	global_store_dwordx4 v[16:17], v[12:15], off offset:16
	v_pk_add_f32 v[2:3], v[2:3], v[106:107]
	v_pk_add_f32 v[0:1], v[0:1], v[104:105]
	global_store_dwordx4 v[16:17], v[4:7], off offset:512
	global_store_dwordx4 v[16:17], v[0:3], off offset:528
	s_cbranch_vccz .LBB0_1417
	s_waitcnt vmcnt(0)
	s_cmpk_gt_u32 s23, 0xff
	s_cbranch_scc1 .LBB0_1428
	s_barrier

; __global__ __launch_bounds__(512) void mega(Params p) {
	.amdhsa_kernel _Z4mega6Params
		.amdhsa_group_segment_fixed_size 0
		.amdhsa_private_segment_fixed_size 0
		.amdhsa_kernarg_size 464
		.amdhsa_user_sgpr_count 2
		.amdhsa_user_sgpr_dispatch_ptr 0
		.amdhsa_user_sgpr_queue_ptr 0
		.amdhsa_user_sgpr_kernarg_segment_ptr 1
		.amdhsa_user_sgpr_dispatch_id 0
		.amdhsa_user_sgpr_kernarg_preload_length 0
		.amdhsa_user_sgpr_kernarg_preload_offset 0
		.amdhsa_user_sgpr_private_segment_size 0
		.amdhsa_uses_dynamic_stack 0
		.amdhsa_enable_private_segment 0
		.amdhsa_system_sgpr_workgroup_id_x 1
		.amdhsa_system_sgpr_workgroup_id_y 0
		.amdhsa_system_sgpr_workgroup_id_z 0
		.amdhsa_system_sgpr_workgroup_info 0
		.amdhsa_system_vgpr_workitem_id 2
		.amdhsa_next_free_vgpr 248
		.amdhsa_next_free_sgpr 102
		.amdhsa_accum_offset 248
		.amdhsa_reserve_vcc 1
		.amdhsa_float_round_mode_32 0
		.amdhsa_float_round_mode_16_64 0
		.amdhsa_float_denorm_mode_32 3
		.amdhsa_float_denorm_mode_16_64 3
		.amdhsa_dx10_clamp 1
		.amdhsa_ieee_mode 1
		.amdhsa_fp16_overflow 0
		.amdhsa_tg_split 0
		.amdhsa_exception_fp_ieee_invalid_op 0
		.amdhsa_exception_fp_denorm_src 0
		.amdhsa_exception_fp_ieee_div_zero 0
		.amdhsa_exception_fp_ieee_overflow 0
		.amdhsa_exception_fp_ieee_underflow 0
		.amdhsa_exception_fp_ieee_inexact 0
		.amdhsa_exception_int_div_zero 0
	.end_amdhsa_kernel

; __global__ __launch_bounds__(512) void mega(Params p) {
amdhsa.kernels:
  - .agpr_count:     0
    .args:
      - .offset:         0
        .size:           208
        .value_kind:     by_value
      - .offset:         208
        .size:           4
        .value_kind:     hidden_block_count_x
      - .offset:         212
        .size:           4
        .value_kind:     hidden_block_count_y
      - .offset:         216
        .size:           4
        .value_kind:     hidden_block_count_z
      - .offset:         220
        .size:           2
        .value_kind:     hidden_group_size_x
      - .offset:         222
        .size:           2
        .value_kind:     hidden_group_size_y
      - .offset:         224
        .size:           2
        .value_kind:     hidden_group_size_z
      - .offset:         226
        .size:           2
        .value_kind:     hidden_remainder_x
      - .offset:         228
        .size:           2
        .value_kind:     hidden_remainder_y
      - .offset:         230
        .size:           2
        .value_kind:     hidden_remainder_z
      - .offset:         248
        .size:           8
        .value_kind:     hidden_global_offset_x
      - .offset:         256
        .size:           8
        .value_kind:     hidden_global_offset_y
      - .offset:         264
        .size:           8
        .value_kind:     hidden_global_offset_z
      - .offset:         272
        .size:           2
        .value_kind:     hidden_grid_dims
      - .offset:         296
        .size:           8
        .value_kind:     hidden_multigrid_sync_arg
      - .offset:         328
        .size:           4
        .value_kind:     hidden_dynamic_lds_size
    .group_segment_fixed_size: 0
    .kernarg_segment_align: 8
    .kernarg_segment_size: 464
    .language:       OpenCL C
    .language_version:
      - 2
      - 0
    .max_flat_workgroup_size: 512
    .name:           _Z4mega6Params
    .private_segment_fixed_size: 0
    .sgpr_count:     108
    .sgpr_spill_count: 125
    .symbol:         _Z4mega6Params.kd
    .uniform_work_group_size: 1
    .uses_dynamic_stack: false
    .vgpr_count:     248
    .vgpr_spill_count: 0
    .wavefront_size: 64
